# K-loop tail straightened: continue path falls through to the barrier (one taken branch per iteration instead of two)
# baseline (speedup 1.0000x reference)
; #define G_STAGE(bufoff, gbase, o0, h64) do { \
;         __builtin_amdgcn_global_load_lds((const unsigned*)((const char*)(gbase) + (o0)), (LAS unsigned*)(lds + (bufoff) + ldsw), 16, 0, 0); \
;         __builtin_amdgcn_global_load_lds((const unsigned*)((const char*)(gbase) + (h64) + (o0)), (LAS unsigned*)(lds + (bufoff) + ldsw + 8192), 16, 0, 0); } while (0)
; #define G_LDA(dst, b, h) do { _Pragma("unroll") for (int m = 0; m < 4; ++m) _Pragma("unroll") for (int k = 0; k < 2; ++k) dst[m][k] = *(const LAS bf16x8*)(lds + G_SA(b, h) + aoff + m * 2048 + k * 1024); } while (0)
; #define G_LDB(dst, b, h) do { _Pragma("unroll") for (int n = 0; n < 2; ++n) _Pragma("unroll") for (int k = 0; k < 2; ++k) dst[n][k] = *(const LAS bf16x8*)(lds + G_SB(b, h) + boff + n * 2048 + k * 1024); } while (0)
; #define G_WAIT_V(n) asm volatile("s_waitcnt vmcnt(" #n ")" ::: "memory")
; #define G_WAIT_L(n) asm volatile("s_waitcnt lgkmcnt(" #n ")" ::: "memory")
; #define G_BAR __builtin_amdgcn_s_barrier()
; #define G_SCHED __builtin_amdgcn_sched_barrier(0)
;     ...
;         for (int t = 0; t < nt; t += 2) {
;             const bool last = (t == nt - 2);
;             const char* a1 = cA + (size_t)(t + 1) * ckA;
;             const char* a2 = last ? nA : cA + (size_t)(t + 2) * ckA; const char* b2 = last ? nB : cB + (size_t)(t + 2) * kB;
;             const char* a3 = a2 + ckA; const char* b3 = b2 + kB;
;             G_LDB(B0, 0, 0); G_SCHED; G_LDA(At, 0, 0); G_STAGE(G_SA(1, 1), a1 + chA, cA0, qA);
;             G_WAIT_L(8); G_BAR; G_WAIT_L(0); G_MMA(0, 0, At, B0); G_BAR; G_SCHED;
;             G_LDB(B1, 0, 1); G_STAGE(G_SB(0, 0), b2, cB0, qB);
;             G_BAR; G_WAIT_L(0); G_MMA(0, 1, At, B1); G_BAR;
;             G_LDA(At, 0, 1); G_STAGE(G_SA(0, 0), a2, cA0, qA);
;             G_BAR; G_WAIT_L(0); G_MMA(1, 0, At, B0); G_BAR; G_SCHED;
;             G_STAGE(G_SB(0, 1), b2 + chB, cB0, qB);
;             G_WAIT_V(6); G_BAR; G_MMA(1, 1, At, B1); G_BAR;
.LBB0_212:
	s_add_u32 s4, s2, 0xfffc0080
	s_addc_u32 s5, s3, -1
	s_add_i32 s41, 0, 0x10000
	ds_read_b128 v[136:139], v255 offset:0
	ds_read_b128 v[144:147], v255 offset:1024
	ds_read_b128 v[148:151], v255 offset:2048
	ds_read_b128 v[152:155], v255 offset:3072
	s_cmp_eq_u32 s23, 12
	s_cselect_b32 s43, s19, s5
	s_cselect_b32 s42, s18, s4
	s_cselect_b32 s51, s21, s22
	s_cselect_b32 s50, s20, s7
	s_add_i32 m0, s27, 0xc000
	ds_read_b128 v[156:159], v172
	ds_read_b128 v[160:163], v172 offset:1024
	ds_read_b128 v[174:177], v172 offset:2048
	ds_read_b128 v[178:181], v172 offset:3072
	ds_read_b128 v[182:185], v172 offset:4096
	ds_read_b128 v[196:199], v172 offset:5120
	ds_read_b128 v[200:203], v172 offset:6144
	ds_read_b128 v[204:207], v172 offset:7168
	global_load_lds_dwordx4 v142, s[2:3]
	s_add_i32 m0, s27, 0xe000
	s_nop 0
	s_add_u32 vcc_lo, s2, s0
	s_addc_u32 vcc_hi, s3, s1
	global_load_lds_dwordx4 v142, vcc
	s_waitcnt lgkmcnt(8)
	s_barrier
	s_waitcnt lgkmcnt(0)
	v_mfma_f32_16x16x32_bf16 v[132:135], v[136:139], v[156:159], v[132:135]
	v_mfma_f32_16x16x32_bf16 v[128:131], v[148:151], v[156:159], v[128:131]
	v_mfma_f32_16x16x32_bf16 v[116:119], v[136:139], v[174:177], v[116:119]
	v_mfma_f32_16x16x32_bf16 v[112:115], v[148:151], v[174:177], v[112:115]
	v_mfma_f32_16x16x32_bf16 v[100:103], v[136:139], v[182:185], v[100:103]
	v_mfma_f32_16x16x32_bf16 v[96:99], v[148:151], v[182:185], v[96:99]
	v_mfma_f32_16x16x32_bf16 v[84:87], v[136:139], v[200:203], v[84:87]
	v_mfma_f32_16x16x32_bf16 v[80:83], v[148:151], v[200:203], v[80:83]
	v_mfma_f32_16x16x32_bf16 v[132:135], v[144:147], v[160:163], v[132:135]
	v_mfma_f32_16x16x32_bf16 v[128:131], v[152:155], v[160:163], v[128:131]
	v_mfma_f32_16x16x32_bf16 v[116:119], v[144:147], v[178:181], v[116:119]
	v_mfma_f32_16x16x32_bf16 v[112:115], v[152:155], v[178:181], v[112:115]
	v_mfma_f32_16x16x32_bf16 v[100:103], v[144:147], v[196:199], v[100:103]
	v_mfma_f32_16x16x32_bf16 v[96:99], v[152:155], v[196:199], v[96:99]
	v_mfma_f32_16x16x32_bf16 v[84:87], v[144:147], v[204:207], v[84:87]
	v_mfma_f32_16x16x32_bf16 v[80:83], v[152:155], v[204:207], v[80:83]
	s_barrier
	s_add_i32 s4, 0, 0x14000
	s_add_i32 s5, s41, s26
	s_mov_b32 m0, s5
	ds_read_b128 v[208:211], v255 offset:16384
	ds_read_b128 v[212:215], v255 offset:17408
	ds_read_b128 v[216:219], v255 offset:18432
	ds_read_b128 v[220:223], v255 offset:19456
	global_load_lds_dwordx4 v140, s[50:51]
	s_add_i32 m0, s5, 0x2000
	s_nop 0
	s_add_u32 vcc_lo, s50, s0
	s_addc_u32 vcc_hi, s51, s1
	global_load_lds_dwordx4 v140, vcc
	s_barrier
	s_waitcnt lgkmcnt(0)
	v_mfma_f32_16x16x32_bf16 v[124:127], v[208:211], v[156:159], v[124:127]
	v_mfma_f32_16x16x32_bf16 v[120:123], v[216:219], v[156:159], v[120:123]
	v_mfma_f32_16x16x32_bf16 v[108:111], v[208:211], v[174:177], v[108:111]
	v_mfma_f32_16x16x32_bf16 v[104:107], v[216:219], v[174:177], v[104:107]
	v_mfma_f32_16x16x32_bf16 v[92:95], v[208:211], v[182:185], v[92:95]
	v_mfma_f32_16x16x32_bf16 v[88:91], v[216:219], v[182:185], v[88:91]
	v_mfma_f32_16x16x32_bf16 v[76:79], v[208:211], v[200:203], v[76:79]
	v_mfma_f32_16x16x32_bf16 v[72:75], v[216:219], v[200:203], v[72:75]
	v_mfma_f32_16x16x32_bf16 v[124:127], v[212:215], v[160:163], v[124:127]
	v_mfma_f32_16x16x32_bf16 v[120:123], v[220:223], v[160:163], v[120:123]
	v_mfma_f32_16x16x32_bf16 v[108:111], v[212:215], v[178:181], v[108:111]
	v_mfma_f32_16x16x32_bf16 v[104:107], v[220:223], v[178:181], v[104:107]
	v_mfma_f32_16x16x32_bf16 v[92:95], v[212:215], v[196:199], v[92:95]
	v_mfma_f32_16x16x32_bf16 v[88:91], v[220:223], v[196:199], v[88:91]
	v_mfma_f32_16x16x32_bf16 v[76:79], v[212:215], v[204:207], v[76:79]
	v_mfma_f32_16x16x32_bf16 v[72:75], v[220:223], v[204:207], v[72:75]
	s_barrier
	s_mov_b32 m0, s27
	ds_read_b128 v[156:159], v172 offset:16384
	ds_read_b128 v[160:163], v172 offset:17408
	ds_read_b128 v[174:177], v172 offset:18432
	ds_read_b128 v[178:181], v172 offset:19456
	ds_read_b128 v[182:185], v172 offset:20480
	ds_read_b128 v[196:199], v172 offset:21504
	ds_read_b128 v[200:203], v172 offset:22528
	ds_read_b128 v[204:207], v172 offset:23552
	global_load_lds_dwordx4 v2, s[42:43]
	s_mov_b32 m0, s28
	s_nop 0
	s_add_u32 vcc_lo, s42, s0
	s_addc_u32 vcc_hi, s43, s1
	global_load_lds_dwordx4 v2, vcc
	s_barrier
	s_waitcnt lgkmcnt(0)
	v_mfma_f32_16x16x32_bf16 v[68:71], v[136:139], v[156:159], v[68:71]
	v_mfma_f32_16x16x32_bf16 v[64:67], v[148:151], v[156:159], v[64:67]
	v_mfma_f32_16x16x32_bf16 v[52:55], v[136:139], v[174:177], v[52:55]
	v_mfma_f32_16x16x32_bf16 v[48:51], v[148:151], v[174:177], v[48:51]
	v_mfma_f32_16x16x32_bf16 v[36:39], v[136:139], v[182:185], v[36:39]
	v_mfma_f32_16x16x32_bf16 v[32:35], v[148:151], v[182:185], v[32:35]
	v_mfma_f32_16x16x32_bf16 v[20:23], v[136:139], v[200:203], v[20:23]
	v_mfma_f32_16x16x32_bf16 v[16:19], v[148:151], v[200:203], v[16:19]
	v_mfma_f32_16x16x32_bf16 v[68:71], v[144:147], v[160:163], v[68:71]
	v_mfma_f32_16x16x32_bf16 v[64:67], v[152:155], v[160:163], v[64:67]
	v_mfma_f32_16x16x32_bf16 v[52:55], v[144:147], v[178:181], v[52:55]
	v_mfma_f32_16x16x32_bf16 v[48:51], v[152:155], v[178:181], v[48:51]
	v_mfma_f32_16x16x32_bf16 v[36:39], v[144:147], v[196:199], v[36:39]
	v_mfma_f32_16x16x32_bf16 v[32:35], v[152:155], v[196:199], v[32:35]
	v_mfma_f32_16x16x32_bf16 v[20:23], v[144:147], v[204:207], v[20:23]
	v_mfma_f32_16x16x32_bf16 v[16:19], v[152:155], v[204:207], v[16:19]
	s_barrier
	s_add_i32 s4, s4, s26
	s_mov_b32 m0, s4
	s_nop 0
	s_add_u32 vcc_lo, s50, s52
	s_addc_u32 vcc_hi, s51, s53
	global_load_lds_dwordx4 v140, vcc
	s_add_i32 m0, s4, 0x2000
	s_nop 0
	s_add_u32 vcc_lo, s50, s54
	s_addc_u32 vcc_hi, s51, s55
	global_load_lds_dwordx4 v140, vcc
	s_waitcnt vmcnt(6)
	s_barrier
; #define G_STAGE(bufoff, gbase, o0, h64) do { \
;         __builtin_amdgcn_global_load_lds((const unsigned*)((const char*)(gbase) + (o0)), (LAS unsigned*)(lds + (bufoff) + ldsw), 16, 0, 0); \
;         __builtin_amdgcn_global_load_lds((const unsigned*)((const char*)(gbase) + (h64) + (o0)), (LAS unsigned*)(lds + (bufoff) + ldsw + 8192), 16, 0, 0); } while (0)
; #define G_LDA(dst, b, h) do { _Pragma("unroll") for (int m = 0; m < 4; ++m) _Pragma("unroll") for (int k = 0; k < 2; ++k) dst[m][k] = *(const LAS bf16x8*)(lds + G_SA(b, h) + aoff + m * 2048 + k * 1024); } while (0)
; #define G_LDB(dst, b, h) do { _Pragma("unroll") for (int n = 0; n < 2; ++n) _Pragma("unroll") for (int k = 0; k < 2; ++k) dst[n][k] = *(const LAS bf16x8*)(lds + G_SB(b, h) + boff + n * 2048 + k * 1024); } while (0)
; #define G_WAIT_V(n) asm volatile("s_waitcnt vmcnt(" #n ")" ::: "memory")
; #define G_WAIT_L(n) asm volatile("s_waitcnt lgkmcnt(" #n ")" ::: "memory")
; #define G_BAR __builtin_amdgcn_s_barrier()
; #define G_SCHED __builtin_amdgcn_sched_barrier(0)
;     ...
;             G_WAIT_V(6); G_BAR; G_MMA(1, 1, At, B1); G_BAR;
;             G_LDB(B0, 1, 0); G_SCHED; G_LDA(At, 1, 0); G_STAGE(G_SA(0, 1), a2 + chA, cA0, qA);
;             G_WAIT_L(8); G_BAR; G_WAIT_L(0); G_MMA(0, 0, At, B0); G_BAR; G_SCHED;
;             G_LDB(B1, 1, 1); G_STAGE(G_SB(1, 0), b3, cB0, qB);
;             G_BAR; G_WAIT_L(0); G_MMA(0, 1, At, B1); G_BAR;
	v_mfma_f32_16x16x32_bf16 v[60:63], v[208:211], v[156:159], v[60:63]
	v_mfma_f32_16x16x32_bf16 v[56:59], v[216:219], v[156:159], v[56:59]
	v_mfma_f32_16x16x32_bf16 v[44:47], v[208:211], v[174:177], v[44:47]
	v_mfma_f32_16x16x32_bf16 v[40:43], v[216:219], v[174:177], v[40:43]
	v_mfma_f32_16x16x32_bf16 v[28:31], v[208:211], v[182:185], v[28:31]
	v_mfma_f32_16x16x32_bf16 v[24:27], v[216:219], v[182:185], v[24:27]
	v_mfma_f32_16x16x32_bf16 v[12:15], v[208:211], v[200:203], v[12:15]
	v_mfma_f32_16x16x32_bf16 v[8:11], v[216:219], v[200:203], v[8:11]
	v_mfma_f32_16x16x32_bf16 v[60:63], v[212:215], v[160:163], v[60:63]
	v_mfma_f32_16x16x32_bf16 v[56:59], v[220:223], v[160:163], v[56:59]
	v_mfma_f32_16x16x32_bf16 v[44:47], v[212:215], v[178:181], v[44:47]
	v_mfma_f32_16x16x32_bf16 v[40:43], v[220:223], v[178:181], v[40:43]
	v_mfma_f32_16x16x32_bf16 v[28:31], v[212:215], v[196:199], v[28:31]
	v_mfma_f32_16x16x32_bf16 v[24:27], v[220:223], v[196:199], v[24:27]
	v_mfma_f32_16x16x32_bf16 v[12:15], v[212:215], v[204:207], v[12:15]
	v_mfma_f32_16x16x32_bf16 v[8:11], v[220:223], v[204:207], v[8:11]
	s_barrier
	s_add_i32 s4, 0, 0x18000
	ds_read_b128 v[136:139], v255 offset:32768
	ds_read_b128 v[144:147], v255 offset:33792
	ds_read_b128 v[148:151], v255 offset:34816
	ds_read_b128 v[152:155], v255 offset:35840
	s_mov_b32 m0, s29
	ds_read_b128 v[156:159], v172 offset:32768
	ds_read_b128 v[160:163], v172 offset:33792
	ds_read_b128 v[174:177], v172 offset:34816
	ds_read_b128 v[178:181], v172 offset:35840
	ds_read_b128 v[182:185], v172 offset:36864
	ds_read_b128 v[196:199], v172 offset:37888
	ds_read_b128 v[200:203], v172 offset:38912
	ds_read_b128 v[204:207], v172 offset:39936
	s_add_u32 vcc_lo, s42, s52
	s_addc_u32 vcc_hi, s43, s53
	global_load_lds_dwordx4 v2, vcc
	s_mov_b32 m0, s30
	s_nop 0
	s_add_u32 vcc_lo, s42, s54
	s_addc_u32 vcc_hi, s43, s55
	global_load_lds_dwordx4 v2, vcc
	s_waitcnt lgkmcnt(8)
	s_barrier
	s_waitcnt lgkmcnt(0)
	v_mfma_f32_16x16x32_bf16 v[132:135], v[136:139], v[156:159], v[132:135]
	v_mfma_f32_16x16x32_bf16 v[128:131], v[148:151], v[156:159], v[128:131]
	v_mfma_f32_16x16x32_bf16 v[116:119], v[136:139], v[174:177], v[116:119]
	v_mfma_f32_16x16x32_bf16 v[112:115], v[148:151], v[174:177], v[112:115]
	v_mfma_f32_16x16x32_bf16 v[100:103], v[136:139], v[182:185], v[100:103]
	v_mfma_f32_16x16x32_bf16 v[96:99], v[148:151], v[182:185], v[96:99]
	v_mfma_f32_16x16x32_bf16 v[84:87], v[136:139], v[200:203], v[84:87]
	v_mfma_f32_16x16x32_bf16 v[80:83], v[148:151], v[200:203], v[80:83]
	v_mfma_f32_16x16x32_bf16 v[132:135], v[144:147], v[160:163], v[132:135]
	v_mfma_f32_16x16x32_bf16 v[128:131], v[152:155], v[160:163], v[128:131]
	v_mfma_f32_16x16x32_bf16 v[116:119], v[144:147], v[178:181], v[116:119]
	v_mfma_f32_16x16x32_bf16 v[112:115], v[152:155], v[178:181], v[112:115]
	v_mfma_f32_16x16x32_bf16 v[100:103], v[144:147], v[196:199], v[100:103]
	v_mfma_f32_16x16x32_bf16 v[96:99], v[152:155], v[196:199], v[96:99]
	v_mfma_f32_16x16x32_bf16 v[84:87], v[144:147], v[204:207], v[84:87]
	v_mfma_f32_16x16x32_bf16 v[80:83], v[152:155], v[204:207], v[80:83]
	s_barrier
	s_add_i32 s5, 0, 0x1c000
	s_add_i32 s4, s4, s26
	s_mov_b32 m0, s4
	ds_read_b128 v[208:211], v255 offset:49152
	ds_read_b128 v[212:215], v255 offset:50176
	ds_read_b128 v[216:219], v255 offset:51200
	ds_read_b128 v[220:223], v255 offset:52224
	s_add_u32 vcc_lo, s50, s46
	s_addc_u32 vcc_hi, s51, s47
	global_load_lds_dwordx4 v140, vcc
	s_add_i32 m0, s4, 0x2000
	s_nop 0
	s_add_u32 vcc_lo, s50, s58
	s_addc_u32 vcc_hi, s51, s59
	global_load_lds_dwordx4 v140, vcc
	s_barrier
; #define G_STAGE(bufoff, gbase, o0, h64) do { \
;         __builtin_amdgcn_global_load_lds((const unsigned*)((const char*)(gbase) + (o0)), (LAS unsigned*)(lds + (bufoff) + ldsw), 16, 0, 0); \
;         __builtin_amdgcn_global_load_lds((const unsigned*)((const char*)(gbase) + (h64) + (o0)), (LAS unsigned*)(lds + (bufoff) + ldsw + 8192), 16, 0, 0); } while (0)
; #define G_LDA(dst, b, h) do { _Pragma("unroll") for (int m = 0; m < 4; ++m) _Pragma("unroll") for (int k = 0; k < 2; ++k) dst[m][k] = *(const LAS bf16x8*)(lds + G_SA(b, h) + aoff + m * 2048 + k * 1024); } while (0)
; #define G_WAIT_V(n) asm volatile("s_waitcnt vmcnt(" #n ")" ::: "memory")
; #define G_WAIT_L(n) asm volatile("s_waitcnt lgkmcnt(" #n ")" ::: "memory")
; #define G_BAR __builtin_amdgcn_s_barrier()
; #define G_SCHED __builtin_amdgcn_sched_barrier(0)
;     ...
;             G_BAR; G_WAIT_L(0); G_MMA(0, 1, At, B1); G_BAR;
;             G_LDA(At, 1, 1); G_STAGE(G_SA(1, 0), a3, cA0, qA);
;             G_BAR; G_WAIT_L(0); G_MMA(1, 0, At, B0); G_BAR; G_SCHED;
;             G_STAGE(G_SB(1, 1), b3 + chB, cB0, qB);
;             G_WAIT_V(6); G_BAR; G_MMA(1, 1, At, B1); G_BAR;
;         }
	s_waitcnt lgkmcnt(0)
	v_mfma_f32_16x16x32_bf16 v[124:127], v[208:211], v[156:159], v[124:127]
	v_mfma_f32_16x16x32_bf16 v[120:123], v[216:219], v[156:159], v[120:123]
	v_mfma_f32_16x16x32_bf16 v[108:111], v[208:211], v[174:177], v[108:111]
	v_mfma_f32_16x16x32_bf16 v[104:107], v[216:219], v[174:177], v[104:107]
	v_mfma_f32_16x16x32_bf16 v[92:95], v[208:211], v[182:185], v[92:95]
	v_mfma_f32_16x16x32_bf16 v[88:91], v[216:219], v[182:185], v[88:91]
	v_mfma_f32_16x16x32_bf16 v[76:79], v[208:211], v[200:203], v[76:79]
	v_mfma_f32_16x16x32_bf16 v[72:75], v[216:219], v[200:203], v[72:75]
	v_mfma_f32_16x16x32_bf16 v[124:127], v[212:215], v[160:163], v[124:127]
	v_mfma_f32_16x16x32_bf16 v[120:123], v[220:223], v[160:163], v[120:123]
	v_mfma_f32_16x16x32_bf16 v[108:111], v[212:215], v[178:181], v[108:111]
	v_mfma_f32_16x16x32_bf16 v[104:107], v[220:223], v[178:181], v[104:107]
	v_mfma_f32_16x16x32_bf16 v[92:95], v[212:215], v[196:199], v[92:95]
	v_mfma_f32_16x16x32_bf16 v[88:91], v[220:223], v[196:199], v[88:91]
	v_mfma_f32_16x16x32_bf16 v[76:79], v[212:215], v[204:207], v[76:79]
	v_mfma_f32_16x16x32_bf16 v[72:75], v[220:223], v[204:207], v[72:75]
	s_barrier
	s_mov_b32 m0, s31
	ds_read_b128 v[156:159], v172 offset:49152
	ds_read_b128 v[160:163], v172 offset:50176
	ds_read_b128 v[174:177], v172 offset:51200
	ds_read_b128 v[178:181], v172 offset:52224
	ds_read_b128 v[182:185], v172 offset:53248
	ds_read_b128 v[196:199], v172 offset:54272
	ds_read_b128 v[200:203], v172 offset:55296
	ds_read_b128 v[204:207], v172 offset:56320
	s_add_u32 vcc_lo, s42, s46
	s_addc_u32 vcc_hi, s43, s47
	global_load_lds_dwordx4 v2, vcc
	s_mov_b32 m0, s34
	s_nop 0
	s_add_u32 vcc_lo, s42, s58
	s_addc_u32 vcc_hi, s43, s59
	global_load_lds_dwordx4 v2, vcc
	s_barrier
	s_waitcnt lgkmcnt(0)
	v_mfma_f32_16x16x32_bf16 v[68:71], v[136:139], v[156:159], v[68:71]
	v_mfma_f32_16x16x32_bf16 v[64:67], v[148:151], v[156:159], v[64:67]
	v_mfma_f32_16x16x32_bf16 v[52:55], v[136:139], v[174:177], v[52:55]
	v_mfma_f32_16x16x32_bf16 v[48:51], v[148:151], v[174:177], v[48:51]
	v_mfma_f32_16x16x32_bf16 v[36:39], v[136:139], v[182:185], v[36:39]
	v_mfma_f32_16x16x32_bf16 v[32:35], v[148:151], v[182:185], v[32:35]
	v_mfma_f32_16x16x32_bf16 v[20:23], v[136:139], v[200:203], v[20:23]
	v_mfma_f32_16x16x32_bf16 v[16:19], v[148:151], v[200:203], v[16:19]
	v_mfma_f32_16x16x32_bf16 v[68:71], v[144:147], v[160:163], v[68:71]
	v_mfma_f32_16x16x32_bf16 v[64:67], v[152:155], v[160:163], v[64:67]
	v_mfma_f32_16x16x32_bf16 v[52:55], v[144:147], v[178:181], v[52:55]
	v_mfma_f32_16x16x32_bf16 v[48:51], v[152:155], v[178:181], v[48:51]
	v_mfma_f32_16x16x32_bf16 v[36:39], v[144:147], v[196:199], v[36:39]
	v_mfma_f32_16x16x32_bf16 v[32:35], v[152:155], v[196:199], v[32:35]
	v_mfma_f32_16x16x32_bf16 v[20:23], v[144:147], v[204:207], v[20:23]
	v_mfma_f32_16x16x32_bf16 v[16:19], v[152:155], v[204:207], v[16:19]
	s_barrier
	s_add_i32 s4, s5, s26
	s_mov_b32 m0, s4
	s_nop 0
	s_add_u32 vcc_lo, s50, s62
	s_addc_u32 vcc_hi, s51, s63
	global_load_lds_dwordx4 v140, vcc
	s_add_i32 m0, s4, 0x2000
	s_nop 0
	s_add_u32 vcc_lo, s50, s64
	s_addc_u32 vcc_hi, s51, s65
	global_load_lds_dwordx4 v140, vcc
	s_add_i32 s23, s23, 2
	s_add_u32 s2, s2, 0x100
	s_addc_u32 s3, s3, 0
	s_add_u32 s7, s7, 0x100
	s_addc_u32 s22, s22, 0
	s_cmp_gt_u32 s23, 13
	s_waitcnt vmcnt(6)
	s_barrier
	v_mfma_f32_16x16x32_bf16 v[60:63], v[208:211], v[156:159], v[60:63]
	v_mfma_f32_16x16x32_bf16 v[56:59], v[216:219], v[156:159], v[56:59]
	v_mfma_f32_16x16x32_bf16 v[44:47], v[208:211], v[174:177], v[44:47]
	v_mfma_f32_16x16x32_bf16 v[40:43], v[216:219], v[174:177], v[40:43]
	v_mfma_f32_16x16x32_bf16 v[28:31], v[208:211], v[182:185], v[28:31]
	v_mfma_f32_16x16x32_bf16 v[24:27], v[216:219], v[182:185], v[24:27]
	v_mfma_f32_16x16x32_bf16 v[12:15], v[208:211], v[200:203], v[12:15]
	v_mfma_f32_16x16x32_bf16 v[8:11], v[216:219], v[200:203], v[8:11]
	v_mfma_f32_16x16x32_bf16 v[60:63], v[212:215], v[160:163], v[60:63]
	v_mfma_f32_16x16x32_bf16 v[56:59], v[220:223], v[160:163], v[56:59]
	v_mfma_f32_16x16x32_bf16 v[44:47], v[212:215], v[178:181], v[44:47]
	v_mfma_f32_16x16x32_bf16 v[40:43], v[220:223], v[178:181], v[40:43]
	v_mfma_f32_16x16x32_bf16 v[28:31], v[212:215], v[196:199], v[28:31]
	v_mfma_f32_16x16x32_bf16 v[24:27], v[220:223], v[196:199], v[24:27]
	v_mfma_f32_16x16x32_bf16 v[12:15], v[212:215], v[204:207], v[12:15]
	v_mfma_f32_16x16x32_bf16 v[8:11], v[220:223], v[204:207], v[8:11]
	s_cbranch_scc1 .Ldb_WIN_xl

; __device__ __forceinline__ u32x4 pack8(const f32x4 a, const f32x4 b) { u32x4 w; w.x = cvt_pk_bf16(a[0], a[1]); w.y = cvt_pk_bf16(a[2], a[3]); w.z = cvt_pk_bf16(b[0], b[1]); w.w = cvt_pk_bf16(b[2], b[3]); return w; }
; #define MEMFENCE asm volatile("" ::: "memory")
;     __device__ __forceinline__ void get_rs(const Unit& u, int wr, int fr, float (&rs)[8]) const {
; #pragma unroll
;         for (int r8 = 0; r8 < 8; ++r8) rs[r8] = rstab[u.ord * 256 + (r8 >> 2) * 128 + wr * 64 + (r8 & 3) * 16 + fr];
;     }
;     template <int KIND> __device__ __forceinline__ void run(f32x4 (&acc)[2][2][4][2], const Unit& u, int tid_in) const {
;     ...
;         if constexpr (KIND == K_WIN) { float rs[8]; get_rs(u, wr, fr, rs);
; #pragma unroll
;             for (int ai = 0; ai < 2; ++ai)
; #pragma unroll
;                 for (int m = 0; m < 4; ++m) { int row = rbase + ai * 128 + m * 16; asm volatile("" : "+v"(row)); const float r = rs[ai * 4 + m];
;                     if (u.pn >= 4 && u.pn < 8) {
;                         const f32x4 v0 = (acc[ai][0][m][0] * r) * (acc[ai][1][m][0] * r), v1 = (acc[ai][0][m][1] * r) * (acc[ai][1][m][1] * r);
;                         *(u32x4*)(zb + (size_t)row * ZW + 1024 + (u.pn - 4) * 128 + cl) = pack8(v0, v1); }
;                     else
; #pragma unroll
;                     for (int bj = 0; bj < 2; ++bj) { const u32x4 w = pack8(acc[ai][bj][m][0] * r, acc[ai][bj][m][1] * r);
;                         if (u.pn < 2) { const int col = u.pn * 256 + bj * 128 + cl; *(u32x4*)((bf16_t*)x + ((size_t)(col >> 4) * T_TOK + row) * 16 + (col & 15)) = w; }
;                         else if (u.pn < 10 || bj == 0) *(u32x4*)(zb + (size_t)row * ZW + u.pn * 256 + bj * 128 + cl) = w;
;                         else { const int b = row >> 13, s = row & 8191; bf16_t* vp = (bf16_t*)(ws + OFF_VT) + ((size_t)(b * 128 + cl)) * SEQ + s;
;                             vp[0 * SEQ] = (bf16_t)(w.x & 0xffff); vp[1 * SEQ] = (bf16_t)(w.x >> 16); vp[2 * SEQ] = (bf16_t)(w.y & 0xffff); vp[3 * SEQ] = (bf16_t)(w.y >> 16);
;                             vp[4 * SEQ] = (bf16_t)(w.z & 0xffff); vp[5 * SEQ] = (bf16_t)(w.z >> 16); vp[6 * SEQ] = (bf16_t)(w.w & 0xffff); vp[7 * SEQ] = (bf16_t)(w.w >> 16); } } MEMFENCE; }
.Ldb_WIN_young:
	s_setprio 3
	s_mov_b32 s101, 2
	s_branch .Ldb_WIN_exit
.Ldb_WIN_exit:
	v_mov_b32_e32 v0, v166
	s_lshl_b32 s5, s6, 10
	v_readfirstlane_b32 s2, v0
	s_ashr_i32 s3, s2, 2
	s_lshr_b32 s4, s2, 1
	s_add_i32 s5, s5, 0
	s_and_b32 s2, s2, 0xffffff00
	v_and_b32_e32 v136, 15, v0
	s_add_i32 s5, s5, s2
	v_lshl_add_u32 v137, v136, 2, s5
	v_add_u32_e32 v137, 0x20010, v137
	ds_read2_b32 v[160:161], v137 offset1:16
	ds_read2_b32 v[154:155], v137 offset0:32 offset1:48
	ds_read2_b32 v[150:151], v137 offset0:128 offset1:144
	ds_read2_b32 v[146:147], v137 offset0:160 offset1:176
	s_andn2_b32 s3, s3, 63
	s_and_b32 s4, s4, 0x60
	v_lshrrev_b32_e32 v0, 1, v0
	v_and_or_b32 v173, v0, 24, s4
	v_or_b32_e32 v136, s3, v136
	s_and_b32 s4, s25, -4
	s_waitcnt lgkmcnt(0)
	v_mov_b32_e32 v156, v161
	v_lshl_add_u32 v145, s33, 8, v136
	s_cmp_lg_u32 s4, 4
	v_mov_b32_e32 v161, v160
	v_mov_b32_e32 v152, v155
	v_mov_b32_e32 v148, v151
	v_mov_b32_e32 v144, v147
	v_and_b32_e32 v174, 8, v0
	v_mov_b32_e32 v158, v145
	s_cselect_b64 s[2:3], -1, 0
	s_cmp_eq_u32 s4, 4
	s_mov_b64 s[6:7], -1
	v_pk_mul_f32 v[132:133], v[132:133], v[160:161]
	v_pk_mul_f32 v[128:129], v[128:129], v[160:161]
	s_cbranch_scc1 .LBB0_227
	v_mov_b64_e32 v[136:137], s[12:13]
	v_mad_i64_i32 v[162:163], s[6:7], v158, s76, v[136:137]
	s_cmp_gt_i32 s25, 1
	v_mov_b32_e32 v136, v160
	v_mov_b32_e32 v137, v160
	s_cselect_b64 s[6:7], -1, 0
	v_pk_mul_f32 v[138:139], v[134:135], v[136:137]
	s_lshl_b32 s74, s25, 8
	s_mov_b64 s[22:23], -1
	s_and_b64 vcc, exec, s[6:7]
	v_pk_mul_f32 v[164:165], v[130:131], v[136:137]
	v_cvt_pk_bf16_f32 v136, v132, v133
	v_cvt_pk_bf16_f32 v137, v138, v139
	v_cvt_pk_bf16_f32 v138, v128, v129
	s_nop 0
	v_cvt_pk_bf16_f32 v139, v164, v165
	s_cbranch_vccz .LBB0_216
	v_lshl_add_u64 v[164:165], s[74:75], 1, v[162:163]
	v_lshlrev_b32_e32 v0, 1, v173
	v_lshl_add_u64 v[164:165], v[164:165], 0, v[0:1]
	global_store_dwordx4 v[164:165], v[136:139], off
	s_mov_b64 s[22:23], 0

; #define G_STAGE(bufoff, gbase, o0, h64) do { \
;         __builtin_amdgcn_global_load_lds((const unsigned*)((const char*)(gbase) + (o0)), (LAS unsigned*)(lds + (bufoff) + ldsw), 16, 0, 0); \
;         __builtin_amdgcn_global_load_lds((const unsigned*)((const char*)(gbase) + (h64) + (o0)), (LAS unsigned*)(lds + (bufoff) + ldsw + 8192), 16, 0, 0); } while (0)
; #define G_LDA(dst, b, h) do { _Pragma("unroll") for (int m = 0; m < 4; ++m) _Pragma("unroll") for (int k = 0; k < 2; ++k) dst[m][k] = *(const LAS bf16x8*)(lds + G_SA(b, h) + aoff + m * 2048 + k * 1024); } while (0)
; #define G_LDB(dst, b, h) do { _Pragma("unroll") for (int n = 0; n < 2; ++n) _Pragma("unroll") for (int k = 0; k < 2; ++k) dst[n][k] = *(const LAS bf16x8*)(lds + G_SB(b, h) + boff + n * 2048 + k * 1024); } while (0)
; #define G_WAIT_V(n) asm volatile("s_waitcnt vmcnt(" #n ")" ::: "memory")
; #define G_WAIT_L(n) asm volatile("s_waitcnt lgkmcnt(" #n ")" ::: "memory")
; #define G_BAR __builtin_amdgcn_s_barrier()
; #define G_SCHED __builtin_amdgcn_sched_barrier(0)
;     ...
;         for (int t = 0; t < nt; t += 2) {
;             const bool last = (t == nt - 2);
;             const char* a1 = cA + (size_t)(t + 1) * ckA;
;             const char* a2 = last ? nA : cA + (size_t)(t + 2) * ckA; const char* b2 = last ? nB : cB + (size_t)(t + 2) * kB;
;             const char* a3 = a2 + ckA; const char* b3 = b2 + kB;
;             G_LDB(B0, 0, 0); G_SCHED; G_LDA(At, 0, 0); G_STAGE(G_SA(1, 1), a1 + chA, cA0, qA);
;             G_WAIT_L(8); G_BAR; G_WAIT_L(0); G_MMA(0, 0, At, B0); G_BAR; G_SCHED;
;             G_LDB(B1, 0, 1); G_STAGE(G_SB(0, 0), b2, cB0, qB);
;             G_BAR; G_WAIT_L(0); G_MMA(0, 1, At, B1); G_BAR;
;             G_LDA(At, 0, 1); G_STAGE(G_SA(0, 0), a2, cA0, qA);
;             G_BAR; G_WAIT_L(0); G_MMA(1, 0, At, B0); G_BAR; G_SCHED;
;             G_STAGE(G_SB(0, 1), b2 + chB, cB0, qB);
;             G_WAIT_V(6); G_BAR; G_MMA(1, 1, At, B1); G_BAR;
.LBB0_450:
	s_add_u32 s4, s6, 0xfffe0080
	s_addc_u32 s5, s7, -1
	s_add_i32 s41, 0, 0x10000
	ds_read_b128 v[140:143], v255 offset:0
	ds_read_b128 v[148:151], v255 offset:1024
	ds_read_b128 v[152:155], v255 offset:2048
	ds_read_b128 v[156:159], v255 offset:3072
	s_cmp_eq_u32 s21, 4
	s_cselect_b32 s23, s11, s5
	s_cselect_b32 s22, s10, s4
	s_cselect_b32 s43, s17, s20
	s_cselect_b32 s42, s16, s19
	s_add_i32 m0, s27, 0xc000
	ds_read_b128 v[160:163], v146
	ds_read_b128 v[164:167], v146 offset:1024
	ds_read_b128 v[172:175], v146 offset:2048
	ds_read_b128 v[176:179], v146 offset:3072
	ds_read_b128 v[180:183], v146 offset:4096
	ds_read_b128 v[196:199], v146 offset:5120
	ds_read_b128 v[200:203], v146 offset:6144
	ds_read_b128 v[204:207], v146 offset:7168
	global_load_lds_dwordx4 v138, s[6:7]
	s_add_i32 m0, s27, 0xe000
	s_nop 0
	s_add_u32 vcc_lo, s6, s52
	s_addc_u32 vcc_hi, s7, s53
	global_load_lds_dwordx4 v138, vcc
	s_waitcnt lgkmcnt(8)
	s_barrier
	s_waitcnt lgkmcnt(0)
	v_mfma_f32_16x16x32_bf16 v[132:135], v[140:143], v[160:163], v[132:135]
	v_mfma_f32_16x16x32_bf16 v[128:131], v[152:155], v[160:163], v[128:131]
	v_mfma_f32_16x16x32_bf16 v[116:119], v[140:143], v[172:175], v[116:119]
	v_mfma_f32_16x16x32_bf16 v[112:115], v[152:155], v[172:175], v[112:115]
	v_mfma_f32_16x16x32_bf16 v[100:103], v[140:143], v[180:183], v[100:103]
	v_mfma_f32_16x16x32_bf16 v[96:99], v[152:155], v[180:183], v[96:99]
	v_mfma_f32_16x16x32_bf16 v[84:87], v[140:143], v[200:203], v[84:87]
	v_mfma_f32_16x16x32_bf16 v[80:83], v[152:155], v[200:203], v[80:83]
	v_mfma_f32_16x16x32_bf16 v[132:135], v[148:151], v[164:167], v[132:135]
	v_mfma_f32_16x16x32_bf16 v[128:131], v[156:159], v[164:167], v[128:131]
	v_mfma_f32_16x16x32_bf16 v[116:119], v[148:151], v[176:179], v[116:119]
	v_mfma_f32_16x16x32_bf16 v[112:115], v[156:159], v[176:179], v[112:115]
	v_mfma_f32_16x16x32_bf16 v[100:103], v[148:151], v[196:199], v[100:103]
	v_mfma_f32_16x16x32_bf16 v[96:99], v[156:159], v[196:199], v[96:99]
	v_mfma_f32_16x16x32_bf16 v[84:87], v[148:151], v[204:207], v[84:87]
	v_mfma_f32_16x16x32_bf16 v[80:83], v[156:159], v[204:207], v[80:83]
	s_barrier
	s_add_i32 s4, 0, 0x14000
	s_add_i32 s5, s41, s26
	s_mov_b32 m0, s5
	ds_read_b128 v[208:211], v255 offset:16384
	ds_read_b128 v[212:215], v255 offset:17408
	ds_read_b128 v[216:219], v255 offset:18432
	ds_read_b128 v[220:223], v255 offset:19456
	global_load_lds_dwordx4 v136, s[42:43]
	s_add_i32 m0, s5, 0x2000
	s_nop 0
	s_add_u32 vcc_lo, s42, s52
	s_addc_u32 vcc_hi, s43, s53
	global_load_lds_dwordx4 v136, vcc
	s_barrier
	s_waitcnt lgkmcnt(0)
	v_mfma_f32_16x16x32_bf16 v[124:127], v[208:211], v[160:163], v[124:127]
	v_mfma_f32_16x16x32_bf16 v[120:123], v[216:219], v[160:163], v[120:123]
	v_mfma_f32_16x16x32_bf16 v[108:111], v[208:211], v[172:175], v[108:111]
	v_mfma_f32_16x16x32_bf16 v[104:107], v[216:219], v[172:175], v[104:107]
	v_mfma_f32_16x16x32_bf16 v[92:95], v[208:211], v[180:183], v[92:95]
	v_mfma_f32_16x16x32_bf16 v[88:91], v[216:219], v[180:183], v[88:91]
	v_mfma_f32_16x16x32_bf16 v[76:79], v[208:211], v[200:203], v[76:79]
	v_mfma_f32_16x16x32_bf16 v[72:75], v[216:219], v[200:203], v[72:75]
	v_mfma_f32_16x16x32_bf16 v[124:127], v[212:215], v[164:167], v[124:127]
	v_mfma_f32_16x16x32_bf16 v[120:123], v[220:223], v[164:167], v[120:123]
	v_mfma_f32_16x16x32_bf16 v[108:111], v[212:215], v[176:179], v[108:111]
	v_mfma_f32_16x16x32_bf16 v[104:107], v[220:223], v[176:179], v[104:107]
	v_mfma_f32_16x16x32_bf16 v[92:95], v[212:215], v[196:199], v[92:95]
	v_mfma_f32_16x16x32_bf16 v[88:91], v[220:223], v[196:199], v[88:91]
	v_mfma_f32_16x16x32_bf16 v[76:79], v[212:215], v[204:207], v[76:79]
	v_mfma_f32_16x16x32_bf16 v[72:75], v[220:223], v[204:207], v[72:75]
	s_barrier
	s_mov_b32 m0, s27
	ds_read_b128 v[160:163], v146 offset:16384
	ds_read_b128 v[164:167], v146 offset:17408
	ds_read_b128 v[172:175], v146 offset:18432
	ds_read_b128 v[176:179], v146 offset:19456
	ds_read_b128 v[180:183], v146 offset:20480
	ds_read_b128 v[196:199], v146 offset:21504
	ds_read_b128 v[200:203], v146 offset:22528
	ds_read_b128 v[204:207], v146 offset:23552
	global_load_lds_dwordx4 v2, s[22:23]
	s_mov_b32 m0, s28
	s_nop 0
	s_add_u32 vcc_lo, s22, s52
	s_addc_u32 vcc_hi, s23, s53
	global_load_lds_dwordx4 v2, vcc
	s_barrier
	s_waitcnt lgkmcnt(0)
	v_mfma_f32_16x16x32_bf16 v[68:71], v[140:143], v[160:163], v[68:71]
	v_mfma_f32_16x16x32_bf16 v[64:67], v[152:155], v[160:163], v[64:67]
	v_mfma_f32_16x16x32_bf16 v[52:55], v[140:143], v[172:175], v[52:55]
	v_mfma_f32_16x16x32_bf16 v[48:51], v[152:155], v[172:175], v[48:51]
	v_mfma_f32_16x16x32_bf16 v[36:39], v[140:143], v[180:183], v[36:39]
	v_mfma_f32_16x16x32_bf16 v[32:35], v[152:155], v[180:183], v[32:35]
	v_mfma_f32_16x16x32_bf16 v[20:23], v[140:143], v[200:203], v[20:23]
	v_mfma_f32_16x16x32_bf16 v[16:19], v[152:155], v[200:203], v[16:19]
	v_mfma_f32_16x16x32_bf16 v[68:71], v[148:151], v[164:167], v[68:71]
	v_mfma_f32_16x16x32_bf16 v[64:67], v[156:159], v[164:167], v[64:67]
	v_mfma_f32_16x16x32_bf16 v[52:55], v[148:151], v[176:179], v[52:55]
	v_mfma_f32_16x16x32_bf16 v[48:51], v[156:159], v[176:179], v[48:51]
	v_mfma_f32_16x16x32_bf16 v[36:39], v[148:151], v[196:199], v[36:39]
	v_mfma_f32_16x16x32_bf16 v[32:35], v[156:159], v[196:199], v[32:35]
	v_mfma_f32_16x16x32_bf16 v[20:23], v[148:151], v[204:207], v[20:23]
	v_mfma_f32_16x16x32_bf16 v[16:19], v[156:159], v[204:207], v[16:19]
	s_barrier
	s_add_i32 s4, s4, s26
	s_mov_b32 m0, s4
	s_nop 0
	s_add_u32 vcc_lo, s42, s0
	s_addc_u32 vcc_hi, s43, s1
	global_load_lds_dwordx4 v136, vcc
	s_add_i32 m0, s4, 0x2000
	s_nop 0
	s_add_u32 vcc_lo, s42, s54
	s_addc_u32 vcc_hi, s43, s55
	global_load_lds_dwordx4 v136, vcc
	s_waitcnt vmcnt(6)
	s_barrier
; #define G_STAGE(bufoff, gbase, o0, h64) do { \
;         __builtin_amdgcn_global_load_lds((const unsigned*)((const char*)(gbase) + (o0)), (LAS unsigned*)(lds + (bufoff) + ldsw), 16, 0, 0); \
;         __builtin_amdgcn_global_load_lds((const unsigned*)((const char*)(gbase) + (h64) + (o0)), (LAS unsigned*)(lds + (bufoff) + ldsw + 8192), 16, 0, 0); } while (0)
; #define G_LDA(dst, b, h) do { _Pragma("unroll") for (int m = 0; m < 4; ++m) _Pragma("unroll") for (int k = 0; k < 2; ++k) dst[m][k] = *(const LAS bf16x8*)(lds + G_SA(b, h) + aoff + m * 2048 + k * 1024); } while (0)
; #define G_LDB(dst, b, h) do { _Pragma("unroll") for (int n = 0; n < 2; ++n) _Pragma("unroll") for (int k = 0; k < 2; ++k) dst[n][k] = *(const LAS bf16x8*)(lds + G_SB(b, h) + boff + n * 2048 + k * 1024); } while (0)
; #define G_WAIT_V(n) asm volatile("s_waitcnt vmcnt(" #n ")" ::: "memory")
; #define G_WAIT_L(n) asm volatile("s_waitcnt lgkmcnt(" #n ")" ::: "memory")
; #define G_BAR __builtin_amdgcn_s_barrier()
; #define G_SCHED __builtin_amdgcn_sched_barrier(0)
;     ...
;             G_WAIT_V(6); G_BAR; G_MMA(1, 1, At, B1); G_BAR;
;             G_LDB(B0, 1, 0); G_SCHED; G_LDA(At, 1, 0); G_STAGE(G_SA(0, 1), a2 + chA, cA0, qA);
;             G_WAIT_L(8); G_BAR; G_WAIT_L(0); G_MMA(0, 0, At, B0); G_BAR; G_SCHED;
;             G_LDB(B1, 1, 1); G_STAGE(G_SB(1, 0), b3, cB0, qB);
;             G_BAR; G_WAIT_L(0); G_MMA(0, 1, At, B1); G_BAR;
	v_mfma_f32_16x16x32_bf16 v[60:63], v[208:211], v[160:163], v[60:63]
	v_mfma_f32_16x16x32_bf16 v[56:59], v[216:219], v[160:163], v[56:59]
	v_mfma_f32_16x16x32_bf16 v[44:47], v[208:211], v[172:175], v[44:47]
	v_mfma_f32_16x16x32_bf16 v[40:43], v[216:219], v[172:175], v[40:43]
	v_mfma_f32_16x16x32_bf16 v[28:31], v[208:211], v[180:183], v[28:31]
	v_mfma_f32_16x16x32_bf16 v[24:27], v[216:219], v[180:183], v[24:27]
	v_mfma_f32_16x16x32_bf16 v[12:15], v[208:211], v[200:203], v[12:15]
	v_mfma_f32_16x16x32_bf16 v[8:11], v[216:219], v[200:203], v[8:11]
	v_mfma_f32_16x16x32_bf16 v[60:63], v[212:215], v[164:167], v[60:63]
	v_mfma_f32_16x16x32_bf16 v[56:59], v[220:223], v[164:167], v[56:59]
	v_mfma_f32_16x16x32_bf16 v[44:47], v[212:215], v[176:179], v[44:47]
	v_mfma_f32_16x16x32_bf16 v[40:43], v[220:223], v[176:179], v[40:43]
	v_mfma_f32_16x16x32_bf16 v[28:31], v[212:215], v[196:199], v[28:31]
	v_mfma_f32_16x16x32_bf16 v[24:27], v[220:223], v[196:199], v[24:27]
	v_mfma_f32_16x16x32_bf16 v[12:15], v[212:215], v[204:207], v[12:15]
	v_mfma_f32_16x16x32_bf16 v[8:11], v[220:223], v[204:207], v[8:11]
	s_barrier
	s_add_i32 s4, 0, 0x18000
	ds_read_b128 v[140:143], v255 offset:32768
	ds_read_b128 v[148:151], v255 offset:33792
	ds_read_b128 v[152:155], v255 offset:34816
	ds_read_b128 v[156:159], v255 offset:35840
	s_mov_b32 m0, s29
	ds_read_b128 v[160:163], v146 offset:32768
	ds_read_b128 v[164:167], v146 offset:33792
	ds_read_b128 v[172:175], v146 offset:34816
	ds_read_b128 v[176:179], v146 offset:35840
	ds_read_b128 v[180:183], v146 offset:36864
	ds_read_b128 v[196:199], v146 offset:37888
	ds_read_b128 v[200:203], v146 offset:38912
	ds_read_b128 v[204:207], v146 offset:39936
	s_add_u32 vcc_lo, s22, s0
	s_addc_u32 vcc_hi, s23, s1
	global_load_lds_dwordx4 v2, vcc
	s_mov_b32 m0, s30
	s_nop 0
	s_add_u32 vcc_lo, s22, s54
	s_addc_u32 vcc_hi, s23, s55
	global_load_lds_dwordx4 v2, vcc
	s_waitcnt lgkmcnt(8)
	s_barrier
	s_waitcnt lgkmcnt(0)
	v_mfma_f32_16x16x32_bf16 v[132:135], v[140:143], v[160:163], v[132:135]
	v_mfma_f32_16x16x32_bf16 v[128:131], v[152:155], v[160:163], v[128:131]
	v_mfma_f32_16x16x32_bf16 v[116:119], v[140:143], v[172:175], v[116:119]
	v_mfma_f32_16x16x32_bf16 v[112:115], v[152:155], v[172:175], v[112:115]
	v_mfma_f32_16x16x32_bf16 v[100:103], v[140:143], v[180:183], v[100:103]
	v_mfma_f32_16x16x32_bf16 v[96:99], v[152:155], v[180:183], v[96:99]
	v_mfma_f32_16x16x32_bf16 v[84:87], v[140:143], v[200:203], v[84:87]
	v_mfma_f32_16x16x32_bf16 v[80:83], v[152:155], v[200:203], v[80:83]
	v_mfma_f32_16x16x32_bf16 v[132:135], v[148:151], v[164:167], v[132:135]
	v_mfma_f32_16x16x32_bf16 v[128:131], v[156:159], v[164:167], v[128:131]
	v_mfma_f32_16x16x32_bf16 v[116:119], v[148:151], v[176:179], v[116:119]
	v_mfma_f32_16x16x32_bf16 v[112:115], v[156:159], v[176:179], v[112:115]
	v_mfma_f32_16x16x32_bf16 v[100:103], v[148:151], v[196:199], v[100:103]
	v_mfma_f32_16x16x32_bf16 v[96:99], v[156:159], v[196:199], v[96:99]
	v_mfma_f32_16x16x32_bf16 v[84:87], v[148:151], v[204:207], v[84:87]
	v_mfma_f32_16x16x32_bf16 v[80:83], v[156:159], v[204:207], v[80:83]
	s_barrier
	s_add_i32 s5, 0, 0x1c000
	s_add_i32 s4, s4, s26
	s_mov_b32 m0, s4
	ds_read_b128 v[208:211], v255 offset:49152
	ds_read_b128 v[212:215], v255 offset:50176
	ds_read_b128 v[216:219], v255 offset:51200
	ds_read_b128 v[220:223], v255 offset:52224
	s_add_u32 vcc_lo, s42, s46
	s_addc_u32 vcc_hi, s43, s47
	global_load_lds_dwordx4 v136, vcc
	s_add_i32 m0, s4, 0x2000
	s_nop 0
	s_add_u32 vcc_lo, s42, s58
	s_addc_u32 vcc_hi, s43, s59
	global_load_lds_dwordx4 v136, vcc
	s_barrier
; #define G_STAGE(bufoff, gbase, o0, h64) do { \
;         __builtin_amdgcn_global_load_lds((const unsigned*)((const char*)(gbase) + (o0)), (LAS unsigned*)(lds + (bufoff) + ldsw), 16, 0, 0); \
;         __builtin_amdgcn_global_load_lds((const unsigned*)((const char*)(gbase) + (h64) + (o0)), (LAS unsigned*)(lds + (bufoff) + ldsw + 8192), 16, 0, 0); } while (0)
; #define G_LDA(dst, b, h) do { _Pragma("unroll") for (int m = 0; m < 4; ++m) _Pragma("unroll") for (int k = 0; k < 2; ++k) dst[m][k] = *(const LAS bf16x8*)(lds + G_SA(b, h) + aoff + m * 2048 + k * 1024); } while (0)
; #define G_WAIT_V(n) asm volatile("s_waitcnt vmcnt(" #n ")" ::: "memory")
; #define G_WAIT_L(n) asm volatile("s_waitcnt lgkmcnt(" #n ")" ::: "memory")
; #define G_BAR __builtin_amdgcn_s_barrier()
; #define G_SCHED __builtin_amdgcn_sched_barrier(0)
;     ...
;             G_BAR; G_WAIT_L(0); G_MMA(0, 1, At, B1); G_BAR;
;             G_LDA(At, 1, 1); G_STAGE(G_SA(1, 0), a3, cA0, qA);
;             G_BAR; G_WAIT_L(0); G_MMA(1, 0, At, B0); G_BAR; G_SCHED;
;             G_STAGE(G_SB(1, 1), b3 + chB, cB0, qB);
;             G_WAIT_V(6); G_BAR; G_MMA(1, 1, At, B1); G_BAR;
;         }
	s_waitcnt lgkmcnt(0)
	v_mfma_f32_16x16x32_bf16 v[124:127], v[208:211], v[160:163], v[124:127]
	v_mfma_f32_16x16x32_bf16 v[120:123], v[216:219], v[160:163], v[120:123]
	v_mfma_f32_16x16x32_bf16 v[108:111], v[208:211], v[172:175], v[108:111]
	v_mfma_f32_16x16x32_bf16 v[104:107], v[216:219], v[172:175], v[104:107]
	v_mfma_f32_16x16x32_bf16 v[92:95], v[208:211], v[180:183], v[92:95]
	v_mfma_f32_16x16x32_bf16 v[88:91], v[216:219], v[180:183], v[88:91]
	v_mfma_f32_16x16x32_bf16 v[76:79], v[208:211], v[200:203], v[76:79]
	v_mfma_f32_16x16x32_bf16 v[72:75], v[216:219], v[200:203], v[72:75]
	v_mfma_f32_16x16x32_bf16 v[124:127], v[212:215], v[164:167], v[124:127]
	v_mfma_f32_16x16x32_bf16 v[120:123], v[220:223], v[164:167], v[120:123]
	v_mfma_f32_16x16x32_bf16 v[108:111], v[212:215], v[176:179], v[108:111]
	v_mfma_f32_16x16x32_bf16 v[104:107], v[220:223], v[176:179], v[104:107]
	v_mfma_f32_16x16x32_bf16 v[92:95], v[212:215], v[196:199], v[92:95]
	v_mfma_f32_16x16x32_bf16 v[88:91], v[220:223], v[196:199], v[88:91]
	v_mfma_f32_16x16x32_bf16 v[76:79], v[212:215], v[204:207], v[76:79]
	v_mfma_f32_16x16x32_bf16 v[72:75], v[220:223], v[204:207], v[72:75]
	s_barrier
	s_mov_b32 m0, s31
	ds_read_b128 v[160:163], v146 offset:49152
	ds_read_b128 v[164:167], v146 offset:50176
	ds_read_b128 v[172:175], v146 offset:51200
	ds_read_b128 v[176:179], v146 offset:52224
	ds_read_b128 v[180:183], v146 offset:53248
	ds_read_b128 v[196:199], v146 offset:54272
	ds_read_b128 v[200:203], v146 offset:55296
	ds_read_b128 v[204:207], v146 offset:56320
	s_add_u32 vcc_lo, s22, s46
	s_addc_u32 vcc_hi, s23, s47
	global_load_lds_dwordx4 v2, vcc
	s_mov_b32 m0, s33
	s_nop 0
	s_add_u32 vcc_lo, s22, s58
	s_addc_u32 vcc_hi, s23, s59
	global_load_lds_dwordx4 v2, vcc
	s_barrier
	s_waitcnt lgkmcnt(0)
	v_mfma_f32_16x16x32_bf16 v[68:71], v[140:143], v[160:163], v[68:71]
	v_mfma_f32_16x16x32_bf16 v[64:67], v[152:155], v[160:163], v[64:67]
	v_mfma_f32_16x16x32_bf16 v[52:55], v[140:143], v[172:175], v[52:55]
	v_mfma_f32_16x16x32_bf16 v[48:51], v[152:155], v[172:175], v[48:51]
	v_mfma_f32_16x16x32_bf16 v[36:39], v[140:143], v[180:183], v[36:39]
	v_mfma_f32_16x16x32_bf16 v[32:35], v[152:155], v[180:183], v[32:35]
	v_mfma_f32_16x16x32_bf16 v[20:23], v[140:143], v[200:203], v[20:23]
	v_mfma_f32_16x16x32_bf16 v[16:19], v[152:155], v[200:203], v[16:19]
	v_mfma_f32_16x16x32_bf16 v[68:71], v[148:151], v[164:167], v[68:71]
	v_mfma_f32_16x16x32_bf16 v[64:67], v[156:159], v[164:167], v[64:67]
	v_mfma_f32_16x16x32_bf16 v[52:55], v[148:151], v[176:179], v[52:55]
	v_mfma_f32_16x16x32_bf16 v[48:51], v[156:159], v[176:179], v[48:51]
	v_mfma_f32_16x16x32_bf16 v[36:39], v[148:151], v[196:199], v[36:39]
	v_mfma_f32_16x16x32_bf16 v[32:35], v[156:159], v[196:199], v[32:35]
	v_mfma_f32_16x16x32_bf16 v[20:23], v[148:151], v[204:207], v[20:23]
	v_mfma_f32_16x16x32_bf16 v[16:19], v[156:159], v[204:207], v[16:19]
	s_barrier
	s_add_i32 s4, s5, s26
	s_mov_b32 m0, s4
	s_nop 0
	s_add_u32 vcc_lo, s42, s50
	s_addc_u32 vcc_hi, s43, s51
	global_load_lds_dwordx4 v136, vcc
	s_add_i32 m0, s4, 0x2000
	s_nop 0
	s_add_u32 vcc_lo, s42, s62
	s_addc_u32 vcc_hi, s43, s63
	global_load_lds_dwordx4 v136, vcc
	s_add_i32 s21, s21, 2
	s_add_u32 s6, s6, 0x100
	s_addc_u32 s7, s7, 0
	s_add_u32 s19, s19, 0x100
	s_addc_u32 s20, s20, 0
	s_cmp_gt_u32 s21, 5
	s_waitcnt vmcnt(6)
	s_barrier
	v_mfma_f32_16x16x32_bf16 v[60:63], v[208:211], v[160:163], v[60:63]
	v_mfma_f32_16x16x32_bf16 v[56:59], v[216:219], v[160:163], v[56:59]
	v_mfma_f32_16x16x32_bf16 v[44:47], v[208:211], v[172:175], v[44:47]
	v_mfma_f32_16x16x32_bf16 v[40:43], v[216:219], v[172:175], v[40:43]
	v_mfma_f32_16x16x32_bf16 v[28:31], v[208:211], v[180:183], v[28:31]
	v_mfma_f32_16x16x32_bf16 v[24:27], v[216:219], v[180:183], v[24:27]
	v_mfma_f32_16x16x32_bf16 v[12:15], v[208:211], v[200:203], v[12:15]
	v_mfma_f32_16x16x32_bf16 v[8:11], v[216:219], v[200:203], v[8:11]
	v_mfma_f32_16x16x32_bf16 v[60:63], v[212:215], v[164:167], v[60:63]
	v_mfma_f32_16x16x32_bf16 v[56:59], v[220:223], v[164:167], v[56:59]
	v_mfma_f32_16x16x32_bf16 v[44:47], v[212:215], v[176:179], v[44:47]
	v_mfma_f32_16x16x32_bf16 v[40:43], v[220:223], v[176:179], v[40:43]
	v_mfma_f32_16x16x32_bf16 v[28:31], v[212:215], v[196:199], v[28:31]
	v_mfma_f32_16x16x32_bf16 v[24:27], v[220:223], v[196:199], v[24:27]
	v_mfma_f32_16x16x32_bf16 v[12:15], v[212:215], v[204:207], v[12:15]
	v_mfma_f32_16x16x32_bf16 v[8:11], v[220:223], v[204:207], v[8:11]
	s_cbranch_scc1 .Ldb_SSM1_xl

; __device__ __forceinline__ u32x4 pack8(const f32x4 a, const f32x4 b) { u32x4 w; w.x = cvt_pk_bf16(a[0], a[1]); w.y = cvt_pk_bf16(a[2], a[3]); w.z = cvt_pk_bf16(b[0], b[1]); w.w = cvt_pk_bf16(b[2], b[3]); return w; }
;     template <int KIND> __device__ __forceinline__ void run(f32x4 (&acc)[2][2][4][2], const Unit& u, int tid_in) const {
;     ...
;         if constexpr (KIND == K_SSM1) { const int g = u.aux;
; #pragma unroll
;             for (int ai = 0; ai < 2; ++ai)
; #pragma unroll
;                 for (int m = 0; m < 4; ++m) { int R = rbase + ai * 128 + m * 16; asm volatile("" : "+v"(R));
;                     if (u.pn < 2) {
; #pragma unroll
;                         for (int bj = 0; bj < 2; ++bj) { const int t = 16 * u.pn + 8 * bj + 2 * wc + (fq >> 1), p0 = 8 * (fq & 1);
;                             *(u32x4*)(yi + ((size_t)g * T_TOK + (size_t)(R * LCH + t)) * 16 + p0) = pack8(acc[ai][bj][m][0], acc[ai][bj][m][1]); }
;                     } else { float* sp = (float*)(ws + OFF_S) + ((size_t)(R * 32 + g)) * 128 + cl; *(f32x4*)sp = acc[ai][0][m][0]; *(f32x4*)(sp + 4) = acc[ai][0][m][1]; } }
.Ldb_SSM1_young:
	s_setprio 3
	s_mov_b32 s101, 2
	s_branch .Ldb_SSM1_exit
.Ldb_SSM1_exit:
	v_mov_b32_e32 v0, v144
	s_mov_b64 s[22:23], -1
	v_readfirstlane_b32 s4, v0
	s_bfe_u32 s19, s4, 0x20006
	s_ashr_i32 s4, s4, 2
	s_andn2_b32 s4, s4, 63
	v_and_or_b32 v141, v0, 15, s4
	v_lshl_add_u32 v147, s13, 8, v141
	s_ashr_i32 s13, s12, 31
	s_lshl_b64 s[6:7], s[12:13], 20
	s_add_u32 s6, s36, s6
	v_bfe_u32 v140, v0, 4, 2
	s_addc_u32 s7, s37, s7
	v_lshlrev_b32_e32 v140, 3, v140
	s_cmp_gt_i32 s25, 1
	v_lshl_or_b32 v140, s19, 5, v140
	v_mov_b32_e32 v141, v147
	s_cselect_b64 s[20:21], -1, 0
	s_and_b64 vcc, exec, s[20:21]
	v_lshlrev_b32_e32 v149, 5, v141
	v_lshlrev_b32_e32 v142, 2, v140
	s_cbranch_vccz .LBB0_453
	v_add_u32_e32 v140, s12, v149
	v_ashrrev_i32_e32 v141, 31, v140
	v_lshlrev_b64 v[140:141], 9, v[140:141]
	v_lshl_add_u64 v[140:141], s[2:3], 0, v[140:141]
	v_mov_b32_e32 v143, v1
	v_lshl_add_u64 v[140:141], v[140:141], 0, v[142:143]
	global_store_dwordx4 v[140:141], v[132:135], off
	global_store_dwordx4 v[140:141], v[128:131], off offset:16
	s_mov_b64 s[22:23], 0

; #define G_STAGE(bufoff, gbase, o0, h64) do { \
;         __builtin_amdgcn_global_load_lds((const unsigned*)((const char*)(gbase) + (o0)), (LAS unsigned*)(lds + (bufoff) + ldsw), 16, 0, 0); \
;         __builtin_amdgcn_global_load_lds((const unsigned*)((const char*)(gbase) + (h64) + (o0)), (LAS unsigned*)(lds + (bufoff) + ldsw + 8192), 16, 0, 0); } while (0)
; #define G_LDA(dst, b, h) do { _Pragma("unroll") for (int m = 0; m < 4; ++m) _Pragma("unroll") for (int k = 0; k < 2; ++k) dst[m][k] = *(const LAS bf16x8*)(lds + G_SA(b, h) + aoff + m * 2048 + k * 1024); } while (0)
; #define G_LDB(dst, b, h) do { _Pragma("unroll") for (int n = 0; n < 2; ++n) _Pragma("unroll") for (int k = 0; k < 2; ++k) dst[n][k] = *(const LAS bf16x8*)(lds + G_SB(b, h) + boff + n * 2048 + k * 1024); } while (0)
; #define G_WAIT_V(n) asm volatile("s_waitcnt vmcnt(" #n ")" ::: "memory")
; #define G_WAIT_L(n) asm volatile("s_waitcnt lgkmcnt(" #n ")" ::: "memory")
; #define G_BAR __builtin_amdgcn_s_barrier()
; #define G_SCHED __builtin_amdgcn_sched_barrier(0)
;     ...
;             G_WAIT_L(8); G_BAR; G_WAIT_L(0); G_MMA(0, 0, At, B0); G_BAR; G_SCHED;
;             G_LDB(B1, 0, 1); G_STAGE(G_SB(0, 0), b2, cB0, qB);
;             G_BAR; G_WAIT_L(0); G_MMA(0, 1, At, B1); G_BAR;
;             G_LDA(At, 0, 1); G_STAGE(G_SA(0, 0), a2, cA0, qA);
;             G_BAR; G_WAIT_L(0); G_MMA(1, 0, At, B0); G_BAR; G_SCHED;
;             G_STAGE(G_SB(0, 1), b2 + chB, cB0, qB);
;             G_WAIT_V(6); G_BAR; G_MMA(1, 1, At, B1); G_BAR;
.Ldb_SSM2_sk:
	s_mov_b32 s101, 0
	s_waitcnt lgkmcnt(0)
	v_mfma_f32_16x16x32_bf16 v[140:143], v[56:59], v[152:155], v[140:143]
	v_mfma_f32_16x16x32_bf16 v[136:139], v[144:147], v[152:155], v[136:139]
	v_mfma_f32_16x16x32_bf16 v[124:127], v[56:59], v[162:165], v[124:127]
	v_mfma_f32_16x16x32_bf16 v[120:123], v[144:147], v[162:165], v[120:123]
	v_mfma_f32_16x16x32_bf16 v[108:111], v[56:59], v[176:179], v[108:111]
	v_mfma_f32_16x16x32_bf16 v[104:107], v[144:147], v[176:179], v[104:107]
	v_mfma_f32_16x16x32_bf16 v[92:95], v[56:59], v[200:203], v[92:95]
	v_mfma_f32_16x16x32_bf16 v[88:91], v[144:147], v[200:203], v[88:91]
	v_mfma_f32_16x16x32_bf16 v[140:143], v[60:63], v[156:159], v[140:143]
	v_mfma_f32_16x16x32_bf16 v[136:139], v[148:151], v[156:159], v[136:139]
	v_mfma_f32_16x16x32_bf16 v[124:127], v[60:63], v[172:175], v[124:127]
	v_mfma_f32_16x16x32_bf16 v[120:123], v[148:151], v[172:175], v[120:123]
	v_mfma_f32_16x16x32_bf16 v[108:111], v[60:63], v[196:199], v[108:111]
	v_mfma_f32_16x16x32_bf16 v[104:107], v[148:151], v[196:199], v[104:107]
	v_mfma_f32_16x16x32_bf16 v[92:95], v[60:63], v[204:207], v[92:95]
	v_mfma_f32_16x16x32_bf16 v[88:91], v[148:151], v[204:207], v[88:91]
	s_barrier
	s_mov_b32 m0, s49
	ds_read_b128 v[208:211], v255 offset:16384
	ds_read_b128 v[212:215], v255 offset:17408
	ds_read_b128 v[216:219], v255 offset:18432
	ds_read_b128 v[220:223], v255 offset:19456
	global_load_lds_dwordx4 v2, s[26:27]
	s_mov_b32 m0, s66
	s_nop 0
	s_add_u32 vcc_lo, s26, s92
	s_addc_u32 vcc_hi, s27, s93
	global_load_lds_dwordx4 v2, vcc
	s_barrier
	s_waitcnt lgkmcnt(0)
	v_mfma_f32_16x16x32_bf16 v[132:135], v[208:211], v[152:155], v[132:135]
	v_mfma_f32_16x16x32_bf16 v[128:131], v[216:219], v[152:155], v[128:131]
	v_mfma_f32_16x16x32_bf16 v[116:119], v[208:211], v[162:165], v[116:119]
	v_mfma_f32_16x16x32_bf16 v[112:115], v[216:219], v[162:165], v[112:115]
	v_mfma_f32_16x16x32_bf16 v[100:103], v[208:211], v[176:179], v[100:103]
	v_mfma_f32_16x16x32_bf16 v[96:99], v[216:219], v[176:179], v[96:99]
	v_mfma_f32_16x16x32_bf16 v[84:87], v[208:211], v[200:203], v[84:87]
	v_mfma_f32_16x16x32_bf16 v[80:83], v[216:219], v[200:203], v[80:83]
	v_mfma_f32_16x16x32_bf16 v[132:135], v[212:215], v[156:159], v[132:135]
	v_mfma_f32_16x16x32_bf16 v[128:131], v[220:223], v[156:159], v[128:131]
	v_mfma_f32_16x16x32_bf16 v[116:119], v[212:215], v[172:175], v[116:119]
	v_mfma_f32_16x16x32_bf16 v[112:115], v[220:223], v[172:175], v[112:115]
	v_mfma_f32_16x16x32_bf16 v[100:103], v[212:215], v[196:199], v[100:103]
	v_mfma_f32_16x16x32_bf16 v[96:99], v[220:223], v[196:199], v[96:99]
	v_mfma_f32_16x16x32_bf16 v[84:87], v[212:215], v[204:207], v[84:87]
	v_mfma_f32_16x16x32_bf16 v[80:83], v[220:223], v[204:207], v[80:83]
	s_barrier
	s_mov_b32 m0, s43
	ds_read_b128 v[152:155], v184 offset:16384
	ds_read_b128 v[156:159], v184 offset:17408
	ds_read_b128 v[162:165], v184 offset:18432
	ds_read_b128 v[172:175], v184 offset:19456
	ds_read_b128 v[176:179], v184 offset:20480
	ds_read_b128 v[196:199], v184 offset:21504
	ds_read_b128 v[200:203], v184 offset:22528
	ds_read_b128 v[204:207], v184 offset:23552
	global_load_lds_dwordx4 v160, s[34:35]
	s_mov_b32 m0, s50
	s_nop 0
	s_add_u32 vcc_lo, s34, s88
	s_addc_u32 vcc_hi, s35, s89
	global_load_lds_dwordx4 v160, vcc
	s_barrier
	s_waitcnt lgkmcnt(0)
	v_mfma_f32_16x16x32_bf16 v[76:79], v[56:59], v[152:155], v[76:79]
	v_mfma_f32_16x16x32_bf16 v[72:75], v[144:147], v[152:155], v[72:75]
	v_mfma_f32_16x16x32_bf16 v[52:55], v[56:59], v[162:165], v[52:55]
	v_mfma_f32_16x16x32_bf16 v[48:51], v[144:147], v[162:165], v[48:51]
	v_mfma_f32_16x16x32_bf16 v[36:39], v[56:59], v[176:179], v[36:39]
	v_mfma_f32_16x16x32_bf16 v[32:35], v[144:147], v[176:179], v[32:35]
	v_mfma_f32_16x16x32_bf16 v[20:23], v[56:59], v[200:203], v[20:23]
	v_mfma_f32_16x16x32_bf16 v[16:19], v[144:147], v[200:203], v[16:19]
	v_mfma_f32_16x16x32_bf16 v[76:79], v[60:63], v[156:159], v[76:79]
	v_mfma_f32_16x16x32_bf16 v[72:75], v[148:151], v[156:159], v[72:75]
	v_mfma_f32_16x16x32_bf16 v[52:55], v[60:63], v[172:175], v[52:55]
	v_mfma_f32_16x16x32_bf16 v[48:51], v[148:151], v[172:175], v[48:51]
	v_mfma_f32_16x16x32_bf16 v[36:39], v[60:63], v[196:199], v[36:39]
	v_mfma_f32_16x16x32_bf16 v[32:35], v[148:151], v[196:199], v[32:35]
	v_mfma_f32_16x16x32_bf16 v[20:23], v[60:63], v[204:207], v[20:23]
	v_mfma_f32_16x16x32_bf16 v[16:19], v[148:151], v[204:207], v[16:19]
	s_barrier
	s_mov_b32 m0, s63
	s_add_u32 vcc_lo, s26, s82
	s_addc_u32 vcc_hi, s27, s83
	global_load_lds_dwordx4 v2, vcc
	s_mov_b32 m0, s62
	s_nop 0
	s_add_u32 vcc_lo, s26, s94
	s_addc_u32 vcc_hi, s27, s95
	global_load_lds_dwordx4 v2, vcc
	s_waitcnt vmcnt(6)
	s_barrier
	v_mfma_f32_16x16x32_bf16 v[44:47], v[208:211], v[162:165], v[44:47]
	v_mfma_f32_16x16x32_bf16 v[40:43], v[216:219], v[162:165], v[40:43]
	v_mfma_f32_16x16x32_bf16 v[28:31], v[208:211], v[176:179], v[28:31]
	v_mfma_f32_16x16x32_bf16 v[24:27], v[216:219], v[176:179], v[24:27]
	v_mfma_f32_16x16x32_bf16 v[12:15], v[208:211], v[200:203], v[12:15]
	v_mfma_f32_16x16x32_bf16 v[8:11], v[216:219], v[200:203], v[8:11]
	v_mfma_f32_16x16x32_bf16 v[56:59], v[208:211], v[152:155], v[68:71]
	v_mfma_f32_16x16x32_bf16 v[60:63], v[216:219], v[152:155], v[64:67]
	v_mfma_f32_16x16x32_bf16 v[44:47], v[212:215], v[172:175], v[44:47]
	v_mfma_f32_16x16x32_bf16 v[40:43], v[220:223], v[172:175], v[40:43]
	v_mfma_f32_16x16x32_bf16 v[28:31], v[212:215], v[196:199], v[28:31]
	v_mfma_f32_16x16x32_bf16 v[24:27], v[220:223], v[196:199], v[24:27]
	v_mfma_f32_16x16x32_bf16 v[12:15], v[212:215], v[204:207], v[12:15]
	v_mfma_f32_16x16x32_bf16 v[8:11], v[220:223], v[204:207], v[8:11]
	v_mfma_f32_16x16x32_bf16 v[56:59], v[212:215], v[156:159], v[56:59]
	v_mfma_f32_16x16x32_bf16 v[60:63], v[220:223], v[156:159], v[60:63]
	s_barrier
; #define G_STAGE(bufoff, gbase, o0, h64) do { \
;         __builtin_amdgcn_global_load_lds((const unsigned*)((const char*)(gbase) + (o0)), (LAS unsigned*)(lds + (bufoff) + ldsw), 16, 0, 0); \
;         __builtin_amdgcn_global_load_lds((const unsigned*)((const char*)(gbase) + (h64) + (o0)), (LAS unsigned*)(lds + (bufoff) + ldsw + 8192), 16, 0, 0); } while (0)
; #define G_LDA(dst, b, h) do { _Pragma("unroll") for (int m = 0; m < 4; ++m) _Pragma("unroll") for (int k = 0; k < 2; ++k) dst[m][k] = *(const LAS bf16x8*)(lds + G_SA(b, h) + aoff + m * 2048 + k * 1024); } while (0)
; #define G_LDB(dst, b, h) do { _Pragma("unroll") for (int n = 0; n < 2; ++n) _Pragma("unroll") for (int k = 0; k < 2; ++k) dst[n][k] = *(const LAS bf16x8*)(lds + G_SB(b, h) + boff + n * 2048 + k * 1024); } while (0)
; #define G_WAIT_V(n) asm volatile("s_waitcnt vmcnt(" #n ")" ::: "memory")
; #define G_WAIT_L(n) asm volatile("s_waitcnt lgkmcnt(" #n ")" ::: "memory")
; #define G_BAR __builtin_amdgcn_s_barrier()
; #define G_SCHED __builtin_amdgcn_sched_barrier(0)
;     ...
;             G_LDB(B0, 1, 0); G_SCHED; G_LDA(At, 1, 0); G_STAGE(G_SA(0, 1), a2 + chA, cA0, qA);
;             G_WAIT_L(8); G_BAR; G_WAIT_L(0); G_MMA(0, 0, At, B0); G_BAR; G_SCHED;
;             G_LDB(B1, 1, 1); G_STAGE(G_SB(1, 0), b3, cB0, qB);
;             G_BAR; G_WAIT_L(0); G_MMA(0, 1, At, B1); G_BAR;
;             G_LDA(At, 1, 1); G_STAGE(G_SA(1, 0), a3, cA0, qA);
;             G_BAR; G_WAIT_L(0); G_MMA(1, 0, At, B0); G_BAR; G_SCHED;
;             G_STAGE(G_SB(1, 1), b3 + chB, cB0, qB);
;             G_WAIT_V(6); G_BAR; G_MMA(1, 1, At, B1); G_BAR;
;         }
	ds_read_b128 v[64:67], v255 offset:32768
	ds_read_b128 v[68:71], v255 offset:33792
	ds_read_b128 v[144:147], v255 offset:34816
	ds_read_b128 v[148:151], v255 offset:35840
	s_mov_b32 m0, s51
	ds_read_b128 v[152:155], v184 offset:32768
	ds_read_b128 v[156:159], v184 offset:33792
	ds_read_b128 v[162:165], v184 offset:34816
	ds_read_b128 v[172:175], v184 offset:35840
	ds_read_b128 v[176:179], v184 offset:36864
	ds_read_b128 v[196:199], v184 offset:37888
	ds_read_b128 v[200:203], v184 offset:38912
	ds_read_b128 v[204:207], v184 offset:39936
	s_add_u32 vcc_lo, s34, s86
	s_addc_u32 vcc_hi, s35, s87
	global_load_lds_dwordx4 v160, vcc
	s_mov_b32 m0, s52
	s_nop 0
	s_add_u32 vcc_lo, s34, s96
	s_addc_u32 vcc_hi, s35, s97
	global_load_lds_dwordx4 v160, vcc
	s_waitcnt lgkmcnt(8)
	s_barrier
	s_waitcnt lgkmcnt(0)
	v_mfma_f32_16x16x32_bf16 v[140:143], v[64:67], v[152:155], v[140:143]
	v_mfma_f32_16x16x32_bf16 v[136:139], v[144:147], v[152:155], v[136:139]
	v_mfma_f32_16x16x32_bf16 v[124:127], v[64:67], v[162:165], v[124:127]
	v_mfma_f32_16x16x32_bf16 v[120:123], v[144:147], v[162:165], v[120:123]
	v_mfma_f32_16x16x32_bf16 v[108:111], v[64:67], v[176:179], v[108:111]
	v_mfma_f32_16x16x32_bf16 v[104:107], v[144:147], v[176:179], v[104:107]
	v_mfma_f32_16x16x32_bf16 v[92:95], v[64:67], v[200:203], v[92:95]
	v_mfma_f32_16x16x32_bf16 v[88:91], v[144:147], v[200:203], v[88:91]
	v_mfma_f32_16x16x32_bf16 v[140:143], v[68:71], v[156:159], v[140:143]
	v_mfma_f32_16x16x32_bf16 v[136:139], v[148:151], v[156:159], v[136:139]
	v_mfma_f32_16x16x32_bf16 v[124:127], v[68:71], v[172:175], v[124:127]
	v_mfma_f32_16x16x32_bf16 v[120:123], v[148:151], v[172:175], v[120:123]
	v_mfma_f32_16x16x32_bf16 v[108:111], v[68:71], v[196:199], v[108:111]
	v_mfma_f32_16x16x32_bf16 v[104:107], v[148:151], v[196:199], v[104:107]
	v_mfma_f32_16x16x32_bf16 v[92:95], v[68:71], v[204:207], v[92:95]
	v_mfma_f32_16x16x32_bf16 v[88:91], v[148:151], v[204:207], v[88:91]
	s_barrier
	s_mov_b32 m0, s30
	ds_read_b128 v[208:211], v255 offset:49152
	ds_read_b128 v[212:215], v255 offset:50176
	ds_read_b128 v[216:219], v255 offset:51200
	ds_read_b128 v[220:223], v255 offset:52224
	s_add_u32 vcc_lo, s26, s46
	s_addc_u32 vcc_hi, s27, s47
	global_load_lds_dwordx4 v2, vcc
	s_mov_b32 m0, s67
	s_nop 0
	s_add_u32 vcc_lo, s26, s70
	s_addc_u32 vcc_hi, s27, s71
	global_load_lds_dwordx4 v2, vcc
	s_barrier
	s_waitcnt lgkmcnt(0)
	v_mfma_f32_16x16x32_bf16 v[132:135], v[208:211], v[152:155], v[132:135]
	v_mfma_f32_16x16x32_bf16 v[128:131], v[216:219], v[152:155], v[128:131]
	v_mfma_f32_16x16x32_bf16 v[116:119], v[208:211], v[162:165], v[116:119]
	v_mfma_f32_16x16x32_bf16 v[112:115], v[216:219], v[162:165], v[112:115]
	v_mfma_f32_16x16x32_bf16 v[100:103], v[208:211], v[176:179], v[100:103]
	v_mfma_f32_16x16x32_bf16 v[96:99], v[216:219], v[176:179], v[96:99]
	v_mfma_f32_16x16x32_bf16 v[84:87], v[208:211], v[200:203], v[84:87]
	v_mfma_f32_16x16x32_bf16 v[80:83], v[216:219], v[200:203], v[80:83]
	v_mfma_f32_16x16x32_bf16 v[132:135], v[212:215], v[156:159], v[132:135]
	v_mfma_f32_16x16x32_bf16 v[128:131], v[220:223], v[156:159], v[128:131]
	v_mfma_f32_16x16x32_bf16 v[116:119], v[212:215], v[172:175], v[116:119]
	v_mfma_f32_16x16x32_bf16 v[112:115], v[220:223], v[172:175], v[112:115]
	v_mfma_f32_16x16x32_bf16 v[100:103], v[212:215], v[196:199], v[100:103]
	v_mfma_f32_16x16x32_bf16 v[96:99], v[220:223], v[196:199], v[96:99]
	v_mfma_f32_16x16x32_bf16 v[84:87], v[212:215], v[204:207], v[84:87]
	v_mfma_f32_16x16x32_bf16 v[80:83], v[220:223], v[204:207], v[80:83]
	s_barrier
	s_mov_b32 m0, s53
	ds_read_b128 v[152:155], v184 offset:49152
	ds_read_b128 v[156:159], v184 offset:50176
	ds_read_b128 v[162:165], v184 offset:51200
	ds_read_b128 v[172:175], v184 offset:52224
	ds_read_b128 v[176:179], v184 offset:53248
	ds_read_b128 v[196:199], v184 offset:54272
	ds_read_b128 v[200:203], v184 offset:55296
	ds_read_b128 v[204:207], v184 offset:56320
	s_add_u32 vcc_lo, s34, s46
	s_addc_u32 vcc_hi, s35, s47
	global_load_lds_dwordx4 v160, vcc
	s_mov_b32 m0, s54
	s_nop 0
	s_add_u32 vcc_lo, s34, s68
	s_addc_u32 vcc_hi, s35, s69
	global_load_lds_dwordx4 v160, vcc
	s_barrier
	s_waitcnt lgkmcnt(0)
	v_mfma_f32_16x16x32_bf16 v[76:79], v[64:67], v[152:155], v[76:79]
	v_mfma_f32_16x16x32_bf16 v[72:75], v[144:147], v[152:155], v[72:75]
	v_mfma_f32_16x16x32_bf16 v[52:55], v[64:67], v[162:165], v[52:55]
	v_mfma_f32_16x16x32_bf16 v[48:51], v[144:147], v[162:165], v[48:51]
	v_mfma_f32_16x16x32_bf16 v[36:39], v[64:67], v[176:179], v[36:39]
	v_mfma_f32_16x16x32_bf16 v[32:35], v[144:147], v[176:179], v[32:35]
	v_mfma_f32_16x16x32_bf16 v[20:23], v[64:67], v[200:203], v[20:23]
	v_mfma_f32_16x16x32_bf16 v[16:19], v[144:147], v[200:203], v[16:19]
	v_mfma_f32_16x16x32_bf16 v[76:79], v[68:71], v[156:159], v[76:79]
	v_mfma_f32_16x16x32_bf16 v[72:75], v[148:151], v[156:159], v[72:75]
	v_mfma_f32_16x16x32_bf16 v[52:55], v[68:71], v[172:175], v[52:55]
	v_mfma_f32_16x16x32_bf16 v[48:51], v[148:151], v[172:175], v[48:51]
	v_mfma_f32_16x16x32_bf16 v[36:39], v[68:71], v[196:199], v[36:39]
	v_mfma_f32_16x16x32_bf16 v[32:35], v[148:151], v[196:199], v[32:35]
	v_mfma_f32_16x16x32_bf16 v[20:23], v[68:71], v[204:207], v[20:23]
	v_mfma_f32_16x16x32_bf16 v[16:19], v[148:151], v[204:207], v[16:19]
	s_barrier
	s_mov_b32 m0, s65
	s_add_u32 vcc_lo, s26, s84
	s_addc_u32 vcc_hi, s27, s85
	global_load_lds_dwordx4 v2, vcc
	s_mov_b32 m0, s64
	s_nop 0
	s_add_u32 vcc_lo, s26, s28
	s_addc_u32 vcc_hi, s27, s29
	global_load_lds_dwordx4 v2, vcc
	s_waitcnt vmcnt(6)
	s_barrier
	v_mfma_f32_16x16x32_bf16 v[56:59], v[208:211], v[152:155], v[56:59]
	v_mfma_f32_16x16x32_bf16 v[68:71], v[212:215], v[156:159], v[56:59]
	v_mfma_f32_16x16x32_bf16 v[56:59], v[216:219], v[152:155], v[60:63]
	v_mfma_f32_16x16x32_bf16 v[44:47], v[208:211], v[162:165], v[44:47]
	v_mfma_f32_16x16x32_bf16 v[40:43], v[216:219], v[162:165], v[40:43]
	v_mfma_f32_16x16x32_bf16 v[28:31], v[208:211], v[176:179], v[28:31]
	v_mfma_f32_16x16x32_bf16 v[24:27], v[216:219], v[176:179], v[24:27]
	v_mfma_f32_16x16x32_bf16 v[12:15], v[208:211], v[200:203], v[12:15]
	v_mfma_f32_16x16x32_bf16 v[8:11], v[216:219], v[200:203], v[8:11]
	v_mfma_f32_16x16x32_bf16 v[64:67], v[220:223], v[156:159], v[56:59]
	v_mfma_f32_16x16x32_bf16 v[44:47], v[212:215], v[172:175], v[44:47]
	v_mfma_f32_16x16x32_bf16 v[40:43], v[220:223], v[172:175], v[40:43]
	v_mfma_f32_16x16x32_bf16 v[28:31], v[212:215], v[196:199], v[28:31]
	v_mfma_f32_16x16x32_bf16 v[24:27], v[220:223], v[196:199], v[24:27]
	v_mfma_f32_16x16x32_bf16 v[12:15], v[212:215], v[204:207], v[12:15]
	v_mfma_f32_16x16x32_bf16 v[8:11], v[220:223], v[204:207], v[8:11]
	s_andn2_b64 vcc, exec, s[24:25]
	s_mov_b64 s[26:27], -1
	s_mov_b64 s[24:25], 0
	s_mov_b64 s[30:31], 0x100
	s_cbranch_vccnz .Ldb_SSM2_xl

; __device__ __forceinline__ float gelu_tanh(float y) { const float z = 1.5957691216057308f * (y + 0.044715f * y * y * y); return y * sigmoidf_(z); }
; __device__ __forceinline__ u32x4 pack8(const f32x4 a, const f32x4 b) { u32x4 w; w.x = cvt_pk_bf16(a[0], a[1]); w.y = cvt_pk_bf16(a[2], a[3]); w.z = cvt_pk_bf16(b[0], b[1]); w.w = cvt_pk_bf16(b[2], b[3]); return w; }
; __device__ __forceinline__ void unpack8(const u32x4 w, f32x4& a, f32x4& b) { a[0] = bf_lo(w.x); a[1] = bf_hi(w.x); a[2] = bf_lo(w.y); a[3] = bf_hi(w.y); b[0] = bf_lo(w.z); b[1] = bf_hi(w.z); b[2] = bf_lo(w.w); b[3] = bf_hi(w.w); }
;     template <int KIND> __device__ __forceinline__ void run(f32x4 (&acc)[2][2][4][2], const Unit& u, int tid_in) const {
;     ...
;         if constexpr (KIND == K_SSM2) { const int g = u.aux; const int ch = g * 16 + 8 * (fq & 1); const f32x4 d0 = *(const f32x4*)(dskip + ch), d1 = *(const f32x4*)(dskip + ch + 4);
; #pragma unroll
;             for (int ai = 0; ai < 2; ++ai)
; #pragma unroll
;                 for (int mh = 0; mh < 2; ++mh) { u32x4 yv[2][2], uv[2][2];
; #pragma unroll
;                     for (int ml = 0; ml < 2; ++ml) { int R = rbase + ai * 128 + (mh * 2 + ml) * 16; asm volatile("" : "+v"(R));
; #pragma unroll
;                         for (int bj = 0; bj < 2; ++bj) { const int t = 16 * u.pn + 8 * bj + 2 * wc + (fq >> 1); const size_t tok = (size_t)R * LCH + t;
;                             yv[ml][bj] = *(const u32x4*)(yi + ((size_t)g * T_TOK + tok) * 16 + 8 * (fq & 1)); uv[ml][bj] = *(const u32x4*)((const bf16_t*)x + ((size_t)g * T_TOK + tok) * 16 + 8 * (fq & 1)); } }
; #pragma unroll
;                     for (int ml = 0; ml < 2; ++ml) { const int m = mh * 2 + ml; int R = rbase + ai * 128 + m * 16; asm volatile("" : "+v"(R));
; #pragma unroll
;                         for (int bj = 0; bj < 2; ++bj) { const int t = 16 * u.pn + 8 * bj + 2 * wc + (fq >> 1); const size_t tok = (size_t)R * LCH + t;
;                             f32x4 y0, y1, u0, u1; unpack8(yv[ml][bj], y0, y1); unpack8(uv[ml][bj], u0, u1);
;                             y0 = acc[ai][bj][m][0] + y0 + d0 * u0; y1 = acc[ai][bj][m][1] + y1 + d1 * u1;
; #pragma unroll
;                             for (int j = 0; j < 4; ++j) { y0[j] = gelu_tanh(y0[j]); y1[j] = gelu_tanh(y1[j]); }
;                             *(u32x4*)(yi + ((size_t)g * T_TOK + tok) * 16 + 8 * (fq & 1)) = pack8(y0, y1); } }
.Ldb_SSM2_young:
	s_setprio 3
	s_mov_b32 s101, 2
	s_branch .Ldb_SSM2_exit
.Ldb_SSM2_exit:
	v_mov_b32_e32 v0, v182
	s_lshl_b32 s3, s23, 8
	v_readfirstlane_b32 s2, v0
	s_ashr_i32 s4, s2, 2
	v_lshrrev_b32_e32 v56, 1, v0
	s_andn2_b32 s4, s4, 63
	v_and_b32_e32 v144, 8, v56
	s_add_i32 s4, s4, s3
	v_lshl_or_b32 v56, s22, 4, v144
	s_lshr_b32 s2, s2, 5
	v_and_or_b32 v185, v0, 15, s4
	v_ashrrev_i32_e32 v57, 31, v56
	s_and_b32 s2, s2, 6
	v_lshrrev_b32_e32 v0, 5, v0
	v_lshl_add_u64 v[60:61], v[56:57], 2, s[6:7]
	v_and_or_b32 v145, v0, 1, s2
	v_lshlrev_b32_e32 v0, 1, v144
	v_mov_b32_e32 v144, v185
	global_load_dwordx4 v[56:59], v[60:61], off offset:16
	s_nop 0
	global_load_dwordx4 v[60:63], v[60:61], off
	s_ashr_i32 s23, s22, 31
	v_lshl_or_b32 v212, s33, 4, v145
	v_ashrrev_i32_e32 v145, 31, v144
	s_lshl_b64 s[20:21], s[22:23], 19
	v_lshlrev_b64 v[144:145], 9, v[144:145]
	v_ashrrev_i32_e32 v213, 31, v212
	v_lshl_add_u64 v[144:145], v[144:145], 0, s[20:21]
	v_lshlrev_b64 v[172:173], 4, v[212:213]
	v_lshl_add_u64 v[146:147], v[144:145], 0, v[172:173]
	v_lshl_add_u64 v[164:165], s[10:11], 0, v[0:1]
	v_lshlrev_b64 v[146:147], 1, v[146:147]
	v_lshl_add_u64 v[148:149], v[164:165], 0, v[146:147]
	v_lshl_add_u64 v[166:167], s[8:9], 0, v[0:1]
	global_load_dwordx4 v[196:199], v[148:149], off
	v_lshl_add_u64 v[146:147], v[166:167], 0, v[146:147]
	global_load_dwordx4 v[200:203], v[146:147], off
	v_or_b32_e32 v176, 8, v212
	v_ashrrev_i32_e32 v177, 31, v176
	v_lshlrev_b64 v[174:175], 4, v[176:177]
	v_lshl_add_u64 v[144:145], v[174:175], 0, v[144:145]
	v_lshlrev_b64 v[144:145], 1, v[144:145]
	v_lshl_add_u64 v[148:149], v[164:165], 0, v[144:145]
	v_lshl_add_u64 v[144:145], v[166:167], 0, v[144:145]
	global_load_dwordx4 v[204:207], v[148:149], off
	global_load_dwordx4 v[208:211], v[144:145], off
	v_or_b32_e32 v178, 16, v185
	s_lshl_b64 s[2:3], s[22:23], 20
	v_mov_b32_e32 v146, v178
	s_add_u32 s2, s10, s2
	s_addc_u32 s3, s11, s3
	v_ashrrev_i32_e32 v147, 31, v146
	v_lshlrev_b64 v[144:145], 9, v[146:147]
	v_lshl_add_u64 v[162:163], s[2:3], 0, v[0:1]
	v_lshl_add_u64 v[144:145], v[144:145], 0, s[20:21]
	v_lshl_add_u64 v[146:147], v[144:145], 0, v[172:173]
	v_lshl_add_u64 v[144:145], v[144:145], 0, v[174:175]
	v_lshlrev_b64 v[146:147], 1, v[146:147]
	v_lshlrev_b64 v[144:145], 1, v[144:145]
	v_lshl_add_u64 v[148:149], v[164:165], 0, v[146:147]
	v_lshl_add_u64 v[146:147], v[166:167], 0, v[146:147]
	v_lshl_add_u64 v[150:151], v[164:165], 0, v[144:145]
	v_lshl_add_u64 v[144:145], v[166:167], 0, v[144:145]
	global_load_dwordx4 v[156:159], v[148:149], off
	global_load_dwordx4 v[152:155], v[146:147], off
	s_nop 0
	global_load_dwordx4 v[148:151], v[150:151], off
	s_nop 0
	global_load_dwordx4 v[144:147], v[144:145], off
	v_mov_b32_e32 v180, v185
	v_readlane_b32 s48, v230, 5
	v_ashrrev_i32_e32 v181, 31, v180
	v_lshlrev_b64 v[180:181], 10, v[180:181]
	v_lshl_add_u64 v[180:181], v[162:163], 0, v[180:181]
	v_readlane_b32 s49, v230, 6
	v_readlane_b32 s44, v230, 7
	s_and_b64 vcc, exec, s[14:15]
	s_mov_b32 s22, s18
	s_mov_b32 s33, s59
	s_mov_b32 s23, s58
	s_mov_b64 s[2:3], s[12:13]
	v_readlane_b32 s45, v230, 8
	s_movk_i32 s49, 0x4000
	s_mov_b64 s[68:69], 0x18080
	s_mov_b64 s[70:71], 0x800
	s_mov_b64 s[82:83], 0x1800
	s_mov_b64 s[84:85], 0x400800
	s_mov_b64 s[86:87], 0x58000
	s_mov_b64 s[88:89], 0xb0000
	s_mov_b64 s[64:65], 0x108000
	s_mov_b64 s[66:67], 0x58080
	s_mov_b32 s28, s74
	s_waitcnt vmcnt(0)
	v_lshlrev_b32_e32 v214, 16, v196
	v_and_b32_e32 v215, 0xffff0000, v196
	v_lshlrev_b32_e32 v216, 16, v198
	v_and_b32_e32 v217, 0xffff0000, v198
	v_lshlrev_b32_e32 v218, 16, v200
	v_and_b32_e32 v219, 0xffff0000, v200
	v_lshlrev_b32_e32 v220, 16, v202
	v_and_b32_e32 v221, 0xffff0000, v202
	v_pk_add_f32 v[140:141], v[140:141], v[214:215]
	v_pk_add_f32 v[136:137], v[136:137], v[216:217]
	v_pk_fma_f32 v[140:141], v[60:61], v[218:219], v[140:141]
	v_pk_fma_f32 v[136:137], v[56:57], v[220:221], v[136:137]
	v_mul_f32_e32 v0, 0x3d372713, v140
	v_mul_f32_e32 v179, 0x3d372713, v136
	v_mul_f32_e32 v195, 0x3d372713, v141
	v_mul_f32_e32 v0, v140, v0
	v_mul_f32_e32 v179, v136, v179
	v_mul_f32_e32 v195, v141, v195
	v_fma_f32 v0, v140, v0, v140
	v_fma_f32 v179, v136, v179, v136
	v_fma_f32 v195, v141, v195, v141
	v_mul_f32_e32 v0, 0x3fcc422a, v0
	v_mul_f32_e32 v179, 0x3fcc422a, v179
	v_mul_f32_e32 v195, 0x3fcc422a, v195
	v_mul_f32_e32 v0, 0xbfb8aa3b, v0
	v_mul_f32_e32 v179, 0xbfb8aa3b, v179
	v_mul_f32_e32 v195, 0xbfb8aa3b, v195
	v_exp_f32_e32 v0, v0
	v_exp_f32_e32 v179, v179
	v_exp_f32_e32 v195, v195
	v_lshlrev_b32_e32 v196, 16, v197
	v_and_b32_e32 v197, 0xffff0000, v197
	v_pk_add_f32 v[142:143], v[142:143], v[196:197]
	v_add_f32_e32 v0, 1.0, v0
	v_add_f32_e32 v179, 1.0, v179
	v_add_f32_e32 v195, 1.0, v195
	v_mul_f32_e32 v196, 0x3d372713, v137
	v_rcp_f32_e32 v0, v0
	v_rcp_f32_e32 v179, v179
	v_rcp_f32_e32 v195, v195
	v_mul_f32_e32 v196, v137, v196
	v_lshlrev_b32_e32 v198, 16, v199
	v_and_b32_e32 v199, 0xffff0000, v199
	v_fma_f32 v196, v137, v196, v137
	v_lshlrev_b32_e32 v200, 16, v201
	v_and_b32_e32 v201, 0xffff0000, v201
	v_lshlrev_b32_e32 v202, 16, v203
	v_and_b32_e32 v203, 0xffff0000, v203
	v_pk_add_f32 v[138:139], v[138:139], v[198:199]
	v_mul_f32_e32 v196, 0x3fcc422a, v196
	v_pk_fma_f32 v[142:143], v[62:63], v[200:201], v[142:143]
	v_pk_fma_f32 v[138:139], v[58:59], v[202:203], v[138:139]
	v_mul_f32_e32 v196, 0xbfb8aa3b, v196
	v_exp_f32_e32 v196, v196
	v_mul_f32_e32 v0, v140, v0
	v_mul_f32_e32 v136, v136, v179
	v_mul_f32_e32 v140, v141, v195
	v_mul_f32_e32 v179, 0x3d372713, v142
	v_mul_f32_e32 v195, 0x3d372713, v138
	v_mul_f32_e32 v179, v142, v179
	v_mul_f32_e32 v195, v138, v195
	v_fma_f32 v179, v142, v179, v142
; __device__ __forceinline__ float gelu_tanh(float y) { const float z = 1.5957691216057308f * (y + 0.044715f * y * y * y); return y * sigmoidf_(z); }
; __device__ __forceinline__ u32x4 pack8(const f32x4 a, const f32x4 b) { u32x4 w; w.x = cvt_pk_bf16(a[0], a[1]); w.y = cvt_pk_bf16(a[2], a[3]); w.z = cvt_pk_bf16(b[0], b[1]); w.w = cvt_pk_bf16(b[2], b[3]); return w; }
; __device__ __forceinline__ void unpack8(const u32x4 w, f32x4& a, f32x4& b) { a[0] = bf_lo(w.x); a[1] = bf_hi(w.x); a[2] = bf_lo(w.y); a[3] = bf_hi(w.y); b[0] = bf_lo(w.z); b[1] = bf_hi(w.z); b[2] = bf_lo(w.w); b[3] = bf_hi(w.w); }
;     template <int KIND> __device__ __forceinline__ void run(f32x4 (&acc)[2][2][4][2], const Unit& u, int tid_in) const {
;     ...
;                     for (int ml = 0; ml < 2; ++ml) { const int m = mh * 2 + ml; int R = rbase + ai * 128 + m * 16; asm volatile("" : "+v"(R));
; #pragma unroll
;                         for (int bj = 0; bj < 2; ++bj) { const int t = 16 * u.pn + 8 * bj + 2 * wc + (fq >> 1); const size_t tok = (size_t)R * LCH + t;
;                             f32x4 y0, y1, u0, u1; unpack8(yv[ml][bj], y0, y1); unpack8(uv[ml][bj], u0, u1);
;                             y0 = acc[ai][bj][m][0] + y0 + d0 * u0; y1 = acc[ai][bj][m][1] + y1 + d1 * u1;
; #pragma unroll
;                             for (int j = 0; j < 4; ++j) { y0[j] = gelu_tanh(y0[j]); y1[j] = gelu_tanh(y1[j]); }
;                             *(u32x4*)(yi + ((size_t)g * T_TOK + tok) * 16 + 8 * (fq & 1)) = pack8(y0, y1); } }
	v_fma_f32 v195, v138, v195, v138
	v_mul_f32_e32 v179, 0x3fcc422a, v179
	v_mul_f32_e32 v195, 0x3fcc422a, v195
	v_add_f32_e32 v141, 1.0, v196
	v_mul_f32_e32 v179, 0xbfb8aa3b, v179
	v_mul_f32_e32 v195, 0xbfb8aa3b, v195
	v_rcp_f32_e32 v141, v141
	v_exp_f32_e32 v179, v179
	v_exp_f32_e32 v195, v195
	v_mul_f32_e32 v196, 0x3d372713, v139
	v_mul_f32_e32 v137, v137, v141
	v_add_f32_e32 v141, 1.0, v179
	v_add_f32_e32 v179, 1.0, v195
	v_mul_f32_e32 v195, 0x3d372713, v143
	v_mul_f32_e32 v195, v143, v195
	v_mul_f32_e32 v196, v139, v196
	v_fma_f32 v195, v143, v195, v143
	v_fma_f32 v196, v139, v196, v139
	v_mul_f32_e32 v195, 0x3fcc422a, v195
	v_mul_f32_e32 v196, 0x3fcc422a, v196
	v_mul_f32_e32 v195, 0xbfb8aa3b, v195
	v_mul_f32_e32 v196, 0xbfb8aa3b, v196
	v_exp_f32_e32 v195, v195
	v_exp_f32_e32 v196, v196
	v_rcp_f32_e32 v141, v141
	v_rcp_f32_e32 v179, v179
	v_add_f32_e32 v195, 1.0, v195
	v_add_f32_e32 v196, 1.0, v196
	v_rcp_f32_e32 v195, v195
	v_rcp_f32_e32 v196, v196
	v_mul_f32_e32 v141, v142, v141
	v_mul_f32_e32 v142, v138, v179
	v_mul_f32_e32 v143, v143, v195
	v_mul_f32_e32 v179, v139, v196
	v_cvt_pk_bf16_f32 v138, v0, v140
	v_cvt_pk_bf16_f32 v139, v141, v143
	v_cvt_pk_bf16_f32 v140, v136, v137
	v_lshlrev_b64 v[136:137], 5, v[212:213]
	v_cvt_pk_bf16_f32 v141, v142, v179
	v_lshl_add_u64 v[142:143], v[180:181], 0, v[136:137]
	global_store_dwordx4 v[142:143], v[138:141], off
	v_lshlrev_b32_e32 v142, 16, v206
	v_and_b32_e32 v143, 0xffff0000, v206
	v_lshlrev_b32_e32 v138, 16, v204
	v_and_b32_e32 v139, 0xffff0000, v204
	v_lshlrev_b32_e32 v198, 16, v208
	v_and_b32_e32 v199, 0xffff0000, v208
	v_lshlrev_b32_e32 v202, 16, v210
	v_and_b32_e32 v203, 0xffff0000, v210
	v_pk_add_f32 v[132:133], v[132:133], v[138:139]
	v_pk_add_f32 v[128:129], v[128:129], v[142:143]
	v_pk_fma_f32 v[132:133], v[60:61], v[198:199], v[132:133]
	v_pk_fma_f32 v[128:129], v[56:57], v[202:203], v[128:129]
	v_mul_f32_e32 v0, 0x3d372713, v132
	v_mul_f32_e32 v138, 0x3d372713, v128
	v_mul_f32_e32 v139, 0x3d372713, v133
	v_mul_f32_e32 v0, v132, v0
	v_mul_f32_e32 v138, v128, v138
	v_mul_f32_e32 v139, v133, v139
	v_fma_f32 v0, v132, v0, v132
	v_fma_f32 v138, v128, v138, v128
	v_fma_f32 v139, v133, v139, v133
	v_mul_f32_e32 v0, 0x3fcc422a, v0
	v_mul_f32_e32 v138, 0x3fcc422a, v138
	v_mul_f32_e32 v139, 0x3fcc422a, v139
	v_mul_f32_e32 v0, 0xbfb8aa3b, v0
	v_mul_f32_e32 v138, 0xbfb8aa3b, v138
	v_mul_f32_e32 v139, 0xbfb8aa3b, v139
	v_exp_f32_e32 v0, v0
	v_exp_f32_e32 v138, v138
	v_exp_f32_e32 v139, v139
	v_lshlrev_b32_e32 v140, 16, v205
	v_and_b32_e32 v141, 0xffff0000, v205
	v_pk_add_f32 v[134:135], v[134:135], v[140:141]
	v_add_f32_e32 v0, 1.0, v0
	v_add_f32_e32 v138, 1.0, v138
	v_add_f32_e32 v139, 1.0, v139
	v_mul_f32_e32 v140, 0x3d372713, v129
	v_rcp_f32_e32 v0, v0
	v_rcp_f32_e32 v138, v138
	v_rcp_f32_e32 v139, v139
	v_mul_f32_e32 v140, v129, v140
	v_lshlrev_b32_e32 v196, 16, v207
	v_and_b32_e32 v197, 0xffff0000, v207
	v_fma_f32 v140, v129, v140, v129
	v_lshlrev_b32_e32 v200, 16, v209
	v_and_b32_e32 v201, 0xffff0000, v209
	v_lshlrev_b32_e32 v204, 16, v211
	v_and_b32_e32 v205, 0xffff0000, v211
	v_pk_add_f32 v[130:131], v[130:131], v[196:197]
	v_mul_f32_e32 v140, 0x3fcc422a, v140
	v_pk_fma_f32 v[134:135], v[62:63], v[200:201], v[134:135]
	v_pk_fma_f32 v[130:131], v[58:59], v[204:205], v[130:131]
	v_mul_f32_e32 v140, 0xbfb8aa3b, v140
	v_exp_f32_e32 v140, v140
	v_mul_f32_e32 v0, v132, v0
	v_mul_f32_e32 v128, v128, v138
	v_mul_f32_e32 v132, v133, v139
	v_mul_f32_e32 v138, 0x3d372713, v134
	v_mul_f32_e32 v139, 0x3d372713, v130
	v_mul_f32_e32 v138, v134, v138
	v_mul_f32_e32 v139, v130, v139
	v_fma_f32 v138, v134, v138, v134
	v_fma_f32 v139, v130, v139, v130
	v_mul_f32_e32 v138, 0x3fcc422a, v138
	v_mul_f32_e32 v139, 0x3fcc422a, v139
	v_add_f32_e32 v133, 1.0, v140
	v_mul_f32_e32 v138, 0xbfb8aa3b, v138
	v_mul_f32_e32 v139, 0xbfb8aa3b, v139
	v_rcp_f32_e32 v133, v133
	v_exp_f32_e32 v138, v138
	v_exp_f32_e32 v139, v139
	v_mul_f32_e32 v140, 0x3d372713, v131
	v_mul_f32_e32 v129, v129, v133
	v_add_f32_e32 v133, 1.0, v138
	v_add_f32_e32 v138, 1.0, v139
	v_mul_f32_e32 v139, 0x3d372713, v135
	v_mul_f32_e32 v139, v135, v139
	v_mul_f32_e32 v140, v131, v140
	v_fma_f32 v139, v135, v139, v135
	v_fma_f32 v140, v131, v140, v131
	v_mul_f32_e32 v139, 0x3fcc422a, v139
	v_mul_f32_e32 v140, 0x3fcc422a, v140
	v_mul_f32_e32 v139, 0xbfb8aa3b, v139
	v_mul_f32_e32 v140, 0xbfb8aa3b, v140
	v_exp_f32_e32 v139, v139
	v_exp_f32_e32 v140, v140
	v_rcp_f32_e32 v133, v133
	v_rcp_f32_e32 v138, v138
	v_add_f32_e32 v139, 1.0, v139
	v_add_f32_e32 v140, 1.0, v140
	v_rcp_f32_e32 v139, v139
	v_rcp_f32_e32 v140, v140
	v_mul_f32_e32 v133, v134, v133
	v_mul_f32_e32 v134, v130, v138
	v_mul_f32_e32 v135, v135, v139
	v_mul_f32_e32 v138, v131, v140
	v_cvt_pk_bf16_f32 v130, v0, v132
	v_cvt_pk_bf16_f32 v131, v133, v135
	v_cvt_pk_bf16_f32 v132, v128, v129
	v_lshlrev_b64 v[128:129], 5, v[176:177]
	v_cvt_pk_bf16_f32 v133, v134, v138
	v_lshl_add_u64 v[134:135], v[180:181], 0, v[128:129]
	global_store_dwordx4 v[134:135], v[130:133], off
	v_lshlrev_b32_e32 v138, 16, v158
	v_and_b32_e32 v139, 0xffff0000, v158
	v_lshlrev_b32_e32 v132, 16, v156
	v_and_b32_e32 v133, 0xffff0000, v156
	v_lshlrev_b32_e32 v134, 16, v157
	v_and_b32_e32 v135, 0xffff0000, v157
	v_lshlrev_b32_e32 v142, 16, v152
	v_and_b32_e32 v143, 0xffff0000, v152
	v_lshlrev_b32_e32 v156, 16, v154
	v_and_b32_e32 v157, 0xffff0000, v154
	v_pk_add_f32 v[124:125], v[124:125], v[132:133]
	v_pk_add_f32 v[120:121], v[120:121], v[138:139]
	v_pk_fma_f32 v[124:125], v[60:61], v[142:143], v[124:125]
	v_pk_fma_f32 v[120:121], v[56:57], v[156:157], v[120:121]
	v_mul_f32_e32 v0, 0x3d372713, v124
	v_mul_f32_e32 v132, 0x3d372713, v120
; __device__ __forceinline__ float gelu_tanh(float y) { const float z = 1.5957691216057308f * (y + 0.044715f * y * y * y); return y * sigmoidf_(z); }
; __device__ __forceinline__ u32x4 pack8(const f32x4 a, const f32x4 b) { u32x4 w; w.x = cvt_pk_bf16(a[0], a[1]); w.y = cvt_pk_bf16(a[2], a[3]); w.z = cvt_pk_bf16(b[0], b[1]); w.w = cvt_pk_bf16(b[2], b[3]); return w; }
; __device__ __forceinline__ void unpack8(const u32x4 w, f32x4& a, f32x4& b) { a[0] = bf_lo(w.x); a[1] = bf_hi(w.x); a[2] = bf_lo(w.y); a[3] = bf_hi(w.y); b[0] = bf_lo(w.z); b[1] = bf_hi(w.z); b[2] = bf_lo(w.w); b[3] = bf_hi(w.w); }
;     template <int KIND> __device__ __forceinline__ void run(f32x4 (&acc)[2][2][4][2], const Unit& u, int tid_in) const {
;     ...
;                     for (int ml = 0; ml < 2; ++ml) { const int m = mh * 2 + ml; int R = rbase + ai * 128 + m * 16; asm volatile("" : "+v"(R));
; #pragma unroll
;                         for (int bj = 0; bj < 2; ++bj) { const int t = 16 * u.pn + 8 * bj + 2 * wc + (fq >> 1); const size_t tok = (size_t)R * LCH + t;
;                             f32x4 y0, y1, u0, u1; unpack8(yv[ml][bj], y0, y1); unpack8(uv[ml][bj], u0, u1);
;                             y0 = acc[ai][bj][m][0] + y0 + d0 * u0; y1 = acc[ai][bj][m][1] + y1 + d1 * u1;
; #pragma unroll
;                             for (int j = 0; j < 4; ++j) { y0[j] = gelu_tanh(y0[j]); y1[j] = gelu_tanh(y1[j]); }
;                             *(u32x4*)(yi + ((size_t)g * T_TOK + tok) * 16 + 8 * (fq & 1)) = pack8(y0, y1); } }
	v_mul_f32_e32 v133, 0x3d372713, v125
	v_mul_f32_e32 v0, v124, v0
	v_mul_f32_e32 v132, v120, v132
	v_mul_f32_e32 v133, v125, v133
	v_fma_f32 v0, v124, v0, v124
	v_fma_f32 v132, v120, v132, v120
	v_fma_f32 v133, v125, v133, v125
	v_mul_f32_e32 v0, 0x3fcc422a, v0
	v_mul_f32_e32 v132, 0x3fcc422a, v132
	v_mul_f32_e32 v133, 0x3fcc422a, v133
	v_mul_f32_e32 v0, 0xbfb8aa3b, v0
	v_mul_f32_e32 v132, 0xbfb8aa3b, v132
	v_mul_f32_e32 v133, 0xbfb8aa3b, v133
	v_exp_f32_e32 v0, v0
	v_exp_f32_e32 v132, v132
	v_exp_f32_e32 v133, v133
	v_pk_add_f32 v[126:127], v[126:127], v[134:135]
	v_add_f32_e32 v0, 1.0, v0
	v_add_f32_e32 v132, 1.0, v132
	v_add_f32_e32 v133, 1.0, v133
	v_mul_f32_e32 v134, 0x3d372713, v121
	v_rcp_f32_e32 v0, v0
	v_rcp_f32_e32 v132, v132
	v_rcp_f32_e32 v133, v133
	v_mul_f32_e32 v134, v121, v134
	v_lshlrev_b32_e32 v140, 16, v159
	v_and_b32_e32 v141, 0xffff0000, v159
	v_fma_f32 v134, v121, v134, v121
	v_lshlrev_b32_e32 v152, 16, v153
	v_and_b32_e32 v153, 0xffff0000, v153
	v_lshlrev_b32_e32 v154, 16, v155
	v_and_b32_e32 v155, 0xffff0000, v155
	v_pk_add_f32 v[122:123], v[122:123], v[140:141]
	v_mul_f32_e32 v134, 0x3fcc422a, v134
	v_pk_fma_f32 v[126:127], v[62:63], v[152:153], v[126:127]
	v_pk_fma_f32 v[122:123], v[58:59], v[154:155], v[122:123]
	v_mul_f32_e32 v134, 0xbfb8aa3b, v134
	v_exp_f32_e32 v134, v134
	v_mul_f32_e32 v0, v124, v0
	v_mul_f32_e32 v124, v120, v132
	v_mul_f32_e32 v120, v125, v133
	v_mul_f32_e32 v132, 0x3d372713, v126
	v_mul_f32_e32 v133, 0x3d372713, v122
	v_mul_f32_e32 v132, v126, v132
	v_mul_f32_e32 v133, v122, v133
	v_fma_f32 v132, v126, v132, v126
	v_fma_f32 v133, v122, v133, v122
	v_mul_f32_e32 v132, 0x3fcc422a, v132
	v_mul_f32_e32 v133, 0x3fcc422a, v133
	v_add_f32_e32 v125, 1.0, v134
	v_mul_f32_e32 v132, 0xbfb8aa3b, v132
	v_mul_f32_e32 v133, 0xbfb8aa3b, v133
	v_rcp_f32_e32 v125, v125
	v_exp_f32_e32 v132, v132
	v_exp_f32_e32 v133, v133
	v_mul_f32_e32 v134, 0x3d372713, v123
	v_mul_f32_e32 v125, v121, v125
	v_add_f32_e32 v121, 1.0, v132
	v_add_f32_e32 v132, 1.0, v133
	v_mul_f32_e32 v133, 0x3d372713, v127
	v_mul_f32_e32 v133, v127, v133
	v_fma_f32 v133, v127, v133, v127
	v_mul_f32_e32 v134, v123, v134
	v_mul_f32_e32 v133, 0x3fcc422a, v133
	v_fma_f32 v134, v123, v134, v123
	v_mul_f32_e32 v133, 0xbfb8aa3b, v133
	v_mul_f32_e32 v134, 0x3fcc422a, v134
	v_exp_f32_e32 v133, v133
	v_mul_f32_e32 v134, 0xbfb8aa3b, v134
	v_exp_f32_e32 v134, v134
	v_rcp_f32_e32 v121, v121
	v_add_f32_e32 v133, 1.0, v133
	v_rcp_f32_e32 v132, v132
	v_rcp_f32_e32 v133, v133
	v_add_f32_e32 v134, 1.0, v134
	v_rcp_f32_e32 v134, v134
	v_mul_f32_e32 v121, v126, v121
	v_ashrrev_i32_e32 v179, 31, v178
	v_lshlrev_b64 v[130:131], 10, v[178:179]
	v_lshl_add_u64 v[130:131], v[162:163], 0, v[130:131]
	v_mul_f32_e32 v126, v122, v132
	v_mul_f32_e32 v122, v127, v133
	v_mul_f32_e32 v123, v123, v134
	v_cvt_pk_bf16_f32 v120, v0, v120
	v_cvt_pk_bf16_f32 v121, v121, v122
	v_cvt_pk_bf16_f32 v122, v124, v125
	v_lshl_add_u64 v[124:125], v[130:131], 0, v[136:137]
	v_cvt_pk_bf16_f32 v123, v126, v123
	global_store_dwordx4 v[124:125], v[120:123], off
	v_lshlrev_b32_e32 v124, 16, v150
	v_and_b32_e32 v125, 0xffff0000, v150
	v_lshlrev_b32_e32 v120, 16, v148
	v_and_b32_e32 v121, 0xffff0000, v148
	v_lshlrev_b32_e32 v132, 16, v144
	v_and_b32_e32 v133, 0xffff0000, v144
	v_lshlrev_b32_e32 v138, 16, v146
	v_and_b32_e32 v139, 0xffff0000, v146
	v_pk_add_f32 v[116:117], v[116:117], v[120:121]
	v_pk_add_f32 v[112:113], v[112:113], v[124:125]
	v_pk_fma_f32 v[116:117], v[60:61], v[132:133], v[116:117]
	v_pk_fma_f32 v[112:113], v[56:57], v[138:139], v[112:113]
	v_mul_f32_e32 v0, 0x3d372713, v116
	v_mul_f32_e32 v120, 0x3d372713, v112
	v_mul_f32_e32 v121, 0x3d372713, v117
	v_mul_f32_e32 v0, v116, v0
	v_mul_f32_e32 v120, v112, v120
	v_mul_f32_e32 v121, v117, v121
	v_fma_f32 v0, v116, v0, v116
	v_fma_f32 v120, v112, v120, v112
	v_fma_f32 v121, v117, v121, v117
	v_mul_f32_e32 v0, 0x3fcc422a, v0
	v_mul_f32_e32 v120, 0x3fcc422a, v120
	v_mul_f32_e32 v121, 0x3fcc422a, v121
	v_mul_f32_e32 v0, 0xbfb8aa3b, v0
	v_mul_f32_e32 v120, 0xbfb8aa3b, v120
	v_mul_f32_e32 v121, 0xbfb8aa3b, v121
	v_exp_f32_e32 v0, v0
	v_exp_f32_e32 v120, v120
	v_exp_f32_e32 v121, v121
	v_lshlrev_b32_e32 v122, 16, v149
	v_and_b32_e32 v123, 0xffff0000, v149
	v_pk_add_f32 v[118:119], v[118:119], v[122:123]
	v_add_f32_e32 v0, 1.0, v0
	v_add_f32_e32 v120, 1.0, v120
	v_add_f32_e32 v121, 1.0, v121
	v_mul_f32_e32 v122, 0x3d372713, v113
	v_rcp_f32_e32 v0, v0
	v_rcp_f32_e32 v120, v120
	v_rcp_f32_e32 v121, v121
	v_mul_f32_e32 v122, v113, v122
	v_lshlrev_b32_e32 v126, 16, v151
	v_and_b32_e32 v127, 0xffff0000, v151
	v_fma_f32 v122, v113, v122, v113
	v_lshlrev_b32_e32 v134, 16, v145
	v_and_b32_e32 v135, 0xffff0000, v145
	v_lshlrev_b32_e32 v140, 16, v147
	v_and_b32_e32 v141, 0xffff0000, v147
	v_pk_add_f32 v[114:115], v[114:115], v[126:127]
	v_mul_f32_e32 v122, 0x3fcc422a, v122
	v_pk_fma_f32 v[118:119], v[62:63], v[134:135], v[118:119]
	v_pk_fma_f32 v[114:115], v[58:59], v[140:141], v[114:115]
	v_mul_f32_e32 v122, 0xbfb8aa3b, v122
	v_exp_f32_e32 v122, v122
	v_mul_f32_e32 v0, v116, v0
	v_mul_f32_e32 v116, v112, v120
	v_mul_f32_e32 v112, v117, v121
	v_mul_f32_e32 v120, 0x3d372713, v118
	v_mul_f32_e32 v121, 0x3d372713, v114
	v_mul_f32_e32 v120, v118, v120
	v_mul_f32_e32 v121, v114, v121
	v_fma_f32 v120, v118, v120, v118
	v_fma_f32 v121, v114, v121, v114
	v_mul_f32_e32 v120, 0x3fcc422a, v120
	v_mul_f32_e32 v121, 0x3fcc422a, v121
	v_add_f32_e32 v117, 1.0, v122
	v_mul_f32_e32 v120, 0xbfb8aa3b, v120
	v_mul_f32_e32 v121, 0xbfb8aa3b, v121
	v_rcp_f32_e32 v117, v117
	v_exp_f32_e32 v120, v120
	v_exp_f32_e32 v121, v121
	v_mul_f32_e32 v122, 0x3d372713, v115
; __device__ __forceinline__ float gelu_tanh(float y) { const float z = 1.5957691216057308f * (y + 0.044715f * y * y * y); return y * sigmoidf_(z); }
; __device__ __forceinline__ u32x4 pack8(const f32x4 a, const f32x4 b) { u32x4 w; w.x = cvt_pk_bf16(a[0], a[1]); w.y = cvt_pk_bf16(a[2], a[3]); w.z = cvt_pk_bf16(b[0], b[1]); w.w = cvt_pk_bf16(b[2], b[3]); return w; }
; __device__ __forceinline__ void unpack8(const u32x4 w, f32x4& a, f32x4& b) { a[0] = bf_lo(w.x); a[1] = bf_hi(w.x); a[2] = bf_lo(w.y); a[3] = bf_hi(w.y); b[0] = bf_lo(w.z); b[1] = bf_hi(w.z); b[2] = bf_lo(w.w); b[3] = bf_hi(w.w); }
;     template <int KIND> __device__ __forceinline__ void run(f32x4 (&acc)[2][2][4][2], const Unit& u, int tid_in) const {
;     ...
;                 for (int mh = 0; mh < 2; ++mh) { u32x4 yv[2][2], uv[2][2];
; #pragma unroll
;                     for (int ml = 0; ml < 2; ++ml) { int R = rbase + ai * 128 + (mh * 2 + ml) * 16; asm volatile("" : "+v"(R));
; #pragma unroll
;                         for (int bj = 0; bj < 2; ++bj) { const int t = 16 * u.pn + 8 * bj + 2 * wc + (fq >> 1); const size_t tok = (size_t)R * LCH + t;
;                             yv[ml][bj] = *(const u32x4*)(yi + ((size_t)g * T_TOK + tok) * 16 + 8 * (fq & 1)); uv[ml][bj] = *(const u32x4*)((const bf16_t*)x + ((size_t)g * T_TOK + tok) * 16 + 8 * (fq & 1)); } }
; #pragma unroll
;                     for (int ml = 0; ml < 2; ++ml) { const int m = mh * 2 + ml; int R = rbase + ai * 128 + m * 16; asm volatile("" : "+v"(R));
; #pragma unroll
;                         for (int bj = 0; bj < 2; ++bj) { const int t = 16 * u.pn + 8 * bj + 2 * wc + (fq >> 1); const size_t tok = (size_t)R * LCH + t;
;                             f32x4 y0, y1, u0, u1; unpack8(yv[ml][bj], y0, y1); unpack8(uv[ml][bj], u0, u1);
;                             y0 = acc[ai][bj][m][0] + y0 + d0 * u0; y1 = acc[ai][bj][m][1] + y1 + d1 * u1;
; #pragma unroll
;                             for (int j = 0; j < 4; ++j) { y0[j] = gelu_tanh(y0[j]); y1[j] = gelu_tanh(y1[j]); }
;                             *(u32x4*)(yi + ((size_t)g * T_TOK + tok) * 16 + 8 * (fq & 1)) = pack8(y0, y1); } }
	v_mul_f32_e32 v117, v113, v117
	v_add_f32_e32 v113, 1.0, v120
	v_add_f32_e32 v120, 1.0, v121
	v_mul_f32_e32 v121, 0x3d372713, v119
	v_mul_f32_e32 v121, v119, v121
	v_fma_f32 v121, v119, v121, v119
	v_mul_f32_e32 v122, v115, v122
	v_mul_f32_e32 v121, 0x3fcc422a, v121
	v_fma_f32 v122, v115, v122, v115
	v_mul_f32_e32 v121, 0xbfb8aa3b, v121
	v_mul_f32_e32 v122, 0x3fcc422a, v122
	v_exp_f32_e32 v121, v121
	v_mul_f32_e32 v122, 0xbfb8aa3b, v122
	v_exp_f32_e32 v122, v122
	v_rcp_f32_e32 v113, v113
	v_add_f32_e32 v121, 1.0, v121
	v_rcp_f32_e32 v120, v120
	v_rcp_f32_e32 v121, v121
	v_add_f32_e32 v122, 1.0, v122
	v_rcp_f32_e32 v122, v122
	v_mul_f32_e32 v113, v118, v113
	v_mul_f32_e32 v118, v114, v120
	v_mul_f32_e32 v114, v119, v121
	v_mul_f32_e32 v115, v115, v122
	v_cvt_pk_bf16_f32 v112, v0, v112
	v_cvt_pk_bf16_f32 v113, v113, v114
	v_cvt_pk_bf16_f32 v114, v116, v117
	v_lshl_add_u64 v[116:117], v[130:131], 0, v[128:129]
	v_or_b32_e32 v132, 32, v185
	v_cvt_pk_bf16_f32 v115, v118, v115
	global_store_dwordx4 v[116:117], v[112:115], off
	v_or_b32_e32 v130, 48, v185
	s_nop 0
	v_mov_b32_e32 v112, v132
	s_nop 0
	v_ashrrev_i32_e32 v113, 31, v112
	v_lshlrev_b64 v[112:113], 9, v[112:113]
	v_lshl_add_u64 v[112:113], v[112:113], 0, s[20:21]
	v_lshl_add_u64 v[114:115], v[112:113], 0, v[172:173]
	v_lshlrev_b64 v[114:115], 1, v[114:115]
	v_lshl_add_u64 v[116:117], v[164:165], 0, v[114:115]
	global_load_dwordx4 v[138:141], v[116:117], off
	v_lshl_add_u64 v[114:115], v[166:167], 0, v[114:115]
	global_load_dwordx4 v[142:145], v[114:115], off
	v_lshl_add_u64 v[112:113], v[112:113], 0, v[174:175]
	v_lshlrev_b64 v[112:113], 1, v[112:113]
	v_lshl_add_u64 v[114:115], v[164:165], 0, v[112:113]
	global_load_dwordx4 v[146:149], v[114:115], off
	v_lshl_add_u64 v[112:113], v[166:167], 0, v[112:113]
	global_load_dwordx4 v[150:153], v[112:113], off
	v_mov_b32_e32 v112, v130
	s_waitcnt vmcnt(0)
	v_lshlrev_b32_e32 v134, 16, v138
	v_ashrrev_i32_e32 v113, 31, v112
	v_lshlrev_b64 v[112:113], 9, v[112:113]
	v_lshl_add_u64 v[112:113], v[112:113], 0, s[20:21]
	v_and_b32_e32 v135, 0xffff0000, v138
	v_lshlrev_b32_e32 v154, 16, v140
	v_and_b32_e32 v155, 0xffff0000, v140
	v_lshl_add_u64 v[114:115], v[112:113], 0, v[172:173]
	v_lshlrev_b32_e32 v156, 16, v142
	v_and_b32_e32 v157, 0xffff0000, v142
	v_lshlrev_b32_e32 v158, 16, v144
	v_and_b32_e32 v159, 0xffff0000, v144
	v_pk_add_f32 v[108:109], v[108:109], v[134:135]
	v_pk_add_f32 v[104:105], v[104:105], v[154:155]
	v_lshlrev_b64 v[114:115], 1, v[114:115]
	v_pk_fma_f32 v[108:109], v[60:61], v[156:157], v[108:109]
	v_pk_fma_f32 v[104:105], v[56:57], v[158:159], v[104:105]
	v_lshl_add_u64 v[116:117], v[164:165], 0, v[114:115]
	v_mul_f32_e32 v0, 0x3d372713, v108
	v_mul_f32_e32 v131, 0x3d372713, v104
	v_mul_f32_e32 v134, 0x3d372713, v109
	global_load_dwordx4 v[124:127], v[116:117], off
	v_lshl_add_u64 v[114:115], v[166:167], 0, v[114:115]
	v_mul_f32_e32 v0, v108, v0
	v_mul_f32_e32 v131, v104, v131
	v_mul_f32_e32 v134, v109, v134
	global_load_dwordx4 v[120:123], v[114:115], off
	v_fma_f32 v0, v108, v0, v108
	v_fma_f32 v131, v104, v131, v104
	v_fma_f32 v134, v109, v134, v109
	v_mul_f32_e32 v0, 0x3fcc422a, v0
	v_mul_f32_e32 v131, 0x3fcc422a, v131
	v_mul_f32_e32 v134, 0x3fcc422a, v134
	v_mul_f32_e32 v0, 0xbfb8aa3b, v0
	v_mul_f32_e32 v131, 0xbfb8aa3b, v131
	v_mul_f32_e32 v134, 0xbfb8aa3b, v134
	v_exp_f32_e32 v0, v0
	v_exp_f32_e32 v131, v131
	v_exp_f32_e32 v134, v134
	v_mul_f32_e32 v135, 0x3d372713, v105
	v_add_f32_e32 v0, 1.0, v0
	v_add_f32_e32 v131, 1.0, v131
	v_add_f32_e32 v134, 1.0, v134
	v_rcp_f32_e32 v0, v0
	v_rcp_f32_e32 v131, v131
	v_rcp_f32_e32 v134, v134
	v_mul_f32_e32 v135, v105, v135
	v_lshlrev_b32_e32 v138, 16, v139
	v_and_b32_e32 v139, 0xffff0000, v139
	v_lshlrev_b32_e32 v140, 16, v141
	v_and_b32_e32 v141, 0xffff0000, v141
	v_fma_f32 v135, v105, v135, v105
	v_lshlrev_b32_e32 v142, 16, v143
	v_and_b32_e32 v143, 0xffff0000, v143
	v_lshlrev_b32_e32 v144, 16, v145
	v_and_b32_e32 v145, 0xffff0000, v145
	v_pk_add_f32 v[110:111], v[110:111], v[138:139]
	v_pk_add_f32 v[106:107], v[106:107], v[140:141]
	v_mul_f32_e32 v135, 0x3fcc422a, v135
	v_pk_fma_f32 v[110:111], v[62:63], v[142:143], v[110:111]
	v_pk_fma_f32 v[106:107], v[58:59], v[144:145], v[106:107]
	v_mul_f32_e32 v135, 0xbfb8aa3b, v135
	v_exp_f32_e32 v135, v135
	v_mul_f32_e32 v0, v108, v0
	v_mul_f32_e32 v108, v104, v131
	v_mul_f32_e32 v104, v109, v134
	v_mul_f32_e32 v131, 0x3d372713, v110
	v_mul_f32_e32 v134, 0x3d372713, v106
	v_mul_f32_e32 v131, v110, v131
	v_mul_f32_e32 v134, v106, v134
	v_fma_f32 v131, v110, v131, v110
	v_fma_f32 v134, v106, v134, v106
	v_mul_f32_e32 v131, 0x3fcc422a, v131
	v_mul_f32_e32 v134, 0x3fcc422a, v134
	v_add_f32_e32 v109, 1.0, v135
	v_mul_f32_e32 v131, 0xbfb8aa3b, v131
	v_mul_f32_e32 v134, 0xbfb8aa3b, v134
	v_rcp_f32_e32 v109, v109
	v_exp_f32_e32 v131, v131
	v_exp_f32_e32 v134, v134
	v_mul_f32_e32 v135, 0x3d372713, v107
	v_mul_f32_e32 v109, v105, v109
	v_add_f32_e32 v105, 1.0, v131
	v_add_f32_e32 v131, 1.0, v134
	v_mul_f32_e32 v134, 0x3d372713, v111
	v_mul_f32_e32 v134, v111, v134
	v_fma_f32 v134, v111, v134, v111
	v_mul_f32_e32 v135, v107, v135
	v_mul_f32_e32 v134, 0x3fcc422a, v134
	v_fma_f32 v135, v107, v135, v107
	v_mul_f32_e32 v134, 0xbfb8aa3b, v134
	v_mul_f32_e32 v135, 0x3fcc422a, v135
	v_exp_f32_e32 v134, v134
	v_mul_f32_e32 v135, 0xbfb8aa3b, v135
	v_exp_f32_e32 v135, v135
	v_lshl_add_u64 v[112:113], v[112:113], 0, v[174:175]
	v_add_f32_e32 v134, 1.0, v134
	v_lshlrev_b64 v[112:113], 1, v[112:113]
	v_rcp_f32_e32 v105, v105
	v_rcp_f32_e32 v131, v131
	v_rcp_f32_e32 v134, v134
	v_add_f32_e32 v135, 1.0, v135
	v_lshl_add_u64 v[114:115], v[164:165], 0, v[112:113]
; __device__ __forceinline__ float gelu_tanh(float y) { const float z = 1.5957691216057308f * (y + 0.044715f * y * y * y); return y * sigmoidf_(z); }
; __device__ __forceinline__ u32x4 pack8(const f32x4 a, const f32x4 b) { u32x4 w; w.x = cvt_pk_bf16(a[0], a[1]); w.y = cvt_pk_bf16(a[2], a[3]); w.z = cvt_pk_bf16(b[0], b[1]); w.w = cvt_pk_bf16(b[2], b[3]); return w; }
; __device__ __forceinline__ void unpack8(const u32x4 w, f32x4& a, f32x4& b) { a[0] = bf_lo(w.x); a[1] = bf_hi(w.x); a[2] = bf_lo(w.y); a[3] = bf_hi(w.y); b[0] = bf_lo(w.z); b[1] = bf_hi(w.z); b[2] = bf_lo(w.w); b[3] = bf_hi(w.w); }
;     template <int KIND> __device__ __forceinline__ void run(f32x4 (&acc)[2][2][4][2], const Unit& u, int tid_in) const {
;     ...
;                 for (int mh = 0; mh < 2; ++mh) { u32x4 yv[2][2], uv[2][2];
; #pragma unroll
;                     for (int ml = 0; ml < 2; ++ml) { int R = rbase + ai * 128 + (mh * 2 + ml) * 16; asm volatile("" : "+v"(R));
; #pragma unroll
;                         for (int bj = 0; bj < 2; ++bj) { const int t = 16 * u.pn + 8 * bj + 2 * wc + (fq >> 1); const size_t tok = (size_t)R * LCH + t;
;                             yv[ml][bj] = *(const u32x4*)(yi + ((size_t)g * T_TOK + tok) * 16 + 8 * (fq & 1)); uv[ml][bj] = *(const u32x4*)((const bf16_t*)x + ((size_t)g * T_TOK + tok) * 16 + 8 * (fq & 1)); } }
; #pragma unroll
;                     for (int ml = 0; ml < 2; ++ml) { const int m = mh * 2 + ml; int R = rbase + ai * 128 + m * 16; asm volatile("" : "+v"(R));
; #pragma unroll
;                         for (int bj = 0; bj < 2; ++bj) { const int t = 16 * u.pn + 8 * bj + 2 * wc + (fq >> 1); const size_t tok = (size_t)R * LCH + t;
;                             f32x4 y0, y1, u0, u1; unpack8(yv[ml][bj], y0, y1); unpack8(uv[ml][bj], u0, u1);
;                             y0 = acc[ai][bj][m][0] + y0 + d0 * u0; y1 = acc[ai][bj][m][1] + y1 + d1 * u1;
; #pragma unroll
;                             for (int j = 0; j < 4; ++j) { y0[j] = gelu_tanh(y0[j]); y1[j] = gelu_tanh(y1[j]); }
;                             *(u32x4*)(yi + ((size_t)g * T_TOK + tok) * 16 + 8 * (fq & 1)) = pack8(y0, y1); } }
	v_lshl_add_u64 v[112:113], v[166:167], 0, v[112:113]
	v_rcp_f32_e32 v135, v135
	global_load_dwordx4 v[116:119], v[114:115], off
	v_mul_f32_e32 v105, v110, v105
	global_load_dwordx4 v[112:115], v[112:113], off
	v_mul_f32_e32 v110, v106, v131
	v_ashrrev_i32_e32 v133, 31, v132
	v_lshlrev_b64 v[132:133], 10, v[132:133]
	v_lshl_add_u64 v[132:133], v[162:163], 0, v[132:133]
	v_mul_f32_e32 v106, v111, v134
	v_mul_f32_e32 v107, v107, v135
	v_cvt_pk_bf16_f32 v104, v0, v104
	v_cvt_pk_bf16_f32 v105, v105, v106
	v_cvt_pk_bf16_f32 v106, v108, v109
	v_lshl_add_u64 v[108:109], v[132:133], 0, v[136:137]
	v_cvt_pk_bf16_f32 v107, v110, v107
	global_store_dwordx4 v[108:109], v[104:107], off
	v_lshlrev_b32_e32 v108, 16, v148
	v_and_b32_e32 v109, 0xffff0000, v148
	v_lshlrev_b32_e32 v104, 16, v146
	v_and_b32_e32 v105, 0xffff0000, v146
	v_lshlrev_b32_e32 v134, 16, v150
	v_and_b32_e32 v135, 0xffff0000, v150
	v_lshlrev_b32_e32 v140, 16, v152
	v_and_b32_e32 v141, 0xffff0000, v152
	v_pk_add_f32 v[100:101], v[100:101], v[104:105]
	v_pk_add_f32 v[96:97], v[96:97], v[108:109]
	v_pk_fma_f32 v[100:101], v[60:61], v[134:135], v[100:101]
	v_pk_fma_f32 v[96:97], v[56:57], v[140:141], v[96:97]
	v_mul_f32_e32 v0, 0x3d372713, v100
	v_mul_f32_e32 v104, 0x3d372713, v96
	v_mul_f32_e32 v105, 0x3d372713, v101
	v_mul_f32_e32 v0, v100, v0
	v_mul_f32_e32 v104, v96, v104
	v_mul_f32_e32 v105, v101, v105
	v_fma_f32 v0, v100, v0, v100
	v_fma_f32 v104, v96, v104, v96
	v_fma_f32 v105, v101, v105, v101
	v_mul_f32_e32 v0, 0x3fcc422a, v0
	v_mul_f32_e32 v104, 0x3fcc422a, v104
	v_mul_f32_e32 v105, 0x3fcc422a, v105
	v_mul_f32_e32 v0, 0xbfb8aa3b, v0
	v_mul_f32_e32 v104, 0xbfb8aa3b, v104
	v_mul_f32_e32 v105, 0xbfb8aa3b, v105
	v_exp_f32_e32 v0, v0
	v_exp_f32_e32 v104, v104
	v_exp_f32_e32 v105, v105
	v_lshlrev_b32_e32 v106, 16, v147
	v_and_b32_e32 v107, 0xffff0000, v147
	v_pk_add_f32 v[102:103], v[102:103], v[106:107]
	v_add_f32_e32 v0, 1.0, v0
	v_add_f32_e32 v104, 1.0, v104
	v_add_f32_e32 v105, 1.0, v105
	v_mul_f32_e32 v106, 0x3d372713, v97
	v_rcp_f32_e32 v0, v0
	v_rcp_f32_e32 v104, v104
	v_rcp_f32_e32 v105, v105
	v_mul_f32_e32 v106, v97, v106
	v_lshlrev_b32_e32 v110, 16, v149
	v_and_b32_e32 v111, 0xffff0000, v149
	v_fma_f32 v106, v97, v106, v97
	v_lshlrev_b32_e32 v138, 16, v151
	v_and_b32_e32 v139, 0xffff0000, v151
	v_lshlrev_b32_e32 v142, 16, v153
	v_and_b32_e32 v143, 0xffff0000, v153
	v_pk_add_f32 v[98:99], v[98:99], v[110:111]
	v_mul_f32_e32 v106, 0x3fcc422a, v106
	v_pk_fma_f32 v[102:103], v[62:63], v[138:139], v[102:103]
	v_pk_fma_f32 v[98:99], v[58:59], v[142:143], v[98:99]
	v_mul_f32_e32 v106, 0xbfb8aa3b, v106
	v_exp_f32_e32 v106, v106
	v_mul_f32_e32 v0, v100, v0
	v_mul_f32_e32 v100, v96, v104
	v_mul_f32_e32 v96, v101, v105
	v_mul_f32_e32 v104, 0x3d372713, v102
	v_mul_f32_e32 v105, 0x3d372713, v98
	v_mul_f32_e32 v104, v102, v104
	v_mul_f32_e32 v105, v98, v105
	v_fma_f32 v104, v102, v104, v102
	v_fma_f32 v105, v98, v105, v98
	v_mul_f32_e32 v104, 0x3fcc422a, v104
	v_mul_f32_e32 v105, 0x3fcc422a, v105
	v_add_f32_e32 v101, 1.0, v106
	v_mul_f32_e32 v104, 0xbfb8aa3b, v104
	v_mul_f32_e32 v105, 0xbfb8aa3b, v105
	v_rcp_f32_e32 v101, v101
	v_exp_f32_e32 v104, v104
	v_exp_f32_e32 v105, v105
	v_mul_f32_e32 v106, 0x3d372713, v99
	v_mul_f32_e32 v101, v97, v101
	v_add_f32_e32 v97, 1.0, v104
	v_add_f32_e32 v104, 1.0, v105
	v_mul_f32_e32 v105, 0x3d372713, v103
	v_mul_f32_e32 v105, v103, v105
	v_mul_f32_e32 v106, v99, v106
	v_fma_f32 v105, v103, v105, v103
	v_fma_f32 v106, v99, v106, v99
	v_mul_f32_e32 v105, 0x3fcc422a, v105
	v_mul_f32_e32 v106, 0x3fcc422a, v106
	v_mul_f32_e32 v105, 0xbfb8aa3b, v105
	v_mul_f32_e32 v106, 0xbfb8aa3b, v106
	v_exp_f32_e32 v105, v105
	v_exp_f32_e32 v106, v106
	v_rcp_f32_e32 v97, v97
	v_rcp_f32_e32 v104, v104
	v_add_f32_e32 v105, 1.0, v105
	v_add_f32_e32 v106, 1.0, v106
	v_rcp_f32_e32 v105, v105
	v_rcp_f32_e32 v106, v106
	v_mul_f32_e32 v97, v102, v97
	v_mul_f32_e32 v102, v98, v104
	v_mul_f32_e32 v98, v103, v105
	v_mul_f32_e32 v99, v99, v106
	v_cvt_pk_bf16_f32 v96, v0, v96
	v_cvt_pk_bf16_f32 v97, v97, v98
	v_cvt_pk_bf16_f32 v98, v100, v101
	v_cvt_pk_bf16_f32 v99, v102, v99
	v_lshl_add_u64 v[100:101], v[132:133], 0, v[128:129]
	global_store_dwordx4 v[100:101], v[96:99], off
	s_waitcnt vmcnt(0)
	v_lshlrev_b32_e32 v102, 16, v126
	v_and_b32_e32 v103, 0xffff0000, v126
	v_lshlrev_b32_e32 v98, 16, v124
	v_and_b32_e32 v99, 0xffff0000, v124
	v_lshlrev_b32_e32 v106, 16, v120
	v_and_b32_e32 v107, 0xffff0000, v120
	v_lshlrev_b32_e32 v110, 16, v122
	v_and_b32_e32 v111, 0xffff0000, v122
	v_pk_add_f32 v[92:93], v[92:93], v[98:99]
	v_pk_add_f32 v[88:89], v[88:89], v[102:103]
	v_pk_fma_f32 v[92:93], v[60:61], v[106:107], v[92:93]
	v_pk_fma_f32 v[88:89], v[56:57], v[110:111], v[88:89]
	v_mul_f32_e32 v0, 0x3d372713, v92
	v_mul_f32_e32 v98, 0x3d372713, v88
	v_mul_f32_e32 v99, 0x3d372713, v93
	v_mul_f32_e32 v0, v92, v0
	v_mul_f32_e32 v98, v88, v98
	v_mul_f32_e32 v99, v93, v99
	v_fma_f32 v0, v92, v0, v92
	v_fma_f32 v98, v88, v98, v88
	v_fma_f32 v99, v93, v99, v93
	v_mul_f32_e32 v0, 0x3fcc422a, v0
	v_mul_f32_e32 v98, 0x3fcc422a, v98
	v_mul_f32_e32 v99, 0x3fcc422a, v99
	v_mul_f32_e32 v0, 0xbfb8aa3b, v0
	v_mul_f32_e32 v98, 0xbfb8aa3b, v98
	v_mul_f32_e32 v99, 0xbfb8aa3b, v99
	v_exp_f32_e32 v0, v0
	v_exp_f32_e32 v98, v98
	v_exp_f32_e32 v99, v99
	v_lshlrev_b32_e32 v100, 16, v125
	v_and_b32_e32 v101, 0xffff0000, v125
	v_pk_add_f32 v[94:95], v[94:95], v[100:101]
	v_add_f32_e32 v0, 1.0, v0
	v_add_f32_e32 v98, 1.0, v98
	v_add_f32_e32 v99, 1.0, v99
	v_mul_f32_e32 v100, 0x3d372713, v89
	v_rcp_f32_e32 v0, v0
	v_rcp_f32_e32 v98, v98
	v_rcp_f32_e32 v99, v99
	v_mul_f32_e32 v100, v89, v100
	v_lshlrev_b32_e32 v104, 16, v127
; __device__ __forceinline__ float gelu_tanh(float y) { const float z = 1.5957691216057308f * (y + 0.044715f * y * y * y); return y * sigmoidf_(z); }
; __device__ __forceinline__ u32x4 pack8(const f32x4 a, const f32x4 b) { u32x4 w; w.x = cvt_pk_bf16(a[0], a[1]); w.y = cvt_pk_bf16(a[2], a[3]); w.z = cvt_pk_bf16(b[0], b[1]); w.w = cvt_pk_bf16(b[2], b[3]); return w; }
; __device__ __forceinline__ void unpack8(const u32x4 w, f32x4& a, f32x4& b) { a[0] = bf_lo(w.x); a[1] = bf_hi(w.x); a[2] = bf_lo(w.y); a[3] = bf_hi(w.y); b[0] = bf_lo(w.z); b[1] = bf_hi(w.z); b[2] = bf_lo(w.w); b[3] = bf_hi(w.w); }
;     template <int KIND> __device__ __forceinline__ void run(f32x4 (&acc)[2][2][4][2], const Unit& u, int tid_in) const {
;     ...
;                 for (int mh = 0; mh < 2; ++mh) { u32x4 yv[2][2], uv[2][2];
; #pragma unroll
;                     for (int ml = 0; ml < 2; ++ml) { int R = rbase + ai * 128 + (mh * 2 + ml) * 16; asm volatile("" : "+v"(R));
; #pragma unroll
;                         for (int bj = 0; bj < 2; ++bj) { const int t = 16 * u.pn + 8 * bj + 2 * wc + (fq >> 1); const size_t tok = (size_t)R * LCH + t;
;                             yv[ml][bj] = *(const u32x4*)(yi + ((size_t)g * T_TOK + tok) * 16 + 8 * (fq & 1)); uv[ml][bj] = *(const u32x4*)((const bf16_t*)x + ((size_t)g * T_TOK + tok) * 16 + 8 * (fq & 1)); } }
; #pragma unroll
;                     for (int ml = 0; ml < 2; ++ml) { const int m = mh * 2 + ml; int R = rbase + ai * 128 + m * 16; asm volatile("" : "+v"(R));
; #pragma unroll
;                         for (int bj = 0; bj < 2; ++bj) { const int t = 16 * u.pn + 8 * bj + 2 * wc + (fq >> 1); const size_t tok = (size_t)R * LCH + t;
;                             f32x4 y0, y1, u0, u1; unpack8(yv[ml][bj], y0, y1); unpack8(uv[ml][bj], u0, u1);
;                             y0 = acc[ai][bj][m][0] + y0 + d0 * u0; y1 = acc[ai][bj][m][1] + y1 + d1 * u1;
; #pragma unroll
;                             for (int j = 0; j < 4; ++j) { y0[j] = gelu_tanh(y0[j]); y1[j] = gelu_tanh(y1[j]); }
;                             *(u32x4*)(yi + ((size_t)g * T_TOK + tok) * 16 + 8 * (fq & 1)) = pack8(y0, y1); } }
	v_and_b32_e32 v105, 0xffff0000, v127
	v_fma_f32 v100, v89, v100, v89
	v_lshlrev_b32_e32 v108, 16, v121
	v_and_b32_e32 v109, 0xffff0000, v121
	v_lshlrev_b32_e32 v120, 16, v123
	v_and_b32_e32 v121, 0xffff0000, v123
	v_pk_add_f32 v[90:91], v[90:91], v[104:105]
	v_mul_f32_e32 v100, 0x3fcc422a, v100
	v_pk_fma_f32 v[94:95], v[62:63], v[108:109], v[94:95]
	v_pk_fma_f32 v[90:91], v[58:59], v[120:121], v[90:91]
	v_mul_f32_e32 v100, 0xbfb8aa3b, v100
	v_exp_f32_e32 v100, v100
	v_mul_f32_e32 v0, v92, v0
	v_mul_f32_e32 v92, v88, v98
	v_mul_f32_e32 v88, v93, v99
	v_mul_f32_e32 v98, 0x3d372713, v94
	v_mul_f32_e32 v99, 0x3d372713, v90
	v_mul_f32_e32 v98, v94, v98
	v_mul_f32_e32 v99, v90, v99
	v_fma_f32 v98, v94, v98, v94
	v_fma_f32 v99, v90, v99, v90
	v_mul_f32_e32 v98, 0x3fcc422a, v98
	v_mul_f32_e32 v99, 0x3fcc422a, v99
	v_add_f32_e32 v93, 1.0, v100
	v_mul_f32_e32 v98, 0xbfb8aa3b, v98
	v_mul_f32_e32 v99, 0xbfb8aa3b, v99
	v_rcp_f32_e32 v93, v93
	v_exp_f32_e32 v98, v98
	v_exp_f32_e32 v99, v99
	v_mul_f32_e32 v100, 0x3d372713, v91
	v_mul_f32_e32 v93, v89, v93
	v_add_f32_e32 v89, 1.0, v98
	v_add_f32_e32 v98, 1.0, v99
	v_mul_f32_e32 v99, 0x3d372713, v95
	v_mul_f32_e32 v99, v95, v99
	v_fma_f32 v99, v95, v99, v95
	v_mul_f32_e32 v100, v91, v100
	v_mul_f32_e32 v99, 0x3fcc422a, v99
	v_fma_f32 v100, v91, v100, v91
	v_mul_f32_e32 v99, 0xbfb8aa3b, v99
	v_mul_f32_e32 v100, 0x3fcc422a, v100
	v_exp_f32_e32 v99, v99
	v_mul_f32_e32 v100, 0xbfb8aa3b, v100
	v_exp_f32_e32 v100, v100
	v_rcp_f32_e32 v89, v89
	v_add_f32_e32 v99, 1.0, v99
	v_rcp_f32_e32 v98, v98
	v_rcp_f32_e32 v99, v99
	v_add_f32_e32 v100, 1.0, v100
	v_rcp_f32_e32 v100, v100
	v_mul_f32_e32 v89, v94, v89
	v_ashrrev_i32_e32 v131, 31, v130
	v_lshlrev_b64 v[96:97], 10, v[130:131]
	v_lshl_add_u64 v[96:97], v[162:163], 0, v[96:97]
	v_mul_f32_e32 v94, v90, v98
	v_mul_f32_e32 v90, v95, v99
	v_mul_f32_e32 v91, v91, v100
	v_cvt_pk_bf16_f32 v88, v0, v88
	v_cvt_pk_bf16_f32 v89, v89, v90
	v_cvt_pk_bf16_f32 v90, v92, v93
	v_lshl_add_u64 v[92:93], v[96:97], 0, v[136:137]
	v_cvt_pk_bf16_f32 v91, v94, v91
	global_store_dwordx4 v[92:93], v[88:91], off
	v_lshlrev_b32_e32 v92, 16, v118
	v_and_b32_e32 v93, 0xffff0000, v118
	v_lshlrev_b32_e32 v88, 16, v116
	v_and_b32_e32 v89, 0xffff0000, v116
	v_lshlrev_b32_e32 v98, 16, v112
	v_and_b32_e32 v99, 0xffff0000, v112
	v_lshlrev_b32_e32 v102, 16, v114
	v_and_b32_e32 v103, 0xffff0000, v114
	v_pk_add_f32 v[84:85], v[84:85], v[88:89]
	v_pk_add_f32 v[80:81], v[80:81], v[92:93]
	v_pk_fma_f32 v[84:85], v[60:61], v[98:99], v[84:85]
	v_pk_fma_f32 v[80:81], v[56:57], v[102:103], v[80:81]
	v_mul_f32_e32 v0, 0x3d372713, v84
	v_mul_f32_e32 v88, 0x3d372713, v80
	v_mul_f32_e32 v89, 0x3d372713, v85
	v_mul_f32_e32 v0, v84, v0
	v_mul_f32_e32 v88, v80, v88
	v_mul_f32_e32 v89, v85, v89
	v_fma_f32 v0, v84, v0, v84
	v_fma_f32 v88, v80, v88, v80
	v_fma_f32 v89, v85, v89, v85
	v_mul_f32_e32 v0, 0x3fcc422a, v0
	v_mul_f32_e32 v88, 0x3fcc422a, v88
	v_mul_f32_e32 v89, 0x3fcc422a, v89
	v_mul_f32_e32 v0, 0xbfb8aa3b, v0
	v_mul_f32_e32 v88, 0xbfb8aa3b, v88
	v_mul_f32_e32 v89, 0xbfb8aa3b, v89
	v_exp_f32_e32 v0, v0
	v_exp_f32_e32 v88, v88
	v_exp_f32_e32 v89, v89
	v_lshlrev_b32_e32 v90, 16, v117
	v_and_b32_e32 v91, 0xffff0000, v117
	v_pk_add_f32 v[86:87], v[86:87], v[90:91]
	v_add_f32_e32 v0, 1.0, v0
	v_add_f32_e32 v88, 1.0, v88
	v_add_f32_e32 v89, 1.0, v89
	v_mul_f32_e32 v90, 0x3d372713, v81
	v_rcp_f32_e32 v0, v0
	v_rcp_f32_e32 v88, v88
	v_rcp_f32_e32 v89, v89
	v_mul_f32_e32 v90, v81, v90
	v_lshlrev_b32_e32 v94, 16, v119
	v_and_b32_e32 v95, 0xffff0000, v119
	v_fma_f32 v90, v81, v90, v81
	v_lshlrev_b32_e32 v100, 16, v113
	v_and_b32_e32 v101, 0xffff0000, v113
	v_lshlrev_b32_e32 v104, 16, v115
	v_and_b32_e32 v105, 0xffff0000, v115
	v_pk_add_f32 v[82:83], v[82:83], v[94:95]
	v_mul_f32_e32 v90, 0x3fcc422a, v90
	v_pk_fma_f32 v[86:87], v[62:63], v[100:101], v[86:87]
	v_pk_fma_f32 v[82:83], v[58:59], v[104:105], v[82:83]
	v_mul_f32_e32 v90, 0xbfb8aa3b, v90
	v_exp_f32_e32 v90, v90
	v_mul_f32_e32 v0, v84, v0
	v_mul_f32_e32 v84, v80, v88
	v_mul_f32_e32 v80, v85, v89
	v_mul_f32_e32 v88, 0x3d372713, v86
	v_mul_f32_e32 v89, 0x3d372713, v82
	v_mul_f32_e32 v88, v86, v88
	v_mul_f32_e32 v89, v82, v89
	v_fma_f32 v88, v86, v88, v86
	v_fma_f32 v89, v82, v89, v82
	v_mul_f32_e32 v88, 0x3fcc422a, v88
	v_mul_f32_e32 v89, 0x3fcc422a, v89
	v_add_f32_e32 v85, 1.0, v90
	v_mul_f32_e32 v88, 0xbfb8aa3b, v88
	v_mul_f32_e32 v89, 0xbfb8aa3b, v89
	v_rcp_f32_e32 v85, v85
	v_exp_f32_e32 v88, v88
	v_exp_f32_e32 v89, v89
	v_mul_f32_e32 v90, 0x3d372713, v83
	v_mul_f32_e32 v85, v81, v85
	v_add_f32_e32 v81, 1.0, v88
	v_add_f32_e32 v88, 1.0, v89
	v_mul_f32_e32 v89, 0x3d372713, v87
	v_mul_f32_e32 v89, v87, v89
	v_fma_f32 v89, v87, v89, v87
	v_mul_f32_e32 v90, v83, v90
	v_mul_f32_e32 v89, 0x3fcc422a, v89
	v_fma_f32 v90, v83, v90, v83
	v_mul_f32_e32 v89, 0xbfb8aa3b, v89
	v_mul_f32_e32 v90, 0x3fcc422a, v90
	v_exp_f32_e32 v89, v89
	v_mul_f32_e32 v90, 0xbfb8aa3b, v90
	v_exp_f32_e32 v90, v90
	v_rcp_f32_e32 v81, v81
	v_add_f32_e32 v89, 1.0, v89
	v_rcp_f32_e32 v88, v88
	v_rcp_f32_e32 v89, v89
	v_add_f32_e32 v90, 1.0, v90
	v_rcp_f32_e32 v90, v90
	v_mul_f32_e32 v81, v86, v81
	v_mul_f32_e32 v86, v82, v88
	v_mul_f32_e32 v82, v87, v89
	v_mul_f32_e32 v83, v83, v90
	v_cvt_pk_bf16_f32 v80, v0, v80
	v_cvt_pk_bf16_f32 v81, v81, v82
	v_cvt_pk_bf16_f32 v82, v84, v85
	v_lshl_add_u64 v[84:85], v[96:97], 0, v[128:129]
	v_add_u32_e32 v98, 0x80, v185
	v_cvt_pk_bf16_f32 v83, v86, v83
	global_store_dwordx4 v[84:85], v[80:83], off
	v_add_u32_e32 v96, 0x90, v185
	s_nop 0
	v_mov_b32_e32 v80, v98
	s_nop 0
	v_ashrrev_i32_e32 v81, 31, v80
	v_lshlrev_b64 v[80:81], 9, v[80:81]
	v_lshl_add_u64 v[80:81], v[80:81], 0, s[20:21]
	v_lshl_add_u64 v[82:83], v[80:81], 0, v[172:173]
	v_lshlrev_b64 v[82:83], 1, v[82:83]
	v_lshl_add_u64 v[84:85], v[164:165], 0, v[82:83]
	global_load_dwordx4 v[100:103], v[84:85], off
	v_lshl_add_u64 v[82:83], v[166:167], 0, v[82:83]
	global_load_dwordx4 v[104:107], v[82:83], off
	v_lshl_add_u64 v[80:81], v[80:81], 0, v[174:175]
	v_lshlrev_b64 v[80:81], 1, v[80:81]
	v_lshl_add_u64 v[82:83], v[164:165], 0, v[80:81]
	global_load_dwordx4 v[108:111], v[82:83], off
	v_lshl_add_u64 v[80:81], v[166:167], 0, v[80:81]
	global_load_dwordx4 v[112:115], v[80:81], off
	v_mov_b32_e32 v80, v96
	s_waitcnt vmcnt(0)
; __device__ __forceinline__ float gelu_tanh(float y) { const float z = 1.5957691216057308f * (y + 0.044715f * y * y * y); return y * sigmoidf_(z); }
; __device__ __forceinline__ u32x4 pack8(const f32x4 a, const f32x4 b) { u32x4 w; w.x = cvt_pk_bf16(a[0], a[1]); w.y = cvt_pk_bf16(a[2], a[3]); w.z = cvt_pk_bf16(b[0], b[1]); w.w = cvt_pk_bf16(b[2], b[3]); return w; }
; __device__ __forceinline__ void unpack8(const u32x4 w, f32x4& a, f32x4& b) { a[0] = bf_lo(w.x); a[1] = bf_hi(w.x); a[2] = bf_lo(w.y); a[3] = bf_hi(w.y); b[0] = bf_lo(w.z); b[1] = bf_hi(w.z); b[2] = bf_lo(w.w); b[3] = bf_hi(w.w); }
;     template <int KIND> __device__ __forceinline__ void run(f32x4 (&acc)[2][2][4][2], const Unit& u, int tid_in) const {
;     ...
;                 for (int mh = 0; mh < 2; ++mh) { u32x4 yv[2][2], uv[2][2];
; #pragma unroll
;                     for (int ml = 0; ml < 2; ++ml) { int R = rbase + ai * 128 + (mh * 2 + ml) * 16; asm volatile("" : "+v"(R));
; #pragma unroll
;                         for (int bj = 0; bj < 2; ++bj) { const int t = 16 * u.pn + 8 * bj + 2 * wc + (fq >> 1); const size_t tok = (size_t)R * LCH + t;
;                             yv[ml][bj] = *(const u32x4*)(yi + ((size_t)g * T_TOK + tok) * 16 + 8 * (fq & 1)); uv[ml][bj] = *(const u32x4*)((const bf16_t*)x + ((size_t)g * T_TOK + tok) * 16 + 8 * (fq & 1)); } }
; #pragma unroll
;                     for (int ml = 0; ml < 2; ++ml) { const int m = mh * 2 + ml; int R = rbase + ai * 128 + m * 16; asm volatile("" : "+v"(R));
; #pragma unroll
;                         for (int bj = 0; bj < 2; ++bj) { const int t = 16 * u.pn + 8 * bj + 2 * wc + (fq >> 1); const size_t tok = (size_t)R * LCH + t;
;                             f32x4 y0, y1, u0, u1; unpack8(yv[ml][bj], y0, y1); unpack8(uv[ml][bj], u0, u1);
;                             y0 = acc[ai][bj][m][0] + y0 + d0 * u0; y1 = acc[ai][bj][m][1] + y1 + d1 * u1;
; #pragma unroll
;                             for (int j = 0; j < 4; ++j) { y0[j] = gelu_tanh(y0[j]); y1[j] = gelu_tanh(y1[j]); }
;                             *(u32x4*)(yi + ((size_t)g * T_TOK + tok) * 16 + 8 * (fq & 1)) = pack8(y0, y1); } }
	v_lshlrev_b32_e32 v116, 16, v100
	v_ashrrev_i32_e32 v81, 31, v80
	v_lshlrev_b64 v[80:81], 9, v[80:81]
	v_lshl_add_u64 v[80:81], v[80:81], 0, s[20:21]
	v_and_b32_e32 v117, 0xffff0000, v100
	v_lshlrev_b32_e32 v118, 16, v102
	v_and_b32_e32 v119, 0xffff0000, v102
	v_lshl_add_u64 v[82:83], v[80:81], 0, v[172:173]
	v_lshlrev_b32_e32 v120, 16, v104
	v_and_b32_e32 v121, 0xffff0000, v104
	v_lshlrev_b32_e32 v122, 16, v106
	v_and_b32_e32 v123, 0xffff0000, v106
	v_pk_add_f32 v[76:77], v[76:77], v[116:117]
	v_pk_add_f32 v[72:73], v[72:73], v[118:119]
	v_lshlrev_b64 v[82:83], 1, v[82:83]
	v_lshlrev_b32_e32 v100, 16, v101
	v_and_b32_e32 v101, 0xffff0000, v101
	v_pk_fma_f32 v[76:77], v[60:61], v[120:121], v[76:77]
	v_pk_fma_f32 v[72:73], v[56:57], v[122:123], v[72:73]
	v_lshl_add_u64 v[84:85], v[164:165], 0, v[82:83]
	v_pk_add_f32 v[78:79], v[78:79], v[100:101]
	v_mul_f32_e32 v0, 0x3d372713, v76
	v_mul_f32_e32 v97, 0x3d372713, v72
	v_mul_f32_e32 v100, 0x3d372713, v77
	global_load_dwordx4 v[92:95], v[84:85], off
	v_lshl_add_u64 v[82:83], v[166:167], 0, v[82:83]
	v_mul_f32_e32 v0, v76, v0
	v_mul_f32_e32 v97, v72, v97
	v_mul_f32_e32 v100, v77, v100
	global_load_dwordx4 v[88:91], v[82:83], off
	v_fma_f32 v0, v76, v0, v76
	v_fma_f32 v97, v72, v97, v72
	v_fma_f32 v100, v77, v100, v77
	v_mul_f32_e32 v0, 0x3fcc422a, v0
	v_mul_f32_e32 v97, 0x3fcc422a, v97
	v_mul_f32_e32 v100, 0x3fcc422a, v100
	v_mul_f32_e32 v0, 0xbfb8aa3b, v0
	v_mul_f32_e32 v97, 0xbfb8aa3b, v97
	v_mul_f32_e32 v100, 0xbfb8aa3b, v100
	v_exp_f32_e32 v0, v0
	v_exp_f32_e32 v97, v97
	v_exp_f32_e32 v100, v100
	v_mul_f32_e32 v101, 0x3d372713, v73
	v_add_f32_e32 v0, 1.0, v0
	v_add_f32_e32 v97, 1.0, v97
	v_add_f32_e32 v100, 1.0, v100
	v_rcp_f32_e32 v0, v0
	v_rcp_f32_e32 v97, v97
	v_rcp_f32_e32 v100, v100
	v_mul_f32_e32 v101, v73, v101
	v_lshlrev_b32_e32 v102, 16, v103
	v_and_b32_e32 v103, 0xffff0000, v103
	v_fma_f32 v101, v73, v101, v73
	v_lshlrev_b32_e32 v104, 16, v105
	v_and_b32_e32 v105, 0xffff0000, v105
	v_lshlrev_b32_e32 v106, 16, v107
	v_and_b32_e32 v107, 0xffff0000, v107
	v_pk_add_f32 v[74:75], v[74:75], v[102:103]
	v_mul_f32_e32 v101, 0x3fcc422a, v101
	v_pk_fma_f32 v[78:79], v[62:63], v[104:105], v[78:79]
	v_pk_fma_f32 v[74:75], v[58:59], v[106:107], v[74:75]
	v_mul_f32_e32 v101, 0xbfb8aa3b, v101
	v_exp_f32_e32 v101, v101
	v_mul_f32_e32 v0, v76, v0
	v_mul_f32_e32 v76, v72, v97
	v_mul_f32_e32 v72, v77, v100
	v_mul_f32_e32 v97, 0x3d372713, v78
	v_mul_f32_e32 v100, 0x3d372713, v74
	v_mul_f32_e32 v97, v78, v97
	v_mul_f32_e32 v100, v74, v100
	v_fma_f32 v97, v78, v97, v78
	v_fma_f32 v100, v74, v100, v74
	v_mul_f32_e32 v97, 0x3fcc422a, v97
	v_mul_f32_e32 v100, 0x3fcc422a, v100
	v_add_f32_e32 v77, 1.0, v101
	v_mul_f32_e32 v97, 0xbfb8aa3b, v97
	v_mul_f32_e32 v100, 0xbfb8aa3b, v100
	v_rcp_f32_e32 v77, v77
	v_exp_f32_e32 v97, v97
	v_exp_f32_e32 v100, v100
	v_mul_f32_e32 v101, 0x3d372713, v75
	v_mul_f32_e32 v77, v73, v77
	v_add_f32_e32 v73, 1.0, v97
	v_add_f32_e32 v97, 1.0, v100
	v_mul_f32_e32 v100, 0x3d372713, v79
	v_mul_f32_e32 v100, v79, v100
	v_fma_f32 v100, v79, v100, v79
	v_mul_f32_e32 v101, v75, v101
	v_mul_f32_e32 v100, 0x3fcc422a, v100
	v_fma_f32 v101, v75, v101, v75
	v_mul_f32_e32 v100, 0xbfb8aa3b, v100
	v_mul_f32_e32 v101, 0x3fcc422a, v101
	v_exp_f32_e32 v100, v100
	v_mul_f32_e32 v101, 0xbfb8aa3b, v101
	v_exp_f32_e32 v101, v101
	v_lshl_add_u64 v[80:81], v[80:81], 0, v[174:175]
	v_add_f32_e32 v100, 1.0, v100
	v_lshlrev_b64 v[80:81], 1, v[80:81]
	v_rcp_f32_e32 v73, v73
	v_rcp_f32_e32 v97, v97
	v_rcp_f32_e32 v100, v100
	v_add_f32_e32 v101, 1.0, v101
	v_lshl_add_u64 v[82:83], v[164:165], 0, v[80:81]
	v_lshl_add_u64 v[80:81], v[166:167], 0, v[80:81]
	v_rcp_f32_e32 v101, v101
	global_load_dwordx4 v[84:87], v[82:83], off
	v_mul_f32_e32 v73, v78, v73
	global_load_dwordx4 v[80:83], v[80:81], off
	v_mul_f32_e32 v78, v74, v97
	v_ashrrev_i32_e32 v99, 31, v98
	v_lshlrev_b64 v[98:99], 10, v[98:99]
	v_lshl_add_u64 v[98:99], v[162:163], 0, v[98:99]
	v_mul_f32_e32 v74, v79, v100
	v_mul_f32_e32 v75, v75, v101
	v_cvt_pk_bf16_f32 v72, v0, v72
	v_cvt_pk_bf16_f32 v73, v73, v74
	v_cvt_pk_bf16_f32 v74, v76, v77
	v_lshl_add_u64 v[76:77], v[98:99], 0, v[136:137]
	v_cvt_pk_bf16_f32 v75, v78, v75
	global_store_dwordx4 v[76:77], v[72:75], off
	v_lshlrev_b32_e32 v76, 16, v110
	v_and_b32_e32 v77, 0xffff0000, v110
	v_lshlrev_b32_e32 v72, 16, v108
	v_and_b32_e32 v73, 0xffff0000, v108
	v_lshlrev_b32_e32 v100, 16, v112
	v_and_b32_e32 v101, 0xffff0000, v112
	v_lshlrev_b32_e32 v104, 16, v114
	v_and_b32_e32 v105, 0xffff0000, v114
	v_pk_add_f32 v[68:69], v[68:69], v[72:73]
	v_pk_add_f32 v[64:65], v[64:65], v[76:77]
	v_pk_fma_f32 v[68:69], v[60:61], v[100:101], v[68:69]
	v_pk_fma_f32 v[64:65], v[56:57], v[104:105], v[64:65]
	v_mul_f32_e32 v0, 0x3d372713, v68
	v_mul_f32_e32 v72, 0x3d372713, v64
	v_mul_f32_e32 v73, 0x3d372713, v69
	v_mul_f32_e32 v0, v68, v0
	v_mul_f32_e32 v72, v64, v72
	v_mul_f32_e32 v73, v69, v73
	v_fma_f32 v0, v68, v0, v68
	v_fma_f32 v72, v64, v72, v64
	v_fma_f32 v73, v69, v73, v69
	v_mul_f32_e32 v0, 0x3fcc422a, v0
	v_mul_f32_e32 v72, 0x3fcc422a, v72
	v_mul_f32_e32 v73, 0x3fcc422a, v73
	v_mul_f32_e32 v0, 0xbfb8aa3b, v0
	v_mul_f32_e32 v72, 0xbfb8aa3b, v72
	v_mul_f32_e32 v73, 0xbfb8aa3b, v73
	v_exp_f32_e32 v0, v0
	v_exp_f32_e32 v72, v72
	v_exp_f32_e32 v73, v73
	v_lshlrev_b32_e32 v74, 16, v109
	v_and_b32_e32 v75, 0xffff0000, v109
	v_pk_add_f32 v[70:71], v[70:71], v[74:75]
	v_add_f32_e32 v0, 1.0, v0
	v_add_f32_e32 v72, 1.0, v72
	v_add_f32_e32 v73, 1.0, v73
	v_mul_f32_e32 v74, 0x3d372713, v65
	v_rcp_f32_e32 v0, v0
	v_rcp_f32_e32 v72, v72
	v_rcp_f32_e32 v73, v73
	v_mul_f32_e32 v74, v65, v74
	v_lshlrev_b32_e32 v78, 16, v111
; __device__ __forceinline__ float gelu_tanh(float y) { const float z = 1.5957691216057308f * (y + 0.044715f * y * y * y); return y * sigmoidf_(z); }
; __device__ __forceinline__ u32x4 pack8(const f32x4 a, const f32x4 b) { u32x4 w; w.x = cvt_pk_bf16(a[0], a[1]); w.y = cvt_pk_bf16(a[2], a[3]); w.z = cvt_pk_bf16(b[0], b[1]); w.w = cvt_pk_bf16(b[2], b[3]); return w; }
; __device__ __forceinline__ void unpack8(const u32x4 w, f32x4& a, f32x4& b) { a[0] = bf_lo(w.x); a[1] = bf_hi(w.x); a[2] = bf_lo(w.y); a[3] = bf_hi(w.y); b[0] = bf_lo(w.z); b[1] = bf_hi(w.z); b[2] = bf_lo(w.w); b[3] = bf_hi(w.w); }
;     template <int KIND> __device__ __forceinline__ void run(f32x4 (&acc)[2][2][4][2], const Unit& u, int tid_in) const {
;     ...
;                 for (int mh = 0; mh < 2; ++mh) { u32x4 yv[2][2], uv[2][2];
; #pragma unroll
;                     for (int ml = 0; ml < 2; ++ml) { int R = rbase + ai * 128 + (mh * 2 + ml) * 16; asm volatile("" : "+v"(R));
; #pragma unroll
;                         for (int bj = 0; bj < 2; ++bj) { const int t = 16 * u.pn + 8 * bj + 2 * wc + (fq >> 1); const size_t tok = (size_t)R * LCH + t;
;                             yv[ml][bj] = *(const u32x4*)(yi + ((size_t)g * T_TOK + tok) * 16 + 8 * (fq & 1)); uv[ml][bj] = *(const u32x4*)((const bf16_t*)x + ((size_t)g * T_TOK + tok) * 16 + 8 * (fq & 1)); } }
; #pragma unroll
;                     for (int ml = 0; ml < 2; ++ml) { const int m = mh * 2 + ml; int R = rbase + ai * 128 + m * 16; asm volatile("" : "+v"(R));
; #pragma unroll
;                         for (int bj = 0; bj < 2; ++bj) { const int t = 16 * u.pn + 8 * bj + 2 * wc + (fq >> 1); const size_t tok = (size_t)R * LCH + t;
;                             f32x4 y0, y1, u0, u1; unpack8(yv[ml][bj], y0, y1); unpack8(uv[ml][bj], u0, u1);
;                             y0 = acc[ai][bj][m][0] + y0 + d0 * u0; y1 = acc[ai][bj][m][1] + y1 + d1 * u1;
; #pragma unroll
;                             for (int j = 0; j < 4; ++j) { y0[j] = gelu_tanh(y0[j]); y1[j] = gelu_tanh(y1[j]); }
;                             *(u32x4*)(yi + ((size_t)g * T_TOK + tok) * 16 + 8 * (fq & 1)) = pack8(y0, y1); } }
	v_and_b32_e32 v79, 0xffff0000, v111
	v_fma_f32 v74, v65, v74, v65
	v_lshlrev_b32_e32 v102, 16, v113
	v_and_b32_e32 v103, 0xffff0000, v113
	v_lshlrev_b32_e32 v106, 16, v115
	v_and_b32_e32 v107, 0xffff0000, v115
	v_pk_add_f32 v[66:67], v[66:67], v[78:79]
	v_mul_f32_e32 v74, 0x3fcc422a, v74
	v_pk_fma_f32 v[70:71], v[62:63], v[102:103], v[70:71]
	v_pk_fma_f32 v[66:67], v[58:59], v[106:107], v[66:67]
	v_mul_f32_e32 v74, 0xbfb8aa3b, v74
	v_exp_f32_e32 v74, v74
	v_mul_f32_e32 v0, v68, v0
	v_mul_f32_e32 v68, v64, v72
	v_mul_f32_e32 v64, v69, v73
	v_mul_f32_e32 v72, 0x3d372713, v70
	v_mul_f32_e32 v73, 0x3d372713, v66
	v_mul_f32_e32 v72, v70, v72
	v_mul_f32_e32 v73, v66, v73
	v_fma_f32 v72, v70, v72, v70
	v_fma_f32 v73, v66, v73, v66
	v_mul_f32_e32 v72, 0x3fcc422a, v72
	v_mul_f32_e32 v73, 0x3fcc422a, v73
	v_add_f32_e32 v69, 1.0, v74
	v_mul_f32_e32 v72, 0xbfb8aa3b, v72
	v_mul_f32_e32 v73, 0xbfb8aa3b, v73
	v_rcp_f32_e32 v69, v69
	v_exp_f32_e32 v72, v72
	v_exp_f32_e32 v73, v73
	v_mul_f32_e32 v74, 0x3d372713, v67
	v_mul_f32_e32 v69, v65, v69
	v_add_f32_e32 v65, 1.0, v72
	v_add_f32_e32 v72, 1.0, v73
	v_mul_f32_e32 v73, 0x3d372713, v71
	v_mul_f32_e32 v73, v71, v73
	v_mul_f32_e32 v74, v67, v74
	v_fma_f32 v73, v71, v73, v71
	v_fma_f32 v74, v67, v74, v67
	v_mul_f32_e32 v73, 0x3fcc422a, v73
	v_mul_f32_e32 v74, 0x3fcc422a, v74
	v_mul_f32_e32 v73, 0xbfb8aa3b, v73
	v_mul_f32_e32 v74, 0xbfb8aa3b, v74
	v_exp_f32_e32 v73, v73
	v_exp_f32_e32 v74, v74
	v_rcp_f32_e32 v65, v65
	v_rcp_f32_e32 v72, v72
	v_add_f32_e32 v73, 1.0, v73
	v_add_f32_e32 v74, 1.0, v74
	v_rcp_f32_e32 v73, v73
	v_rcp_f32_e32 v74, v74
	v_mul_f32_e32 v65, v70, v65
	v_mul_f32_e32 v70, v66, v72
	v_mul_f32_e32 v66, v71, v73
	v_mul_f32_e32 v67, v67, v74
	v_cvt_pk_bf16_f32 v64, v0, v64
	v_cvt_pk_bf16_f32 v65, v65, v66
	v_cvt_pk_bf16_f32 v66, v68, v69
	v_cvt_pk_bf16_f32 v67, v70, v67
	v_lshl_add_u64 v[68:69], v[98:99], 0, v[128:129]
	global_store_dwordx4 v[68:69], v[64:67], off
	s_waitcnt vmcnt(0)
	v_lshlrev_b32_e32 v70, 16, v94
	v_and_b32_e32 v71, 0xffff0000, v94
	v_lshlrev_b32_e32 v66, 16, v92
	v_and_b32_e32 v67, 0xffff0000, v92
	v_lshlrev_b32_e32 v74, 16, v88
	v_and_b32_e32 v75, 0xffff0000, v88
	v_lshlrev_b32_e32 v78, 16, v90
	v_and_b32_e32 v79, 0xffff0000, v90
	v_pk_add_f32 v[52:53], v[52:53], v[66:67]
	v_pk_add_f32 v[48:49], v[48:49], v[70:71]
	v_pk_fma_f32 v[52:53], v[60:61], v[74:75], v[52:53]
	v_pk_fma_f32 v[48:49], v[56:57], v[78:79], v[48:49]
	v_mul_f32_e32 v0, 0x3d372713, v52
	v_mul_f32_e32 v66, 0x3d372713, v48
	v_mul_f32_e32 v67, 0x3d372713, v53
	v_mul_f32_e32 v0, v52, v0
	v_mul_f32_e32 v66, v48, v66
	v_mul_f32_e32 v67, v53, v67
	v_fma_f32 v0, v52, v0, v52
	v_fma_f32 v66, v48, v66, v48
	v_fma_f32 v67, v53, v67, v53
	v_mul_f32_e32 v0, 0x3fcc422a, v0
	v_mul_f32_e32 v66, 0x3fcc422a, v66
	v_mul_f32_e32 v67, 0x3fcc422a, v67
	v_mul_f32_e32 v0, 0xbfb8aa3b, v0
	v_mul_f32_e32 v66, 0xbfb8aa3b, v66
	v_mul_f32_e32 v67, 0xbfb8aa3b, v67
	v_exp_f32_e32 v0, v0
	v_exp_f32_e32 v66, v66
	v_exp_f32_e32 v67, v67
	v_lshlrev_b32_e32 v68, 16, v93
	v_and_b32_e32 v69, 0xffff0000, v93
	v_pk_add_f32 v[54:55], v[54:55], v[68:69]
	v_add_f32_e32 v0, 1.0, v0
	v_add_f32_e32 v66, 1.0, v66
	v_add_f32_e32 v67, 1.0, v67
	v_mul_f32_e32 v68, 0x3d372713, v49
	v_rcp_f32_e32 v0, v0
	v_rcp_f32_e32 v66, v66
	v_rcp_f32_e32 v67, v67
	v_mul_f32_e32 v68, v49, v68
	v_lshlrev_b32_e32 v72, 16, v95
	v_and_b32_e32 v73, 0xffff0000, v95
	v_fma_f32 v68, v49, v68, v49
	v_lshlrev_b32_e32 v76, 16, v89
	v_and_b32_e32 v77, 0xffff0000, v89
	v_lshlrev_b32_e32 v88, 16, v91
	v_and_b32_e32 v89, 0xffff0000, v91
	v_pk_add_f32 v[50:51], v[50:51], v[72:73]
	v_mul_f32_e32 v68, 0x3fcc422a, v68
	v_pk_fma_f32 v[54:55], v[62:63], v[76:77], v[54:55]
	v_pk_fma_f32 v[50:51], v[58:59], v[88:89], v[50:51]
	v_mul_f32_e32 v68, 0xbfb8aa3b, v68
	v_exp_f32_e32 v68, v68
	v_mul_f32_e32 v0, v52, v0
	v_mul_f32_e32 v52, v48, v66
	v_mul_f32_e32 v48, v53, v67
	v_mul_f32_e32 v66, 0x3d372713, v54
	v_mul_f32_e32 v67, 0x3d372713, v50
	v_mul_f32_e32 v66, v54, v66
	v_mul_f32_e32 v67, v50, v67
	v_fma_f32 v66, v54, v66, v54
	v_fma_f32 v67, v50, v67, v50
	v_mul_f32_e32 v66, 0x3fcc422a, v66
	v_mul_f32_e32 v67, 0x3fcc422a, v67
	v_add_f32_e32 v53, 1.0, v68
	v_mul_f32_e32 v66, 0xbfb8aa3b, v66
	v_mul_f32_e32 v67, 0xbfb8aa3b, v67
	v_rcp_f32_e32 v53, v53
	v_exp_f32_e32 v66, v66
	v_exp_f32_e32 v67, v67
	v_mul_f32_e32 v68, 0x3d372713, v51
	v_mul_f32_e32 v53, v49, v53
	v_add_f32_e32 v49, 1.0, v66
	v_add_f32_e32 v66, 1.0, v67
	v_mul_f32_e32 v67, 0x3d372713, v55
	v_mul_f32_e32 v67, v55, v67
	v_fma_f32 v67, v55, v67, v55
	v_mul_f32_e32 v68, v51, v68
	v_mul_f32_e32 v67, 0x3fcc422a, v67
	v_fma_f32 v68, v51, v68, v51
	v_mul_f32_e32 v67, 0xbfb8aa3b, v67
	v_mul_f32_e32 v68, 0x3fcc422a, v68
	v_exp_f32_e32 v67, v67
	v_mul_f32_e32 v68, 0xbfb8aa3b, v68
	v_exp_f32_e32 v68, v68
	v_rcp_f32_e32 v49, v49
	v_add_f32_e32 v67, 1.0, v67
	v_rcp_f32_e32 v66, v66
	v_rcp_f32_e32 v67, v67
	v_add_f32_e32 v68, 1.0, v68
	v_rcp_f32_e32 v68, v68
	v_mul_f32_e32 v49, v54, v49
	v_ashrrev_i32_e32 v97, 31, v96
	v_lshlrev_b64 v[64:65], 10, v[96:97]
	v_lshl_add_u64 v[64:65], v[162:163], 0, v[64:65]
	v_mul_f32_e32 v54, v50, v66
	v_mul_f32_e32 v50, v55, v67
	v_mul_f32_e32 v51, v51, v68
	v_cvt_pk_bf16_f32 v48, v0, v48
	v_cvt_pk_bf16_f32 v49, v49, v50
	v_cvt_pk_bf16_f32 v50, v52, v53
	v_lshl_add_u64 v[52:53], v[64:65], 0, v[136:137]
	v_cvt_pk_bf16_f32 v51, v54, v51
	global_store_dwordx4 v[52:53], v[48:51], off
	v_lshlrev_b32_e32 v52, 16, v86
	v_and_b32_e32 v53, 0xffff0000, v86
	v_lshlrev_b32_e32 v48, 16, v84
	v_and_b32_e32 v49, 0xffff0000, v84
	v_lshlrev_b32_e32 v66, 16, v80
	v_and_b32_e32 v67, 0xffff0000, v80
	v_lshlrev_b32_e32 v70, 16, v82
; __device__ __forceinline__ float gelu_tanh(float y) { const float z = 1.5957691216057308f * (y + 0.044715f * y * y * y); return y * sigmoidf_(z); }
; __device__ __forceinline__ u32x4 pack8(const f32x4 a, const f32x4 b) { u32x4 w; w.x = cvt_pk_bf16(a[0], a[1]); w.y = cvt_pk_bf16(a[2], a[3]); w.z = cvt_pk_bf16(b[0], b[1]); w.w = cvt_pk_bf16(b[2], b[3]); return w; }
; __device__ __forceinline__ void unpack8(const u32x4 w, f32x4& a, f32x4& b) { a[0] = bf_lo(w.x); a[1] = bf_hi(w.x); a[2] = bf_lo(w.y); a[3] = bf_hi(w.y); b[0] = bf_lo(w.z); b[1] = bf_hi(w.z); b[2] = bf_lo(w.w); b[3] = bf_hi(w.w); }
;     template <int KIND> __device__ __forceinline__ void run(f32x4 (&acc)[2][2][4][2], const Unit& u, int tid_in) const {
;     ...
;                 for (int mh = 0; mh < 2; ++mh) { u32x4 yv[2][2], uv[2][2];
; #pragma unroll
;                     for (int ml = 0; ml < 2; ++ml) { int R = rbase + ai * 128 + (mh * 2 + ml) * 16; asm volatile("" : "+v"(R));
; #pragma unroll
;                         for (int bj = 0; bj < 2; ++bj) { const int t = 16 * u.pn + 8 * bj + 2 * wc + (fq >> 1); const size_t tok = (size_t)R * LCH + t;
;                             yv[ml][bj] = *(const u32x4*)(yi + ((size_t)g * T_TOK + tok) * 16 + 8 * (fq & 1)); uv[ml][bj] = *(const u32x4*)((const bf16_t*)x + ((size_t)g * T_TOK + tok) * 16 + 8 * (fq & 1)); } }
; #pragma unroll
;                     for (int ml = 0; ml < 2; ++ml) { const int m = mh * 2 + ml; int R = rbase + ai * 128 + m * 16; asm volatile("" : "+v"(R));
; #pragma unroll
;                         for (int bj = 0; bj < 2; ++bj) { const int t = 16 * u.pn + 8 * bj + 2 * wc + (fq >> 1); const size_t tok = (size_t)R * LCH + t;
;                             f32x4 y0, y1, u0, u1; unpack8(yv[ml][bj], y0, y1); unpack8(uv[ml][bj], u0, u1);
;                             y0 = acc[ai][bj][m][0] + y0 + d0 * u0; y1 = acc[ai][bj][m][1] + y1 + d1 * u1;
; #pragma unroll
;                             for (int j = 0; j < 4; ++j) { y0[j] = gelu_tanh(y0[j]); y1[j] = gelu_tanh(y1[j]); }
;                             *(u32x4*)(yi + ((size_t)g * T_TOK + tok) * 16 + 8 * (fq & 1)) = pack8(y0, y1); } }
	v_and_b32_e32 v71, 0xffff0000, v82
	v_pk_add_f32 v[44:45], v[44:45], v[48:49]
	v_pk_add_f32 v[40:41], v[40:41], v[52:53]
	v_pk_fma_f32 v[44:45], v[60:61], v[66:67], v[44:45]
	v_pk_fma_f32 v[40:41], v[56:57], v[70:71], v[40:41]
	v_mul_f32_e32 v0, 0x3d372713, v44
	v_mul_f32_e32 v48, 0x3d372713, v40
	v_mul_f32_e32 v49, 0x3d372713, v45
	v_mul_f32_e32 v0, v44, v0
	v_mul_f32_e32 v48, v40, v48
	v_mul_f32_e32 v49, v45, v49
	v_fma_f32 v0, v44, v0, v44
	v_fma_f32 v48, v40, v48, v40
	v_fma_f32 v49, v45, v49, v45
	v_mul_f32_e32 v0, 0x3fcc422a, v0
	v_mul_f32_e32 v48, 0x3fcc422a, v48
	v_mul_f32_e32 v49, 0x3fcc422a, v49
	v_mul_f32_e32 v0, 0xbfb8aa3b, v0
	v_mul_f32_e32 v48, 0xbfb8aa3b, v48
	v_mul_f32_e32 v49, 0xbfb8aa3b, v49
	v_exp_f32_e32 v0, v0
	v_exp_f32_e32 v48, v48
	v_exp_f32_e32 v49, v49
	v_lshlrev_b32_e32 v50, 16, v85
	v_and_b32_e32 v51, 0xffff0000, v85
	v_pk_add_f32 v[46:47], v[46:47], v[50:51]
	v_add_f32_e32 v0, 1.0, v0
	v_add_f32_e32 v48, 1.0, v48
	v_add_f32_e32 v49, 1.0, v49
	v_mul_f32_e32 v50, 0x3d372713, v41
	v_rcp_f32_e32 v0, v0
	v_rcp_f32_e32 v48, v48
	v_rcp_f32_e32 v49, v49
	v_mul_f32_e32 v50, v41, v50
	v_lshlrev_b32_e32 v54, 16, v87
	v_and_b32_e32 v55, 0xffff0000, v87
	v_fma_f32 v50, v41, v50, v41
	v_lshlrev_b32_e32 v68, 16, v81
	v_and_b32_e32 v69, 0xffff0000, v81
	v_lshlrev_b32_e32 v72, 16, v83
	v_and_b32_e32 v73, 0xffff0000, v83
	v_pk_add_f32 v[42:43], v[42:43], v[54:55]
	v_mul_f32_e32 v50, 0x3fcc422a, v50
	v_pk_fma_f32 v[46:47], v[62:63], v[68:69], v[46:47]
	v_pk_fma_f32 v[42:43], v[58:59], v[72:73], v[42:43]
	v_mul_f32_e32 v50, 0xbfb8aa3b, v50
	v_exp_f32_e32 v50, v50
	v_mul_f32_e32 v0, v44, v0
	v_mul_f32_e32 v44, v40, v48
	v_mul_f32_e32 v40, v45, v49
	v_mul_f32_e32 v48, 0x3d372713, v46
	v_mul_f32_e32 v49, 0x3d372713, v42
	v_mul_f32_e32 v48, v46, v48
	v_mul_f32_e32 v49, v42, v49
	v_fma_f32 v48, v46, v48, v46
	v_fma_f32 v49, v42, v49, v42
	v_mul_f32_e32 v48, 0x3fcc422a, v48
	v_mul_f32_e32 v49, 0x3fcc422a, v49
	v_add_f32_e32 v45, 1.0, v50
	v_mul_f32_e32 v48, 0xbfb8aa3b, v48
	v_mul_f32_e32 v49, 0xbfb8aa3b, v49
	v_rcp_f32_e32 v45, v45
	v_exp_f32_e32 v48, v48
	v_exp_f32_e32 v49, v49
	v_mul_f32_e32 v50, 0x3d372713, v43
	v_mul_f32_e32 v45, v41, v45
	v_add_f32_e32 v41, 1.0, v48
	v_add_f32_e32 v48, 1.0, v49
	v_mul_f32_e32 v49, 0x3d372713, v47
	v_mul_f32_e32 v49, v47, v49
	v_fma_f32 v49, v47, v49, v47
	v_mul_f32_e32 v50, v43, v50
	v_mul_f32_e32 v49, 0x3fcc422a, v49
	v_fma_f32 v50, v43, v50, v43
	v_mul_f32_e32 v49, 0xbfb8aa3b, v49
	v_mul_f32_e32 v50, 0x3fcc422a, v50
	v_exp_f32_e32 v49, v49
	v_mul_f32_e32 v50, 0xbfb8aa3b, v50
	v_exp_f32_e32 v50, v50
	v_rcp_f32_e32 v41, v41
	v_add_f32_e32 v49, 1.0, v49
	v_rcp_f32_e32 v48, v48
	v_rcp_f32_e32 v49, v49
	v_add_f32_e32 v50, 1.0, v50
	v_rcp_f32_e32 v50, v50
	v_mul_f32_e32 v41, v46, v41
	v_mul_f32_e32 v46, v42, v48
	v_mul_f32_e32 v42, v47, v49
	v_mul_f32_e32 v43, v43, v50
	v_cvt_pk_bf16_f32 v40, v0, v40
	v_cvt_pk_bf16_f32 v41, v41, v42
	v_cvt_pk_bf16_f32 v42, v44, v45
	v_lshl_add_u64 v[44:45], v[64:65], 0, v[128:129]
	v_add_u32_e32 v66, 0xa0, v185
	v_cvt_pk_bf16_f32 v43, v46, v43
	global_store_dwordx4 v[44:45], v[40:43], off
	v_add_u32_e32 v64, 0xb0, v185
	s_nop 0
	v_mov_b32_e32 v40, v66
	s_nop 0
	v_ashrrev_i32_e32 v41, 31, v40
	v_lshlrev_b64 v[40:41], 9, v[40:41]
	v_lshl_add_u64 v[40:41], v[40:41], 0, s[20:21]
	v_lshl_add_u64 v[42:43], v[40:41], 0, v[172:173]
	v_lshlrev_b64 v[42:43], 1, v[42:43]
	v_lshl_add_u64 v[44:45], v[164:165], 0, v[42:43]
	global_load_dwordx4 v[68:71], v[44:45], off
	v_lshl_add_u64 v[42:43], v[166:167], 0, v[42:43]
	global_load_dwordx4 v[72:75], v[42:43], off
	v_lshl_add_u64 v[40:41], v[40:41], 0, v[174:175]
	v_lshlrev_b64 v[40:41], 1, v[40:41]
	v_lshl_add_u64 v[42:43], v[164:165], 0, v[40:41]
	global_load_dwordx4 v[76:79], v[42:43], off
	v_lshl_add_u64 v[40:41], v[166:167], 0, v[40:41]
	global_load_dwordx4 v[80:83], v[40:41], off
	v_mov_b32_e32 v40, v64
	s_waitcnt vmcnt(0)
	v_lshlrev_b32_e32 v84, 16, v68
	v_ashrrev_i32_e32 v41, 31, v40
	v_lshlrev_b64 v[40:41], 9, v[40:41]
	v_lshl_add_u64 v[40:41], v[40:41], 0, s[20:21]
	v_and_b32_e32 v85, 0xffff0000, v68
	v_lshlrev_b32_e32 v86, 16, v70
	v_and_b32_e32 v87, 0xffff0000, v70
	v_lshl_add_u64 v[42:43], v[40:41], 0, v[172:173]
	v_lshlrev_b32_e32 v88, 16, v72
	v_and_b32_e32 v89, 0xffff0000, v72
	v_lshlrev_b32_e32 v90, 16, v74
	v_and_b32_e32 v91, 0xffff0000, v74
	v_pk_add_f32 v[36:37], v[36:37], v[84:85]
	v_pk_add_f32 v[32:33], v[32:33], v[86:87]
	v_lshlrev_b64 v[42:43], 1, v[42:43]
	v_lshlrev_b32_e32 v68, 16, v69
	v_and_b32_e32 v69, 0xffff0000, v69
	v_pk_fma_f32 v[36:37], v[60:61], v[88:89], v[36:37]
	v_pk_fma_f32 v[32:33], v[56:57], v[90:91], v[32:33]
	v_lshl_add_u64 v[44:45], v[164:165], 0, v[42:43]
	v_pk_add_f32 v[38:39], v[38:39], v[68:69]
	v_mul_f32_e32 v0, 0x3d372713, v36
	v_mul_f32_e32 v65, 0x3d372713, v32
	v_mul_f32_e32 v68, 0x3d372713, v37
	global_load_dwordx4 v[52:55], v[44:45], off
	v_lshl_add_u64 v[42:43], v[166:167], 0, v[42:43]
	v_mul_f32_e32 v0, v36, v0
	v_mul_f32_e32 v65, v32, v65
	v_mul_f32_e32 v68, v37, v68
	global_load_dwordx4 v[48:51], v[42:43], off
	v_fma_f32 v0, v36, v0, v36
	v_fma_f32 v65, v32, v65, v32
	v_fma_f32 v68, v37, v68, v37
	v_mul_f32_e32 v0, 0x3fcc422a, v0
	v_mul_f32_e32 v65, 0x3fcc422a, v65
	v_mul_f32_e32 v68, 0x3fcc422a, v68
	v_mul_f32_e32 v0, 0xbfb8aa3b, v0
	v_mul_f32_e32 v65, 0xbfb8aa3b, v65
	v_mul_f32_e32 v68, 0xbfb8aa3b, v68
	v_exp_f32_e32 v0, v0
	v_exp_f32_e32 v65, v65
	v_exp_f32_e32 v68, v68
	v_mul_f32_e32 v69, 0x3d372713, v33
	v_add_f32_e32 v0, 1.0, v0
	v_add_f32_e32 v65, 1.0, v65
	v_add_f32_e32 v68, 1.0, v68
	v_rcp_f32_e32 v0, v0
	v_rcp_f32_e32 v65, v65
	v_rcp_f32_e32 v68, v68
; __device__ __forceinline__ float gelu_tanh(float y) { const float z = 1.5957691216057308f * (y + 0.044715f * y * y * y); return y * sigmoidf_(z); }
; __device__ __forceinline__ u32x4 pack8(const f32x4 a, const f32x4 b) { u32x4 w; w.x = cvt_pk_bf16(a[0], a[1]); w.y = cvt_pk_bf16(a[2], a[3]); w.z = cvt_pk_bf16(b[0], b[1]); w.w = cvt_pk_bf16(b[2], b[3]); return w; }
; __device__ __forceinline__ void unpack8(const u32x4 w, f32x4& a, f32x4& b) { a[0] = bf_lo(w.x); a[1] = bf_hi(w.x); a[2] = bf_lo(w.y); a[3] = bf_hi(w.y); b[0] = bf_lo(w.z); b[1] = bf_hi(w.z); b[2] = bf_lo(w.w); b[3] = bf_hi(w.w); }
;     template <int KIND> __device__ __forceinline__ void run(f32x4 (&acc)[2][2][4][2], const Unit& u, int tid_in) const {
;     ...
;                 for (int mh = 0; mh < 2; ++mh) { u32x4 yv[2][2], uv[2][2];
; #pragma unroll
;                     for (int ml = 0; ml < 2; ++ml) { int R = rbase + ai * 128 + (mh * 2 + ml) * 16; asm volatile("" : "+v"(R));
; #pragma unroll
;                         for (int bj = 0; bj < 2; ++bj) { const int t = 16 * u.pn + 8 * bj + 2 * wc + (fq >> 1); const size_t tok = (size_t)R * LCH + t;
;                             yv[ml][bj] = *(const u32x4*)(yi + ((size_t)g * T_TOK + tok) * 16 + 8 * (fq & 1)); uv[ml][bj] = *(const u32x4*)((const bf16_t*)x + ((size_t)g * T_TOK + tok) * 16 + 8 * (fq & 1)); } }
; #pragma unroll
;                     for (int ml = 0; ml < 2; ++ml) { const int m = mh * 2 + ml; int R = rbase + ai * 128 + m * 16; asm volatile("" : "+v"(R));
; #pragma unroll
;                         for (int bj = 0; bj < 2; ++bj) { const int t = 16 * u.pn + 8 * bj + 2 * wc + (fq >> 1); const size_t tok = (size_t)R * LCH + t;
;                             f32x4 y0, y1, u0, u1; unpack8(yv[ml][bj], y0, y1); unpack8(uv[ml][bj], u0, u1);
;                             y0 = acc[ai][bj][m][0] + y0 + d0 * u0; y1 = acc[ai][bj][m][1] + y1 + d1 * u1;
; #pragma unroll
;                             for (int j = 0; j < 4; ++j) { y0[j] = gelu_tanh(y0[j]); y1[j] = gelu_tanh(y1[j]); }
;                             *(u32x4*)(yi + ((size_t)g * T_TOK + tok) * 16 + 8 * (fq & 1)) = pack8(y0, y1); } }
	v_mul_f32_e32 v69, v33, v69
	v_lshlrev_b32_e32 v70, 16, v71
	v_and_b32_e32 v71, 0xffff0000, v71
	v_fma_f32 v69, v33, v69, v33
	v_lshlrev_b32_e32 v72, 16, v73
	v_and_b32_e32 v73, 0xffff0000, v73
	v_lshlrev_b32_e32 v74, 16, v75
	v_and_b32_e32 v75, 0xffff0000, v75
	v_pk_add_f32 v[34:35], v[34:35], v[70:71]
	v_mul_f32_e32 v69, 0x3fcc422a, v69
	v_pk_fma_f32 v[38:39], v[62:63], v[72:73], v[38:39]
	v_pk_fma_f32 v[34:35], v[58:59], v[74:75], v[34:35]
	v_mul_f32_e32 v69, 0xbfb8aa3b, v69
	v_exp_f32_e32 v69, v69
	v_mul_f32_e32 v0, v36, v0
	v_mul_f32_e32 v36, v32, v65
	v_mul_f32_e32 v32, v37, v68
	v_mul_f32_e32 v65, 0x3d372713, v38
	v_mul_f32_e32 v68, 0x3d372713, v34
	v_mul_f32_e32 v65, v38, v65
	v_mul_f32_e32 v68, v34, v68
	v_fma_f32 v65, v38, v65, v38
	v_fma_f32 v68, v34, v68, v34
	v_mul_f32_e32 v65, 0x3fcc422a, v65
	v_mul_f32_e32 v68, 0x3fcc422a, v68
	v_add_f32_e32 v37, 1.0, v69
	v_mul_f32_e32 v65, 0xbfb8aa3b, v65
	v_mul_f32_e32 v68, 0xbfb8aa3b, v68
	v_rcp_f32_e32 v37, v37
	v_exp_f32_e32 v65, v65
	v_exp_f32_e32 v68, v68
	v_mul_f32_e32 v69, 0x3d372713, v35
	v_mul_f32_e32 v37, v33, v37
	v_add_f32_e32 v33, 1.0, v65
	v_add_f32_e32 v65, 1.0, v68
	v_mul_f32_e32 v68, 0x3d372713, v39
	v_mul_f32_e32 v68, v39, v68
	v_fma_f32 v68, v39, v68, v39
	v_mul_f32_e32 v69, v35, v69
	v_mul_f32_e32 v68, 0x3fcc422a, v68
	v_fma_f32 v69, v35, v69, v35
	v_mul_f32_e32 v68, 0xbfb8aa3b, v68
	v_mul_f32_e32 v69, 0x3fcc422a, v69
	v_exp_f32_e32 v68, v68
	v_mul_f32_e32 v69, 0xbfb8aa3b, v69
	v_exp_f32_e32 v69, v69
	v_lshl_add_u64 v[40:41], v[40:41], 0, v[174:175]
	v_add_f32_e32 v68, 1.0, v68
	v_lshlrev_b64 v[40:41], 1, v[40:41]
	v_rcp_f32_e32 v33, v33
	v_rcp_f32_e32 v65, v65
	v_rcp_f32_e32 v68, v68
	v_add_f32_e32 v69, 1.0, v69
	v_lshl_add_u64 v[42:43], v[164:165], 0, v[40:41]
	v_lshl_add_u64 v[40:41], v[166:167], 0, v[40:41]
	v_rcp_f32_e32 v69, v69
	global_load_dwordx4 v[44:47], v[42:43], off
	v_mul_f32_e32 v33, v38, v33
	global_load_dwordx4 v[40:43], v[40:41], off
	v_mul_f32_e32 v38, v34, v65
	v_ashrrev_i32_e32 v67, 31, v66
	v_lshlrev_b64 v[66:67], 10, v[66:67]
	v_lshl_add_u64 v[66:67], v[162:163], 0, v[66:67]
	v_mul_f32_e32 v34, v39, v68
	v_mul_f32_e32 v35, v35, v69
	v_cvt_pk_bf16_f32 v32, v0, v32
	v_cvt_pk_bf16_f32 v33, v33, v34
	v_cvt_pk_bf16_f32 v34, v36, v37
	v_lshl_add_u64 v[36:37], v[66:67], 0, v[136:137]
	v_cvt_pk_bf16_f32 v35, v38, v35
	global_store_dwordx4 v[36:37], v[32:35], off
	v_lshlrev_b32_e32 v36, 16, v78
	v_and_b32_e32 v37, 0xffff0000, v78
	v_lshlrev_b32_e32 v32, 16, v76
	v_and_b32_e32 v33, 0xffff0000, v76
	v_lshlrev_b32_e32 v68, 16, v80
	v_and_b32_e32 v69, 0xffff0000, v80
	v_lshlrev_b32_e32 v72, 16, v82
	v_and_b32_e32 v73, 0xffff0000, v82
	v_pk_add_f32 v[28:29], v[28:29], v[32:33]
	v_pk_add_f32 v[24:25], v[24:25], v[36:37]
	v_pk_fma_f32 v[28:29], v[60:61], v[68:69], v[28:29]
	v_pk_fma_f32 v[24:25], v[56:57], v[72:73], v[24:25]
	v_mul_f32_e32 v0, 0x3d372713, v28
	v_mul_f32_e32 v32, 0x3d372713, v24
	v_mul_f32_e32 v33, 0x3d372713, v29
	v_mul_f32_e32 v0, v28, v0
	v_mul_f32_e32 v32, v24, v32
	v_mul_f32_e32 v33, v29, v33
	v_fma_f32 v0, v28, v0, v28
	v_fma_f32 v32, v24, v32, v24
	v_fma_f32 v33, v29, v33, v29
	v_mul_f32_e32 v0, 0x3fcc422a, v0
	v_mul_f32_e32 v32, 0x3fcc422a, v32
	v_mul_f32_e32 v33, 0x3fcc422a, v33
	v_mul_f32_e32 v0, 0xbfb8aa3b, v0
	v_mul_f32_e32 v32, 0xbfb8aa3b, v32
	v_mul_f32_e32 v33, 0xbfb8aa3b, v33
	v_exp_f32_e32 v0, v0
	v_exp_f32_e32 v32, v32
	v_exp_f32_e32 v33, v33
	v_lshlrev_b32_e32 v34, 16, v77
	v_and_b32_e32 v35, 0xffff0000, v77
	v_pk_add_f32 v[30:31], v[30:31], v[34:35]
	v_add_f32_e32 v0, 1.0, v0
	v_add_f32_e32 v32, 1.0, v32
	v_add_f32_e32 v33, 1.0, v33
	v_mul_f32_e32 v34, 0x3d372713, v25
	v_rcp_f32_e32 v0, v0
	v_rcp_f32_e32 v32, v32
	v_rcp_f32_e32 v33, v33
	v_mul_f32_e32 v34, v25, v34
	v_lshlrev_b32_e32 v38, 16, v79
	v_and_b32_e32 v39, 0xffff0000, v79
	v_fma_f32 v34, v25, v34, v25
	v_lshlrev_b32_e32 v70, 16, v81
	v_and_b32_e32 v71, 0xffff0000, v81
	v_lshlrev_b32_e32 v74, 16, v83
	v_and_b32_e32 v75, 0xffff0000, v83
	v_pk_add_f32 v[26:27], v[26:27], v[38:39]
	v_mul_f32_e32 v34, 0x3fcc422a, v34
	v_pk_fma_f32 v[30:31], v[62:63], v[70:71], v[30:31]
	v_pk_fma_f32 v[26:27], v[58:59], v[74:75], v[26:27]
	v_mul_f32_e32 v34, 0xbfb8aa3b, v34
	v_exp_f32_e32 v34, v34
	v_mul_f32_e32 v0, v28, v0
	v_mul_f32_e32 v28, v24, v32
	v_mul_f32_e32 v24, v29, v33
	v_mul_f32_e32 v32, 0x3d372713, v30
	v_mul_f32_e32 v33, 0x3d372713, v26
	v_mul_f32_e32 v32, v30, v32
	v_mul_f32_e32 v33, v26, v33
	v_fma_f32 v32, v30, v32, v30
	v_fma_f32 v33, v26, v33, v26
	v_mul_f32_e32 v32, 0x3fcc422a, v32
	v_mul_f32_e32 v33, 0x3fcc422a, v33
	v_add_f32_e32 v29, 1.0, v34
	v_mul_f32_e32 v32, 0xbfb8aa3b, v32
	v_mul_f32_e32 v33, 0xbfb8aa3b, v33
	v_rcp_f32_e32 v29, v29
	v_exp_f32_e32 v32, v32
	v_exp_f32_e32 v33, v33
	v_mul_f32_e32 v34, 0x3d372713, v27
	v_mul_f32_e32 v29, v25, v29
	v_add_f32_e32 v25, 1.0, v32
	v_add_f32_e32 v32, 1.0, v33
	v_mul_f32_e32 v33, 0x3d372713, v31
	v_mul_f32_e32 v33, v31, v33
	v_mul_f32_e32 v34, v27, v34
	v_fma_f32 v33, v31, v33, v31
	v_fma_f32 v34, v27, v34, v27
	v_mul_f32_e32 v33, 0x3fcc422a, v33
	v_mul_f32_e32 v34, 0x3fcc422a, v34
	v_mul_f32_e32 v33, 0xbfb8aa3b, v33
	v_mul_f32_e32 v34, 0xbfb8aa3b, v34
	v_exp_f32_e32 v33, v33
	v_exp_f32_e32 v34, v34
	v_rcp_f32_e32 v25, v25
	v_rcp_f32_e32 v32, v32
	v_add_f32_e32 v33, 1.0, v33
	v_add_f32_e32 v34, 1.0, v34
	v_rcp_f32_e32 v33, v33
	v_rcp_f32_e32 v34, v34
	v_mul_f32_e32 v25, v30, v25
	v_mul_f32_e32 v30, v26, v32
	v_mul_f32_e32 v26, v31, v33
	v_mul_f32_e32 v27, v27, v34
	v_cvt_pk_bf16_f32 v24, v0, v24
	v_cvt_pk_bf16_f32 v25, v25, v26
	v_cvt_pk_bf16_f32 v26, v28, v29
	v_cvt_pk_bf16_f32 v27, v30, v27
	v_lshl_add_u64 v[28:29], v[66:67], 0, v[128:129]
	global_store_dwordx4 v[28:29], v[24:27], off
	s_waitcnt vmcnt(0)
; __device__ __forceinline__ float gelu_tanh(float y) { const float z = 1.5957691216057308f * (y + 0.044715f * y * y * y); return y * sigmoidf_(z); }
; __device__ __forceinline__ u32x4 pack8(const f32x4 a, const f32x4 b) { u32x4 w; w.x = cvt_pk_bf16(a[0], a[1]); w.y = cvt_pk_bf16(a[2], a[3]); w.z = cvt_pk_bf16(b[0], b[1]); w.w = cvt_pk_bf16(b[2], b[3]); return w; }
; __device__ __forceinline__ void unpack8(const u32x4 w, f32x4& a, f32x4& b) { a[0] = bf_lo(w.x); a[1] = bf_hi(w.x); a[2] = bf_lo(w.y); a[3] = bf_hi(w.y); b[0] = bf_lo(w.z); b[1] = bf_hi(w.z); b[2] = bf_lo(w.w); b[3] = bf_hi(w.w); }
; #define G_WAIT_V(n) asm volatile("s_waitcnt vmcnt(" #n ")" ::: "memory")
; #define G_BAR __builtin_amdgcn_s_barrier()
;     template <int KIND> __device__ __forceinline__ void run(f32x4 (&acc)[2][2][4][2], const Unit& u, int tid_in) const {
;     ...
;                     for (int ml = 0; ml < 2; ++ml) { const int m = mh * 2 + ml; int R = rbase + ai * 128 + m * 16; asm volatile("" : "+v"(R));
; #pragma unroll
;                         for (int bj = 0; bj < 2; ++bj) { const int t = 16 * u.pn + 8 * bj + 2 * wc + (fq >> 1); const size_t tok = (size_t)R * LCH + t;
;                             f32x4 y0, y1, u0, u1; unpack8(yv[ml][bj], y0, y1); unpack8(uv[ml][bj], u0, u1);
;                             y0 = acc[ai][bj][m][0] + y0 + d0 * u0; y1 = acc[ai][bj][m][1] + y1 + d1 * u1;
; #pragma unroll
;                             for (int j = 0; j < 4; ++j) { y0[j] = gelu_tanh(y0[j]); y1[j] = gelu_tanh(y1[j]); }
;                             *(u32x4*)(yi + ((size_t)g * T_TOK + tok) * 16 + 8 * (fq & 1)) = pack8(y0, y1); } }
;     ...
;         E.template run<cs.kind>(acc, cur, tid);
;         if (!has_next) break;
;         if (!(cs.kind == K_MG_B && cur.aux < 2))
; #pragma unroll
;         for (int a = 0; a < 2; ++a)
; #pragma unroll
;             for (int b = 0; b < 2; ++b)
; #pragma unroll
;                 for (int m = 0; m < 4; ++m)
; #pragma unroll
;                     for (int n = 0; n < 2; ++n) acc[a][b][m][n] = (f32x4){0.f, 0.f, 0.f, 0.f};
;         cur = nxt; cA = nA; cB = nB; ++ui;
;     }
;     G_WAIT_V(0);
;     if (wr == 0) G_BAR;
;     G_BAR;
	v_lshlrev_b32_e32 v30, 16, v54
	v_and_b32_e32 v31, 0xffff0000, v54
	v_lshlrev_b32_e32 v26, 16, v52
	v_and_b32_e32 v27, 0xffff0000, v52
	v_lshlrev_b32_e32 v34, 16, v48
	v_and_b32_e32 v35, 0xffff0000, v48
	v_lshlrev_b32_e32 v38, 16, v50
	v_and_b32_e32 v39, 0xffff0000, v50
	v_pk_add_f32 v[20:21], v[20:21], v[26:27]
	v_pk_add_f32 v[16:17], v[16:17], v[30:31]
	v_pk_fma_f32 v[20:21], v[60:61], v[34:35], v[20:21]
	v_pk_fma_f32 v[16:17], v[56:57], v[38:39], v[16:17]
	v_mul_f32_e32 v0, 0x3d372713, v20
	v_mul_f32_e32 v26, 0x3d372713, v16
	v_mul_f32_e32 v27, 0x3d372713, v21
	v_mul_f32_e32 v0, v20, v0
	v_mul_f32_e32 v26, v16, v26
	v_mul_f32_e32 v27, v21, v27
	v_fma_f32 v0, v20, v0, v20
	v_fma_f32 v26, v16, v26, v16
	v_fma_f32 v27, v21, v27, v21
	v_mul_f32_e32 v0, 0x3fcc422a, v0
	v_mul_f32_e32 v26, 0x3fcc422a, v26
	v_mul_f32_e32 v27, 0x3fcc422a, v27
	v_mul_f32_e32 v0, 0xbfb8aa3b, v0
	v_mul_f32_e32 v26, 0xbfb8aa3b, v26
	v_mul_f32_e32 v27, 0xbfb8aa3b, v27
	v_exp_f32_e32 v0, v0
	v_exp_f32_e32 v26, v26
	v_exp_f32_e32 v27, v27
	v_lshlrev_b32_e32 v28, 16, v53
	v_and_b32_e32 v29, 0xffff0000, v53
	v_pk_add_f32 v[22:23], v[22:23], v[28:29]
	v_add_f32_e32 v0, 1.0, v0
	v_add_f32_e32 v26, 1.0, v26
	v_add_f32_e32 v27, 1.0, v27
	v_mul_f32_e32 v28, 0x3d372713, v17
	v_rcp_f32_e32 v0, v0
	v_rcp_f32_e32 v26, v26
	v_rcp_f32_e32 v27, v27
	v_mul_f32_e32 v28, v17, v28
	v_lshlrev_b32_e32 v32, 16, v55
	v_and_b32_e32 v33, 0xffff0000, v55
	v_fma_f32 v28, v17, v28, v17
	v_lshlrev_b32_e32 v36, 16, v49
	v_and_b32_e32 v37, 0xffff0000, v49
	v_lshlrev_b32_e32 v48, 16, v51
	v_and_b32_e32 v49, 0xffff0000, v51
	v_pk_add_f32 v[18:19], v[18:19], v[32:33]
	v_mul_f32_e32 v28, 0x3fcc422a, v28
	v_pk_fma_f32 v[22:23], v[62:63], v[36:37], v[22:23]
	v_pk_fma_f32 v[18:19], v[58:59], v[48:49], v[18:19]
	v_mul_f32_e32 v28, 0xbfb8aa3b, v28
	v_exp_f32_e32 v28, v28
	v_mul_f32_e32 v0, v20, v0
	v_mul_f32_e32 v20, v16, v26
	v_mul_f32_e32 v16, v21, v27
	v_mul_f32_e32 v26, 0x3d372713, v22
	v_mul_f32_e32 v27, 0x3d372713, v18
	v_mul_f32_e32 v26, v22, v26
	v_mul_f32_e32 v27, v18, v27
	v_fma_f32 v26, v22, v26, v22
	v_fma_f32 v27, v18, v27, v18
	v_mul_f32_e32 v26, 0x3fcc422a, v26
	v_mul_f32_e32 v27, 0x3fcc422a, v27
	v_add_f32_e32 v21, 1.0, v28
	v_mul_f32_e32 v26, 0xbfb8aa3b, v26
	v_mul_f32_e32 v27, 0xbfb8aa3b, v27
	v_rcp_f32_e32 v21, v21
	v_exp_f32_e32 v26, v26
	v_exp_f32_e32 v27, v27
	v_mul_f32_e32 v28, 0x3d372713, v19
	v_mul_f32_e32 v21, v17, v21
	v_add_f32_e32 v17, 1.0, v26
	v_add_f32_e32 v26, 1.0, v27
	v_mul_f32_e32 v27, 0x3d372713, v23
	v_mul_f32_e32 v27, v23, v27
	v_fma_f32 v27, v23, v27, v23
	v_mul_f32_e32 v28, v19, v28
	v_mul_f32_e32 v27, 0x3fcc422a, v27
	v_fma_f32 v28, v19, v28, v19
	v_mul_f32_e32 v27, 0xbfb8aa3b, v27
	v_mul_f32_e32 v28, 0x3fcc422a, v28
	v_exp_f32_e32 v27, v27
	v_mul_f32_e32 v28, 0xbfb8aa3b, v28
	v_exp_f32_e32 v28, v28
	v_rcp_f32_e32 v17, v17
	v_add_f32_e32 v27, 1.0, v27
	v_rcp_f32_e32 v26, v26
	v_rcp_f32_e32 v27, v27
	v_add_f32_e32 v28, 1.0, v28
	v_rcp_f32_e32 v28, v28
	v_mul_f32_e32 v17, v22, v17
	v_ashrrev_i32_e32 v65, 31, v64
	v_lshlrev_b64 v[24:25], 10, v[64:65]
	v_lshl_add_u64 v[24:25], v[162:163], 0, v[24:25]
	v_mul_f32_e32 v22, v18, v26
	v_mul_f32_e32 v18, v23, v27
	v_mul_f32_e32 v19, v19, v28
	v_cvt_pk_bf16_f32 v16, v0, v16
	v_cvt_pk_bf16_f32 v17, v17, v18
	v_cvt_pk_bf16_f32 v18, v20, v21
	v_lshl_add_u64 v[20:21], v[24:25], 0, v[136:137]
	v_cvt_pk_bf16_f32 v19, v22, v19
	global_store_dwordx4 v[20:21], v[16:19], off
	v_lshlrev_b32_e32 v20, 16, v46
	v_and_b32_e32 v21, 0xffff0000, v46
	v_lshlrev_b32_e32 v16, 16, v44
	v_and_b32_e32 v17, 0xffff0000, v44
	v_lshlrev_b32_e32 v26, 16, v40
	v_and_b32_e32 v27, 0xffff0000, v40
	v_lshlrev_b32_e32 v30, 16, v42
	v_and_b32_e32 v31, 0xffff0000, v42
	v_pk_add_f32 v[12:13], v[12:13], v[16:17]
	v_pk_add_f32 v[8:9], v[8:9], v[20:21]
	v_pk_fma_f32 v[12:13], v[60:61], v[26:27], v[12:13]
	v_pk_fma_f32 v[8:9], v[56:57], v[30:31], v[8:9]
	v_mul_f32_e32 v0, 0x3d372713, v12
	v_mul_f32_e32 v16, 0x3d372713, v8
	v_mul_f32_e32 v17, 0x3d372713, v13
	v_mul_f32_e32 v0, v12, v0
	v_mul_f32_e32 v16, v8, v16
	v_mul_f32_e32 v17, v13, v17
	v_fma_f32 v0, v12, v0, v12
	v_fma_f32 v16, v8, v16, v8
	v_fma_f32 v17, v13, v17, v13
	v_mul_f32_e32 v0, 0x3fcc422a, v0
	v_mul_f32_e32 v16, 0x3fcc422a, v16
	v_mul_f32_e32 v17, 0x3fcc422a, v17
	v_mul_f32_e32 v0, 0xbfb8aa3b, v0
	v_mul_f32_e32 v16, 0xbfb8aa3b, v16
	v_mul_f32_e32 v17, 0xbfb8aa3b, v17
	v_exp_f32_e32 v0, v0
	v_exp_f32_e32 v16, v16
	v_exp_f32_e32 v17, v17
	v_lshlrev_b32_e32 v18, 16, v45
	v_and_b32_e32 v19, 0xffff0000, v45
	v_pk_add_f32 v[14:15], v[14:15], v[18:19]
	v_add_f32_e32 v0, 1.0, v0
	v_add_f32_e32 v16, 1.0, v16
	v_add_f32_e32 v17, 1.0, v17
	v_mul_f32_e32 v18, 0x3d372713, v9
	v_rcp_f32_e32 v0, v0
	v_rcp_f32_e32 v16, v16
	v_rcp_f32_e32 v17, v17
	v_mul_f32_e32 v18, v9, v18
	v_lshlrev_b32_e32 v22, 16, v47
	v_and_b32_e32 v23, 0xffff0000, v47
	v_fma_f32 v18, v9, v18, v9
	v_lshlrev_b32_e32 v28, 16, v41
	v_and_b32_e32 v29, 0xffff0000, v41
	v_lshlrev_b32_e32 v32, 16, v43
	v_and_b32_e32 v33, 0xffff0000, v43
	v_pk_add_f32 v[10:11], v[10:11], v[22:23]
	v_mul_f32_e32 v18, 0x3fcc422a, v18
	v_pk_fma_f32 v[14:15], v[62:63], v[28:29], v[14:15]
	v_pk_fma_f32 v[10:11], v[58:59], v[32:33], v[10:11]
	v_mul_f32_e32 v18, 0xbfb8aa3b, v18
	v_exp_f32_e32 v18, v18
	v_mul_f32_e32 v0, v12, v0
	v_mul_f32_e32 v12, v8, v16
	v_mul_f32_e32 v8, v13, v17
	v_mul_f32_e32 v16, 0x3d372713, v14
	v_mul_f32_e32 v17, 0x3d372713, v10
	v_mul_f32_e32 v16, v14, v16
	v_mul_f32_e32 v17, v10, v17
	v_fma_f32 v16, v14, v16, v14
	v_fma_f32 v17, v10, v17, v10
	v_mul_f32_e32 v16, 0x3fcc422a, v16
	v_mul_f32_e32 v17, 0x3fcc422a, v17
	v_add_f32_e32 v13, 1.0, v18
	v_mul_f32_e32 v16, 0xbfb8aa3b, v16
	v_mul_f32_e32 v17, 0xbfb8aa3b, v17
	v_rcp_f32_e32 v13, v13
	v_exp_f32_e32 v16, v16
	v_exp_f32_e32 v17, v17
	v_mul_f32_e32 v18, 0x3d372713, v11
	v_mul_f32_e32 v13, v9, v13
	v_add_f32_e32 v9, 1.0, v16
	v_add_f32_e32 v16, 1.0, v17
	v_mul_f32_e32 v17, 0x3d372713, v15
	v_mul_f32_e32 v17, v15, v17
	v_fma_f32 v17, v15, v17, v15
	v_mul_f32_e32 v18, v11, v18
	v_mul_f32_e32 v17, 0x3fcc422a, v17
	v_fma_f32 v18, v11, v18, v11
	v_mul_f32_e32 v17, 0xbfb8aa3b, v17
	v_mul_f32_e32 v18, 0x3fcc422a, v18
	v_exp_f32_e32 v17, v17
	v_mul_f32_e32 v18, 0xbfb8aa3b, v18
	v_exp_f32_e32 v18, v18
	v_rcp_f32_e32 v9, v9
	v_add_f32_e32 v17, 1.0, v17
	v_rcp_f32_e32 v16, v16
	v_rcp_f32_e32 v17, v17
	v_add_f32_e32 v18, 1.0, v18
	v_rcp_f32_e32 v18, v18
	v_mul_f32_e32 v9, v14, v9
	v_mul_f32_e32 v14, v10, v16
	v_mul_f32_e32 v10, v15, v17
	v_mul_f32_e32 v11, v11, v18
	v_cvt_pk_bf16_f32 v8, v0, v8
	v_cvt_pk_bf16_f32 v9, v9, v10
	v_cvt_pk_bf16_f32 v10, v12, v13
	v_lshl_add_u64 v[12:13], v[24:25], 0, v[128:129]
	v_cvt_pk_bf16_f32 v11, v14, v11
	global_store_dwordx4 v[12:13], v[8:11], off
	s_mov_b64 s[20:21], s[16:17]
	s_cbranch_vccz .LBB0_737
	s_cmp_eq_u32 s101, 2
	s_cbranch_scc0 .Ldbj_SSM2_pe
	s_barrier

; #define G_STAGE(bufoff, gbase, o0, h64) do { \
;         __builtin_amdgcn_global_load_lds((const unsigned*)((const char*)(gbase) + (o0)), (LAS unsigned*)(lds + (bufoff) + ldsw), 16, 0, 0); \
;         __builtin_amdgcn_global_load_lds((const unsigned*)((const char*)(gbase) + (h64) + (o0)), (LAS unsigned*)(lds + (bufoff) + ldsw + 8192), 16, 0, 0); } while (0)
; #define G_LDA(dst, b, h) do { _Pragma("unroll") for (int m = 0; m < 4; ++m) _Pragma("unroll") for (int k = 0; k < 2; ++k) dst[m][k] = *(const LAS bf16x8*)(lds + G_SA(b, h) + aoff + m * 2048 + k * 1024); } while (0)
; #define G_LDB(dst, b, h) do { _Pragma("unroll") for (int n = 0; n < 2; ++n) _Pragma("unroll") for (int k = 0; k < 2; ++k) dst[n][k] = *(const LAS bf16x8*)(lds + G_SB(b, h) + boff + n * 2048 + k * 1024); } while (0)
; #define G_WAIT_L(n) asm volatile("s_waitcnt lgkmcnt(" #n ")" ::: "memory")
; #define G_BAR __builtin_amdgcn_s_barrier()
; #define G_SCHED __builtin_amdgcn_sched_barrier(0)
;     ...
;         for (int t = 0; t < nt; t += 2) {
;             const bool last = (t == nt - 2);
;             const char* a1 = cA + (size_t)(t + 1) * ckA;
;             const char* a2 = last ? nA : cA + (size_t)(t + 2) * ckA; const char* b2 = last ? nB : cB + (size_t)(t + 2) * kB;
;             const char* a3 = a2 + ckA; const char* b3 = b2 + kB;
;             G_LDB(B0, 0, 0); G_SCHED; G_LDA(At, 0, 0); G_STAGE(G_SA(1, 1), a1 + chA, cA0, qA);
;             G_WAIT_L(8); G_BAR; G_WAIT_L(0); G_MMA(0, 0, At, B0); G_BAR; G_SCHED;
;             G_LDB(B1, 0, 1); G_STAGE(G_SB(0, 0), b2, cB0, qB);
;             G_BAR; G_WAIT_L(0); G_MMA(0, 1, At, B1); G_BAR;
;             G_LDA(At, 0, 1); G_STAGE(G_SA(0, 0), a2, cA0, qA);
;             G_BAR; G_WAIT_L(0); G_MMA(1, 0, At, B0); G_BAR; G_SCHED;
.LBB0_804:
	s_add_i32 s40, 0, 0x10000
	ds_read_b128 v[112:115], v255 offset:0
	ds_read_b128 v[124:127], v255 offset:1024
	ds_read_b128 v[136:139], v255 offset:2048
	ds_read_b128 v[148:151], v255 offset:3072
	s_cmp_eq_u32 s19, 4
	s_cselect_b32 s5, s15, s3
	s_cselect_b32 s4, s14, s2
	s_cselect_b32 s37, s17, s18
	s_cselect_b32 s36, s16, s13
	s_mov_b32 s38, 0xffc01000
	s_mov_b32 s39, -1
	s_add_u32 vcc_lo, s2, s38
	s_addc_u32 vcc_hi, s3, s39
	s_mov_b32 s38, 0xffc01800
	s_add_i32 m0, s24, 0xc000
	s_mov_b32 s39, -1
	ds_read_b128 v[152:155], v197
	ds_read_b128 v[156:159], v197 offset:1024
	ds_read_b128 v[160:163], v197 offset:2048
	ds_read_b128 v[172:175], v197 offset:3072
	ds_read_b128 v[176:179], v197 offset:4096
	ds_read_b128 v[180:183], v197 offset:5120
	ds_read_b128 v[198:201], v197 offset:6144
	ds_read_b128 v[202:205], v197 offset:7168
	global_load_lds_dwordx4 v166, vcc
	s_add_i32 m0, s24, 0xe000
	s_nop 0
	s_add_u32 vcc_lo, s2, s38
	s_addc_u32 vcc_hi, s3, s39
	global_load_lds_dwordx4 v166, vcc
	s_waitcnt lgkmcnt(8)
	s_barrier
	s_waitcnt lgkmcnt(0)
	v_mfma_f32_16x16x32_bf16 v[144:147], v[112:115], v[152:155], v[144:147]
	v_mfma_f32_16x16x32_bf16 v[140:143], v[136:139], v[152:155], v[140:143]
	v_mfma_f32_16x16x32_bf16 v[120:123], v[112:115], v[160:163], v[120:123]
	v_mfma_f32_16x16x32_bf16 v[116:119], v[136:139], v[160:163], v[116:119]
	v_mfma_f32_16x16x32_bf16 v[100:103], v[112:115], v[176:179], v[100:103]
	v_mfma_f32_16x16x32_bf16 v[96:99], v[136:139], v[176:179], v[96:99]
	v_mfma_f32_16x16x32_bf16 v[84:87], v[112:115], v[198:201], v[84:87]
	v_mfma_f32_16x16x32_bf16 v[80:83], v[136:139], v[198:201], v[80:83]
	v_mfma_f32_16x16x32_bf16 v[144:147], v[124:127], v[156:159], v[144:147]
	v_mfma_f32_16x16x32_bf16 v[140:143], v[148:151], v[156:159], v[140:143]
	v_mfma_f32_16x16x32_bf16 v[120:123], v[124:127], v[172:175], v[120:123]
	v_mfma_f32_16x16x32_bf16 v[116:119], v[148:151], v[172:175], v[116:119]
	v_mfma_f32_16x16x32_bf16 v[100:103], v[124:127], v[180:183], v[100:103]
	v_mfma_f32_16x16x32_bf16 v[96:99], v[148:151], v[180:183], v[96:99]
	v_mfma_f32_16x16x32_bf16 v[84:87], v[124:127], v[202:205], v[84:87]
	v_mfma_f32_16x16x32_bf16 v[80:83], v[148:151], v[202:205], v[80:83]
	s_barrier
	s_add_i32 s38, 0, 0x14000
	s_add_i32 s100, s40, s21
	s_mov_b32 m0, s100
	ds_read_b128 v[206:209], v255 offset:16384
	ds_read_b128 v[210:213], v255 offset:17408
	ds_read_b128 v[214:217], v255 offset:18432
	ds_read_b128 v[218:221], v255 offset:19456
	global_load_lds_dwordx4 v2, s[36:37]
	s_add_i32 m0, s100, 0x2000
	s_nop 0
	s_add_u32 vcc_lo, s36, s50
	s_addc_u32 vcc_hi, s37, s51
	global_load_lds_dwordx4 v2, vcc
	s_barrier
	s_waitcnt lgkmcnt(0)
	v_mfma_f32_16x16x32_bf16 v[132:135], v[206:209], v[152:155], v[132:135]
	v_mfma_f32_16x16x32_bf16 v[128:131], v[214:217], v[152:155], v[128:131]
	v_mfma_f32_16x16x32_bf16 v[108:111], v[206:209], v[160:163], v[108:111]
	v_mfma_f32_16x16x32_bf16 v[104:107], v[214:217], v[160:163], v[104:107]
	v_mfma_f32_16x16x32_bf16 v[92:95], v[206:209], v[176:179], v[92:95]
	v_mfma_f32_16x16x32_bf16 v[88:91], v[214:217], v[176:179], v[88:91]
	v_mfma_f32_16x16x32_bf16 v[76:79], v[206:209], v[198:201], v[76:79]
	v_mfma_f32_16x16x32_bf16 v[72:75], v[214:217], v[198:201], v[72:75]
	v_mfma_f32_16x16x32_bf16 v[132:135], v[210:213], v[156:159], v[132:135]
	v_mfma_f32_16x16x32_bf16 v[128:131], v[218:221], v[156:159], v[128:131]
	v_mfma_f32_16x16x32_bf16 v[108:111], v[210:213], v[172:175], v[108:111]
	v_mfma_f32_16x16x32_bf16 v[104:107], v[218:221], v[172:175], v[104:107]
	v_mfma_f32_16x16x32_bf16 v[92:95], v[210:213], v[180:183], v[92:95]
	v_mfma_f32_16x16x32_bf16 v[88:91], v[218:221], v[180:183], v[88:91]
	v_mfma_f32_16x16x32_bf16 v[76:79], v[210:213], v[202:205], v[76:79]
	v_mfma_f32_16x16x32_bf16 v[72:75], v[218:221], v[202:205], v[72:75]
	s_barrier
	s_mov_b32 m0, s24
	v_lshl_add_u64 v[222:223], s[4:5], 0, v[164:165]
	ds_read_b128 v[152:155], v197 offset:16384
	ds_read_b128 v[156:159], v197 offset:17408
	ds_read_b128 v[160:163], v197 offset:18432
	ds_read_b128 v[172:175], v197 offset:19456
	ds_read_b128 v[176:179], v197 offset:20480
	ds_read_b128 v[180:183], v197 offset:21504
	ds_read_b128 v[198:201], v197 offset:22528
	ds_read_b128 v[202:205], v197 offset:23552
	global_load_lds_dwordx4 v164, s[4:5]
	s_mov_b32 m0, s25
	s_nop 0
	s_add_u32 vcc_lo, s4, s70
	s_addc_u32 vcc_hi, s5, s71
	global_load_lds_dwordx4 v164, vcc
	s_barrier
	s_waitcnt lgkmcnt(0)
	v_mfma_f32_16x16x32_bf16 v[68:71], v[112:115], v[152:155], v[68:71]
	v_mfma_f32_16x16x32_bf16 v[64:67], v[136:139], v[152:155], v[64:67]
	v_mfma_f32_16x16x32_bf16 v[52:55], v[112:115], v[160:163], v[52:55]
	v_mfma_f32_16x16x32_bf16 v[48:51], v[136:139], v[160:163], v[48:51]
	v_mfma_f32_16x16x32_bf16 v[36:39], v[112:115], v[176:179], v[36:39]
	v_mfma_f32_16x16x32_bf16 v[32:35], v[136:139], v[176:179], v[32:35]
	v_mfma_f32_16x16x32_bf16 v[20:23], v[112:115], v[198:201], v[20:23]
	v_mfma_f32_16x16x32_bf16 v[16:19], v[136:139], v[198:201], v[16:19]
	v_mfma_f32_16x16x32_bf16 v[68:71], v[124:127], v[156:159], v[68:71]
	v_mfma_f32_16x16x32_bf16 v[64:67], v[148:151], v[156:159], v[64:67]
	v_mfma_f32_16x16x32_bf16 v[52:55], v[124:127], v[172:175], v[52:55]
	v_mfma_f32_16x16x32_bf16 v[48:51], v[148:151], v[172:175], v[48:51]
	v_mfma_f32_16x16x32_bf16 v[36:39], v[124:127], v[180:183], v[36:39]
	v_mfma_f32_16x16x32_bf16 v[32:35], v[148:151], v[180:183], v[32:35]
	v_mfma_f32_16x16x32_bf16 v[20:23], v[124:127], v[202:205], v[20:23]
	v_mfma_f32_16x16x32_bf16 v[16:19], v[148:151], v[202:205], v[16:19]
	s_barrier
; #define G_STAGE(bufoff, gbase, o0, h64) do { \
;         __builtin_amdgcn_global_load_lds((const unsigned*)((const char*)(gbase) + (o0)), (LAS unsigned*)(lds + (bufoff) + ldsw), 16, 0, 0); \
;         __builtin_amdgcn_global_load_lds((const unsigned*)((const char*)(gbase) + (h64) + (o0)), (LAS unsigned*)(lds + (bufoff) + ldsw + 8192), 16, 0, 0); } while (0)
; #define G_LDA(dst, b, h) do { _Pragma("unroll") for (int m = 0; m < 4; ++m) _Pragma("unroll") for (int k = 0; k < 2; ++k) dst[m][k] = *(const LAS bf16x8*)(lds + G_SA(b, h) + aoff + m * 2048 + k * 1024); } while (0)
; #define G_LDB(dst, b, h) do { _Pragma("unroll") for (int n = 0; n < 2; ++n) _Pragma("unroll") for (int k = 0; k < 2; ++k) dst[n][k] = *(const LAS bf16x8*)(lds + G_SB(b, h) + boff + n * 2048 + k * 1024); } while (0)
; #define G_WAIT_V(n) asm volatile("s_waitcnt vmcnt(" #n ")" ::: "memory")
; #define G_WAIT_L(n) asm volatile("s_waitcnt lgkmcnt(" #n ")" ::: "memory")
; #define G_BAR __builtin_amdgcn_s_barrier()
; #define G_SCHED __builtin_amdgcn_sched_barrier(0)
;     ...
;             G_STAGE(G_SB(0, 1), b2 + chB, cB0, qB);
;             G_WAIT_V(6); G_BAR; G_MMA(1, 1, At, B1); G_BAR;
;             G_LDB(B0, 1, 0); G_SCHED; G_LDA(At, 1, 0); G_STAGE(G_SA(0, 1), a2 + chA, cA0, qA);
;             G_WAIT_L(8); G_BAR; G_WAIT_L(0); G_MMA(0, 0, At, B0); G_BAR; G_SCHED;
;             G_LDB(B1, 1, 1); G_STAGE(G_SB(1, 0), b3, cB0, qB);
;             G_BAR; G_WAIT_L(0); G_MMA(0, 1, At, B1); G_BAR;
;             G_LDA(At, 1, 1); G_STAGE(G_SA(1, 0), a3, cA0, qA);
;             G_BAR; G_WAIT_L(0); G_MMA(1, 0, At, B0); G_BAR; G_SCHED;
	s_add_i32 s100, s38, s21
	s_mov_b32 m0, s100
	s_nop 0
	s_add_u32 vcc_lo, s36, s0
	s_addc_u32 vcc_hi, s37, s1
	global_load_lds_dwordx4 v2, vcc
	s_add_i32 m0, s100, 0x2000
	s_nop 0
	s_add_u32 vcc_lo, s36, s52
	s_addc_u32 vcc_hi, s37, s53
	global_load_lds_dwordx4 v2, vcc
	s_waitcnt vmcnt(6)
	s_barrier
	v_mfma_f32_16x16x32_bf16 v[60:63], v[206:209], v[152:155], v[60:63]
	v_mfma_f32_16x16x32_bf16 v[56:59], v[214:217], v[152:155], v[56:59]
	v_mfma_f32_16x16x32_bf16 v[44:47], v[206:209], v[160:163], v[44:47]
	v_mfma_f32_16x16x32_bf16 v[40:43], v[214:217], v[160:163], v[40:43]
	v_mfma_f32_16x16x32_bf16 v[28:31], v[206:209], v[176:179], v[28:31]
	v_mfma_f32_16x16x32_bf16 v[24:27], v[214:217], v[176:179], v[24:27]
	v_mfma_f32_16x16x32_bf16 v[12:15], v[206:209], v[198:201], v[12:15]
	v_mfma_f32_16x16x32_bf16 v[8:11], v[214:217], v[198:201], v[8:11]
	v_mfma_f32_16x16x32_bf16 v[60:63], v[210:213], v[156:159], v[60:63]
	v_mfma_f32_16x16x32_bf16 v[56:59], v[218:221], v[156:159], v[56:59]
	v_mfma_f32_16x16x32_bf16 v[44:47], v[210:213], v[172:175], v[44:47]
	v_mfma_f32_16x16x32_bf16 v[40:43], v[218:221], v[172:175], v[40:43]
	v_mfma_f32_16x16x32_bf16 v[28:31], v[210:213], v[180:183], v[28:31]
	v_mfma_f32_16x16x32_bf16 v[24:27], v[218:221], v[180:183], v[24:27]
	v_mfma_f32_16x16x32_bf16 v[12:15], v[210:213], v[202:205], v[12:15]
	v_mfma_f32_16x16x32_bf16 v[8:11], v[218:221], v[202:205], v[8:11]
	s_barrier
	s_add_i32 s100, 0, 0x18000
	ds_read_b128 v[112:115], v255 offset:32768
	ds_read_b128 v[124:127], v255 offset:33792
	ds_read_b128 v[136:139], v255 offset:34816
	ds_read_b128 v[148:151], v255 offset:35840
	s_mov_b32 m0, s26
	ds_read_b128 v[152:155], v197 offset:32768
	ds_read_b128 v[156:159], v197 offset:33792
	ds_read_b128 v[160:163], v197 offset:34816
	ds_read_b128 v[172:175], v197 offset:35840
	ds_read_b128 v[176:179], v197 offset:36864
	ds_read_b128 v[180:183], v197 offset:37888
	ds_read_b128 v[198:201], v197 offset:38912
	ds_read_b128 v[202:205], v197 offset:39936
	s_add_u32 vcc_lo, s4, s80
	s_addc_u32 vcc_hi, s5, s81
	global_load_lds_dwordx4 v164, vcc
	s_mov_b32 m0, s27
	s_nop 0
	s_add_u32 vcc_lo, s4, s82
	s_addc_u32 vcc_hi, s5, s83
	global_load_lds_dwordx4 v164, vcc
	s_waitcnt lgkmcnt(8)
	s_barrier
	s_waitcnt lgkmcnt(0)
	v_mfma_f32_16x16x32_bf16 v[144:147], v[112:115], v[152:155], v[144:147]
	v_mfma_f32_16x16x32_bf16 v[140:143], v[136:139], v[152:155], v[140:143]
	v_mfma_f32_16x16x32_bf16 v[120:123], v[112:115], v[160:163], v[120:123]
	v_mfma_f32_16x16x32_bf16 v[116:119], v[136:139], v[160:163], v[116:119]
	v_mfma_f32_16x16x32_bf16 v[100:103], v[112:115], v[176:179], v[100:103]
	v_mfma_f32_16x16x32_bf16 v[96:99], v[136:139], v[176:179], v[96:99]
	v_mfma_f32_16x16x32_bf16 v[84:87], v[112:115], v[198:201], v[84:87]
	v_mfma_f32_16x16x32_bf16 v[80:83], v[136:139], v[198:201], v[80:83]
	v_mfma_f32_16x16x32_bf16 v[144:147], v[124:127], v[156:159], v[144:147]
	v_mfma_f32_16x16x32_bf16 v[140:143], v[148:151], v[156:159], v[140:143]
	v_mfma_f32_16x16x32_bf16 v[120:123], v[124:127], v[172:175], v[120:123]
	v_mfma_f32_16x16x32_bf16 v[116:119], v[148:151], v[172:175], v[116:119]
	v_mfma_f32_16x16x32_bf16 v[100:103], v[124:127], v[180:183], v[100:103]
	v_mfma_f32_16x16x32_bf16 v[96:99], v[148:151], v[180:183], v[96:99]
	v_mfma_f32_16x16x32_bf16 v[84:87], v[124:127], v[202:205], v[84:87]
	v_mfma_f32_16x16x32_bf16 v[80:83], v[148:151], v[202:205], v[80:83]
	s_barrier
	s_add_i32 s5, 0, 0x1c000
	s_add_i32 s4, s100, s21
	s_mov_b32 m0, s4
	ds_read_b128 v[206:209], v255 offset:49152
	ds_read_b128 v[210:213], v255 offset:50176
	ds_read_b128 v[214:217], v255 offset:51200
	ds_read_b128 v[218:221], v255 offset:52224
	s_add_u32 vcc_lo, s36, s46
	s_addc_u32 vcc_hi, s37, s47
	global_load_lds_dwordx4 v2, vcc
	s_add_i32 m0, s4, 0x2000
	s_nop 0
	s_add_u32 vcc_lo, s36, s54
	s_addc_u32 vcc_hi, s37, s55
	global_load_lds_dwordx4 v2, vcc
	s_barrier
; #define G_STAGE(bufoff, gbase, o0, h64) do { \
;         __builtin_amdgcn_global_load_lds((const unsigned*)((const char*)(gbase) + (o0)), (LAS unsigned*)(lds + (bufoff) + ldsw), 16, 0, 0); \
;         __builtin_amdgcn_global_load_lds((const unsigned*)((const char*)(gbase) + (h64) + (o0)), (LAS unsigned*)(lds + (bufoff) + ldsw + 8192), 16, 0, 0); } while (0)
; #define G_LDA(dst, b, h) do { _Pragma("unroll") for (int m = 0; m < 4; ++m) _Pragma("unroll") for (int k = 0; k < 2; ++k) dst[m][k] = *(const LAS bf16x8*)(lds + G_SA(b, h) + aoff + m * 2048 + k * 1024); } while (0)
; #define G_LDB(dst, b, h) do { _Pragma("unroll") for (int n = 0; n < 2; ++n) _Pragma("unroll") for (int k = 0; k < 2; ++k) dst[n][k] = *(const LAS bf16x8*)(lds + G_SB(b, h) + boff + n * 2048 + k * 1024); } while (0)
; #define G_WAIT_V(n) asm volatile("s_waitcnt vmcnt(" #n ")" ::: "memory")
; #define G_WAIT_L(n) asm volatile("s_waitcnt lgkmcnt(" #n ")" ::: "memory")
; #define G_BAR __builtin_amdgcn_s_barrier()
; #define G_SCHED __builtin_amdgcn_sched_barrier(0)
;     ...
;             G_LDB(B1, 1, 1); G_STAGE(G_SB(1, 0), b3, cB0, qB);
;             G_BAR; G_WAIT_L(0); G_MMA(0, 1, At, B1); G_BAR;
;             G_LDA(At, 1, 1); G_STAGE(G_SA(1, 0), a3, cA0, qA);
;             G_BAR; G_WAIT_L(0); G_MMA(1, 0, At, B0); G_BAR; G_SCHED;
;             G_STAGE(G_SB(1, 1), b3 + chB, cB0, qB);
;             G_WAIT_V(6); G_BAR; G_MMA(1, 1, At, B1); G_BAR;
;         }
	s_waitcnt lgkmcnt(0)
	v_mfma_f32_16x16x32_bf16 v[132:135], v[206:209], v[152:155], v[132:135]
	v_mfma_f32_16x16x32_bf16 v[128:131], v[214:217], v[152:155], v[128:131]
	v_mfma_f32_16x16x32_bf16 v[108:111], v[206:209], v[160:163], v[108:111]
	v_mfma_f32_16x16x32_bf16 v[104:107], v[214:217], v[160:163], v[104:107]
	v_mfma_f32_16x16x32_bf16 v[92:95], v[206:209], v[176:179], v[92:95]
	v_mfma_f32_16x16x32_bf16 v[88:91], v[214:217], v[176:179], v[88:91]
	v_mfma_f32_16x16x32_bf16 v[76:79], v[206:209], v[198:201], v[76:79]
	v_mfma_f32_16x16x32_bf16 v[72:75], v[214:217], v[198:201], v[72:75]
	v_mfma_f32_16x16x32_bf16 v[132:135], v[210:213], v[156:159], v[132:135]
	v_mfma_f32_16x16x32_bf16 v[128:131], v[218:221], v[156:159], v[128:131]
	v_mfma_f32_16x16x32_bf16 v[108:111], v[210:213], v[172:175], v[108:111]
	v_mfma_f32_16x16x32_bf16 v[104:107], v[218:221], v[172:175], v[104:107]
	v_mfma_f32_16x16x32_bf16 v[92:95], v[210:213], v[180:183], v[92:95]
	v_mfma_f32_16x16x32_bf16 v[88:91], v[218:221], v[180:183], v[88:91]
	v_mfma_f32_16x16x32_bf16 v[76:79], v[210:213], v[202:205], v[76:79]
	v_mfma_f32_16x16x32_bf16 v[72:75], v[218:221], v[202:205], v[72:75]
	s_barrier
	s_mov_b32 m0, s29
	v_lshl_add_u64 v[224:225], v[222:223], 0, s[62:63]
	ds_read_b128 v[152:155], v197 offset:49152
	ds_read_b128 v[156:159], v197 offset:50176
	ds_read_b128 v[160:163], v197 offset:51200
	ds_read_b128 v[172:175], v197 offset:52224
	ds_read_b128 v[176:179], v197 offset:53248
	ds_read_b128 v[180:183], v197 offset:54272
	ds_read_b128 v[198:201], v197 offset:55296
	ds_read_b128 v[202:205], v197 offset:56320
	global_load_lds_dwordx4 v[224:225], off
	v_lshl_add_u64 v[222:223], v[222:223], 0, s[84:85]
	s_mov_b32 m0, s30
	s_nop 0
	global_load_lds_dwordx4 v[222:223], off
	s_barrier
	s_waitcnt lgkmcnt(0)
	v_mfma_f32_16x16x32_bf16 v[68:71], v[112:115], v[152:155], v[68:71]
	v_mfma_f32_16x16x32_bf16 v[64:67], v[136:139], v[152:155], v[64:67]
	v_mfma_f32_16x16x32_bf16 v[52:55], v[112:115], v[160:163], v[52:55]
	v_mfma_f32_16x16x32_bf16 v[48:51], v[136:139], v[160:163], v[48:51]
	v_mfma_f32_16x16x32_bf16 v[36:39], v[112:115], v[176:179], v[36:39]
	v_mfma_f32_16x16x32_bf16 v[32:35], v[136:139], v[176:179], v[32:35]
	v_mfma_f32_16x16x32_bf16 v[20:23], v[112:115], v[198:201], v[20:23]
	v_mfma_f32_16x16x32_bf16 v[16:19], v[136:139], v[198:201], v[16:19]
	v_mfma_f32_16x16x32_bf16 v[68:71], v[124:127], v[156:159], v[68:71]
	v_mfma_f32_16x16x32_bf16 v[64:67], v[148:151], v[156:159], v[64:67]
	v_mfma_f32_16x16x32_bf16 v[52:55], v[124:127], v[172:175], v[52:55]
	v_mfma_f32_16x16x32_bf16 v[48:51], v[148:151], v[172:175], v[48:51]
	v_mfma_f32_16x16x32_bf16 v[36:39], v[124:127], v[180:183], v[36:39]
	v_mfma_f32_16x16x32_bf16 v[32:35], v[148:151], v[180:183], v[32:35]
	v_mfma_f32_16x16x32_bf16 v[20:23], v[124:127], v[202:205], v[20:23]
	v_mfma_f32_16x16x32_bf16 v[16:19], v[148:151], v[202:205], v[16:19]
	s_barrier
	s_add_i32 s4, s5, s21
	s_mov_b32 m0, s4
	s_nop 0
	s_add_u32 vcc_lo, s36, s42
	s_addc_u32 vcc_hi, s37, s43
	global_load_lds_dwordx4 v2, vcc
	s_add_i32 m0, s4, 0x2000
	s_nop 0
	s_add_u32 vcc_lo, s36, s58
	s_addc_u32 vcc_hi, s37, s59
	global_load_lds_dwordx4 v2, vcc
	s_add_i32 s19, s19, 2
	s_add_u32 s13, s13, 0x100
	s_addc_u32 s18, s18, 0
	s_add_u32 s2, s2, 0x800000
	s_addc_u32 s3, s3, 0
	s_cmp_gt_u32 s19, 5
	s_waitcnt vmcnt(6)
	s_barrier
	v_mfma_f32_16x16x32_bf16 v[60:63], v[206:209], v[152:155], v[60:63]
	v_mfma_f32_16x16x32_bf16 v[56:59], v[214:217], v[152:155], v[56:59]
	v_mfma_f32_16x16x32_bf16 v[44:47], v[206:209], v[160:163], v[44:47]
	v_mfma_f32_16x16x32_bf16 v[40:43], v[214:217], v[160:163], v[40:43]
	v_mfma_f32_16x16x32_bf16 v[28:31], v[206:209], v[176:179], v[28:31]
	v_mfma_f32_16x16x32_bf16 v[24:27], v[214:217], v[176:179], v[24:27]
	v_mfma_f32_16x16x32_bf16 v[12:15], v[206:209], v[198:201], v[12:15]
	v_mfma_f32_16x16x32_bf16 v[8:11], v[214:217], v[198:201], v[8:11]
	v_mfma_f32_16x16x32_bf16 v[60:63], v[210:213], v[156:159], v[60:63]
	v_mfma_f32_16x16x32_bf16 v[56:59], v[218:221], v[156:159], v[56:59]
	v_mfma_f32_16x16x32_bf16 v[44:47], v[210:213], v[172:175], v[44:47]
	v_mfma_f32_16x16x32_bf16 v[40:43], v[218:221], v[172:175], v[40:43]
	v_mfma_f32_16x16x32_bf16 v[28:31], v[210:213], v[180:183], v[28:31]
	v_mfma_f32_16x16x32_bf16 v[24:27], v[218:221], v[180:183], v[24:27]
	v_mfma_f32_16x16x32_bf16 v[12:15], v[210:213], v[202:205], v[12:15]
	v_mfma_f32_16x16x32_bf16 v[8:11], v[218:221], v[202:205], v[8:11]
	s_cbranch_scc1 .Ldb_GLU_xl

; __device__ __forceinline__ float sigmoidf_(float v) { return __builtin_amdgcn_rcpf(1.0f + __expf(-v)); }
; __device__ __forceinline__ u32x4 pack8(const f32x4 a, const f32x4 b) { u32x4 w; w.x = cvt_pk_bf16(a[0], a[1]); w.y = cvt_pk_bf16(a[2], a[3]); w.z = cvt_pk_bf16(b[0], b[1]); w.w = cvt_pk_bf16(b[2], b[3]); return w; }
; __device__ __forceinline__ void unpack8(const u32x4 w, f32x4& a, f32x4& b) { a[0] = bf_lo(w.x); a[1] = bf_hi(w.x); a[2] = bf_lo(w.y); a[3] = bf_hi(w.y); b[0] = bf_lo(w.z); b[1] = bf_hi(w.z); b[2] = bf_lo(w.w); b[3] = bf_hi(w.w); }
;     template <int KIND> __device__ __forceinline__ void run(f32x4 (&acc)[2][2][4][2], const Unit& u, int tid_in) const {
;     ...
;         if constexpr (KIND == K_GLU) {
; #pragma unroll
;             for (int ai = 0; ai < 2; ++ai) { u32x4 yv[4][2];
; #pragma unroll
;                 for (int m = 0; m < 4; ++m) { int row = rbase + ai * 128 + m * 16; asm volatile("" : "+v"(row));
; #pragma unroll
;                     for (int bj = 0; bj < 2; ++bj) { const int col = u.pn * 256 + bj * 128 + cl; yv[m][bj] = *(const u32x4*)(yi + ((size_t)(col >> 4) * T_TOK + row) * 16 + (col & 15)); } }
; #pragma unroll
;                 for (int m = 0; m < 4; ++m) { int row = rbase + ai * 128 + m * 16; asm volatile("" : "+v"(row));
; #pragma unroll
;                     for (int bj = 0; bj < 2; ++bj) { const int col = u.pn * 256 + bj * 128 + cl; f32x4 y0, y1; unpack8(yv[m][bj], y0, y1);
; #pragma unroll
;                         for (int j = 0; j < 4; ++j) { y0[j] *= sigmoidf_(acc[ai][bj][m][0][j]); y1[j] *= sigmoidf_(acc[ai][bj][m][1][j]); }
;                         *(u32x4*)(zb + (size_t)row * ZW + 1024 + col) = pack8(y0, y1); } }
.Ldb_GLU_young:
	s_setprio 3
	s_mov_b32 s101, 2
	s_branch .Ldb_GLU_exit
.Ldb_GLU_exit:
	v_mov_b32_e32 v0, v195
	s_lshl_b32 s3, s35, 8
	v_readfirstlane_b32 s2, v0
	s_ashr_i32 s4, s2, 2
	s_lshr_b32 s2, s2, 1
	s_and_b32 s2, s2, 0x60
	v_lshrrev_b32_e32 v112, 1, v0
	v_and_or_b32 v112, v112, 24, s2
	s_andn2_b32 s4, s4, 63
	v_lshl_or_b32 v182, s33, 8, v112
	s_add_i32 s4, s4, s3
	v_ashrrev_i32_e32 v112, 4, v182
	v_and_or_b32 v198, v0, 15, s4
	v_ashrrev_i32_e32 v113, 31, v112
	v_lshlrev_b64 v[176:177], 20, v[112:113]
	v_mov_b32_e32 v112, v198
	v_and_b32_e32 v0, 16, v0
	v_lshl_add_u64 v[174:175], s[8:9], 0, v[0:1]
	v_ashrrev_i32_e32 v113, 31, v112
	v_lshlrev_b64 v[112:113], 5, v[112:113]
	v_lshl_add_u64 v[112:113], v[174:175], 0, v[112:113]
	v_lshl_add_u64 v[114:115], v[112:113], 0, v[176:177]
	global_load_dwordx4 v[202:205], v[114:115], off
	v_or_b32_e32 v180, 0x80, v182
	v_ashrrev_i32_e32 v114, 4, v180
	v_ashrrev_i32_e32 v115, 31, v114
	v_lshlrev_b64 v[178:179], 20, v[114:115]
	v_lshl_add_u64 v[112:113], v[112:113], 0, v[178:179]
	global_load_dwordx4 v[160:163], v[112:113], off
	v_or_b32_e32 v200, 16, v198
	v_mov_b32_e32 v112, v200
	v_or_b32_e32 v199, 32, v198
	v_ashrrev_i32_e32 v113, 31, v112
	v_lshlrev_b64 v[112:113], 5, v[112:113]
	v_lshl_add_u64 v[112:113], v[174:175], 0, v[112:113]
	v_lshl_add_u64 v[114:115], v[112:113], 0, v[176:177]
	global_load_dwordx4 v[156:159], v[114:115], off
	v_lshl_add_u64 v[112:113], v[112:113], 0, v[178:179]
	global_load_dwordx4 v[152:155], v[112:113], off
	v_mov_b32_e32 v112, v199
	v_mul_f32_e32 v144, 0xbfb8aa3b, v144
	v_ashrrev_i32_e32 v113, 31, v112
	v_lshlrev_b64 v[112:113], 5, v[112:113]
	v_mul_f32_e32 v142, 0xbfb8aa3b, v142
	v_lshl_add_u64 v[112:113], v[174:175], 0, v[112:113]
	v_exp_f32_e32 v144, v144
	v_exp_f32_e32 v142, v142
	v_lshl_add_u64 v[114:115], v[112:113], 0, v[176:177]
	v_lshl_add_u64 v[112:113], v[112:113], 0, v[178:179]
	v_or_b32_e32 v0, 48, v198
	global_load_dwordx4 v[148:151], v[114:115], off
	global_load_dwordx4 v[136:139], v[112:113], off
	v_mov_b32_e32 v112, v0
	v_add_f32_e32 v144, 1.0, v144
	v_ashrrev_i32_e32 v113, 31, v112
	v_lshlrev_b64 v[112:113], 5, v[112:113]
	v_add_f32_e32 v142, 1.0, v142
	v_lshl_add_u64 v[112:113], v[174:175], 0, v[112:113]
	v_rcp_f32_e32 v144, v144
	v_rcp_f32_e32 v142, v142
	v_lshl_add_u64 v[114:115], v[112:113], 0, v[176:177]
	v_lshl_add_u64 v[112:113], v[112:113], 0, v[178:179]
	v_mov_b32_e32 v181, v198
	global_load_dwordx4 v[124:127], v[114:115], off
	v_mov_b64_e32 v[172:173], s[6:7]
	global_load_dwordx4 v[112:115], v[112:113], off
	v_mul_f32_e32 v145, 0xbfb8aa3b, v145
	v_mad_i64_i32 v[184:185], s[2:3], v181, s76, v[172:173]
	v_mul_f32_e32 v140, 0xbfb8aa3b, v140
	v_exp_f32_e32 v145, v145
	v_mul_f32_e32 v141, 0xbfb8aa3b, v141
	v_mul_f32_e32 v146, 0xbfb8aa3b, v146
	v_exp_f32_e32 v140, v140
	v_exp_f32_e32 v141, v141
	v_exp_f32_e32 v146, v146
	v_add_f32_e32 v145, 1.0, v145
	v_mul_f32_e32 v132, 0xbfb8aa3b, v132
	v_mul_f32_e32 v130, 0xbfb8aa3b, v130
	v_add_f32_e32 v140, 1.0, v140
	v_rcp_f32_e32 v145, v145
	v_add_f32_e32 v141, 1.0, v141
	v_add_f32_e32 v146, 1.0, v146
	v_exp_f32_e32 v132, v132
	v_exp_f32_e32 v130, v130
	v_rcp_f32_e32 v140, v140
	v_rcp_f32_e32 v141, v141
	v_rcp_f32_e32 v146, v146
	v_add_f32_e32 v132, 1.0, v132
	v_add_f32_e32 v130, 1.0, v130
	s_mov_b64 s[4:5], 0xae00800
	v_rcp_f32_e32 v132, v132
	v_rcp_f32_e32 v130, v130
	v_lshl_add_u64 v[184:185], v[184:185], 0, s[4:5]
	v_mul_f32_e32 v128, 0xbfb8aa3b, v128
	v_mul_f32_e32 v129, 0xbfb8aa3b, v129
	v_exp_f32_e32 v128, v128
	v_mul_f32_e32 v133, 0xbfb8aa3b, v133
	s_waitcnt vmcnt(0)
	v_lshlrev_b32_e32 v181, 16, v202
	v_lshlrev_b32_e32 v206, 16, v205
	v_mul_f32_e32 v144, v144, v181
	v_mul_f32_e32 v181, v142, v206
	v_mul_f32_e32 v142, 0xbfb8aa3b, v147
	v_exp_f32_e32 v142, v142
	v_and_b32_e32 v183, 0xffff0000, v202
	v_and_b32_e32 v202, 0xffff0000, v203
	v_and_b32_e32 v205, 0xffff0000, v205
	v_add_f32_e32 v142, 1.0, v142
	v_rcp_f32_e32 v142, v142
	v_lshlrev_b32_e32 v201, 16, v203
	v_lshlrev_b32_e32 v203, 16, v204
	v_and_b32_e32 v204, 0xffff0000, v204
	v_mul_f32_e32 v147, v142, v202
	v_mul_f32_e32 v142, 0xbfb8aa3b, v143
	v_exp_f32_e32 v142, v142
	v_mul_f32_e32 v145, v145, v183
	v_mul_f32_e32 v140, v140, v203
	v_mul_f32_e32 v141, v141, v204
	v_add_f32_e32 v142, 1.0, v142
	v_rcp_f32_e32 v142, v142
	v_mul_f32_e32 v146, v146, v201
	v_exp_f32_e32 v129, v129
	v_mul_f32_e32 v134, 0xbfb8aa3b, v134
	v_mul_f32_e32 v183, v142, v205
	v_cvt_pk_bf16_f32 v142, v144, v145
	v_cvt_pk_bf16_f32 v143, v146, v147
	v_cvt_pk_bf16_f32 v144, v140, v141
	v_cvt_pk_bf16_f32 v145, v181, v183
	v_ashrrev_i32_e32 v183, 31, v182
	v_lshlrev_b64 v[140:141], 1, v[182:183]
	v_lshl_add_u64 v[146:147], v[184:185], 0, v[140:141]
	global_store_dwordx4 v[146:147], v[142:145], off
	v_exp_f32_e32 v133, v133
	v_exp_f32_e32 v134, v134
	v_lshlrev_b32_e32 v142, 16, v160
	v_and_b32_e32 v143, 0xffff0000, v160
	v_lshlrev_b32_e32 v160, 16, v163
	v_mul_f32_e32 v132, v132, v142
	v_mul_f32_e32 v142, v130, v160
	v_mul_f32_e32 v130, 0xbfb8aa3b, v135
	v_exp_f32_e32 v130, v130
	v_and_b32_e32 v145, 0xffff0000, v161
	v_mul_f32_e32 v120, 0xbfb8aa3b, v120
	v_mul_f32_e32 v116, 0xbfb8aa3b, v116
	v_add_f32_e32 v130, 1.0, v130
	v_rcp_f32_e32 v130, v130
	v_mul_f32_e32 v117, 0xbfb8aa3b, v117
	v_mul_f32_e32 v118, 0xbfb8aa3b, v118
	v_add_f32_e32 v128, 1.0, v128
	v_mul_f32_e32 v135, v130, v145
	v_mul_f32_e32 v130, 0xbfb8aa3b, v131
	v_exp_f32_e32 v130, v130
	v_add_f32_e32 v129, 1.0, v129
	v_exp_f32_e32 v120, v120
	v_exp_f32_e32 v116, v116
	v_exp_f32_e32 v117, v117
	v_exp_f32_e32 v118, v118
	v_rcp_f32_e32 v128, v128
	v_add_f32_e32 v133, 1.0, v133
	v_rcp_f32_e32 v129, v129
; __device__ __forceinline__ float sigmoidf_(float v) { return __builtin_amdgcn_rcpf(1.0f + __expf(-v)); }
; __device__ __forceinline__ u32x4 pack8(const f32x4 a, const f32x4 b) { u32x4 w; w.x = cvt_pk_bf16(a[0], a[1]); w.y = cvt_pk_bf16(a[2], a[3]); w.z = cvt_pk_bf16(b[0], b[1]); w.w = cvt_pk_bf16(b[2], b[3]); return w; }
; __device__ __forceinline__ void unpack8(const u32x4 w, f32x4& a, f32x4& b) { a[0] = bf_lo(w.x); a[1] = bf_hi(w.x); a[2] = bf_lo(w.y); a[3] = bf_hi(w.y); b[0] = bf_lo(w.z); b[1] = bf_hi(w.z); b[2] = bf_lo(w.w); b[3] = bf_hi(w.w); }
;     template <int KIND> __device__ __forceinline__ void run(f32x4 (&acc)[2][2][4][2], const Unit& u, int tid_in) const {
;     ...
;                 for (int m = 0; m < 4; ++m) { int row = rbase + ai * 128 + m * 16; asm volatile("" : "+v"(row));
; #pragma unroll
;                     for (int bj = 0; bj < 2; ++bj) { const int col = u.pn * 256 + bj * 128 + cl; yv[m][bj] = *(const u32x4*)(yi + ((size_t)(col >> 4) * T_TOK + row) * 16 + (col & 15)); } }
; #pragma unroll
;                 for (int m = 0; m < 4; ++m) { int row = rbase + ai * 128 + m * 16; asm volatile("" : "+v"(row));
; #pragma unroll
;                     for (int bj = 0; bj < 2; ++bj) { const int col = u.pn * 256 + bj * 128 + cl; f32x4 y0, y1; unpack8(yv[m][bj], y0, y1);
; #pragma unroll
;                         for (int j = 0; j < 4; ++j) { y0[j] *= sigmoidf_(acc[ai][bj][m][0][j]); y1[j] *= sigmoidf_(acc[ai][bj][m][1][j]); }
;                         *(u32x4*)(zb + (size_t)row * ZW + 1024 + col) = pack8(y0, y1); } }
	v_add_f32_e32 v134, 1.0, v134
	v_add_f32_e32 v130, 1.0, v130
	v_rcp_f32_e32 v133, v133
	v_rcp_f32_e32 v134, v134
	v_rcp_f32_e32 v130, v130
	v_lshlrev_b32_e32 v146, 16, v162
	v_and_b32_e32 v147, 0xffff0000, v162
	v_add_f32_e32 v120, 1.0, v120
	v_add_f32_e32 v116, 1.0, v116
	v_add_f32_e32 v117, 1.0, v117
	v_add_f32_e32 v118, 1.0, v118
	v_lshlrev_b32_e32 v144, 16, v161
	v_and_b32_e32 v161, 0xffff0000, v163
	v_mul_f32_e32 v128, v128, v146
	v_mul_f32_e32 v129, v129, v147
	v_ashrrev_i32_e32 v181, 31, v180
	v_rcp_f32_e32 v120, v120
	v_rcp_f32_e32 v116, v116
	v_rcp_f32_e32 v117, v117
	v_rcp_f32_e32 v118, v118
	v_mul_f32_e32 v133, v133, v143
	v_mul_f32_e32 v134, v134, v144
	v_mul_f32_e32 v143, v130, v161
	v_cvt_pk_bf16_f32 v130, v132, v133
	v_cvt_pk_bf16_f32 v131, v134, v135
	v_cvt_pk_bf16_f32 v132, v128, v129
	v_lshlrev_b64 v[128:129], 1, v[180:181]
	v_lshl_add_u64 v[134:135], v[184:185], 0, v[128:129]
	v_cvt_pk_bf16_f32 v133, v142, v143
	global_store_dwordx4 v[134:135], v[130:133], off
	v_lshlrev_b32_e32 v142, 16, v158
	v_and_b32_e32 v143, 0xffff0000, v158
	v_lshlrev_b32_e32 v132, 16, v156
	v_lshlrev_b32_e32 v144, 16, v159
	v_mul_f32_e32 v120, v120, v132
	v_mul_f32_e32 v132, v116, v142
	v_mul_f32_e32 v116, 0xbfb8aa3b, v121
	v_mul_f32_e32 v121, v117, v143
	v_mul_f32_e32 v117, 0xbfb8aa3b, v122
	v_mul_f32_e32 v122, v118, v144
	v_mul_f32_e32 v118, 0xbfb8aa3b, v123
	v_exp_f32_e32 v116, v116
	v_exp_f32_e32 v117, v117
	v_exp_f32_e32 v118, v118
	v_mul_f32_e32 v119, 0xbfb8aa3b, v119
	v_exp_f32_e32 v119, v119
	v_mul_f32_e32 v108, 0xbfb8aa3b, v108
	v_mul_f32_e32 v104, 0xbfb8aa3b, v104
	v_mul_f32_e32 v105, 0xbfb8aa3b, v105
	v_mul_f32_e32 v106, 0xbfb8aa3b, v106
	v_exp_f32_e32 v108, v108
	v_exp_f32_e32 v104, v104
	v_exp_f32_e32 v105, v105
	v_exp_f32_e32 v106, v106
	v_add_f32_e32 v116, 1.0, v116
	v_add_f32_e32 v117, 1.0, v117
	v_add_f32_e32 v118, 1.0, v118
	v_rcp_f32_e32 v116, v116
	v_rcp_f32_e32 v117, v117
	v_rcp_f32_e32 v118, v118
	v_add_f32_e32 v119, 1.0, v119
	v_rcp_f32_e32 v119, v119
	v_add_f32_e32 v108, 1.0, v108
	v_add_f32_e32 v104, 1.0, v104
	v_add_f32_e32 v105, 1.0, v105
	v_add_f32_e32 v106, 1.0, v106
	v_and_b32_e32 v133, 0xffff0000, v156
	v_mad_i64_i32 v[130:131], s[2:3], v200, s76, v[172:173]
	v_lshlrev_b32_e32 v134, 16, v157
	v_and_b32_e32 v135, 0xffff0000, v157
	v_rcp_f32_e32 v108, v108
	v_rcp_f32_e32 v104, v104
	v_rcp_f32_e32 v105, v105
	v_rcp_f32_e32 v106, v106
	v_lshl_add_u64 v[130:131], v[130:131], 0, s[4:5]
	v_and_b32_e32 v145, 0xffff0000, v159
	v_mul_f32_e32 v116, v116, v133
	v_mul_f32_e32 v117, v117, v134
	v_mul_f32_e32 v118, v118, v135
	v_mul_f32_e32 v119, v119, v145
	v_cvt_pk_bf16_f32 v116, v120, v116
	v_cvt_pk_bf16_f32 v117, v117, v118
	v_cvt_pk_bf16_f32 v118, v132, v121
	v_lshl_add_u64 v[120:121], v[130:131], 0, v[140:141]
	v_cvt_pk_bf16_f32 v119, v122, v119
	global_store_dwordx4 v[120:121], v[116:119], off
	v_lshlrev_b32_e32 v120, 16, v154
	v_and_b32_e32 v121, 0xffff0000, v154
	v_lshlrev_b32_e32 v116, 16, v152
	v_lshlrev_b32_e32 v122, 16, v155
	v_mul_f32_e32 v108, v108, v116
	v_mul_f32_e32 v116, v104, v120
	v_mul_f32_e32 v104, 0xbfb8aa3b, v109
	v_mul_f32_e32 v109, v105, v121
	v_mul_f32_e32 v105, 0xbfb8aa3b, v110
	v_mul_f32_e32 v110, v106, v122
	v_mul_f32_e32 v106, 0xbfb8aa3b, v111
	v_exp_f32_e32 v104, v104
	v_exp_f32_e32 v105, v105
	v_exp_f32_e32 v106, v106
	v_mul_f32_e32 v107, 0xbfb8aa3b, v107
	v_exp_f32_e32 v107, v107
	v_mul_f32_e32 v100, 0xbfb8aa3b, v100
	v_mul_f32_e32 v96, 0xbfb8aa3b, v96
	v_mul_f32_e32 v97, 0xbfb8aa3b, v97
	v_mul_f32_e32 v98, 0xbfb8aa3b, v98
	v_exp_f32_e32 v100, v100
	v_exp_f32_e32 v96, v96
	v_exp_f32_e32 v97, v97
	v_exp_f32_e32 v98, v98
	v_add_f32_e32 v104, 1.0, v104
	v_add_f32_e32 v105, 1.0, v105
	v_add_f32_e32 v106, 1.0, v106
	v_rcp_f32_e32 v104, v104
	v_rcp_f32_e32 v105, v105
	v_rcp_f32_e32 v106, v106
	v_add_f32_e32 v107, 1.0, v107
	v_rcp_f32_e32 v107, v107
	v_add_f32_e32 v100, 1.0, v100
	v_add_f32_e32 v96, 1.0, v96
	v_add_f32_e32 v97, 1.0, v97
	v_add_f32_e32 v98, 1.0, v98
	v_and_b32_e32 v117, 0xffff0000, v152
	v_lshlrev_b32_e32 v118, 16, v153
	v_and_b32_e32 v119, 0xffff0000, v153
	v_rcp_f32_e32 v100, v100
	v_rcp_f32_e32 v96, v96
	v_rcp_f32_e32 v97, v97
	v_rcp_f32_e32 v98, v98
	v_and_b32_e32 v123, 0xffff0000, v155
	v_mul_f32_e32 v104, v104, v117
	v_mul_f32_e32 v105, v105, v118
	v_mul_f32_e32 v106, v106, v119
	v_mul_f32_e32 v107, v107, v123
	v_cvt_pk_bf16_f32 v104, v108, v104
	v_cvt_pk_bf16_f32 v105, v105, v106
	v_cvt_pk_bf16_f32 v106, v116, v109
	v_lshl_add_u64 v[108:109], v[130:131], 0, v[128:129]
	v_cvt_pk_bf16_f32 v107, v110, v107
	global_store_dwordx4 v[108:109], v[104:107], off
	v_lshlrev_b32_e32 v110, 16, v150
	v_and_b32_e32 v111, 0xffff0000, v150
	v_lshlrev_b32_e32 v106, 16, v148
	v_lshlrev_b32_e32 v116, 16, v151
	v_mul_f32_e32 v100, v100, v106
	v_mul_f32_e32 v106, v96, v110
	v_mul_f32_e32 v96, 0xbfb8aa3b, v101
	v_mul_f32_e32 v101, v97, v111
	v_mul_f32_e32 v97, 0xbfb8aa3b, v102
	v_mul_f32_e32 v102, v98, v116
	v_mul_f32_e32 v98, 0xbfb8aa3b, v103
	v_exp_f32_e32 v96, v96
	v_exp_f32_e32 v97, v97
	v_exp_f32_e32 v98, v98
	v_mul_f32_e32 v99, 0xbfb8aa3b, v99
	v_exp_f32_e32 v99, v99
	v_mul_f32_e32 v92, 0xbfb8aa3b, v92
	v_mul_f32_e32 v88, 0xbfb8aa3b, v88
	v_mul_f32_e32 v89, 0xbfb8aa3b, v89
	v_mul_f32_e32 v90, 0xbfb8aa3b, v90
	v_exp_f32_e32 v92, v92
	v_exp_f32_e32 v88, v88
	v_exp_f32_e32 v89, v89
	v_exp_f32_e32 v90, v90
	v_add_f32_e32 v96, 1.0, v96
	v_add_f32_e32 v97, 1.0, v97
	v_add_f32_e32 v98, 1.0, v98
	v_rcp_f32_e32 v96, v96
	v_rcp_f32_e32 v97, v97
	v_rcp_f32_e32 v98, v98
	v_add_f32_e32 v99, 1.0, v99
	v_rcp_f32_e32 v99, v99
	v_add_f32_e32 v92, 1.0, v92
	v_add_f32_e32 v88, 1.0, v88
	v_add_f32_e32 v89, 1.0, v89
; __device__ __forceinline__ float sigmoidf_(float v) { return __builtin_amdgcn_rcpf(1.0f + __expf(-v)); }
; __device__ __forceinline__ u32x4 pack8(const f32x4 a, const f32x4 b) { u32x4 w; w.x = cvt_pk_bf16(a[0], a[1]); w.y = cvt_pk_bf16(a[2], a[3]); w.z = cvt_pk_bf16(b[0], b[1]); w.w = cvt_pk_bf16(b[2], b[3]); return w; }
; __device__ __forceinline__ void unpack8(const u32x4 w, f32x4& a, f32x4& b) { a[0] = bf_lo(w.x); a[1] = bf_hi(w.x); a[2] = bf_lo(w.y); a[3] = bf_hi(w.y); b[0] = bf_lo(w.z); b[1] = bf_hi(w.z); b[2] = bf_lo(w.w); b[3] = bf_hi(w.w); }
;     template <int KIND> __device__ __forceinline__ void run(f32x4 (&acc)[2][2][4][2], const Unit& u, int tid_in) const {
;     ...
;                 for (int m = 0; m < 4; ++m) { int row = rbase + ai * 128 + m * 16; asm volatile("" : "+v"(row));
; #pragma unroll
;                     for (int bj = 0; bj < 2; ++bj) { const int col = u.pn * 256 + bj * 128 + cl; yv[m][bj] = *(const u32x4*)(yi + ((size_t)(col >> 4) * T_TOK + row) * 16 + (col & 15)); } }
; #pragma unroll
;                 for (int m = 0; m < 4; ++m) { int row = rbase + ai * 128 + m * 16; asm volatile("" : "+v"(row));
; #pragma unroll
;                     for (int bj = 0; bj < 2; ++bj) { const int col = u.pn * 256 + bj * 128 + cl; f32x4 y0, y1; unpack8(yv[m][bj], y0, y1);
; #pragma unroll
;                         for (int j = 0; j < 4; ++j) { y0[j] *= sigmoidf_(acc[ai][bj][m][0][j]); y1[j] *= sigmoidf_(acc[ai][bj][m][1][j]); }
;                         *(u32x4*)(zb + (size_t)row * ZW + 1024 + col) = pack8(y0, y1); } }
	v_add_f32_e32 v90, 1.0, v90
	v_and_b32_e32 v107, 0xffff0000, v148
	v_mad_i64_i32 v[104:105], s[2:3], v199, s76, v[172:173]
	v_lshlrev_b32_e32 v108, 16, v149
	v_and_b32_e32 v109, 0xffff0000, v149
	v_rcp_f32_e32 v92, v92
	v_rcp_f32_e32 v88, v88
	v_rcp_f32_e32 v89, v89
	v_rcp_f32_e32 v90, v90
	v_lshl_add_u64 v[104:105], v[104:105], 0, s[4:5]
	v_and_b32_e32 v117, 0xffff0000, v151
	v_mul_f32_e32 v96, v96, v107
	v_mul_f32_e32 v97, v97, v108
	v_mul_f32_e32 v98, v98, v109
	v_mul_f32_e32 v99, v99, v117
	v_cvt_pk_bf16_f32 v96, v100, v96
	v_cvt_pk_bf16_f32 v97, v97, v98
	v_cvt_pk_bf16_f32 v98, v106, v101
	v_lshl_add_u64 v[100:101], v[104:105], 0, v[140:141]
	v_cvt_pk_bf16_f32 v99, v102, v99
	global_store_dwordx4 v[100:101], v[96:99], off
	v_lshlrev_b32_e32 v100, 16, v138
	v_and_b32_e32 v101, 0xffff0000, v138
	v_lshlrev_b32_e32 v96, 16, v136
	v_lshlrev_b32_e32 v102, 16, v139
	v_mul_f32_e32 v92, v92, v96
	v_mul_f32_e32 v96, v88, v100
	v_mul_f32_e32 v88, 0xbfb8aa3b, v93
	v_mul_f32_e32 v93, v89, v101
	v_mul_f32_e32 v89, 0xbfb8aa3b, v94
	v_mul_f32_e32 v94, v90, v102
	v_mul_f32_e32 v90, 0xbfb8aa3b, v95
	v_exp_f32_e32 v88, v88
	v_exp_f32_e32 v89, v89
	v_exp_f32_e32 v90, v90
	v_mul_f32_e32 v91, 0xbfb8aa3b, v91
	v_exp_f32_e32 v91, v91
	v_mul_f32_e32 v84, 0xbfb8aa3b, v84
	v_mul_f32_e32 v80, 0xbfb8aa3b, v80
	v_mul_f32_e32 v81, 0xbfb8aa3b, v81
	v_mul_f32_e32 v82, 0xbfb8aa3b, v82
	v_add_f32_e32 v88, 1.0, v88
	v_add_f32_e32 v89, 1.0, v89
	v_add_f32_e32 v90, 1.0, v90
	v_exp_f32_e32 v84, v84
	v_exp_f32_e32 v80, v80
	v_exp_f32_e32 v81, v81
	v_exp_f32_e32 v82, v82
	v_rcp_f32_e32 v88, v88
	v_rcp_f32_e32 v89, v89
	v_rcp_f32_e32 v90, v90
	v_add_f32_e32 v91, 1.0, v91
	v_rcp_f32_e32 v91, v91
	v_and_b32_e32 v97, 0xffff0000, v136
	v_lshlrev_b32_e32 v98, 16, v137
	v_and_b32_e32 v99, 0xffff0000, v137
	v_add_f32_e32 v84, 1.0, v84
	v_add_f32_e32 v80, 1.0, v80
	v_add_f32_e32 v81, 1.0, v81
	v_add_f32_e32 v82, 1.0, v82
	v_and_b32_e32 v103, 0xffff0000, v139
	v_mul_f32_e32 v88, v88, v97
	v_mul_f32_e32 v89, v89, v98
	v_mul_f32_e32 v90, v90, v99
	v_rcp_f32_e32 v84, v84
	v_rcp_f32_e32 v80, v80
	v_rcp_f32_e32 v81, v81
	v_rcp_f32_e32 v82, v82
	v_mul_f32_e32 v91, v91, v103
	v_cvt_pk_bf16_f32 v88, v92, v88
	v_cvt_pk_bf16_f32 v89, v89, v90
	v_cvt_pk_bf16_f32 v90, v96, v93
	v_lshl_add_u64 v[92:93], v[104:105], 0, v[128:129]
	v_cvt_pk_bf16_f32 v91, v94, v91
	global_store_dwordx4 v[92:93], v[88:91], off
	v_lshlrev_b32_e32 v93, 16, v126
	v_and_b32_e32 v94, 0xffff0000, v126
	v_mad_i64_i32 v[88:89], s[2:3], v0, s76, v[172:173]
	v_lshlrev_b32_e32 v0, 16, v124
	v_lshlrev_b32_e32 v95, 16, v127
	v_mul_f32_e32 v0, v84, v0
	v_mul_f32_e32 v84, v80, v93
	v_mul_f32_e32 v80, 0xbfb8aa3b, v85
	v_mul_f32_e32 v85, v81, v94
	v_mul_f32_e32 v81, 0xbfb8aa3b, v86
	v_mul_f32_e32 v86, v82, v95
	v_mul_f32_e32 v82, 0xbfb8aa3b, v87
	v_mul_f32_e32 v83, 0xbfb8aa3b, v83
	v_exp_f32_e32 v80, v80
	v_exp_f32_e32 v81, v81
	v_exp_f32_e32 v82, v82
	v_exp_f32_e32 v83, v83
	v_mul_f32_e32 v76, 0xbfb8aa3b, v76
	v_mul_f32_e32 v72, 0xbfb8aa3b, v72
	v_mul_f32_e32 v73, 0xbfb8aa3b, v73
	v_mul_f32_e32 v74, 0xbfb8aa3b, v74
	v_exp_f32_e32 v76, v76
	v_exp_f32_e32 v72, v72
	v_exp_f32_e32 v73, v73
	v_exp_f32_e32 v74, v74
	v_add_f32_e32 v80, 1.0, v80
	v_add_f32_e32 v81, 1.0, v81
	v_add_f32_e32 v82, 1.0, v82
	v_add_f32_e32 v83, 1.0, v83
	v_rcp_f32_e32 v80, v80
	v_rcp_f32_e32 v81, v81
	v_rcp_f32_e32 v82, v82
	v_rcp_f32_e32 v83, v83
	v_add_f32_e32 v76, 1.0, v76
	v_add_f32_e32 v72, 1.0, v72
	v_add_f32_e32 v73, 1.0, v73
	v_add_f32_e32 v74, 1.0, v74
	v_and_b32_e32 v90, 0xffff0000, v124
	v_lshlrev_b32_e32 v91, 16, v125
	v_and_b32_e32 v92, 0xffff0000, v125
	v_and_b32_e32 v96, 0xffff0000, v127
	v_rcp_f32_e32 v76, v76
	v_rcp_f32_e32 v72, v72
	v_rcp_f32_e32 v73, v73
	v_rcp_f32_e32 v74, v74
	v_lshl_add_u64 v[88:89], v[88:89], 0, s[4:5]
	v_mul_f32_e32 v80, v80, v90
	v_mul_f32_e32 v81, v81, v91
	v_mul_f32_e32 v82, v82, v92
	v_mul_f32_e32 v83, v83, v96
	v_cvt_pk_bf16_f32 v80, v0, v80
	v_cvt_pk_bf16_f32 v81, v81, v82
	v_cvt_pk_bf16_f32 v82, v84, v85
	v_cvt_pk_bf16_f32 v83, v86, v83
	v_lshl_add_u64 v[84:85], v[88:89], 0, v[140:141]
	global_store_dwordx4 v[84:85], v[80:83], off
	v_lshlrev_b32_e32 v0, 16, v112
	v_and_b32_e32 v84, 0xffff0000, v114
	v_lshlrev_b32_e32 v83, 16, v114
	v_lshlrev_b32_e32 v85, 16, v115
	v_mul_f32_e32 v0, v76, v0
	v_mul_f32_e32 v76, v72, v83
	v_mul_f32_e32 v72, 0xbfb8aa3b, v77
	v_mul_f32_e32 v77, v73, v84
	v_mul_f32_e32 v73, 0xbfb8aa3b, v78
	v_mul_f32_e32 v78, v74, v85
	v_mul_f32_e32 v74, 0xbfb8aa3b, v79
	v_exp_f32_e32 v72, v72
	v_exp_f32_e32 v73, v73
	v_exp_f32_e32 v74, v74
	v_mul_f32_e32 v75, 0xbfb8aa3b, v75
	v_exp_f32_e32 v75, v75
	v_add_f32_e32 v72, 1.0, v72
	v_add_f32_e32 v73, 1.0, v73
	v_add_f32_e32 v74, 1.0, v74
	v_rcp_f32_e32 v72, v72
	v_rcp_f32_e32 v73, v73
	v_rcp_f32_e32 v74, v74
	v_add_f32_e32 v75, 1.0, v75
	v_rcp_f32_e32 v75, v75
	v_and_b32_e32 v80, 0xffff0000, v112
	v_lshlrev_b32_e32 v81, 16, v113
	v_and_b32_e32 v82, 0xffff0000, v113
	v_and_b32_e32 v86, 0xffff0000, v115
	v_mul_f32_e32 v72, v72, v80
	v_mul_f32_e32 v73, v73, v81
	v_mul_f32_e32 v74, v74, v82
	v_mul_f32_e32 v75, v75, v86
	v_cvt_pk_bf16_f32 v72, v0, v72
	v_cvt_pk_bf16_f32 v73, v73, v74
	v_cvt_pk_bf16_f32 v74, v76, v77
	v_lshl_add_u64 v[76:77], v[88:89], 0, v[128:129]
	v_add_u32_e32 v100, 0x80, v198
	v_cvt_pk_bf16_f32 v75, v78, v75
	global_store_dwordx4 v[76:77], v[72:75], off
	v_add_u32_e32 v103, 0x90, v198
	v_add_u32_e32 v102, 0xa0, v198
	v_mov_b32_e32 v72, v100
	v_mul_f32_e32 v68, 0xbfb8aa3b, v68
	v_ashrrev_i32_e32 v73, 31, v72
	v_lshlrev_b64 v[72:73], 5, v[72:73]
	v_lshl_add_u64 v[72:73], v[174:175], 0, v[72:73]
	v_lshl_add_u64 v[74:75], v[72:73], 0, v[176:177]
; __device__ __forceinline__ float sigmoidf_(float v) { return __builtin_amdgcn_rcpf(1.0f + __expf(-v)); }
; __device__ __forceinline__ u32x4 pack8(const f32x4 a, const f32x4 b) { u32x4 w; w.x = cvt_pk_bf16(a[0], a[1]); w.y = cvt_pk_bf16(a[2], a[3]); w.z = cvt_pk_bf16(b[0], b[1]); w.w = cvt_pk_bf16(b[2], b[3]); return w; }
; __device__ __forceinline__ void unpack8(const u32x4 w, f32x4& a, f32x4& b) { a[0] = bf_lo(w.x); a[1] = bf_hi(w.x); a[2] = bf_lo(w.y); a[3] = bf_hi(w.y); b[0] = bf_lo(w.z); b[1] = bf_hi(w.z); b[2] = bf_lo(w.w); b[3] = bf_hi(w.w); }
;     template <int KIND> __device__ __forceinline__ void run(f32x4 (&acc)[2][2][4][2], const Unit& u, int tid_in) const {
;     ...
;             for (int ai = 0; ai < 2; ++ai) { u32x4 yv[4][2];
; #pragma unroll
;                 for (int m = 0; m < 4; ++m) { int row = rbase + ai * 128 + m * 16; asm volatile("" : "+v"(row));
; #pragma unroll
;                     for (int bj = 0; bj < 2; ++bj) { const int col = u.pn * 256 + bj * 128 + cl; yv[m][bj] = *(const u32x4*)(yi + ((size_t)(col >> 4) * T_TOK + row) * 16 + (col & 15)); } }
; #pragma unroll
;                 for (int m = 0; m < 4; ++m) { int row = rbase + ai * 128 + m * 16; asm volatile("" : "+v"(row));
; #pragma unroll
;                     for (int bj = 0; bj < 2; ++bj) { const int col = u.pn * 256 + bj * 128 + cl; f32x4 y0, y1; unpack8(yv[m][bj], y0, y1);
; #pragma unroll
;                         for (int j = 0; j < 4; ++j) { y0[j] *= sigmoidf_(acc[ai][bj][m][0][j]); y1[j] *= sigmoidf_(acc[ai][bj][m][1][j]); }
;                         *(u32x4*)(zb + (size_t)row * ZW + 1024 + col) = pack8(y0, y1); } }
	global_load_dwordx4 v[104:107], v[74:75], off
	v_lshl_add_u64 v[72:73], v[72:73], 0, v[178:179]
	global_load_dwordx4 v[96:99], v[72:73], off
	v_mov_b32_e32 v72, v103
	v_mul_f32_e32 v64, 0xbfb8aa3b, v64
	v_ashrrev_i32_e32 v73, 31, v72
	v_lshlrev_b64 v[72:73], 5, v[72:73]
	v_lshl_add_u64 v[72:73], v[174:175], 0, v[72:73]
	v_lshl_add_u64 v[74:75], v[72:73], 0, v[176:177]
	global_load_dwordx4 v[92:95], v[74:75], off
	v_lshl_add_u64 v[72:73], v[72:73], 0, v[178:179]
	global_load_dwordx4 v[88:91], v[72:73], off
	v_mov_b32_e32 v72, v102
	v_mul_f32_e32 v65, 0xbfb8aa3b, v65
	v_ashrrev_i32_e32 v73, 31, v72
	v_lshlrev_b64 v[72:73], 5, v[72:73]
	v_lshl_add_u64 v[72:73], v[174:175], 0, v[72:73]
	v_lshl_add_u64 v[74:75], v[72:73], 0, v[176:177]
	global_load_dwordx4 v[84:87], v[74:75], off
	v_lshl_add_u64 v[72:73], v[72:73], 0, v[178:179]
	global_load_dwordx4 v[80:83], v[72:73], off
	v_mul_f32_e32 v66, 0xbfb8aa3b, v66
	v_exp_f32_e32 v68, v68
	v_exp_f32_e32 v64, v64
	v_exp_f32_e32 v65, v65
	v_exp_f32_e32 v66, v66
	v_add_u32_e32 v0, 0xb0, v198
	v_mov_b32_e32 v72, v0
	v_add_f32_e32 v68, 1.0, v68
	v_ashrrev_i32_e32 v73, 31, v72
	v_lshlrev_b64 v[72:73], 5, v[72:73]
	v_add_f32_e32 v64, 1.0, v64
	v_add_f32_e32 v65, 1.0, v65
	v_add_f32_e32 v66, 1.0, v66
	v_lshl_add_u64 v[72:73], v[174:175], 0, v[72:73]
	v_rcp_f32_e32 v68, v68
	v_rcp_f32_e32 v64, v64
	v_rcp_f32_e32 v65, v65
	v_rcp_f32_e32 v66, v66
	v_lshl_add_u64 v[74:75], v[72:73], 0, v[176:177]
	global_load_dwordx4 v[76:79], v[74:75], off
	v_mul_f32_e32 v67, 0xbfb8aa3b, v67
	v_exp_f32_e32 v67, v67
	v_mul_f32_e32 v60, 0xbfb8aa3b, v60
	v_mul_f32_e32 v56, 0xbfb8aa3b, v56
	v_mul_f32_e32 v57, 0xbfb8aa3b, v57
	v_mul_f32_e32 v58, 0xbfb8aa3b, v58
	v_exp_f32_e32 v60, v60
	v_exp_f32_e32 v56, v56
	v_exp_f32_e32 v57, v57
	v_exp_f32_e32 v58, v58
	v_add_f32_e32 v67, 1.0, v67
	v_lshl_add_u64 v[72:73], v[72:73], 0, v[178:179]
	v_rcp_f32_e32 v67, v67
	global_load_dwordx4 v[72:75], v[72:73], off
	v_add_f32_e32 v60, 1.0, v60
	v_add_f32_e32 v56, 1.0, v56
	v_add_f32_e32 v57, 1.0, v57
	v_add_f32_e32 v58, 1.0, v58
	v_mad_i64_i32 v[100:101], s[2:3], v100, s76, v[172:173]
	v_rcp_f32_e32 v60, v60
	v_rcp_f32_e32 v56, v56
	v_rcp_f32_e32 v57, v57
	v_rcp_f32_e32 v58, v58
	v_lshl_add_u64 v[100:101], v[100:101], 0, s[4:5]
	v_mul_f32_e32 v59, 0xbfb8aa3b, v59
	v_exp_f32_e32 v59, v59
	v_mul_f32_e32 v52, 0xbfb8aa3b, v52
	v_mul_f32_e32 v48, 0xbfb8aa3b, v48
	v_mul_f32_e32 v49, 0xbfb8aa3b, v49
	v_mul_f32_e32 v50, 0xbfb8aa3b, v50
	v_exp_f32_e32 v52, v52
	v_exp_f32_e32 v48, v48
	v_exp_f32_e32 v49, v49
	v_exp_f32_e32 v50, v50
	s_waitcnt vmcnt(0)
	v_lshlrev_b32_e32 v108, 16, v104
	v_lshlrev_b32_e32 v110, 16, v106
	v_and_b32_e32 v106, 0xffff0000, v106
	v_lshlrev_b32_e32 v111, 16, v107
	v_mul_f32_e32 v68, v68, v108
	v_mul_f32_e32 v108, v64, v110
	v_mul_f32_e32 v64, 0xbfb8aa3b, v69
	v_mul_f32_e32 v69, v65, v106
	v_mul_f32_e32 v65, 0xbfb8aa3b, v70
	v_mul_f32_e32 v70, v66, v111
	v_mul_f32_e32 v66, 0xbfb8aa3b, v71
	v_exp_f32_e32 v64, v64
	v_exp_f32_e32 v65, v65
	v_exp_f32_e32 v66, v66
	v_and_b32_e32 v104, 0xffff0000, v104
	v_add_f32_e32 v64, 1.0, v64
	v_add_f32_e32 v65, 1.0, v65
	v_add_f32_e32 v66, 1.0, v66
	v_rcp_f32_e32 v64, v64
	v_rcp_f32_e32 v65, v65
	v_rcp_f32_e32 v66, v66
	v_lshlrev_b32_e32 v109, 16, v105
	v_and_b32_e32 v105, 0xffff0000, v105
	v_and_b32_e32 v107, 0xffff0000, v107
	v_mul_f32_e32 v64, v64, v104
	v_mul_f32_e32 v65, v65, v109
	v_mul_f32_e32 v66, v66, v105
	v_mul_f32_e32 v67, v67, v107
	v_cvt_pk_bf16_f32 v64, v68, v64
	v_cvt_pk_bf16_f32 v65, v65, v66
	v_cvt_pk_bf16_f32 v66, v108, v69
	v_lshl_add_u64 v[68:69], v[100:101], 0, v[140:141]
	v_cvt_pk_bf16_f32 v67, v70, v67
	global_store_dwordx4 v[68:69], v[64:67], off
	v_lshlrev_b32_e32 v68, 16, v98
	v_and_b32_e32 v69, 0xffff0000, v98
	v_lshlrev_b32_e32 v64, 16, v96
	v_lshlrev_b32_e32 v70, 16, v99
	v_mul_f32_e32 v60, v60, v64
	v_mul_f32_e32 v64, v56, v68
	v_mul_f32_e32 v56, 0xbfb8aa3b, v61
	v_mul_f32_e32 v61, v57, v69
	v_mul_f32_e32 v57, 0xbfb8aa3b, v62
	v_mul_f32_e32 v62, v58, v70
	v_mul_f32_e32 v58, 0xbfb8aa3b, v63
	v_exp_f32_e32 v56, v56
	v_exp_f32_e32 v57, v57
	v_exp_f32_e32 v58, v58
	v_add_f32_e32 v59, 1.0, v59
	v_add_f32_e32 v56, 1.0, v56
	v_add_f32_e32 v57, 1.0, v57
	v_add_f32_e32 v58, 1.0, v58
	v_rcp_f32_e32 v56, v56
	v_rcp_f32_e32 v57, v57
	v_rcp_f32_e32 v58, v58
	v_rcp_f32_e32 v59, v59
	v_add_f32_e32 v52, 1.0, v52
	v_add_f32_e32 v48, 1.0, v48
	v_add_f32_e32 v49, 1.0, v49
	v_add_f32_e32 v50, 1.0, v50
	v_and_b32_e32 v65, 0xffff0000, v96
	v_lshlrev_b32_e32 v66, 16, v97
	v_and_b32_e32 v67, 0xffff0000, v97
	v_rcp_f32_e32 v52, v52
	v_rcp_f32_e32 v48, v48
	v_rcp_f32_e32 v49, v49
	v_rcp_f32_e32 v50, v50
	v_and_b32_e32 v71, 0xffff0000, v99
	v_mul_f32_e32 v56, v56, v65
	v_mul_f32_e32 v57, v57, v66
	v_mul_f32_e32 v58, v58, v67
	v_mul_f32_e32 v59, v59, v71
	v_cvt_pk_bf16_f32 v56, v60, v56
	v_cvt_pk_bf16_f32 v57, v57, v58
	v_cvt_pk_bf16_f32 v58, v64, v61
	v_lshl_add_u64 v[60:61], v[100:101], 0, v[128:129]
	v_cvt_pk_bf16_f32 v59, v62, v59
	global_store_dwordx4 v[60:61], v[56:59], off
	v_lshlrev_b32_e32 v62, 16, v94
	v_and_b32_e32 v63, 0xffff0000, v94
	v_lshlrev_b32_e32 v58, 16, v92
	v_lshlrev_b32_e32 v64, 16, v95
	v_mul_f32_e32 v52, v52, v58
	v_mul_f32_e32 v58, v48, v62
	v_mul_f32_e32 v48, 0xbfb8aa3b, v53
	v_mul_f32_e32 v53, v49, v63
	v_mul_f32_e32 v49, 0xbfb8aa3b, v54
	v_mul_f32_e32 v54, v50, v64
	v_mul_f32_e32 v50, 0xbfb8aa3b, v55
	v_exp_f32_e32 v48, v48
	v_exp_f32_e32 v49, v49
	v_exp_f32_e32 v50, v50
	v_mul_f32_e32 v51, 0xbfb8aa3b, v51
	v_exp_f32_e32 v51, v51
	v_mul_f32_e32 v44, 0xbfb8aa3b, v44
	v_mul_f32_e32 v40, 0xbfb8aa3b, v40
	v_mul_f32_e32 v41, 0xbfb8aa3b, v41
	v_mul_f32_e32 v42, 0xbfb8aa3b, v42
; __device__ __forceinline__ float sigmoidf_(float v) { return __builtin_amdgcn_rcpf(1.0f + __expf(-v)); }
; __device__ __forceinline__ u32x4 pack8(const f32x4 a, const f32x4 b) { u32x4 w; w.x = cvt_pk_bf16(a[0], a[1]); w.y = cvt_pk_bf16(a[2], a[3]); w.z = cvt_pk_bf16(b[0], b[1]); w.w = cvt_pk_bf16(b[2], b[3]); return w; }
; __device__ __forceinline__ void unpack8(const u32x4 w, f32x4& a, f32x4& b) { a[0] = bf_lo(w.x); a[1] = bf_hi(w.x); a[2] = bf_lo(w.y); a[3] = bf_hi(w.y); b[0] = bf_lo(w.z); b[1] = bf_hi(w.z); b[2] = bf_lo(w.w); b[3] = bf_hi(w.w); }
;     template <int KIND> __device__ __forceinline__ void run(f32x4 (&acc)[2][2][4][2], const Unit& u, int tid_in) const {
;     ...
;                 for (int m = 0; m < 4; ++m) { int row = rbase + ai * 128 + m * 16; asm volatile("" : "+v"(row));
; #pragma unroll
;                     for (int bj = 0; bj < 2; ++bj) { const int col = u.pn * 256 + bj * 128 + cl; f32x4 y0, y1; unpack8(yv[m][bj], y0, y1);
; #pragma unroll
;                         for (int j = 0; j < 4; ++j) { y0[j] *= sigmoidf_(acc[ai][bj][m][0][j]); y1[j] *= sigmoidf_(acc[ai][bj][m][1][j]); }
;                         *(u32x4*)(zb + (size_t)row * ZW + 1024 + col) = pack8(y0, y1); } }
	v_exp_f32_e32 v44, v44
	v_exp_f32_e32 v40, v40
	v_exp_f32_e32 v41, v41
	v_exp_f32_e32 v42, v42
	v_add_f32_e32 v48, 1.0, v48
	v_add_f32_e32 v49, 1.0, v49
	v_add_f32_e32 v50, 1.0, v50
	v_rcp_f32_e32 v48, v48
	v_rcp_f32_e32 v49, v49
	v_rcp_f32_e32 v50, v50
	v_add_f32_e32 v51, 1.0, v51
	v_rcp_f32_e32 v51, v51
	v_add_f32_e32 v44, 1.0, v44
	v_add_f32_e32 v40, 1.0, v40
	v_add_f32_e32 v41, 1.0, v41
	v_add_f32_e32 v42, 1.0, v42
	v_and_b32_e32 v59, 0xffff0000, v92
	v_mad_i64_i32 v[56:57], s[2:3], v103, s76, v[172:173]
	v_lshlrev_b32_e32 v60, 16, v93
	v_and_b32_e32 v61, 0xffff0000, v93
	v_rcp_f32_e32 v44, v44
	v_rcp_f32_e32 v40, v40
	v_rcp_f32_e32 v41, v41
	v_rcp_f32_e32 v42, v42
	v_lshl_add_u64 v[56:57], v[56:57], 0, s[4:5]
	v_and_b32_e32 v65, 0xffff0000, v95
	v_mul_f32_e32 v48, v48, v59
	v_mul_f32_e32 v49, v49, v60
	v_mul_f32_e32 v50, v50, v61
	v_mul_f32_e32 v51, v51, v65
	v_cvt_pk_bf16_f32 v48, v52, v48
	v_cvt_pk_bf16_f32 v49, v49, v50
	v_cvt_pk_bf16_f32 v50, v58, v53
	v_lshl_add_u64 v[52:53], v[56:57], 0, v[140:141]
	v_cvt_pk_bf16_f32 v51, v54, v51
	global_store_dwordx4 v[52:53], v[48:51], off
	v_lshlrev_b32_e32 v52, 16, v90
	v_and_b32_e32 v53, 0xffff0000, v90
	v_lshlrev_b32_e32 v48, 16, v88
	v_lshlrev_b32_e32 v54, 16, v91
	v_mul_f32_e32 v44, v44, v48
	v_mul_f32_e32 v48, v40, v52
	v_mul_f32_e32 v40, 0xbfb8aa3b, v45
	v_mul_f32_e32 v45, v41, v53
	v_mul_f32_e32 v41, 0xbfb8aa3b, v46
	v_mul_f32_e32 v46, v42, v54
	v_mul_f32_e32 v42, 0xbfb8aa3b, v47
	v_exp_f32_e32 v40, v40
	v_exp_f32_e32 v41, v41
	v_exp_f32_e32 v42, v42
	v_mul_f32_e32 v43, 0xbfb8aa3b, v43
	v_exp_f32_e32 v43, v43
	v_mul_f32_e32 v36, 0xbfb8aa3b, v36
	v_mul_f32_e32 v32, 0xbfb8aa3b, v32
	v_mul_f32_e32 v33, 0xbfb8aa3b, v33
	v_mul_f32_e32 v34, 0xbfb8aa3b, v34
	v_exp_f32_e32 v36, v36
	v_exp_f32_e32 v32, v32
	v_exp_f32_e32 v33, v33
	v_exp_f32_e32 v34, v34
	v_add_f32_e32 v40, 1.0, v40
	v_add_f32_e32 v41, 1.0, v41
	v_add_f32_e32 v42, 1.0, v42
	v_rcp_f32_e32 v40, v40
	v_rcp_f32_e32 v41, v41
	v_rcp_f32_e32 v42, v42
	v_add_f32_e32 v43, 1.0, v43
	v_rcp_f32_e32 v43, v43
	v_add_f32_e32 v36, 1.0, v36
	v_add_f32_e32 v32, 1.0, v32
	v_add_f32_e32 v33, 1.0, v33
	v_add_f32_e32 v34, 1.0, v34
	v_and_b32_e32 v49, 0xffff0000, v88
	v_lshlrev_b32_e32 v50, 16, v89
	v_and_b32_e32 v51, 0xffff0000, v89
	v_rcp_f32_e32 v36, v36
	v_rcp_f32_e32 v32, v32
	v_rcp_f32_e32 v33, v33
	v_rcp_f32_e32 v34, v34
	v_and_b32_e32 v55, 0xffff0000, v91
	v_mul_f32_e32 v40, v40, v49
	v_mul_f32_e32 v41, v41, v50
	v_mul_f32_e32 v42, v42, v51
	v_mul_f32_e32 v43, v43, v55
	v_cvt_pk_bf16_f32 v40, v44, v40
	v_cvt_pk_bf16_f32 v41, v41, v42
	v_cvt_pk_bf16_f32 v42, v48, v45
	v_lshl_add_u64 v[44:45], v[56:57], 0, v[128:129]
	v_cvt_pk_bf16_f32 v43, v46, v43
	global_store_dwordx4 v[44:45], v[40:43], off
	v_lshlrev_b32_e32 v46, 16, v86
	v_and_b32_e32 v47, 0xffff0000, v86
	v_lshlrev_b32_e32 v42, 16, v84
	v_lshlrev_b32_e32 v48, 16, v87
	v_mul_f32_e32 v36, v36, v42
	v_mul_f32_e32 v42, v32, v46
	v_mul_f32_e32 v32, 0xbfb8aa3b, v37
	v_mul_f32_e32 v37, v33, v47
	v_mul_f32_e32 v33, 0xbfb8aa3b, v38
	v_mul_f32_e32 v38, v34, v48
	v_mul_f32_e32 v34, 0xbfb8aa3b, v39
	v_exp_f32_e32 v32, v32
	v_exp_f32_e32 v33, v33
	v_exp_f32_e32 v34, v34
	v_mul_f32_e32 v35, 0xbfb8aa3b, v35
	v_exp_f32_e32 v35, v35
	v_mul_f32_e32 v28, 0xbfb8aa3b, v28
	v_mul_f32_e32 v24, 0xbfb8aa3b, v24
	v_mul_f32_e32 v25, 0xbfb8aa3b, v25
	v_mul_f32_e32 v26, 0xbfb8aa3b, v26
	v_exp_f32_e32 v28, v28
	v_exp_f32_e32 v24, v24
	v_exp_f32_e32 v25, v25
	v_exp_f32_e32 v26, v26
	v_add_f32_e32 v32, 1.0, v32
	v_add_f32_e32 v33, 1.0, v33
	v_add_f32_e32 v34, 1.0, v34
	v_rcp_f32_e32 v32, v32
	v_rcp_f32_e32 v33, v33
	v_rcp_f32_e32 v34, v34
	v_add_f32_e32 v35, 1.0, v35
	v_rcp_f32_e32 v35, v35
	v_add_f32_e32 v28, 1.0, v28
	v_add_f32_e32 v24, 1.0, v24
	v_add_f32_e32 v25, 1.0, v25
	v_add_f32_e32 v26, 1.0, v26
	v_and_b32_e32 v43, 0xffff0000, v84
	v_mad_i64_i32 v[40:41], s[2:3], v102, s76, v[172:173]
	v_lshlrev_b32_e32 v44, 16, v85
	v_and_b32_e32 v45, 0xffff0000, v85
	v_rcp_f32_e32 v28, v28
	v_rcp_f32_e32 v24, v24
	v_rcp_f32_e32 v25, v25
	v_rcp_f32_e32 v26, v26
	v_lshl_add_u64 v[40:41], v[40:41], 0, s[4:5]
	v_and_b32_e32 v49, 0xffff0000, v87
	v_mul_f32_e32 v32, v32, v43
	v_mul_f32_e32 v33, v33, v44
	v_mul_f32_e32 v34, v34, v45
	v_mul_f32_e32 v35, v35, v49
	v_cvt_pk_bf16_f32 v32, v36, v32
	v_cvt_pk_bf16_f32 v33, v33, v34
	v_cvt_pk_bf16_f32 v34, v42, v37
	v_lshl_add_u64 v[36:37], v[40:41], 0, v[140:141]
	v_cvt_pk_bf16_f32 v35, v38, v35
	global_store_dwordx4 v[36:37], v[32:35], off
	v_lshlrev_b32_e32 v36, 16, v82
	v_and_b32_e32 v37, 0xffff0000, v82
	v_lshlrev_b32_e32 v32, 16, v80
	v_lshlrev_b32_e32 v38, 16, v83
; __device__ __forceinline__ float sigmoidf_(float v) { return __builtin_amdgcn_rcpf(1.0f + __expf(-v)); }
; __device__ __forceinline__ u32x4 pack8(const f32x4 a, const f32x4 b) { u32x4 w; w.x = cvt_pk_bf16(a[0], a[1]); w.y = cvt_pk_bf16(a[2], a[3]); w.z = cvt_pk_bf16(b[0], b[1]); w.w = cvt_pk_bf16(b[2], b[3]); return w; }
; __device__ __forceinline__ void unpack8(const u32x4 w, f32x4& a, f32x4& b) { a[0] = bf_lo(w.x); a[1] = bf_hi(w.x); a[2] = bf_lo(w.y); a[3] = bf_hi(w.y); b[0] = bf_lo(w.z); b[1] = bf_hi(w.z); b[2] = bf_lo(w.w); b[3] = bf_hi(w.w); }
; #define MEMFENCE asm volatile("" ::: "memory")
;     template <int KIND> __device__ __forceinline__ void run(f32x4 (&acc)[2][2][4][2], const Unit& u, int tid_in) const {
;     ...
;                 for (int m = 0; m < 4; ++m) { int row = rbase + ai * 128 + m * 16; asm volatile("" : "+v"(row));
; #pragma unroll
;                     for (int bj = 0; bj < 2; ++bj) { const int col = u.pn * 256 + bj * 128 + cl; f32x4 y0, y1; unpack8(yv[m][bj], y0, y1);
; #pragma unroll
;                         for (int j = 0; j < 4; ++j) { y0[j] *= sigmoidf_(acc[ai][bj][m][0][j]); y1[j] *= sigmoidf_(acc[ai][bj][m][1][j]); }
;                         *(u32x4*)(zb + (size_t)row * ZW + 1024 + col) = pack8(y0, y1); } }
;                 MEMFENCE; }
;     ...
;         E.template run<cs.kind>(acc, cur, tid);
;         if (!has_next) break;
;         if (!(cs.kind == K_MG_B && cur.aux < 2))
; #pragma unroll
;         for (int a = 0; a < 2; ++a)
; #pragma unroll
;             for (int b = 0; b < 2; ++b)
; #pragma unroll
;                 for (int m = 0; m < 4; ++m)
; #pragma unroll
;                     for (int n = 0; n < 2; ++n) acc[a][b][m][n] = (f32x4){0.f, 0.f, 0.f, 0.f};
;         cur = nxt; cA = nA; cB = nB; ++ui;
;     }
	v_mul_f32_e32 v28, v28, v32
	v_mul_f32_e32 v32, v24, v36
	v_mul_f32_e32 v24, 0xbfb8aa3b, v29
	v_mul_f32_e32 v29, v25, v37
	v_mul_f32_e32 v25, 0xbfb8aa3b, v30
	v_mul_f32_e32 v30, v26, v38
	v_mul_f32_e32 v26, 0xbfb8aa3b, v31
	v_exp_f32_e32 v24, v24
	v_exp_f32_e32 v25, v25
	v_exp_f32_e32 v26, v26
	v_mul_f32_e32 v27, 0xbfb8aa3b, v27
	v_exp_f32_e32 v27, v27
	v_mul_f32_e32 v20, 0xbfb8aa3b, v20
	v_mul_f32_e32 v16, 0xbfb8aa3b, v16
	v_mul_f32_e32 v17, 0xbfb8aa3b, v17
	v_mul_f32_e32 v18, 0xbfb8aa3b, v18
	v_add_f32_e32 v24, 1.0, v24
	v_add_f32_e32 v25, 1.0, v25
	v_add_f32_e32 v26, 1.0, v26
	v_exp_f32_e32 v20, v20
	v_exp_f32_e32 v16, v16
	v_exp_f32_e32 v17, v17
	v_exp_f32_e32 v18, v18
	v_rcp_f32_e32 v24, v24
	v_rcp_f32_e32 v25, v25
	v_rcp_f32_e32 v26, v26
	v_add_f32_e32 v27, 1.0, v27
	v_rcp_f32_e32 v27, v27
	v_and_b32_e32 v33, 0xffff0000, v80
	v_lshlrev_b32_e32 v34, 16, v81
	v_and_b32_e32 v35, 0xffff0000, v81
	v_add_f32_e32 v20, 1.0, v20
	v_add_f32_e32 v16, 1.0, v16
	v_add_f32_e32 v17, 1.0, v17
	v_add_f32_e32 v18, 1.0, v18
	v_and_b32_e32 v39, 0xffff0000, v83
	v_mul_f32_e32 v24, v24, v33
	v_mul_f32_e32 v25, v25, v34
	v_mul_f32_e32 v26, v26, v35
	v_rcp_f32_e32 v20, v20
	v_rcp_f32_e32 v16, v16
	v_rcp_f32_e32 v17, v17
	v_rcp_f32_e32 v18, v18
	v_mul_f32_e32 v27, v27, v39
	v_cvt_pk_bf16_f32 v24, v28, v24
	v_cvt_pk_bf16_f32 v25, v25, v26
	v_cvt_pk_bf16_f32 v26, v32, v29
	v_lshl_add_u64 v[28:29], v[40:41], 0, v[128:129]
	v_cvt_pk_bf16_f32 v27, v30, v27
	global_store_dwordx4 v[28:29], v[24:27], off
	v_lshlrev_b32_e32 v29, 16, v78
	v_and_b32_e32 v30, 0xffff0000, v78
	v_mad_i64_i32 v[24:25], s[2:3], v0, s76, v[172:173]
	v_lshlrev_b32_e32 v0, 16, v76
	v_lshlrev_b32_e32 v31, 16, v79
	v_mul_f32_e32 v0, v20, v0
	v_mul_f32_e32 v20, v16, v29
	v_mul_f32_e32 v16, 0xbfb8aa3b, v21
	v_mul_f32_e32 v21, v17, v30
	v_mul_f32_e32 v17, 0xbfb8aa3b, v22
	v_mul_f32_e32 v22, v18, v31
	v_mul_f32_e32 v18, 0xbfb8aa3b, v23
	v_mul_f32_e32 v19, 0xbfb8aa3b, v19
	v_exp_f32_e32 v16, v16
	v_exp_f32_e32 v17, v17
	v_exp_f32_e32 v18, v18
	v_exp_f32_e32 v19, v19
	v_mul_f32_e32 v12, 0xbfb8aa3b, v12
	v_mul_f32_e32 v8, 0xbfb8aa3b, v8
	v_mul_f32_e32 v9, 0xbfb8aa3b, v9
	v_mul_f32_e32 v10, 0xbfb8aa3b, v10
	v_exp_f32_e32 v12, v12
	v_exp_f32_e32 v8, v8
	v_exp_f32_e32 v9, v9
	v_exp_f32_e32 v10, v10
	v_add_f32_e32 v16, 1.0, v16
	v_add_f32_e32 v17, 1.0, v17
	v_add_f32_e32 v18, 1.0, v18
	v_add_f32_e32 v19, 1.0, v19
	v_rcp_f32_e32 v16, v16
	v_rcp_f32_e32 v17, v17
	v_rcp_f32_e32 v18, v18
	v_rcp_f32_e32 v19, v19
	v_add_f32_e32 v12, 1.0, v12
	v_add_f32_e32 v8, 1.0, v8
	v_add_f32_e32 v9, 1.0, v9
	v_add_f32_e32 v10, 1.0, v10
	v_and_b32_e32 v26, 0xffff0000, v76
	v_lshlrev_b32_e32 v27, 16, v77
	v_and_b32_e32 v28, 0xffff0000, v77
	v_and_b32_e32 v32, 0xffff0000, v79
	v_rcp_f32_e32 v12, v12
	v_rcp_f32_e32 v8, v8
	v_rcp_f32_e32 v9, v9
	v_rcp_f32_e32 v10, v10
	v_lshl_add_u64 v[24:25], v[24:25], 0, s[4:5]
	v_mul_f32_e32 v16, v16, v26
	v_mul_f32_e32 v17, v17, v27
	v_mul_f32_e32 v18, v18, v28
	v_mul_f32_e32 v19, v19, v32
	v_cvt_pk_bf16_f32 v16, v0, v16
	v_cvt_pk_bf16_f32 v17, v17, v18
	v_cvt_pk_bf16_f32 v18, v20, v21
	v_cvt_pk_bf16_f32 v19, v22, v19
	v_lshl_add_u64 v[20:21], v[24:25], 0, v[140:141]
	global_store_dwordx4 v[20:21], v[16:19], off
	v_lshlrev_b32_e32 v0, 16, v72
	v_and_b32_e32 v20, 0xffff0000, v74
	v_lshlrev_b32_e32 v19, 16, v74
	v_lshlrev_b32_e32 v21, 16, v75
	v_mul_f32_e32 v0, v12, v0
	v_mul_f32_e32 v12, v8, v19
	v_mul_f32_e32 v8, 0xbfb8aa3b, v13
	v_mul_f32_e32 v13, v9, v20
	v_mul_f32_e32 v9, 0xbfb8aa3b, v14
	v_mul_f32_e32 v14, v10, v21
	v_mul_f32_e32 v10, 0xbfb8aa3b, v15
	v_exp_f32_e32 v8, v8
	v_exp_f32_e32 v9, v9
	v_exp_f32_e32 v10, v10
	v_mul_f32_e32 v11, 0xbfb8aa3b, v11
	v_exp_f32_e32 v11, v11
	v_add_f32_e32 v8, 1.0, v8
	v_add_f32_e32 v9, 1.0, v9
	v_add_f32_e32 v10, 1.0, v10
	v_rcp_f32_e32 v8, v8
	v_rcp_f32_e32 v9, v9
	v_rcp_f32_e32 v10, v10
	v_add_f32_e32 v11, 1.0, v11
	v_rcp_f32_e32 v11, v11
	v_and_b32_e32 v16, 0xffff0000, v72
	v_lshlrev_b32_e32 v17, 16, v73
	v_and_b32_e32 v18, 0xffff0000, v73
	v_and_b32_e32 v22, 0xffff0000, v75
	v_mul_f32_e32 v8, v8, v16
	v_mul_f32_e32 v9, v9, v17
	v_mul_f32_e32 v10, v10, v18
	v_mul_f32_e32 v11, v11, v22
	v_cvt_pk_bf16_f32 v8, v0, v8
	v_cvt_pk_bf16_f32 v9, v9, v10
	v_cvt_pk_bf16_f32 v10, v12, v13
	v_lshl_add_u64 v[12:13], v[24:25], 0, v[128:129]
	v_cvt_pk_bf16_f32 v11, v14, v11
	global_store_dwordx4 v[12:13], v[8:11], off
	s_and_b64 vcc, exec, s[10:11]
	s_mov_b32 s33, s34
	s_mov_b32 s35, s12
	s_mov_b64 s[18:19], s[16:17]
	s_mov_b64 s[2:3], s[14:15]
	s_cbranch_vccz .LBB0_799
	s_cmp_eq_u32 s101, 2
	s_cbranch_scc0 .Ldbj_GLU_pe
	s_barrier

; #define G_STAGE(bufoff, gbase, o0, h64) do { \
;         __builtin_amdgcn_global_load_lds((const unsigned*)((const char*)(gbase) + (o0)), (LAS unsigned*)(lds + (bufoff) + ldsw), 16, 0, 0); \
;         __builtin_amdgcn_global_load_lds((const unsigned*)((const char*)(gbase) + (h64) + (o0)), (LAS unsigned*)(lds + (bufoff) + ldsw + 8192), 16, 0, 0); } while (0)
; #define G_LDA(dst, b, h) do { _Pragma("unroll") for (int m = 0; m < 4; ++m) _Pragma("unroll") for (int k = 0; k < 2; ++k) dst[m][k] = *(const LAS bf16x8*)(lds + G_SA(b, h) + aoff + m * 2048 + k * 1024); } while (0)
; #define G_LDB(dst, b, h) do { _Pragma("unroll") for (int n = 0; n < 2; ++n) _Pragma("unroll") for (int k = 0; k < 2; ++k) dst[n][k] = *(const LAS bf16x8*)(lds + G_SB(b, h) + boff + n * 2048 + k * 1024); } while (0)
; #define G_WAIT_V(n) asm volatile("s_waitcnt vmcnt(" #n ")" ::: "memory")
; #define G_WAIT_L(n) asm volatile("s_waitcnt lgkmcnt(" #n ")" ::: "memory")
; #define G_BAR __builtin_amdgcn_s_barrier()
; #define G_SCHED __builtin_amdgcn_sched_barrier(0)
;     ...
;         for (int t = 0; t < nt; t += 2) {
;             const bool last = (t == nt - 2);
;             const char* a1 = cA + (size_t)(t + 1) * ckA;
;             const char* a2 = last ? nA : cA + (size_t)(t + 2) * ckA; const char* b2 = last ? nB : cB + (size_t)(t + 2) * kB;
;             const char* a3 = a2 + ckA; const char* b3 = b2 + kB;
;             G_LDB(B0, 0, 0); G_SCHED; G_LDA(At, 0, 0); G_STAGE(G_SA(1, 1), a1 + chA, cA0, qA);
;             G_WAIT_L(8); G_BAR; G_WAIT_L(0); G_MMA(0, 0, At, B0); G_BAR; G_SCHED;
;             G_LDB(B1, 0, 1); G_STAGE(G_SB(0, 0), b2, cB0, qB);
;             G_BAR; G_WAIT_L(0); G_MMA(0, 1, At, B1); G_BAR;
;             G_LDA(At, 0, 1); G_STAGE(G_SA(0, 0), a2, cA0, qA);
;             G_BAR; G_WAIT_L(0); G_MMA(1, 0, At, B0); G_BAR; G_SCHED;
;             G_STAGE(G_SB(0, 1), b2 + chB, cB0, qB);
;             G_WAIT_V(6); G_BAR; G_MMA(1, 1, At, B1); G_BAR;
;             G_LDB(B0, 1, 0); G_SCHED; G_LDA(At, 1, 0); G_STAGE(G_SA(0, 1), a2 + chA, cA0, qA);
;             G_WAIT_L(8); G_BAR; G_WAIT_L(0); G_MMA(0, 0, At, B0); G_BAR; G_SCHED;
.LBB0_872:
	s_add_u32 s4, s2, 0xfff50080
	s_addc_u32 s5, s3, -1
	s_add_i32 s40, 0, 0x10000
	ds_read_b128 v[144:147], v239 offset:0
	ds_read_b128 v[148:151], v239 offset:1024
	ds_read_b128 v[136:139], v239 offset:2048
	ds_read_b128 v[140:143], v239 offset:3072
	s_cmp_eq_u32 s39, 4
	s_cselect_b32 s13, s9, s5
	s_cselect_b32 s12, s8, s4
	s_cselect_b32 s15, s11, s38
	s_cselect_b32 s14, s10, s37
	s_add_i32 m0, s22, 0xc000
	ds_read_b128 v[160:163], v236
	ds_read_b128 v[164:167], v236 offset:1024
	ds_read_b128 v[176:179], v236 offset:2048
	ds_read_b128 v[180:183], v236 offset:3072
	ds_read_b128 v[196:199], v236 offset:4096
	ds_read_b128 v[200:203], v236 offset:5120
	ds_read_b128 v[204:207], v236 offset:6144
	ds_read_b128 v[208:211], v236 offset:7168
	global_load_lds_dwordx4 v152, s[2:3]
	s_add_i32 m0, s22, 0xe000
	s_nop 0
	s_add_u32 vcc_lo, s2, s86
	s_addc_u32 vcc_hi, s3, s87
	global_load_lds_dwordx4 v152, vcc
	s_waitcnt lgkmcnt(8)
	s_barrier
	s_waitcnt lgkmcnt(0)
	v_mfma_f32_16x16x128_f8f6f4 v[128:131], v[144:151], v[160:167], v[128:131]
	v_mfma_f32_16x16x128_f8f6f4 v[132:135], v[136:143], v[160:167], v[132:135]
	v_mfma_f32_16x16x128_f8f6f4 v[112:115], v[144:151], v[176:183], v[112:115]
	v_mfma_f32_16x16x128_f8f6f4 v[116:119], v[136:143], v[176:183], v[116:119]
	v_mfma_f32_16x16x128_f8f6f4 v[96:99], v[144:151], v[196:203], v[96:99]
	v_mfma_f32_16x16x128_f8f6f4 v[100:103], v[136:143], v[196:203], v[100:103]
	v_mfma_f32_16x16x128_f8f6f4 v[80:83], v[144:151], v[204:211], v[80:83]
	v_mfma_f32_16x16x128_f8f6f4 v[84:87], v[136:143], v[204:211], v[84:87]
	s_barrier
	s_add_i32 s4, 0, 0x14000
	s_add_i32 s5, s40, s17
	ds_read_b128 v[212:215], v239 offset:16384
	ds_read_b128 v[216:219], v239 offset:17408
	ds_read_b128 v[220:223], v239 offset:18432
	ds_read_b128 v[224:227], v239 offset:19456
	s_mov_b32 m0, s5
	global_load_lds_dwordx4 v0, s[14:15]
	s_add_i32 m0, s5, 0x2000
	s_nop 0
	s_add_u32 vcc_lo, s14, s50
	s_addc_u32 vcc_hi, s15, s51
	global_load_lds_dwordx4 v0, vcc
	s_barrier
	s_waitcnt lgkmcnt(0)
	v_mfma_f32_16x16x128_f8f6f4 v[124:127], v[212:219], v[160:167], v[124:127]
	v_mfma_f32_16x16x128_f8f6f4 v[120:123], v[220:227], v[160:167], v[120:123]
	v_mfma_f32_16x16x128_f8f6f4 v[108:111], v[212:219], v[176:183], v[108:111]
	v_mfma_f32_16x16x128_f8f6f4 v[104:107], v[220:227], v[176:183], v[104:107]
	v_mfma_f32_16x16x128_f8f6f4 v[92:95], v[212:219], v[196:203], v[92:95]
	v_mfma_f32_16x16x128_f8f6f4 v[88:91], v[220:227], v[196:203], v[88:91]
	v_mfma_f32_16x16x128_f8f6f4 v[76:79], v[212:219], v[204:211], v[76:79]
	v_mfma_f32_16x16x128_f8f6f4 v[72:75], v[220:227], v[204:211], v[72:75]
	s_barrier
	s_mov_b32 m0, s22
	ds_read_b128 v[160:163], v236 offset:16384
	ds_read_b128 v[164:167], v236 offset:17408
	ds_read_b128 v[176:179], v236 offset:18432
	ds_read_b128 v[180:183], v236 offset:19456
	ds_read_b128 v[196:199], v236 offset:20480
	ds_read_b128 v[200:203], v236 offset:21504
	ds_read_b128 v[204:207], v236 offset:22528
	ds_read_b128 v[208:211], v236 offset:23552
	global_load_lds_dwordx4 v2, s[12:13]
	s_mov_b32 m0, s23
	s_nop 0
	s_add_u32 vcc_lo, s12, s86
	s_addc_u32 vcc_hi, s13, s87
	global_load_lds_dwordx4 v2, vcc
	s_barrier
	s_waitcnt lgkmcnt(0)
	v_mfma_f32_16x16x128_f8f6f4 v[64:67], v[144:151], v[160:167], v[64:67]
	v_mfma_f32_16x16x128_f8f6f4 v[68:71], v[136:143], v[160:167], v[68:71]
	v_mfma_f32_16x16x128_f8f6f4 v[48:51], v[144:151], v[176:183], v[48:51]
	v_mfma_f32_16x16x128_f8f6f4 v[52:55], v[136:143], v[176:183], v[52:55]
	v_mfma_f32_16x16x128_f8f6f4 v[32:35], v[144:151], v[196:203], v[32:35]
	v_mfma_f32_16x16x128_f8f6f4 v[36:39], v[136:143], v[196:203], v[36:39]
	v_mfma_f32_16x16x128_f8f6f4 v[20:23], v[144:151], v[204:211], v[20:23]
	v_mfma_f32_16x16x128_f8f6f4 v[16:19], v[136:143], v[204:211], v[16:19]
	s_barrier
	s_add_i32 s4, s4, s17
	s_mov_b32 m0, s4
	s_nop 0
	s_add_u32 vcc_lo, s14, s0
	s_addc_u32 vcc_hi, s15, s1
	global_load_lds_dwordx4 v0, vcc
	s_add_i32 m0, s4, 0x2000
	s_nop 0
	s_add_u32 vcc_lo, s14, s52
	s_addc_u32 vcc_hi, s15, s53
	global_load_lds_dwordx4 v0, vcc
	s_waitcnt vmcnt(6)
	s_barrier
	v_mfma_f32_16x16x128_f8f6f4 v[60:63], v[212:219], v[160:167], v[60:63]
	v_mfma_f32_16x16x128_f8f6f4 v[56:59], v[220:227], v[160:167], v[56:59]
	v_mfma_f32_16x16x128_f8f6f4 v[44:47], v[212:219], v[176:183], v[44:47]
	v_mfma_f32_16x16x128_f8f6f4 v[40:43], v[220:227], v[176:183], v[40:43]
	v_mfma_f32_16x16x128_f8f6f4 v[28:31], v[212:219], v[196:203], v[28:31]
	v_mfma_f32_16x16x128_f8f6f4 v[24:27], v[220:227], v[196:203], v[24:27]
	v_mfma_f32_16x16x128_f8f6f4 v[12:15], v[212:219], v[204:211], v[12:15]
	v_mfma_f32_16x16x128_f8f6f4 v[8:11], v[220:227], v[204:211], v[8:11]
	s_barrier
; #define G_STAGE(bufoff, gbase, o0, h64) do { \
;         __builtin_amdgcn_global_load_lds((const unsigned*)((const char*)(gbase) + (o0)), (LAS unsigned*)(lds + (bufoff) + ldsw), 16, 0, 0); \
;         __builtin_amdgcn_global_load_lds((const unsigned*)((const char*)(gbase) + (h64) + (o0)), (LAS unsigned*)(lds + (bufoff) + ldsw + 8192), 16, 0, 0); } while (0)
; #define G_LDA(dst, b, h) do { _Pragma("unroll") for (int m = 0; m < 4; ++m) _Pragma("unroll") for (int k = 0; k < 2; ++k) dst[m][k] = *(const LAS bf16x8*)(lds + G_SA(b, h) + aoff + m * 2048 + k * 1024); } while (0)
; #define G_LDB(dst, b, h) do { _Pragma("unroll") for (int n = 0; n < 2; ++n) _Pragma("unroll") for (int k = 0; k < 2; ++k) dst[n][k] = *(const LAS bf16x8*)(lds + G_SB(b, h) + boff + n * 2048 + k * 1024); } while (0)
; #define G_WAIT_V(n) asm volatile("s_waitcnt vmcnt(" #n ")" ::: "memory")
; #define G_WAIT_L(n) asm volatile("s_waitcnt lgkmcnt(" #n ")" ::: "memory")
; #define G_BAR __builtin_amdgcn_s_barrier()
; #define G_SCHED __builtin_amdgcn_sched_barrier(0)
;     ...
;             G_LDB(B0, 1, 0); G_SCHED; G_LDA(At, 1, 0); G_STAGE(G_SA(0, 1), a2 + chA, cA0, qA);
;             G_WAIT_L(8); G_BAR; G_WAIT_L(0); G_MMA(0, 0, At, B0); G_BAR; G_SCHED;
;             G_LDB(B1, 1, 1); G_STAGE(G_SB(1, 0), b3, cB0, qB);
;             G_BAR; G_WAIT_L(0); G_MMA(0, 1, At, B1); G_BAR;
;             G_LDA(At, 1, 1); G_STAGE(G_SA(1, 0), a3, cA0, qA);
;             G_BAR; G_WAIT_L(0); G_MMA(1, 0, At, B0); G_BAR; G_SCHED;
;             G_STAGE(G_SB(1, 1), b3 + chB, cB0, qB);
;             G_WAIT_V(6); G_BAR; G_MMA(1, 1, At, B1); G_BAR;
;         }
	s_add_i32 s4, 0, 0x18000
	ds_read_b128 v[144:147], v239 offset:32768
	ds_read_b128 v[148:151], v239 offset:33792
	ds_read_b128 v[136:139], v239 offset:34816
	ds_read_b128 v[140:143], v239 offset:35840
	s_mov_b32 m0, s24
	ds_read_b128 v[160:163], v236 offset:32768
	ds_read_b128 v[164:167], v236 offset:33792
	ds_read_b128 v[176:179], v236 offset:34816
	ds_read_b128 v[180:183], v236 offset:35840
	ds_read_b128 v[196:199], v236 offset:36864
	ds_read_b128 v[200:203], v236 offset:37888
	ds_read_b128 v[204:207], v236 offset:38912
	ds_read_b128 v[208:211], v236 offset:39936
	s_add_u32 vcc_lo, s12, s88
	s_addc_u32 vcc_hi, s13, s89
	global_load_lds_dwordx4 v2, vcc
	s_mov_b32 m0, s25
	s_nop 0
	s_add_u32 vcc_lo, s12, s64
	s_addc_u32 vcc_hi, s13, s65
	global_load_lds_dwordx4 v2, vcc
	s_waitcnt lgkmcnt(8)
	s_barrier
	s_waitcnt lgkmcnt(0)
	v_mfma_f32_16x16x128_f8f6f4 v[128:131], v[144:151], v[160:167], v[128:131]
	v_mfma_f32_16x16x128_f8f6f4 v[132:135], v[136:143], v[160:167], v[132:135]
	v_mfma_f32_16x16x128_f8f6f4 v[112:115], v[144:151], v[176:183], v[112:115]
	v_mfma_f32_16x16x128_f8f6f4 v[116:119], v[136:143], v[176:183], v[116:119]
	v_mfma_f32_16x16x128_f8f6f4 v[96:99], v[144:151], v[196:203], v[96:99]
	v_mfma_f32_16x16x128_f8f6f4 v[100:103], v[136:143], v[196:203], v[100:103]
	v_mfma_f32_16x16x128_f8f6f4 v[80:83], v[144:151], v[204:211], v[80:83]
	v_mfma_f32_16x16x128_f8f6f4 v[84:87], v[136:143], v[204:211], v[84:87]
	s_barrier
	s_add_i32 s5, 0, 0x1c000
	s_add_i32 s4, s4, s17
	s_mov_b32 m0, s4
	ds_read_b128 v[212:215], v239 offset:49152
	ds_read_b128 v[216:219], v239 offset:50176
	ds_read_b128 v[220:223], v239 offset:51200
	ds_read_b128 v[224:227], v239 offset:52224
	s_add_u32 vcc_lo, s14, s46
	s_addc_u32 vcc_hi, s15, s47
	global_load_lds_dwordx4 v0, vcc
	s_add_i32 m0, s4, 0x2000
	s_nop 0
	s_add_u32 vcc_lo, s14, s54
	s_addc_u32 vcc_hi, s15, s55
	global_load_lds_dwordx4 v0, vcc
	s_barrier
	s_waitcnt lgkmcnt(0)
	v_mfma_f32_16x16x128_f8f6f4 v[124:127], v[212:219], v[160:167], v[124:127]
	v_mfma_f32_16x16x128_f8f6f4 v[120:123], v[220:227], v[160:167], v[120:123]
	v_mfma_f32_16x16x128_f8f6f4 v[108:111], v[212:219], v[176:183], v[108:111]
	v_mfma_f32_16x16x128_f8f6f4 v[104:107], v[220:227], v[176:183], v[104:107]
	v_mfma_f32_16x16x128_f8f6f4 v[92:95], v[212:219], v[196:203], v[92:95]
	v_mfma_f32_16x16x128_f8f6f4 v[88:91], v[220:227], v[196:203], v[88:91]
	v_mfma_f32_16x16x128_f8f6f4 v[76:79], v[212:219], v[204:211], v[76:79]
	v_mfma_f32_16x16x128_f8f6f4 v[72:75], v[220:227], v[204:211], v[72:75]
	s_barrier
	s_mov_b32 m0, s26
	ds_read_b128 v[160:163], v236 offset:49152
	ds_read_b128 v[164:167], v236 offset:50176
	ds_read_b128 v[176:179], v236 offset:51200
	ds_read_b128 v[180:183], v236 offset:52224
	ds_read_b128 v[196:199], v236 offset:53248
	ds_read_b128 v[200:203], v236 offset:54272
	ds_read_b128 v[204:207], v236 offset:55296
	ds_read_b128 v[208:211], v236 offset:56320
	s_add_u32 vcc_lo, s12, s46
	s_addc_u32 vcc_hi, s13, s47
	global_load_lds_dwordx4 v2, vcc
	s_mov_b32 m0, s27
	s_nop 0
	s_add_u32 vcc_lo, s12, s66
	s_addc_u32 vcc_hi, s13, s67
	global_load_lds_dwordx4 v2, vcc
	s_barrier
	s_waitcnt lgkmcnt(0)
	v_mfma_f32_16x16x128_f8f6f4 v[64:67], v[144:151], v[160:167], v[64:67]
	v_mfma_f32_16x16x128_f8f6f4 v[68:71], v[136:143], v[160:167], v[68:71]
	v_mfma_f32_16x16x128_f8f6f4 v[48:51], v[144:151], v[176:183], v[48:51]
	v_mfma_f32_16x16x128_f8f6f4 v[52:55], v[136:143], v[176:183], v[52:55]
	v_mfma_f32_16x16x128_f8f6f4 v[32:35], v[144:151], v[196:203], v[32:35]
	v_mfma_f32_16x16x128_f8f6f4 v[36:39], v[136:143], v[196:203], v[36:39]
	v_mfma_f32_16x16x128_f8f6f4 v[20:23], v[144:151], v[204:211], v[20:23]
	v_mfma_f32_16x16x128_f8f6f4 v[16:19], v[136:143], v[204:211], v[16:19]
	s_barrier
	s_add_i32 s4, s5, s17
	s_mov_b32 m0, s4
	s_nop 0
	s_add_u32 vcc_lo, s14, s42
	s_addc_u32 vcc_hi, s15, s43
	global_load_lds_dwordx4 v0, vcc
	s_add_i32 m0, s4, 0x2000
	s_nop 0
	s_add_u32 vcc_lo, s14, s58
	s_addc_u32 vcc_hi, s15, s59
	global_load_lds_dwordx4 v0, vcc
	s_add_i32 s39, s39, 2
	s_add_u32 s2, s2, 0x100
	s_addc_u32 s3, s3, 0
	s_add_u32 s37, s37, 0x100
	s_addc_u32 s38, s38, 0
	s_cmp_gt_u32 s39, 5
	s_waitcnt vmcnt(6)
	s_barrier
	v_mfma_f32_16x16x128_f8f6f4 v[60:63], v[212:219], v[160:167], v[60:63]
	v_mfma_f32_16x16x128_f8f6f4 v[56:59], v[220:227], v[160:167], v[56:59]
	v_mfma_f32_16x16x128_f8f6f4 v[44:47], v[212:219], v[176:183], v[44:47]
	v_mfma_f32_16x16x128_f8f6f4 v[40:43], v[220:227], v[176:183], v[40:43]
	v_mfma_f32_16x16x128_f8f6f4 v[28:31], v[212:219], v[196:203], v[28:31]
	v_mfma_f32_16x16x128_f8f6f4 v[24:27], v[220:227], v[196:203], v[24:27]
	v_mfma_f32_16x16x128_f8f6f4 v[12:15], v[212:219], v[204:211], v[12:15]
	v_mfma_f32_16x16x128_f8f6f4 v[8:11], v[220:227], v[204:211], v[8:11]
	s_cbranch_scc1 .Ldb_MG0_xl

; __device__ __forceinline__ float sigmoidf_(float v) { return __builtin_amdgcn_rcpf(1.0f + __expf(-v)); }
; #define MEMFENCE asm volatile("" ::: "memory")
;     __device__ __forceinline__ void get_rs(const Unit& u, int wr, int fr, float (&rs)[8]) const {
; #pragma unroll
;         for (int r8 = 0; r8 < 8; ++r8) rs[r8] = rstab[u.ord * 256 + (r8 >> 2) * 128 + wr * 64 + (r8 & 3) * 16 + fr];
;     }
;     template <int KIND> __device__ __forceinline__ void run(f32x4 (&acc)[2][2][4][2], const Unit& u, int tid_in) const {
;     ...
;         if constexpr (KIND == K_MG_G) { float rs[8]; get_rs(u, wr, fr, rs);
;             u32x4* gst = (u32x4*)((unsigned char*)x + 32 * MiB) + ((size_t)(blockIdx.x * 2 + (u.ord & 1)) * 3 + u.aux) * 4096;
; #pragma unroll
;             for (int ai = 0; ai < 2; ++ai)
; #pragma unroll
;                 for (int m = 0; m < 4; ++m) { const float r = rs[ai * 4 + m] * (1.0f / GATE_WSCALE); u32x4 w;
; #pragma unroll
;                     for (int bj = 0; bj < 2; ++bj) { f32x4 a = acc[ai][bj][m][0] * r, b = acc[ai][bj][m][1] * r;
; #pragma unroll
;                         for (int j = 0; j < 4; ++j) { a[j] = sigmoidf_(a[j]); b[j] = sigmoidf_(b[j]); }
;                         if (bj == 0) { w.x = pack4_u8c(a); w.y = pack4_u8c(b); } else { w.z = pack4_u8c(a); w.w = pack4_u8c(b); } }
;                     gst[(ai * 4 + m) * 512 + tid] = w; MEMFENCE; }
.Ldb_MG0_young:
	s_setprio 3
	s_mov_b32 s101, 2
	s_branch .Ldb_MG0_exit
.Ldb_MG0_exit:
	v_mov_b32_e32 v142, v158
	s_lshl_b32 s3, s33, 10
	v_readfirstlane_b32 s2, v142
	s_add_i32 s3, s3, 0
	s_and_b32 s2, s2, 0xffffff00
	v_and_b32_e32 v136, 15, v142
	s_add_i32 s3, s3, s2
	v_lshl_add_u32 v136, v136, 2, s3
	v_add_u32_e32 v136, 0x20010, v136
	ds_read2_b32 v[144:145], v136 offset1:16
	ds_read2_b32 v[140:141], v136 offset0:32 offset1:48
	ds_read2_b32 v[138:139], v136 offset0:128 offset1:144
	ds_read2_b32 v[136:137], v136 offset0:160 offset1:176
	s_and_b32 s2, s33, 1
	s_waitcnt lgkmcnt(0)
	v_mul_f32_e32 v144, 0x3c800000, v144
	v_pk_mul_f32 v[128:129], v[128:129], v[144:145] op_sel_hi:[1,0]
	v_pk_mul_f32 v[130:131], v[130:131], v[144:145] op_sel_hi:[1,0]
	v_mul_f32_e32 v128, 0xbfb8aa3b, v128
	v_mul_f32_e32 v129, 0xbfb8aa3b, v129
	v_mul_f32_e32 v131, 0xbfb8aa3b, v131
	v_exp_f32_e32 v128, v128
	v_exp_f32_e32 v129, v129
	v_mul_f32_e32 v130, 0xbfb8aa3b, v130
	v_exp_f32_e32 v131, v131
	v_exp_f32_e32 v130, v130
	v_add_f32_e32 v128, 1.0, v128
	v_add_f32_e32 v129, 1.0, v129
	s_or_b32 s2, s2, s60
	v_pk_mul_f32 v[132:133], v[132:133], v[144:145] op_sel_hi:[1,0]
	v_add_f32_e32 v131, 1.0, v131
	v_rcp_f32_e32 v128, v128
	v_rcp_f32_e32 v129, v129
	v_add_f32_e32 v130, 1.0, v130
	s_mul_hi_u32 s3, s2, 3
	s_mul_i32 s2, s2, 3
	s_ashr_i32 s4, s36, 31
	v_pk_mul_f32 v[134:135], v[134:135], v[144:145] op_sel_hi:[1,0]
	v_mul_f32_e32 v132, 0xbfb8aa3b, v132
	v_mul_f32_e32 v133, 0xbfb8aa3b, v133
	v_rcp_f32_e32 v131, v131
	v_rcp_f32_e32 v130, v130
	s_add_u32 s2, s2, s36
	v_mul_f32_e32 v135, 0xbfb8aa3b, v135
	v_exp_f32_e32 v132, v132
	v_exp_f32_e32 v133, v133
	v_mul_f32_e32 v134, 0xbfb8aa3b, v134
	s_addc_u32 s3, s3, s4
	v_exp_f32_e32 v135, v135
	v_exp_f32_e32 v134, v134
	s_mov_b32 s4, 0x437f0000
	v_fma_f32 v128, v128, s4, 0.5
	v_fma_f32 v129, v129, s4, 0.5
	v_max_f32_e32 v128, 1.0, v128
	v_max_f32_e32 v129, 1.0, v129
	v_fma_f32 v130, v130, s4, 0.5
	v_fma_f32 v131, v131, s4, 0.5
	v_add_f32_e32 v132, 1.0, v132
	v_add_f32_e32 v133, 1.0, v133
	v_cvt_u32_f32_e32 v128, v128
	v_cvt_u32_f32_e32 v129, v129
	v_max_f32_e32 v130, 1.0, v130
	v_max_f32_e32 v131, 1.0, v131
	v_add_f32_e32 v135, 1.0, v135
	v_rcp_f32_e32 v132, v132
	v_rcp_f32_e32 v133, v133
	v_cvt_u32_f32_sdwa v130, v130 dst_sel:WORD_1 dst_unused:UNUSED_PAD src0_sel:DWORD
	v_cvt_u32_f32_sdwa v131, v131 dst_sel:BYTE_3 dst_unused:UNUSED_PAD src0_sel:DWORD
	v_add_f32_e32 v134, 1.0, v134
	v_rcp_f32_e32 v135, v135
	v_rcp_f32_e32 v134, v134
	v_lshl_or_b32 v128, v129, 8, v128
	v_or3_b32 v128, v128, v130, v131
	v_fma_f32 v129, v132, s4, 0.5
	v_fma_f32 v130, v133, s4, 0.5
	v_pk_mul_f32 v[124:125], v[124:125], v[144:145] op_sel_hi:[1,0]
	v_max_f32_e32 v129, 1.0, v129
	v_max_f32_e32 v130, 1.0, v130
	v_fma_f32 v131, v134, s4, 0.5
	v_fma_f32 v132, v135, s4, 0.5
	v_mul_f32_e32 v125, 0xbfb8aa3b, v125
	v_cvt_u32_f32_e32 v129, v129
	v_cvt_u32_f32_e32 v130, v130
	v_max_f32_e32 v131, 1.0, v131
	v_max_f32_e32 v132, 1.0, v132
	v_exp_f32_e32 v125, v125
	v_cvt_u32_f32_sdwa v131, v131 dst_sel:WORD_1 dst_unused:UNUSED_PAD src0_sel:DWORD
	v_cvt_u32_f32_sdwa v132, v132 dst_sel:BYTE_3 dst_unused:UNUSED_PAD src0_sel:DWORD
	v_pk_mul_f32 v[120:121], v[120:121], v[144:145] op_sel_hi:[1,0]
	v_mul_f32_e32 v124, 0xbfb8aa3b, v124
	v_mul_f32_e32 v121, 0xbfb8aa3b, v121
	v_lshl_or_b32 v129, v130, 8, v129
	v_exp_f32_e32 v130, v124
	v_add_f32_e32 v124, 1.0, v125
	v_exp_f32_e32 v121, v121
	v_or3_b32 v129, v129, v131, v132
	v_rcp_f32_e32 v131, v124
	v_mul_f32_e32 v120, 0xbfb8aa3b, v120
	v_pk_mul_f32 v[124:125], v[126:127], v[144:145] op_sel_hi:[1,0]
	v_add_f32_e32 v126, 1.0, v130
	v_exp_f32_e32 v130, v120
	v_add_f32_e32 v120, 1.0, v121
	v_fma_f32 v127, v131, s4, 0.5
	v_rcp_f32_e32 v131, v120
	v_pk_mul_f32 v[120:121], v[122:123], v[144:145] op_sel_hi:[1,0]
	v_add_f32_e32 v122, 1.0, v130
	v_mul_f32_e32 v120, 0xbfb8aa3b, v120
	v_mul_f32_e32 v121, 0xbfb8aa3b, v121
	v_exp_f32_e32 v120, v120
	v_exp_f32_e32 v121, v121
	v_rcp_f32_e32 v122, v122
	v_fma_f32 v123, v131, s4, 0.5
	v_add_f32_e32 v120, 1.0, v120
	v_add_f32_e32 v121, 1.0, v121
	v_rcp_f32_e32 v120, v120
	v_rcp_f32_e32 v121, v121
	v_fma_f32 v122, v122, s4, 0.5
	v_max_f32_e32 v123, 1.0, v123
	v_max_f32_e32 v122, 1.0, v122
	v_fma_f32 v120, v120, s4, 0.5
	v_fma_f32 v121, v121, s4, 0.5
	v_cvt_u32_f32_e32 v123, v123
	v_cvt_u32_f32_e32 v122, v122
	v_max_f32_e32 v120, 1.0, v120
	v_max_f32_e32 v121, 1.0, v121
	v_cvt_u32_f32_sdwa v120, v120 dst_sel:WORD_1 dst_unused:UNUSED_PAD src0_sel:DWORD
	v_cvt_u32_f32_sdwa v121, v121 dst_sel:BYTE_3 dst_unused:UNUSED_PAD src0_sel:DWORD
	v_lshl_or_b32 v122, v123, 8, v122
	v_mul_f32_e32 v124, 0xbfb8aa3b, v124
	v_mul_f32_e32 v125, 0xbfb8aa3b, v125
	v_or3_b32 v131, v122, v120, v121
	v_mul_f32_e32 v122, 0x3c800000, v145
	v_pk_mul_f32 v[112:113], v[112:113], v[122:123] op_sel_hi:[1,0]
	v_pk_mul_f32 v[114:115], v[114:115], v[122:123] op_sel_hi:[1,0]
	v_mul_f32_e32 v112, 0xbfb8aa3b, v112
	v_mul_f32_e32 v113, 0xbfb8aa3b, v113
	v_mul_f32_e32 v115, 0xbfb8aa3b, v115
	v_exp_f32_e32 v112, v112
	v_exp_f32_e32 v113, v113
	v_mul_f32_e32 v114, 0xbfb8aa3b, v114
	v_exp_f32_e32 v115, v115
	v_exp_f32_e32 v114, v114
	v_add_f32_e32 v112, 1.0, v112
	v_add_f32_e32 v113, 1.0, v113
	v_pk_mul_f32 v[116:117], v[116:117], v[122:123] op_sel_hi:[1,0]
	v_add_f32_e32 v115, 1.0, v115
	v_rcp_f32_e32 v112, v112
	v_rcp_f32_e32 v113, v113
	v_add_f32_e32 v114, 1.0, v114
	v_pk_mul_f32 v[118:119], v[118:119], v[122:123] op_sel_hi:[1,0]
	v_mul_f32_e32 v116, 0xbfb8aa3b, v116
	v_mul_f32_e32 v117, 0xbfb8aa3b, v117
	v_rcp_f32_e32 v115, v115
	v_rcp_f32_e32 v114, v114
	v_mul_f32_e32 v119, 0xbfb8aa3b, v119
	v_exp_f32_e32 v116, v116
; __device__ __forceinline__ float sigmoidf_(float v) { return __builtin_amdgcn_rcpf(1.0f + __expf(-v)); }
;     template <int KIND> __device__ __forceinline__ void run(f32x4 (&acc)[2][2][4][2], const Unit& u, int tid_in) const {
;     ...
;             for (int ai = 0; ai < 2; ++ai)
; #pragma unroll
;                 for (int m = 0; m < 4; ++m) { const float r = rs[ai * 4 + m] * (1.0f / GATE_WSCALE); u32x4 w;
; #pragma unroll
;                     for (int bj = 0; bj < 2; ++bj) { f32x4 a = acc[ai][bj][m][0] * r, b = acc[ai][bj][m][1] * r;
; #pragma unroll
;                         for (int j = 0; j < 4; ++j) { a[j] = sigmoidf_(a[j]); b[j] = sigmoidf_(b[j]); }
;                         if (bj == 0) { w.x = pack4_u8c(a); w.y = pack4_u8c(b); } else { w.z = pack4_u8c(a); w.w = pack4_u8c(b); } }
	v_exp_f32_e32 v117, v117
	v_mul_f32_e32 v118, 0xbfb8aa3b, v118
	v_exp_f32_e32 v119, v119
	v_exp_f32_e32 v118, v118
	v_fma_f32 v112, v112, s4, 0.5
	v_fma_f32 v113, v113, s4, 0.5
	v_max_f32_e32 v112, 1.0, v112
	v_max_f32_e32 v113, 1.0, v113
	v_fma_f32 v114, v114, s4, 0.5
	v_fma_f32 v115, v115, s4, 0.5
	v_add_f32_e32 v116, 1.0, v116
	v_add_f32_e32 v117, 1.0, v117
	v_cvt_u32_f32_e32 v112, v112
	v_cvt_u32_f32_e32 v113, v113
	v_max_f32_e32 v114, 1.0, v114
	v_max_f32_e32 v115, 1.0, v115
	v_add_f32_e32 v119, 1.0, v119
	v_rcp_f32_e32 v116, v116
	v_rcp_f32_e32 v117, v117
	v_cvt_u32_f32_sdwa v114, v114 dst_sel:WORD_1 dst_unused:UNUSED_PAD src0_sel:DWORD
	v_cvt_u32_f32_sdwa v115, v115 dst_sel:BYTE_3 dst_unused:UNUSED_PAD src0_sel:DWORD
	v_add_f32_e32 v118, 1.0, v118
	v_rcp_f32_e32 v119, v119
	v_rcp_f32_e32 v118, v118
	v_lshl_or_b32 v112, v113, 8, v112
	v_or3_b32 v112, v112, v114, v115
	v_fma_f32 v113, v116, s4, 0.5
	v_fma_f32 v114, v117, s4, 0.5
	v_pk_mul_f32 v[108:109], v[108:109], v[122:123] op_sel_hi:[1,0]
	v_max_f32_e32 v113, 1.0, v113
	v_max_f32_e32 v114, 1.0, v114
	v_fma_f32 v115, v118, s4, 0.5
	v_fma_f32 v116, v119, s4, 0.5
	v_mul_f32_e32 v109, 0xbfb8aa3b, v109
	v_cvt_u32_f32_e32 v113, v113
	v_cvt_u32_f32_e32 v114, v114
	v_max_f32_e32 v115, 1.0, v115
	v_max_f32_e32 v116, 1.0, v116
	v_exp_f32_e32 v109, v109
	v_cvt_u32_f32_sdwa v115, v115 dst_sel:WORD_1 dst_unused:UNUSED_PAD src0_sel:DWORD
	v_cvt_u32_f32_sdwa v116, v116 dst_sel:BYTE_3 dst_unused:UNUSED_PAD src0_sel:DWORD
	v_pk_mul_f32 v[104:105], v[104:105], v[122:123] op_sel_hi:[1,0]
	v_mul_f32_e32 v108, 0xbfb8aa3b, v108
	v_mul_f32_e32 v105, 0xbfb8aa3b, v105
	v_lshl_or_b32 v113, v114, 8, v113
	v_exp_f32_e32 v114, v108
	v_add_f32_e32 v108, 1.0, v109
	v_exp_f32_e32 v105, v105
	v_or3_b32 v113, v113, v115, v116
	v_rcp_f32_e32 v115, v108
	v_mul_f32_e32 v104, 0xbfb8aa3b, v104
	v_pk_mul_f32 v[108:109], v[110:111], v[122:123] op_sel_hi:[1,0]
	v_add_f32_e32 v110, 1.0, v114
	v_exp_f32_e32 v114, v104
	v_add_f32_e32 v104, 1.0, v105
	v_fma_f32 v111, v115, s4, 0.5
	v_rcp_f32_e32 v115, v104
	v_pk_mul_f32 v[104:105], v[106:107], v[122:123] op_sel_hi:[1,0]
	v_add_f32_e32 v106, 1.0, v114
	v_mul_f32_e32 v104, 0xbfb8aa3b, v104
	v_mul_f32_e32 v105, 0xbfb8aa3b, v105
	v_exp_f32_e32 v104, v104
	v_exp_f32_e32 v105, v105
	v_rcp_f32_e32 v106, v106
	v_fma_f32 v107, v115, s4, 0.5
	v_add_f32_e32 v104, 1.0, v104
	v_add_f32_e32 v105, 1.0, v105
	v_rcp_f32_e32 v104, v104
	v_rcp_f32_e32 v105, v105
	v_fma_f32 v106, v106, s4, 0.5
	v_max_f32_e32 v107, 1.0, v107
	v_max_f32_e32 v106, 1.0, v106
	v_fma_f32 v104, v104, s4, 0.5
	v_fma_f32 v105, v105, s4, 0.5
	v_cvt_u32_f32_e32 v107, v107
	v_cvt_u32_f32_e32 v106, v106
	v_max_f32_e32 v104, 1.0, v104
	v_max_f32_e32 v105, 1.0, v105
	v_cvt_u32_f32_sdwa v104, v104 dst_sel:WORD_1 dst_unused:UNUSED_PAD src0_sel:DWORD
	v_cvt_u32_f32_sdwa v105, v105 dst_sel:BYTE_3 dst_unused:UNUSED_PAD src0_sel:DWORD
	v_lshl_or_b32 v106, v107, 8, v106
	v_exp_f32_e32 v124, v124
	v_exp_f32_e32 v125, v125
	v_or3_b32 v115, v106, v104, v105
	v_mul_f32_e32 v106, 0x3c800000, v140
	v_pk_mul_f32 v[96:97], v[96:97], v[106:107] op_sel_hi:[1,0]
	v_pk_mul_f32 v[98:99], v[98:99], v[106:107] op_sel_hi:[1,0]
	v_mul_f32_e32 v96, 0xbfb8aa3b, v96
	v_mul_f32_e32 v97, 0xbfb8aa3b, v97
	v_mul_f32_e32 v99, 0xbfb8aa3b, v99
	v_exp_f32_e32 v96, v96
	v_exp_f32_e32 v97, v97
	v_mul_f32_e32 v98, 0xbfb8aa3b, v98
	v_exp_f32_e32 v99, v99
	v_exp_f32_e32 v98, v98
	v_add_f32_e32 v96, 1.0, v96
	v_add_f32_e32 v97, 1.0, v97
	v_pk_mul_f32 v[100:101], v[100:101], v[106:107] op_sel_hi:[1,0]
	v_add_f32_e32 v99, 1.0, v99
	v_rcp_f32_e32 v96, v96
	v_rcp_f32_e32 v97, v97
	v_add_f32_e32 v98, 1.0, v98
	v_pk_mul_f32 v[102:103], v[102:103], v[106:107] op_sel_hi:[1,0]
	v_mul_f32_e32 v100, 0xbfb8aa3b, v100
	v_mul_f32_e32 v101, 0xbfb8aa3b, v101
	v_rcp_f32_e32 v99, v99
	v_rcp_f32_e32 v98, v98
	v_mul_f32_e32 v103, 0xbfb8aa3b, v103
	v_exp_f32_e32 v100, v100
	v_exp_f32_e32 v101, v101
	v_mul_f32_e32 v102, 0xbfb8aa3b, v102
	v_exp_f32_e32 v103, v103
	v_exp_f32_e32 v102, v102
	v_fma_f32 v96, v96, s4, 0.5
	v_fma_f32 v97, v97, s4, 0.5
	v_max_f32_e32 v96, 1.0, v96
	v_max_f32_e32 v97, 1.0, v97
	v_fma_f32 v98, v98, s4, 0.5
	v_fma_f32 v99, v99, s4, 0.5
	v_add_f32_e32 v100, 1.0, v100
	v_add_f32_e32 v101, 1.0, v101
	v_cvt_u32_f32_e32 v96, v96
	v_cvt_u32_f32_e32 v97, v97
	v_max_f32_e32 v98, 1.0, v98
	v_max_f32_e32 v99, 1.0, v99
	v_add_f32_e32 v103, 1.0, v103
	v_rcp_f32_e32 v100, v100
	v_rcp_f32_e32 v101, v101
	v_cvt_u32_f32_sdwa v98, v98 dst_sel:WORD_1 dst_unused:UNUSED_PAD src0_sel:DWORD
	v_cvt_u32_f32_sdwa v99, v99 dst_sel:BYTE_3 dst_unused:UNUSED_PAD src0_sel:DWORD
	v_add_f32_e32 v102, 1.0, v102
	v_rcp_f32_e32 v103, v103
	v_rcp_f32_e32 v102, v102
	v_lshl_or_b32 v96, v97, 8, v96
	v_or3_b32 v96, v96, v98, v99
	v_fma_f32 v97, v100, s4, 0.5
	v_fma_f32 v98, v101, s4, 0.5
	v_pk_mul_f32 v[92:93], v[92:93], v[106:107] op_sel_hi:[1,0]
	v_max_f32_e32 v97, 1.0, v97
	v_max_f32_e32 v98, 1.0, v98
	v_fma_f32 v99, v102, s4, 0.5
	v_fma_f32 v100, v103, s4, 0.5
	v_mul_f32_e32 v93, 0xbfb8aa3b, v93
	v_cvt_u32_f32_e32 v97, v97
	v_cvt_u32_f32_e32 v98, v98
	v_max_f32_e32 v99, 1.0, v99
	v_max_f32_e32 v100, 1.0, v100
	v_exp_f32_e32 v93, v93
	v_cvt_u32_f32_sdwa v99, v99 dst_sel:WORD_1 dst_unused:UNUSED_PAD src0_sel:DWORD
	v_cvt_u32_f32_sdwa v100, v100 dst_sel:BYTE_3 dst_unused:UNUSED_PAD src0_sel:DWORD
	v_pk_mul_f32 v[88:89], v[88:89], v[106:107] op_sel_hi:[1,0]
	v_mul_f32_e32 v92, 0xbfb8aa3b, v92
	v_mul_f32_e32 v89, 0xbfb8aa3b, v89
	v_lshl_or_b32 v97, v98, 8, v97
	v_exp_f32_e32 v98, v92
	v_add_f32_e32 v92, 1.0, v93
	v_exp_f32_e32 v89, v89
	v_or3_b32 v97, v97, v99, v100
	v_rcp_f32_e32 v99, v92
; __device__ __forceinline__ float sigmoidf_(float v) { return __builtin_amdgcn_rcpf(1.0f + __expf(-v)); }
;     template <int KIND> __device__ __forceinline__ void run(f32x4 (&acc)[2][2][4][2], const Unit& u, int tid_in) const {
;     ...
;             for (int ai = 0; ai < 2; ++ai)
; #pragma unroll
;                 for (int m = 0; m < 4; ++m) { const float r = rs[ai * 4 + m] * (1.0f / GATE_WSCALE); u32x4 w;
; #pragma unroll
;                     for (int bj = 0; bj < 2; ++bj) { f32x4 a = acc[ai][bj][m][0] * r, b = acc[ai][bj][m][1] * r;
; #pragma unroll
;                         for (int j = 0; j < 4; ++j) { a[j] = sigmoidf_(a[j]); b[j] = sigmoidf_(b[j]); }
;                         if (bj == 0) { w.x = pack4_u8c(a); w.y = pack4_u8c(b); } else { w.z = pack4_u8c(a); w.w = pack4_u8c(b); } }
	v_mul_f32_e32 v88, 0xbfb8aa3b, v88
	v_pk_mul_f32 v[92:93], v[94:95], v[106:107] op_sel_hi:[1,0]
	v_add_f32_e32 v94, 1.0, v98
	v_exp_f32_e32 v98, v88
	v_add_f32_e32 v88, 1.0, v89
	v_fma_f32 v95, v99, s4, 0.5
	v_rcp_f32_e32 v99, v88
	v_pk_mul_f32 v[88:89], v[90:91], v[106:107] op_sel_hi:[1,0]
	v_add_f32_e32 v90, 1.0, v98
	v_mul_f32_e32 v88, 0xbfb8aa3b, v88
	v_mul_f32_e32 v89, 0xbfb8aa3b, v89
	v_exp_f32_e32 v88, v88
	v_exp_f32_e32 v89, v89
	v_rcp_f32_e32 v90, v90
	v_fma_f32 v91, v99, s4, 0.5
	v_add_f32_e32 v88, 1.0, v88
	v_add_f32_e32 v89, 1.0, v89
	v_rcp_f32_e32 v88, v88
	v_rcp_f32_e32 v89, v89
	v_fma_f32 v90, v90, s4, 0.5
	v_max_f32_e32 v91, 1.0, v91
	v_max_f32_e32 v90, 1.0, v90
	v_fma_f32 v88, v88, s4, 0.5
	v_fma_f32 v89, v89, s4, 0.5
	v_cvt_u32_f32_e32 v91, v91
	v_cvt_u32_f32_e32 v90, v90
	v_max_f32_e32 v88, 1.0, v88
	v_max_f32_e32 v89, 1.0, v89
	v_cvt_u32_f32_sdwa v88, v88 dst_sel:WORD_1 dst_unused:UNUSED_PAD src0_sel:DWORD
	v_cvt_u32_f32_sdwa v89, v89 dst_sel:BYTE_3 dst_unused:UNUSED_PAD src0_sel:DWORD
	v_lshl_or_b32 v90, v91, 8, v90
	v_mul_f32_e32 v108, 0xbfb8aa3b, v108
	v_mul_f32_e32 v109, 0xbfb8aa3b, v109
	v_or3_b32 v99, v90, v88, v89
	v_mul_f32_e32 v90, 0x3c800000, v141
	v_pk_mul_f32 v[80:81], v[80:81], v[90:91] op_sel_hi:[1,0]
	v_pk_mul_f32 v[82:83], v[82:83], v[90:91] op_sel_hi:[1,0]
	v_mul_f32_e32 v80, 0xbfb8aa3b, v80
	v_mul_f32_e32 v81, 0xbfb8aa3b, v81
	v_mul_f32_e32 v83, 0xbfb8aa3b, v83
	v_exp_f32_e32 v80, v80
	v_exp_f32_e32 v81, v81
	v_mul_f32_e32 v82, 0xbfb8aa3b, v82
	v_exp_f32_e32 v83, v83
	v_exp_f32_e32 v82, v82
	v_add_f32_e32 v80, 1.0, v80
	v_add_f32_e32 v81, 1.0, v81
	v_pk_mul_f32 v[84:85], v[84:85], v[90:91] op_sel_hi:[1,0]
	v_add_f32_e32 v83, 1.0, v83
	v_rcp_f32_e32 v80, v80
	v_rcp_f32_e32 v81, v81
	v_add_f32_e32 v82, 1.0, v82
	v_pk_mul_f32 v[86:87], v[86:87], v[90:91] op_sel_hi:[1,0]
	v_mul_f32_e32 v84, 0xbfb8aa3b, v84
	v_mul_f32_e32 v85, 0xbfb8aa3b, v85
	v_rcp_f32_e32 v83, v83
	v_rcp_f32_e32 v82, v82
	v_mul_f32_e32 v87, 0xbfb8aa3b, v87
	v_exp_f32_e32 v84, v84
	v_exp_f32_e32 v85, v85
	v_mul_f32_e32 v86, 0xbfb8aa3b, v86
	v_exp_f32_e32 v87, v87
	v_exp_f32_e32 v86, v86
	v_fma_f32 v80, v80, s4, 0.5
	v_fma_f32 v81, v81, s4, 0.5
	v_max_f32_e32 v80, 1.0, v80
	v_max_f32_e32 v81, 1.0, v81
	v_fma_f32 v82, v82, s4, 0.5
	v_fma_f32 v83, v83, s4, 0.5
	v_add_f32_e32 v84, 1.0, v84
	v_add_f32_e32 v85, 1.0, v85
	v_cvt_u32_f32_e32 v80, v80
	v_cvt_u32_f32_e32 v81, v81
	v_max_f32_e32 v82, 1.0, v82
	v_max_f32_e32 v83, 1.0, v83
	v_add_f32_e32 v87, 1.0, v87
	v_rcp_f32_e32 v84, v84
	v_rcp_f32_e32 v85, v85
	v_cvt_u32_f32_sdwa v82, v82 dst_sel:WORD_1 dst_unused:UNUSED_PAD src0_sel:DWORD
	v_cvt_u32_f32_sdwa v83, v83 dst_sel:BYTE_3 dst_unused:UNUSED_PAD src0_sel:DWORD
	v_add_f32_e32 v86, 1.0, v86
	v_rcp_f32_e32 v87, v87
	v_rcp_f32_e32 v86, v86
	v_lshl_or_b32 v80, v81, 8, v80
	v_or3_b32 v80, v80, v82, v83
	v_fma_f32 v81, v84, s4, 0.5
	v_fma_f32 v82, v85, s4, 0.5
	v_pk_mul_f32 v[76:77], v[76:77], v[90:91] op_sel_hi:[1,0]
	v_max_f32_e32 v81, 1.0, v81
	v_max_f32_e32 v82, 1.0, v82
	v_fma_f32 v83, v86, s4, 0.5
	v_fma_f32 v84, v87, s4, 0.5
	v_mul_f32_e32 v77, 0xbfb8aa3b, v77
	v_cvt_u32_f32_e32 v81, v81
	v_cvt_u32_f32_e32 v82, v82
	v_max_f32_e32 v83, 1.0, v83
	v_max_f32_e32 v84, 1.0, v84
	v_exp_f32_e32 v77, v77
	v_cvt_u32_f32_sdwa v83, v83 dst_sel:WORD_1 dst_unused:UNUSED_PAD src0_sel:DWORD
	v_cvt_u32_f32_sdwa v84, v84 dst_sel:BYTE_3 dst_unused:UNUSED_PAD src0_sel:DWORD
	v_pk_mul_f32 v[72:73], v[72:73], v[90:91] op_sel_hi:[1,0]
	v_mul_f32_e32 v76, 0xbfb8aa3b, v76
	v_mul_f32_e32 v73, 0xbfb8aa3b, v73
	v_lshl_or_b32 v81, v82, 8, v81
	v_exp_f32_e32 v82, v76
	v_add_f32_e32 v76, 1.0, v77
	v_exp_f32_e32 v73, v73
	v_or3_b32 v81, v81, v83, v84
	v_rcp_f32_e32 v83, v76
	v_mul_f32_e32 v72, 0xbfb8aa3b, v72
	v_pk_mul_f32 v[76:77], v[78:79], v[90:91] op_sel_hi:[1,0]
	v_add_f32_e32 v78, 1.0, v82
	v_exp_f32_e32 v82, v72
	v_add_f32_e32 v72, 1.0, v73
	v_fma_f32 v79, v83, s4, 0.5
	v_rcp_f32_e32 v83, v72
	v_pk_mul_f32 v[72:73], v[74:75], v[90:91] op_sel_hi:[1,0]
	v_add_f32_e32 v74, 1.0, v82
	v_mul_f32_e32 v72, 0xbfb8aa3b, v72
	v_mul_f32_e32 v73, 0xbfb8aa3b, v73
	v_exp_f32_e32 v72, v72
	v_exp_f32_e32 v73, v73
	v_rcp_f32_e32 v74, v74
	v_fma_f32 v75, v83, s4, 0.5
	v_add_f32_e32 v72, 1.0, v72
	v_add_f32_e32 v73, 1.0, v73
	v_rcp_f32_e32 v72, v72
	v_rcp_f32_e32 v73, v73
	v_fma_f32 v74, v74, s4, 0.5
	v_max_f32_e32 v75, 1.0, v75
	v_max_f32_e32 v74, 1.0, v74
	v_fma_f32 v72, v72, s4, 0.5
	v_fma_f32 v73, v73, s4, 0.5
	v_cvt_u32_f32_e32 v75, v75
	v_cvt_u32_f32_e32 v74, v74
	v_max_f32_e32 v72, 1.0, v72
	v_max_f32_e32 v73, 1.0, v73
	v_cvt_u32_f32_sdwa v72, v72 dst_sel:WORD_1 dst_unused:UNUSED_PAD src0_sel:DWORD
	v_cvt_u32_f32_sdwa v73, v73 dst_sel:BYTE_3 dst_unused:UNUSED_PAD src0_sel:DWORD
	v_lshl_or_b32 v74, v75, 8, v74
	v_exp_f32_e32 v108, v108
	v_exp_f32_e32 v109, v109
	v_or3_b32 v83, v74, v72, v73
	v_mul_f32_e32 v74, 0x3c800000, v138
	v_pk_mul_f32 v[64:65], v[64:65], v[74:75] op_sel_hi:[1,0]
	v_pk_mul_f32 v[66:67], v[66:67], v[74:75] op_sel_hi:[1,0]
	v_mul_f32_e32 v64, 0xbfb8aa3b, v64
	v_mul_f32_e32 v65, 0xbfb8aa3b, v65
	v_mul_f32_e32 v67, 0xbfb8aa3b, v67
	v_exp_f32_e32 v64, v64
	v_exp_f32_e32 v65, v65
	v_mul_f32_e32 v66, 0xbfb8aa3b, v66
	v_exp_f32_e32 v67, v67
	v_exp_f32_e32 v66, v66
	v_add_f32_e32 v64, 1.0, v64
	v_add_f32_e32 v65, 1.0, v65
	v_pk_mul_f32 v[68:69], v[68:69], v[74:75] op_sel_hi:[1,0]
	v_add_f32_e32 v67, 1.0, v67
	v_rcp_f32_e32 v64, v64
	v_rcp_f32_e32 v65, v65
	v_add_f32_e32 v66, 1.0, v66
	v_pk_mul_f32 v[70:71], v[70:71], v[74:75] op_sel_hi:[1,0]
	v_mul_f32_e32 v68, 0xbfb8aa3b, v68
	v_mul_f32_e32 v69, 0xbfb8aa3b, v69
	v_rcp_f32_e32 v67, v67
	v_rcp_f32_e32 v66, v66
; __device__ __forceinline__ float sigmoidf_(float v) { return __builtin_amdgcn_rcpf(1.0f + __expf(-v)); }
;     template <int KIND> __device__ __forceinline__ void run(f32x4 (&acc)[2][2][4][2], const Unit& u, int tid_in) const {
;     ...
;             for (int ai = 0; ai < 2; ++ai)
; #pragma unroll
;                 for (int m = 0; m < 4; ++m) { const float r = rs[ai * 4 + m] * (1.0f / GATE_WSCALE); u32x4 w;
; #pragma unroll
;                     for (int bj = 0; bj < 2; ++bj) { f32x4 a = acc[ai][bj][m][0] * r, b = acc[ai][bj][m][1] * r;
; #pragma unroll
;                         for (int j = 0; j < 4; ++j) { a[j] = sigmoidf_(a[j]); b[j] = sigmoidf_(b[j]); }
;                         if (bj == 0) { w.x = pack4_u8c(a); w.y = pack4_u8c(b); } else { w.z = pack4_u8c(a); w.w = pack4_u8c(b); } }
	v_mul_f32_e32 v71, 0xbfb8aa3b, v71
	v_exp_f32_e32 v68, v68
	v_exp_f32_e32 v69, v69
	v_mul_f32_e32 v70, 0xbfb8aa3b, v70
	v_exp_f32_e32 v71, v71
	v_exp_f32_e32 v70, v70
	v_fma_f32 v64, v64, s4, 0.5
	v_fma_f32 v65, v65, s4, 0.5
	v_max_f32_e32 v64, 1.0, v64
	v_max_f32_e32 v65, 1.0, v65
	v_fma_f32 v66, v66, s4, 0.5
	v_fma_f32 v67, v67, s4, 0.5
	v_add_f32_e32 v68, 1.0, v68
	v_add_f32_e32 v69, 1.0, v69
	v_cvt_u32_f32_e32 v64, v64
	v_cvt_u32_f32_e32 v65, v65
	v_max_f32_e32 v66, 1.0, v66
	v_max_f32_e32 v67, 1.0, v67
	v_add_f32_e32 v71, 1.0, v71
	v_rcp_f32_e32 v68, v68
	v_rcp_f32_e32 v69, v69
	v_cvt_u32_f32_sdwa v66, v66 dst_sel:WORD_1 dst_unused:UNUSED_PAD src0_sel:DWORD
	v_cvt_u32_f32_sdwa v67, v67 dst_sel:BYTE_3 dst_unused:UNUSED_PAD src0_sel:DWORD
	v_add_f32_e32 v70, 1.0, v70
	v_rcp_f32_e32 v71, v71
	v_rcp_f32_e32 v70, v70
	v_lshl_or_b32 v64, v65, 8, v64
	v_or3_b32 v64, v64, v66, v67
	v_fma_f32 v65, v68, s4, 0.5
	v_fma_f32 v66, v69, s4, 0.5
	v_pk_mul_f32 v[60:61], v[60:61], v[74:75] op_sel_hi:[1,0]
	v_max_f32_e32 v65, 1.0, v65
	v_max_f32_e32 v66, 1.0, v66
	v_fma_f32 v67, v70, s4, 0.5
	v_fma_f32 v68, v71, s4, 0.5
	v_mul_f32_e32 v61, 0xbfb8aa3b, v61
	v_cvt_u32_f32_e32 v65, v65
	v_cvt_u32_f32_e32 v66, v66
	v_max_f32_e32 v67, 1.0, v67
	v_max_f32_e32 v68, 1.0, v68
	v_exp_f32_e32 v61, v61
	v_cvt_u32_f32_sdwa v67, v67 dst_sel:WORD_1 dst_unused:UNUSED_PAD src0_sel:DWORD
	v_cvt_u32_f32_sdwa v68, v68 dst_sel:BYTE_3 dst_unused:UNUSED_PAD src0_sel:DWORD
	v_pk_mul_f32 v[56:57], v[56:57], v[74:75] op_sel_hi:[1,0]
	v_mul_f32_e32 v60, 0xbfb8aa3b, v60
	v_mul_f32_e32 v57, 0xbfb8aa3b, v57
	v_lshl_or_b32 v65, v66, 8, v65
	v_exp_f32_e32 v66, v60
	v_add_f32_e32 v60, 1.0, v61
	v_exp_f32_e32 v57, v57
	v_or3_b32 v65, v65, v67, v68
	v_rcp_f32_e32 v67, v60
	v_mul_f32_e32 v56, 0xbfb8aa3b, v56
	v_pk_mul_f32 v[60:61], v[62:63], v[74:75] op_sel_hi:[1,0]
	v_add_f32_e32 v62, 1.0, v66
	v_exp_f32_e32 v66, v56
	v_add_f32_e32 v56, 1.0, v57
	v_fma_f32 v63, v67, s4, 0.5
	v_rcp_f32_e32 v67, v56
	v_pk_mul_f32 v[56:57], v[58:59], v[74:75] op_sel_hi:[1,0]
	v_add_f32_e32 v58, 1.0, v66
	v_mul_f32_e32 v56, 0xbfb8aa3b, v56
	v_mul_f32_e32 v57, 0xbfb8aa3b, v57
	v_exp_f32_e32 v56, v56
	v_exp_f32_e32 v57, v57
	v_rcp_f32_e32 v58, v58
	v_fma_f32 v59, v67, s4, 0.5
	v_add_f32_e32 v56, 1.0, v56
	v_add_f32_e32 v57, 1.0, v57
	v_rcp_f32_e32 v56, v56
	v_rcp_f32_e32 v57, v57
	v_fma_f32 v58, v58, s4, 0.5
	v_max_f32_e32 v59, 1.0, v59
	v_max_f32_e32 v58, 1.0, v58
	v_fma_f32 v56, v56, s4, 0.5
	v_fma_f32 v57, v57, s4, 0.5
	v_cvt_u32_f32_e32 v59, v59
	v_cvt_u32_f32_e32 v58, v58
	v_max_f32_e32 v56, 1.0, v56
	v_max_f32_e32 v57, 1.0, v57
	v_cvt_u32_f32_sdwa v56, v56 dst_sel:WORD_1 dst_unused:UNUSED_PAD src0_sel:DWORD
	v_cvt_u32_f32_sdwa v57, v57 dst_sel:BYTE_3 dst_unused:UNUSED_PAD src0_sel:DWORD
	v_lshl_or_b32 v58, v59, 8, v58
	v_mul_f32_e32 v92, 0xbfb8aa3b, v92
	v_mul_f32_e32 v93, 0xbfb8aa3b, v93
	v_or3_b32 v67, v58, v56, v57
	v_mul_f32_e32 v58, 0x3c800000, v139
	v_pk_mul_f32 v[48:49], v[48:49], v[58:59] op_sel_hi:[1,0]
	v_pk_mul_f32 v[50:51], v[50:51], v[58:59] op_sel_hi:[1,0]
	v_mul_f32_e32 v48, 0xbfb8aa3b, v48
	v_mul_f32_e32 v49, 0xbfb8aa3b, v49
	v_mul_f32_e32 v51, 0xbfb8aa3b, v51
	v_exp_f32_e32 v48, v48
	v_exp_f32_e32 v49, v49
	v_mul_f32_e32 v50, 0xbfb8aa3b, v50
	v_exp_f32_e32 v51, v51
	v_exp_f32_e32 v50, v50
	v_add_f32_e32 v48, 1.0, v48
	v_add_f32_e32 v49, 1.0, v49
	v_pk_mul_f32 v[52:53], v[52:53], v[58:59] op_sel_hi:[1,0]
	v_add_f32_e32 v51, 1.0, v51
	v_rcp_f32_e32 v48, v48
	v_rcp_f32_e32 v49, v49
	v_add_f32_e32 v50, 1.0, v50
	v_pk_mul_f32 v[54:55], v[54:55], v[58:59] op_sel_hi:[1,0]
	v_mul_f32_e32 v52, 0xbfb8aa3b, v52
	v_mul_f32_e32 v53, 0xbfb8aa3b, v53
	v_rcp_f32_e32 v51, v51
	v_rcp_f32_e32 v50, v50
	v_mul_f32_e32 v55, 0xbfb8aa3b, v55
	v_exp_f32_e32 v52, v52
	v_exp_f32_e32 v53, v53
	v_mul_f32_e32 v54, 0xbfb8aa3b, v54
	v_exp_f32_e32 v55, v55
	v_exp_f32_e32 v54, v54
	v_fma_f32 v48, v48, s4, 0.5
	v_fma_f32 v49, v49, s4, 0.5
	v_max_f32_e32 v48, 1.0, v48
	v_max_f32_e32 v49, 1.0, v49
	v_fma_f32 v50, v50, s4, 0.5
	v_fma_f32 v51, v51, s4, 0.5
	v_add_f32_e32 v52, 1.0, v52
	v_add_f32_e32 v53, 1.0, v53
	v_cvt_u32_f32_e32 v48, v48
	v_cvt_u32_f32_e32 v49, v49
	v_max_f32_e32 v50, 1.0, v50
	v_max_f32_e32 v51, 1.0, v51
	v_add_f32_e32 v55, 1.0, v55
	v_rcp_f32_e32 v52, v52
	v_rcp_f32_e32 v53, v53
	v_cvt_u32_f32_sdwa v50, v50 dst_sel:WORD_1 dst_unused:UNUSED_PAD src0_sel:DWORD
	v_cvt_u32_f32_sdwa v51, v51 dst_sel:BYTE_3 dst_unused:UNUSED_PAD src0_sel:DWORD
	v_add_f32_e32 v54, 1.0, v54
	v_rcp_f32_e32 v55, v55
	v_rcp_f32_e32 v54, v54
	v_lshl_or_b32 v48, v49, 8, v48
	v_or3_b32 v48, v48, v50, v51
	v_fma_f32 v49, v52, s4, 0.5
	v_fma_f32 v50, v53, s4, 0.5
	v_pk_mul_f32 v[44:45], v[44:45], v[58:59] op_sel_hi:[1,0]
	v_max_f32_e32 v49, 1.0, v49
	v_max_f32_e32 v50, 1.0, v50
	v_fma_f32 v51, v54, s4, 0.5
	v_fma_f32 v52, v55, s4, 0.5
	v_mul_f32_e32 v45, 0xbfb8aa3b, v45
	v_cvt_u32_f32_e32 v49, v49
	v_cvt_u32_f32_e32 v50, v50
	v_max_f32_e32 v51, 1.0, v51
	v_max_f32_e32 v52, 1.0, v52
	v_exp_f32_e32 v45, v45
	v_cvt_u32_f32_sdwa v51, v51 dst_sel:WORD_1 dst_unused:UNUSED_PAD src0_sel:DWORD
	v_cvt_u32_f32_sdwa v52, v52 dst_sel:BYTE_3 dst_unused:UNUSED_PAD src0_sel:DWORD
	v_pk_mul_f32 v[40:41], v[40:41], v[58:59] op_sel_hi:[1,0]
	v_mul_f32_e32 v44, 0xbfb8aa3b, v44
	v_mul_f32_e32 v41, 0xbfb8aa3b, v41
	v_lshl_or_b32 v49, v50, 8, v49
	v_exp_f32_e32 v50, v44
	v_add_f32_e32 v44, 1.0, v45
	v_exp_f32_e32 v41, v41
	v_or3_b32 v49, v49, v51, v52
	v_rcp_f32_e32 v51, v44
	v_mul_f32_e32 v40, 0xbfb8aa3b, v40
	v_pk_mul_f32 v[44:45], v[46:47], v[58:59] op_sel_hi:[1,0]
	v_add_f32_e32 v46, 1.0, v50
	v_exp_f32_e32 v50, v40
	v_add_f32_e32 v40, 1.0, v41
; __device__ __forceinline__ float sigmoidf_(float v) { return __builtin_amdgcn_rcpf(1.0f + __expf(-v)); }
;     template <int KIND> __device__ __forceinline__ void run(f32x4 (&acc)[2][2][4][2], const Unit& u, int tid_in) const {
;     ...
;             u32x4* gst = (u32x4*)((unsigned char*)x + 32 * MiB) + ((size_t)(blockIdx.x * 2 + (u.ord & 1)) * 3 + u.aux) * 4096;
; #pragma unroll
;             for (int ai = 0; ai < 2; ++ai)
; #pragma unroll
;                 for (int m = 0; m < 4; ++m) { const float r = rs[ai * 4 + m] * (1.0f / GATE_WSCALE); u32x4 w;
; #pragma unroll
;                     for (int bj = 0; bj < 2; ++bj) { f32x4 a = acc[ai][bj][m][0] * r, b = acc[ai][bj][m][1] * r;
; #pragma unroll
;                         for (int j = 0; j < 4; ++j) { a[j] = sigmoidf_(a[j]); b[j] = sigmoidf_(b[j]); }
;                         if (bj == 0) { w.x = pack4_u8c(a); w.y = pack4_u8c(b); } else { w.z = pack4_u8c(a); w.w = pack4_u8c(b); } }
	v_fma_f32 v47, v51, s4, 0.5
	v_rcp_f32_e32 v51, v40
	v_pk_mul_f32 v[40:41], v[42:43], v[58:59] op_sel_hi:[1,0]
	v_add_f32_e32 v42, 1.0, v50
	v_mul_f32_e32 v40, 0xbfb8aa3b, v40
	v_mul_f32_e32 v41, 0xbfb8aa3b, v41
	v_exp_f32_e32 v40, v40
	v_exp_f32_e32 v41, v41
	v_rcp_f32_e32 v42, v42
	v_fma_f32 v43, v51, s4, 0.5
	v_add_f32_e32 v40, 1.0, v40
	v_add_f32_e32 v41, 1.0, v41
	v_rcp_f32_e32 v40, v40
	v_rcp_f32_e32 v41, v41
	v_fma_f32 v42, v42, s4, 0.5
	v_max_f32_e32 v43, 1.0, v43
	v_max_f32_e32 v42, 1.0, v42
	v_fma_f32 v40, v40, s4, 0.5
	v_fma_f32 v41, v41, s4, 0.5
	v_cvt_u32_f32_e32 v43, v43
	v_cvt_u32_f32_e32 v42, v42
	v_max_f32_e32 v40, 1.0, v40
	v_max_f32_e32 v41, 1.0, v41
	v_cvt_u32_f32_sdwa v40, v40 dst_sel:WORD_1 dst_unused:UNUSED_PAD src0_sel:DWORD
	v_cvt_u32_f32_sdwa v41, v41 dst_sel:BYTE_3 dst_unused:UNUSED_PAD src0_sel:DWORD
	v_lshl_or_b32 v42, v43, 8, v42
	v_exp_f32_e32 v92, v92
	v_exp_f32_e32 v93, v93
	v_or3_b32 v51, v42, v40, v41
	v_mul_f32_e32 v42, 0x3c800000, v136
	v_pk_mul_f32 v[32:33], v[32:33], v[42:43] op_sel_hi:[1,0]
	v_pk_mul_f32 v[34:35], v[34:35], v[42:43] op_sel_hi:[1,0]
	v_mul_f32_e32 v32, 0xbfb8aa3b, v32
	v_mul_f32_e32 v33, 0xbfb8aa3b, v33
	v_mul_f32_e32 v35, 0xbfb8aa3b, v35
	v_exp_f32_e32 v32, v32
	v_exp_f32_e32 v33, v33
	v_mul_f32_e32 v34, 0xbfb8aa3b, v34
	v_exp_f32_e32 v35, v35
	v_exp_f32_e32 v34, v34
	v_add_f32_e32 v32, 1.0, v32
	v_add_f32_e32 v33, 1.0, v33
	v_pk_mul_f32 v[36:37], v[36:37], v[42:43] op_sel_hi:[1,0]
	v_add_f32_e32 v35, 1.0, v35
	v_rcp_f32_e32 v32, v32
	v_rcp_f32_e32 v33, v33
	v_add_f32_e32 v34, 1.0, v34
	v_pk_mul_f32 v[38:39], v[38:39], v[42:43] op_sel_hi:[1,0]
	v_mul_f32_e32 v36, 0xbfb8aa3b, v36
	v_mul_f32_e32 v37, 0xbfb8aa3b, v37
	v_rcp_f32_e32 v35, v35
	v_rcp_f32_e32 v34, v34
	v_mul_f32_e32 v39, 0xbfb8aa3b, v39
	v_exp_f32_e32 v36, v36
	v_exp_f32_e32 v37, v37
	v_mul_f32_e32 v38, 0xbfb8aa3b, v38
	v_exp_f32_e32 v39, v39
	v_exp_f32_e32 v38, v38
	v_fma_f32 v32, v32, s4, 0.5
	v_fma_f32 v33, v33, s4, 0.5
	v_max_f32_e32 v32, 1.0, v32
	v_max_f32_e32 v33, 1.0, v33
	v_fma_f32 v34, v34, s4, 0.5
	v_fma_f32 v35, v35, s4, 0.5
	v_add_f32_e32 v36, 1.0, v36
	v_add_f32_e32 v37, 1.0, v37
	v_cvt_u32_f32_e32 v32, v32
	v_cvt_u32_f32_e32 v33, v33
	v_max_f32_e32 v34, 1.0, v34
	v_max_f32_e32 v35, 1.0, v35
	v_add_f32_e32 v39, 1.0, v39
	v_rcp_f32_e32 v36, v36
	v_rcp_f32_e32 v37, v37
	v_cvt_u32_f32_sdwa v34, v34 dst_sel:WORD_1 dst_unused:UNUSED_PAD src0_sel:DWORD
	v_cvt_u32_f32_sdwa v35, v35 dst_sel:BYTE_3 dst_unused:UNUSED_PAD src0_sel:DWORD
	v_add_f32_e32 v38, 1.0, v38
	v_rcp_f32_e32 v39, v39
	v_rcp_f32_e32 v38, v38
	v_lshl_or_b32 v32, v33, 8, v32
	v_or3_b32 v32, v32, v34, v35
	v_fma_f32 v33, v36, s4, 0.5
	v_fma_f32 v34, v37, s4, 0.5
	v_pk_mul_f32 v[28:29], v[28:29], v[42:43] op_sel_hi:[1,0]
	v_max_f32_e32 v33, 1.0, v33
	v_max_f32_e32 v34, 1.0, v34
	v_fma_f32 v35, v38, s4, 0.5
	v_fma_f32 v36, v39, s4, 0.5
	v_mul_f32_e32 v29, 0xbfb8aa3b, v29
	v_cvt_u32_f32_e32 v33, v33
	v_cvt_u32_f32_e32 v34, v34
	v_max_f32_e32 v35, 1.0, v35
	v_max_f32_e32 v36, 1.0, v36
	v_exp_f32_e32 v29, v29
	v_cvt_u32_f32_sdwa v35, v35 dst_sel:WORD_1 dst_unused:UNUSED_PAD src0_sel:DWORD
	v_cvt_u32_f32_sdwa v36, v36 dst_sel:BYTE_3 dst_unused:UNUSED_PAD src0_sel:DWORD
	v_pk_mul_f32 v[24:25], v[24:25], v[42:43] op_sel_hi:[1,0]
	v_mul_f32_e32 v28, 0xbfb8aa3b, v28
	v_mul_f32_e32 v25, 0xbfb8aa3b, v25
	v_lshl_or_b32 v33, v34, 8, v33
	v_exp_f32_e32 v34, v28
	v_add_f32_e32 v28, 1.0, v29
	v_exp_f32_e32 v25, v25
	v_or3_b32 v33, v33, v35, v36
	v_rcp_f32_e32 v35, v28
	v_mul_f32_e32 v24, 0xbfb8aa3b, v24
	v_mul_f32_e32 v76, 0xbfb8aa3b, v76
	v_mul_f32_e32 v77, 0xbfb8aa3b, v77
	v_pk_mul_f32 v[28:29], v[30:31], v[42:43] op_sel_hi:[1,0]
	v_add_f32_e32 v30, 1.0, v34
	v_exp_f32_e32 v34, v24
	v_add_f32_e32 v24, 1.0, v25
	v_exp_f32_e32 v76, v76
	v_exp_f32_e32 v77, v77
	v_mul_f32_e32 v60, 0xbfb8aa3b, v60
	v_mul_f32_e32 v61, 0xbfb8aa3b, v61
	v_fma_f32 v31, v35, s4, 0.5
	v_rcp_f32_e32 v35, v24
	v_pk_mul_f32 v[24:25], v[26:27], v[42:43] op_sel_hi:[1,0]
	v_rcp_f32_e32 v126, v126
	v_add_f32_e32 v124, 1.0, v124
	v_add_f32_e32 v125, 1.0, v125
	v_exp_f32_e32 v60, v60
	v_exp_f32_e32 v61, v61
	v_mul_f32_e32 v44, 0xbfb8aa3b, v44
	v_mul_f32_e32 v45, 0xbfb8aa3b, v45
	v_mul_f32_e32 v24, 0xbfb8aa3b, v24
	v_mul_f32_e32 v25, 0xbfb8aa3b, v25
	v_rcp_f32_e32 v124, v124
	v_rcp_f32_e32 v125, v125
	v_rcp_f32_e32 v110, v110
	v_add_f32_e32 v108, 1.0, v108
	v_add_f32_e32 v109, 1.0, v109
	v_exp_f32_e32 v44, v44
	v_exp_f32_e32 v45, v45
	v_mul_f32_e32 v28, 0xbfb8aa3b, v28
	v_mul_f32_e32 v29, 0xbfb8aa3b, v29
	v_exp_f32_e32 v24, v24
	v_exp_f32_e32 v25, v25
	s_lshl_b64 s[2:3], s[2:3], 16
	v_rcp_f32_e32 v108, v108
	v_rcp_f32_e32 v109, v109
	v_rcp_f32_e32 v94, v94
	v_add_f32_e32 v92, 1.0, v92
	v_add_f32_e32 v93, 1.0, v93
	v_exp_f32_e32 v28, v28
	v_exp_f32_e32 v29, v29
	s_add_u32 s2, s29, s2
	v_rcp_f32_e32 v92, v92
	v_rcp_f32_e32 v93, v93
	v_rcp_f32_e32 v78, v78
	v_add_f32_e32 v76, 1.0, v76
	v_add_f32_e32 v77, 1.0, v77
	s_addc_u32 s3, s30, s3
	v_fma_f32 v126, v126, s4, 0.5
	v_ashrrev_i32_e32 v143, 31, v142
	v_rcp_f32_e32 v76, v76
	v_rcp_f32_e32 v77, v77
	v_rcp_f32_e32 v62, v62
	v_add_f32_e32 v60, 1.0, v60
	v_add_f32_e32 v61, 1.0, v61
	v_add_f32_e32 v26, 1.0, v34
	v_max_f32_e32 v127, 1.0, v127
	v_max_f32_e32 v126, 1.0, v126
	v_fma_f32 v124, v124, s4, 0.5
	v_fma_f32 v125, v125, s4, 0.5
	v_lshl_add_u64 v[120:121], v[142:143], 4, s[2:3]
	v_fma_f32 v110, v110, s4, 0.5
	s_movk_i32 s2, 0x2000
	v_rcp_f32_e32 v60, v60
	v_rcp_f32_e32 v61, v61
	v_rcp_f32_e32 v46, v46
	v_add_f32_e32 v44, 1.0, v44
	v_add_f32_e32 v45, 1.0, v45
	v_rcp_f32_e32 v26, v26
	v_add_f32_e32 v24, 1.0, v24
	v_add_f32_e32 v25, 1.0, v25
; #define MEMFENCE asm volatile("" ::: "memory")
;     template <int KIND> __device__ __forceinline__ void run(f32x4 (&acc)[2][2][4][2], const Unit& u, int tid_in) const {
;     ...
;                         if (bj == 0) { w.x = pack4_u8c(a); w.y = pack4_u8c(b); } else { w.z = pack4_u8c(a); w.w = pack4_u8c(b); } }
;                     gst[(ai * 4 + m) * 512 + tid] = w; MEMFENCE; }
	v_cvt_u32_f32_e32 v127, v127
	v_cvt_u32_f32_e32 v126, v126
	v_max_f32_e32 v124, 1.0, v124
	v_max_f32_e32 v125, 1.0, v125
	v_max_f32_e32 v111, 1.0, v111
	v_max_f32_e32 v110, 1.0, v110
	v_fma_f32 v108, v108, s4, 0.5
	v_fma_f32 v109, v109, s4, 0.5
	v_add_co_u32_e32 v104, vcc, s2, v120
	v_fma_f32 v94, v94, s4, 0.5
	v_rcp_f32_e32 v44, v44
	v_rcp_f32_e32 v45, v45
	v_rcp_f32_e32 v30, v30
	v_add_f32_e32 v28, 1.0, v28
	v_add_f32_e32 v29, 1.0, v29
	v_rcp_f32_e32 v24, v24
	v_rcp_f32_e32 v25, v25
	v_cvt_u32_f32_sdwa v124, v124 dst_sel:WORD_1 dst_unused:UNUSED_PAD src0_sel:DWORD
	v_cvt_u32_f32_sdwa v125, v125 dst_sel:BYTE_3 dst_unused:UNUSED_PAD src0_sel:DWORD
	v_cvt_u32_f32_e32 v111, v111
	v_cvt_u32_f32_e32 v110, v110
	v_max_f32_e32 v108, 1.0, v108
	v_max_f32_e32 v109, 1.0, v109
	v_addc_co_u32_e32 v105, vcc, 0, v121, vcc
	v_max_f32_e32 v95, 1.0, v95
	v_max_f32_e32 v94, 1.0, v94
	v_fma_f32 v92, v92, s4, 0.5
	v_fma_f32 v93, v93, s4, 0.5
	v_fma_f32 v78, v78, s4, 0.5
	v_rcp_f32_e32 v28, v28
	v_rcp_f32_e32 v29, v29
	v_cvt_u32_f32_sdwa v108, v108 dst_sel:WORD_1 dst_unused:UNUSED_PAD src0_sel:DWORD
	v_cvt_u32_f32_sdwa v109, v109 dst_sel:BYTE_3 dst_unused:UNUSED_PAD src0_sel:DWORD
	v_cvt_u32_f32_e32 v95, v95
	v_cvt_u32_f32_e32 v94, v94
	v_max_f32_e32 v92, 1.0, v92
	v_max_f32_e32 v93, 1.0, v93
	v_add_co_u32_e32 v88, vcc, s49, v120
	v_max_f32_e32 v79, 1.0, v79
	v_max_f32_e32 v78, 1.0, v78
	v_fma_f32 v76, v76, s4, 0.5
	v_fma_f32 v77, v77, s4, 0.5
	v_fma_f32 v62, v62, s4, 0.5
	v_cvt_u32_f32_sdwa v92, v92 dst_sel:WORD_1 dst_unused:UNUSED_PAD src0_sel:DWORD
	v_cvt_u32_f32_sdwa v93, v93 dst_sel:BYTE_3 dst_unused:UNUSED_PAD src0_sel:DWORD
	v_addc_co_u32_e32 v89, vcc, 0, v121, vcc
	v_cvt_u32_f32_e32 v79, v79
	v_cvt_u32_f32_e32 v78, v78
	v_max_f32_e32 v76, 1.0, v76
	v_max_f32_e32 v77, 1.0, v77
	s_movk_i32 s2, 0x6000
	v_max_f32_e32 v63, 1.0, v63
	v_max_f32_e32 v62, 1.0, v62
	v_fma_f32 v60, v60, s4, 0.5
	v_fma_f32 v61, v61, s4, 0.5
	v_fma_f32 v46, v46, s4, 0.5
	v_fma_f32 v27, v35, s4, 0.5
	v_fma_f32 v26, v26, s4, 0.5
	v_lshl_or_b32 v126, v127, 8, v126
	v_cvt_u32_f32_sdwa v76, v76 dst_sel:WORD_1 dst_unused:UNUSED_PAD src0_sel:DWORD
	v_cvt_u32_f32_sdwa v77, v77 dst_sel:BYTE_3 dst_unused:UNUSED_PAD src0_sel:DWORD
	v_add_co_u32_e32 v72, vcc, s2, v120
	v_cvt_u32_f32_e32 v63, v63
	v_cvt_u32_f32_e32 v62, v62
	v_max_f32_e32 v60, 1.0, v60
	v_max_f32_e32 v61, 1.0, v61
	v_max_f32_e32 v47, 1.0, v47
	v_max_f32_e32 v46, 1.0, v46
	v_fma_f32 v44, v44, s4, 0.5
	v_fma_f32 v45, v45, s4, 0.5
	v_fma_f32 v30, v30, s4, 0.5
	v_max_f32_e32 v27, 1.0, v27
	v_max_f32_e32 v26, 1.0, v26
	v_fma_f32 v24, v24, s4, 0.5
	v_fma_f32 v25, v25, s4, 0.5
	v_or3_b32 v130, v126, v124, v125
	v_lshl_or_b32 v110, v111, 8, v110
	v_addc_co_u32_e32 v73, vcc, 0, v121, vcc
	v_cvt_u32_f32_sdwa v60, v60 dst_sel:WORD_1 dst_unused:UNUSED_PAD src0_sel:DWORD
	v_cvt_u32_f32_sdwa v61, v61 dst_sel:BYTE_3 dst_unused:UNUSED_PAD src0_sel:DWORD
	v_cvt_u32_f32_e32 v47, v47
	v_cvt_u32_f32_e32 v46, v46
	v_max_f32_e32 v44, 1.0, v44
	v_max_f32_e32 v45, 1.0, v45
	v_max_f32_e32 v31, 1.0, v31
	v_max_f32_e32 v30, 1.0, v30
	v_fma_f32 v28, v28, s4, 0.5
	v_fma_f32 v29, v29, s4, 0.5
	v_cvt_u32_f32_e32 v27, v27
	v_cvt_u32_f32_e32 v26, v26
	v_max_f32_e32 v24, 1.0, v24
	v_max_f32_e32 v25, 1.0, v25
	global_store_dwordx4 v[120:121], v[128:131], off
	v_or3_b32 v114, v110, v108, v109
	v_lshl_or_b32 v94, v95, 8, v94
	v_add_co_u32_e32 v56, vcc, s77, v120
	v_cvt_u32_f32_sdwa v44, v44 dst_sel:WORD_1 dst_unused:UNUSED_PAD src0_sel:DWORD
	v_cvt_u32_f32_sdwa v45, v45 dst_sel:BYTE_3 dst_unused:UNUSED_PAD src0_sel:DWORD
	v_cvt_u32_f32_e32 v31, v31
	v_cvt_u32_f32_e32 v30, v30
	v_max_f32_e32 v28, 1.0, v28
	v_max_f32_e32 v29, 1.0, v29
	v_cvt_u32_f32_sdwa v24, v24 dst_sel:WORD_1 dst_unused:UNUSED_PAD src0_sel:DWORD
	v_cvt_u32_f32_sdwa v25, v25 dst_sel:BYTE_3 dst_unused:UNUSED_PAD src0_sel:DWORD
	global_store_dwordx4 v[104:105], v[112:115], off
	v_or3_b32 v98, v94, v92, v93
	v_lshl_or_b32 v78, v79, 8, v78
	v_addc_co_u32_e32 v57, vcc, 0, v121, vcc
	s_mov_b32 s2, 0xa000
	v_cvt_u32_f32_sdwa v28, v28 dst_sel:WORD_1 dst_unused:UNUSED_PAD src0_sel:DWORD
	v_cvt_u32_f32_sdwa v29, v29 dst_sel:BYTE_3 dst_unused:UNUSED_PAD src0_sel:DWORD
	global_store_dwordx4 v[88:89], v[96:99], off
	v_or3_b32 v82, v78, v76, v77
	v_lshl_or_b32 v62, v63, 8, v62
	v_add_co_u32_e32 v40, vcc, s2, v120
	global_store_dwordx4 v[72:73], v[80:83], off
	v_or3_b32 v66, v62, v60, v61
	v_lshl_or_b32 v46, v47, 8, v46
	v_addc_co_u32_e32 v41, vcc, 0, v121, vcc
	v_lshl_or_b32 v26, v27, 8, v26
	s_mov_b32 s2, 0xc000
	global_store_dwordx4 v[56:57], v[64:67], off
	v_or3_b32 v50, v46, v44, v45
	v_lshl_or_b32 v30, v31, 8, v30
	v_or3_b32 v35, v26, v24, v25
	v_add_co_u32_e32 v24, vcc, s2, v120
	global_store_dwordx4 v[40:41], v[48:51], off
	v_or3_b32 v34, v30, v28, v29
; __device__ __forceinline__ float sigmoidf_(float v) { return __builtin_amdgcn_rcpf(1.0f + __expf(-v)); }
; #define MEMFENCE asm volatile("" ::: "memory")
;     template <int KIND> __device__ __forceinline__ void run(f32x4 (&acc)[2][2][4][2], const Unit& u, int tid_in) const {
;     ...
;                 for (int m = 0; m < 4; ++m) { const float r = rs[ai * 4 + m] * (1.0f / GATE_WSCALE); u32x4 w;
; #pragma unroll
;                     for (int bj = 0; bj < 2; ++bj) { f32x4 a = acc[ai][bj][m][0] * r, b = acc[ai][bj][m][1] * r;
; #pragma unroll
;                         for (int j = 0; j < 4; ++j) { a[j] = sigmoidf_(a[j]); b[j] = sigmoidf_(b[j]); }
;                         if (bj == 0) { w.x = pack4_u8c(a); w.y = pack4_u8c(b); } else { w.z = pack4_u8c(a); w.w = pack4_u8c(b); } }
;                     gst[(ai * 4 + m) * 512 + tid] = w; MEMFENCE; }
;     ...
;         cur = nxt; cA = nA; cB = nB; ++ui;
	v_addc_co_u32_e32 v25, vcc, 0, v121, vcc
	global_store_dwordx4 v[24:25], v[32:35], off
	v_mul_f32_e32 v24, 0x3c800000, v137
	v_pk_mul_f32 v[20:21], v[20:21], v[24:25] op_sel_hi:[1,0]
	s_mov_b32 s33, s35
	v_mul_f32_e32 v21, 0xbfb8aa3b, v21
	v_exp_f32_e32 v21, v21
	v_mul_f32_e32 v20, 0xbfb8aa3b, v20
	v_exp_f32_e32 v25, v20
	s_mov_b32 s36, s34
	v_add_f32_e32 v20, 1.0, v21
	v_rcp_f32_e32 v26, v20
	v_pk_mul_f32 v[20:21], v[22:23], v[24:25] op_sel_hi:[1,0]
	v_add_f32_e32 v22, 1.0, v25
	v_mul_f32_e32 v20, 0xbfb8aa3b, v20
	v_exp_f32_e32 v20, v20
	v_rcp_f32_e32 v22, v22
	v_mul_f32_e32 v21, 0xbfb8aa3b, v21
	v_exp_f32_e32 v21, v21
	v_add_f32_e32 v20, 1.0, v20
	v_fma_f32 v23, v26, s4, 0.5
	v_fma_f32 v22, v22, s4, 0.5
	v_rcp_f32_e32 v20, v20
	v_max_f32_e32 v23, 1.0, v23
	v_max_f32_e32 v22, 1.0, v22
	v_add_f32_e32 v21, 1.0, v21
	v_cvt_u32_f32_e32 v23, v23
	v_cvt_u32_f32_e32 v22, v22
	v_rcp_f32_e32 v21, v21
	v_fma_f32 v20, v20, s4, 0.5
	v_max_f32_e32 v20, 1.0, v20
	v_lshl_or_b32 v22, v23, 8, v22
	v_cvt_u32_f32_sdwa v23, v20 dst_sel:WORD_1 dst_unused:UNUSED_PAD src0_sel:DWORD
	v_fma_f32 v20, v21, s4, 0.5
	v_max_f32_e32 v20, 1.0, v20
	v_cvt_u32_f32_sdwa v25, v20 dst_sel:BYTE_3 dst_unused:UNUSED_PAD src0_sel:DWORD
	s_mov_b64 s[12:13], s[10:11]
	s_mov_b64 s[2:3], s[8:9]
	v_pk_mul_f32 v[20:21], v[16:17], v[24:25] op_sel_hi:[1,0]
	s_nop 0
	v_mul_f32_e32 v16, 0xbfb8aa3b, v21
	v_mul_f32_e32 v20, 0xbfb8aa3b, v20
	v_pk_mul_f32 v[18:19], v[18:19], v[24:25] op_sel_hi:[1,0]
	v_exp_f32_e32 v17, v16
	v_exp_f32_e32 v20, v20
	v_mul_f32_e32 v18, 0xbfb8aa3b, v18
	v_mul_f32_e32 v19, 0xbfb8aa3b, v19
	v_exp_f32_e32 v18, v18
	v_exp_f32_e32 v19, v19
	v_add_f32_e32 v17, 1.0, v17
	v_add_f32_e32 v20, 1.0, v20
	v_rcp_f32_e32 v17, v17
	v_rcp_f32_e32 v20, v20
	v_add_f32_e32 v18, 1.0, v18
	v_add_f32_e32 v19, 1.0, v19
	v_rcp_f32_e32 v18, v18
	v_rcp_f32_e32 v19, v19
	v_fma_f32 v17, v17, s4, 0.5
	v_fma_f32 v20, v20, s4, 0.5
	v_max_f32_e32 v17, 1.0, v17
	v_max_f32_e32 v20, 1.0, v20
	v_fma_f32 v18, v18, s4, 0.5
	v_fma_f32 v19, v19, s4, 0.5
	v_pk_mul_f32 v[12:13], v[12:13], v[24:25] op_sel_hi:[1,0]
	v_cvt_u32_f32_e32 v17, v17
	v_cvt_u32_f32_e32 v20, v20
	v_max_f32_e32 v18, 1.0, v18
	v_max_f32_e32 v19, 1.0, v19
	v_mul_f32_e32 v13, 0xbfb8aa3b, v13
	v_cvt_u32_f32_sdwa v18, v18 dst_sel:WORD_1 dst_unused:UNUSED_PAD src0_sel:DWORD
	v_cvt_u32_f32_sdwa v19, v19 dst_sel:BYTE_3 dst_unused:UNUSED_PAD src0_sel:DWORD
	v_exp_f32_e32 v13, v13
	v_pk_mul_f32 v[8:9], v[8:9], v[24:25] op_sel_hi:[1,0]
	v_lshl_or_b32 v17, v17, 8, v20
	v_mul_f32_e32 v12, 0xbfb8aa3b, v12
	v_mul_f32_e32 v9, 0xbfb8aa3b, v9
	v_or3_b32 v17, v17, v18, v19
	v_exp_f32_e32 v18, v12
	v_add_f32_e32 v12, 1.0, v13
	v_exp_f32_e32 v9, v9
	v_rcp_f32_e32 v19, v12
	v_mul_f32_e32 v8, 0xbfb8aa3b, v8
	v_pk_mul_f32 v[12:13], v[14:15], v[24:25] op_sel_hi:[1,0]
	v_add_f32_e32 v14, 1.0, v18
	v_exp_f32_e32 v18, v8
	v_add_f32_e32 v8, 1.0, v9
	v_fma_f32 v15, v19, s4, 0.5
	v_rcp_f32_e32 v19, v8
	v_pk_mul_f32 v[8:9], v[10:11], v[24:25] op_sel_hi:[1,0]
	v_mul_f32_e32 v12, 0xbfb8aa3b, v12
	v_mul_f32_e32 v8, 0xbfb8aa3b, v8
	v_mul_f32_e32 v9, 0xbfb8aa3b, v9
	v_mul_f32_e32 v13, 0xbfb8aa3b, v13
	v_exp_f32_e32 v8, v8
	v_exp_f32_e32 v9, v9
	v_exp_f32_e32 v12, v12
	v_exp_f32_e32 v13, v13
	v_add_f32_e32 v10, 1.0, v18
	v_rcp_f32_e32 v10, v10
	v_add_f32_e32 v8, 1.0, v8
	v_add_f32_e32 v9, 1.0, v9
	v_rcp_f32_e32 v14, v14
	v_add_f32_e32 v12, 1.0, v12
	v_add_f32_e32 v13, 1.0, v13
	v_rcp_f32_e32 v8, v8
	v_rcp_f32_e32 v9, v9
	v_rcp_f32_e32 v12, v12
	v_rcp_f32_e32 v13, v13
	v_fma_f32 v11, v19, s4, 0.5
	v_fma_f32 v10, v10, s4, 0.5
	v_fma_f32 v14, v14, s4, 0.5
	v_max_f32_e32 v11, 1.0, v11
	v_max_f32_e32 v10, 1.0, v10
	v_fma_f32 v8, v8, s4, 0.5
	v_fma_f32 v9, v9, s4, 0.5
	v_max_f32_e32 v15, 1.0, v15
	v_max_f32_e32 v14, 1.0, v14
	v_fma_f32 v12, v12, s4, 0.5
	v_fma_f32 v13, v13, s4, 0.5
	v_cvt_u32_f32_e32 v11, v11
	v_cvt_u32_f32_e32 v10, v10
	v_max_f32_e32 v8, 1.0, v8
	v_max_f32_e32 v9, 1.0, v9
	v_cvt_u32_f32_e32 v15, v15
	v_cvt_u32_f32_e32 v14, v14
	v_max_f32_e32 v12, 1.0, v12
	v_max_f32_e32 v13, 1.0, v13
	v_cvt_u32_f32_sdwa v8, v8 dst_sel:WORD_1 dst_unused:UNUSED_PAD src0_sel:DWORD
	v_cvt_u32_f32_sdwa v9, v9 dst_sel:BYTE_3 dst_unused:UNUSED_PAD src0_sel:DWORD
	v_cvt_u32_f32_sdwa v12, v12 dst_sel:WORD_1 dst_unused:UNUSED_PAD src0_sel:DWORD
	v_cvt_u32_f32_sdwa v13, v13 dst_sel:BYTE_3 dst_unused:UNUSED_PAD src0_sel:DWORD
	v_lshl_or_b32 v10, v11, 8, v10
	v_lshl_or_b32 v14, v15, 8, v14
	v_or3_b32 v19, v10, v8, v9
	v_add_co_u32_e32 v8, vcc, 0xe000, v120
	v_or3_b32 v16, v22, v23, v25
	v_or3_b32 v18, v14, v12, v13
	v_addc_co_u32_e32 v9, vcc, 0, v121, vcc
	global_store_dwordx4 v[8:9], v[16:19], off
	s_and_b64 vcc, exec, s[6:7]
	s_cbranch_vccz .LBB0_867
	s_cmp_eq_u32 s101, 2
	s_cbranch_scc0 .Ldbj_MG0_pe
	s_barrier

; #define G_STAGE(bufoff, gbase, o0, h64) do { \
;         __builtin_amdgcn_global_load_lds((const unsigned*)((const char*)(gbase) + (o0)), (LAS unsigned*)(lds + (bufoff) + ldsw), 16, 0, 0); \
;         __builtin_amdgcn_global_load_lds((const unsigned*)((const char*)(gbase) + (h64) + (o0)), (LAS unsigned*)(lds + (bufoff) + ldsw + 8192), 16, 0, 0); } while (0)
; #define G_LDA(dst, b, h) do { _Pragma("unroll") for (int m = 0; m < 4; ++m) _Pragma("unroll") for (int k = 0; k < 2; ++k) dst[m][k] = *(const LAS bf16x8*)(lds + G_SA(b, h) + aoff + m * 2048 + k * 1024); } while (0)
; #define G_LDB(dst, b, h) do { _Pragma("unroll") for (int n = 0; n < 2; ++n) _Pragma("unroll") for (int k = 0; k < 2; ++k) dst[n][k] = *(const LAS bf16x8*)(lds + G_SB(b, h) + boff + n * 2048 + k * 1024); } while (0)
; #define G_WAIT_V(n) asm volatile("s_waitcnt vmcnt(" #n ")" ::: "memory")
; #define G_WAIT_L(n) asm volatile("s_waitcnt lgkmcnt(" #n ")" ::: "memory")
; #define G_BAR __builtin_amdgcn_s_barrier()
; #define G_SCHED __builtin_amdgcn_sched_barrier(0)
;     ...
;             G_WAIT_L(8); G_BAR; G_WAIT_L(0); G_MMA(0, 0, At, B0); G_BAR; G_SCHED;
;             G_LDB(B1, 0, 1); G_STAGE(G_SB(0, 0), b2, cB0, qB);
;             G_BAR; G_WAIT_L(0); G_MMA(0, 1, At, B1); G_BAR;
;             G_LDA(At, 0, 1); G_STAGE(G_SA(0, 0), a2, cA0, qA);
;             G_BAR; G_WAIT_L(0); G_MMA(1, 0, At, B0); G_BAR; G_SCHED;
;             G_STAGE(G_SB(0, 1), b2 + chB, cB0, qB);
;             G_WAIT_V(6); G_BAR; G_MMA(1, 1, At, B1); G_BAR;
;             G_LDB(B0, 1, 0); G_SCHED; G_LDA(At, 1, 0); G_STAGE(G_SA(0, 1), a2 + chA, cA0, qA);
;             G_WAIT_L(8); G_BAR; G_WAIT_L(0); G_MMA(0, 0, At, B0); G_BAR; G_SCHED;
;             G_LDB(B1, 1, 1); G_STAGE(G_SB(1, 0), b3, cB0, qB);
;             G_BAR; G_WAIT_L(0); G_MMA(0, 1, At, B1); G_BAR;
;             G_LDA(At, 1, 1); G_STAGE(G_SA(1, 0), a3, cA0, qA);
;             G_BAR; G_WAIT_L(0); G_MMA(1, 0, At, B0); G_BAR; G_SCHED;
;             G_STAGE(G_SB(1, 1), b3 + chB, cB0, qB);
;             G_WAIT_V(6); G_BAR; G_MMA(1, 1, At, B1); G_BAR;
.Ldb_MG1_sk:
	s_mov_b32 s101, 0
	s_waitcnt lgkmcnt(0)
	v_mfma_f32_16x16x32_bf16 v[104:107], v[136:139], v[158:161], v[104:107]
	v_mfma_f32_16x16x32_bf16 v[108:111], v[144:147], v[158:161], v[108:111]
	v_mfma_f32_16x16x32_bf16 v[132:135], v[136:139], v[178:181], v[132:135]
	v_mfma_f32_16x16x32_bf16 v[128:131], v[144:147], v[178:181], v[128:131]
	v_mfma_f32_16x16x32_bf16 v[124:127], v[136:139], v[196:199], v[124:127]
	v_mfma_f32_16x16x32_bf16 v[120:123], v[144:147], v[196:199], v[120:123]
	v_mfma_f32_16x16x32_bf16 v[116:119], v[136:139], v[204:207], v[116:119]
	v_mfma_f32_16x16x32_bf16 v[112:115], v[144:147], v[204:207], v[112:115]
	v_mfma_f32_16x16x32_bf16 v[104:107], v[140:143], v[162:165], v[104:107]
	v_mfma_f32_16x16x32_bf16 v[108:111], v[148:151], v[162:165], v[108:111]
	v_mfma_f32_16x16x32_bf16 v[132:135], v[140:143], v[182:185], v[132:135]
	v_mfma_f32_16x16x32_bf16 v[128:131], v[148:151], v[182:185], v[128:131]
	v_mfma_f32_16x16x32_bf16 v[124:127], v[140:143], v[200:203], v[124:127]
	v_mfma_f32_16x16x32_bf16 v[120:123], v[148:151], v[200:203], v[120:123]
	v_mfma_f32_16x16x32_bf16 v[116:119], v[140:143], v[208:211], v[116:119]
	v_mfma_f32_16x16x32_bf16 v[112:115], v[148:151], v[208:211], v[112:115]
	s_barrier
	s_add_i32 s43, 0, 0x14000
	s_add_i32 s19, s19, s21
	v_lshl_add_u64 v[2:3], s[44:45], 0, v[154:155]
	s_mov_b64 vcc, s[44:45]
	s_mov_b64 s[44:45], 0x10000
	s_mov_b32 m0, s19
	ds_read_b128 v[212:215], v239 offset:16384
	ds_read_b128 v[216:219], v239 offset:17408
	ds_read_b128 v[220:223], v239 offset:18432
	ds_read_b128 v[224:227], v239 offset:19456
	global_load_lds_dwordx4 v154, vcc
	v_lshl_add_u64 v[166:167], v[2:3], 0, s[44:45]
	s_add_i32 m0, s19, 0x2000
	s_nop 0
	global_load_lds_dwordx4 v[166:167], off
	s_barrier
	s_waitcnt lgkmcnt(0)
	v_mfma_f32_16x16x32_bf16 v[100:103], v[212:215], v[158:161], v[100:103]
	v_mfma_f32_16x16x32_bf16 v[96:99], v[220:223], v[158:161], v[96:99]
	v_mfma_f32_16x16x32_bf16 v[92:95], v[212:215], v[178:181], v[92:95]
	v_mfma_f32_16x16x32_bf16 v[88:91], v[220:223], v[178:181], v[88:91]
	v_mfma_f32_16x16x32_bf16 v[84:87], v[212:215], v[196:199], v[84:87]
	v_mfma_f32_16x16x32_bf16 v[80:83], v[220:223], v[196:199], v[80:83]
	v_mfma_f32_16x16x32_bf16 v[76:79], v[212:215], v[204:207], v[76:79]
	v_mfma_f32_16x16x32_bf16 v[72:75], v[220:223], v[204:207], v[72:75]
	v_mfma_f32_16x16x32_bf16 v[100:103], v[216:219], v[162:165], v[100:103]
	v_mfma_f32_16x16x32_bf16 v[96:99], v[224:227], v[162:165], v[96:99]
	v_mfma_f32_16x16x32_bf16 v[92:95], v[216:219], v[182:185], v[92:95]
	v_mfma_f32_16x16x32_bf16 v[88:91], v[224:227], v[182:185], v[88:91]
	v_mfma_f32_16x16x32_bf16 v[84:87], v[216:219], v[200:203], v[84:87]
	v_mfma_f32_16x16x32_bf16 v[80:83], v[224:227], v[200:203], v[80:83]
	v_mfma_f32_16x16x32_bf16 v[76:79], v[216:219], v[208:211], v[76:79]
	v_mfma_f32_16x16x32_bf16 v[72:75], v[224:227], v[208:211], v[72:75]
	s_barrier
	s_mov_b32 m0, s22
	v_lshl_add_u64 v[166:167], s[4:5], 0, v[152:153]
	ds_read_b128 v[158:161], v176 offset:16384
	ds_read_b128 v[162:165], v176 offset:17408
	ds_read_b128 v[178:181], v176 offset:18432
	ds_read_b128 v[182:185], v176 offset:19456
	ds_read_b128 v[196:199], v176 offset:20480
	ds_read_b128 v[200:203], v176 offset:21504
	ds_read_b128 v[204:207], v176 offset:22528
	ds_read_b128 v[208:211], v176 offset:23552
	global_load_lds_dwordx4 v152, s[4:5]
	s_mov_b32 m0, s23
	s_nop 0
	s_add_u32 vcc_lo, s4, s86
	s_addc_u32 vcc_hi, s5, s87
	global_load_lds_dwordx4 v152, vcc
	s_barrier
	s_waitcnt lgkmcnt(0)
	v_mfma_f32_16x16x32_bf16 v[68:71], v[136:139], v[158:161], v[68:71]
	v_mfma_f32_16x16x32_bf16 v[64:67], v[144:147], v[158:161], v[64:67]
	v_mfma_f32_16x16x32_bf16 v[60:63], v[136:139], v[178:181], v[60:63]
	v_mfma_f32_16x16x32_bf16 v[56:59], v[144:147], v[178:181], v[56:59]
	v_mfma_f32_16x16x32_bf16 v[52:55], v[136:139], v[196:199], v[52:55]
	v_mfma_f32_16x16x32_bf16 v[48:51], v[144:147], v[196:199], v[48:51]
	v_mfma_f32_16x16x32_bf16 v[44:47], v[136:139], v[204:207], v[44:47]
	v_mfma_f32_16x16x32_bf16 v[40:43], v[144:147], v[204:207], v[40:43]
	v_mfma_f32_16x16x32_bf16 v[68:71], v[140:143], v[162:165], v[68:71]
	v_mfma_f32_16x16x32_bf16 v[64:67], v[148:151], v[162:165], v[64:67]
	v_mfma_f32_16x16x32_bf16 v[60:63], v[140:143], v[182:185], v[60:63]
	v_mfma_f32_16x16x32_bf16 v[56:59], v[148:151], v[182:185], v[56:59]
	v_mfma_f32_16x16x32_bf16 v[52:55], v[140:143], v[200:203], v[52:55]
	v_mfma_f32_16x16x32_bf16 v[48:51], v[148:151], v[200:203], v[48:51]
	v_mfma_f32_16x16x32_bf16 v[44:47], v[140:143], v[208:211], v[44:47]
	v_mfma_f32_16x16x32_bf16 v[40:43], v[148:151], v[208:211], v[40:43]
	s_barrier
	s_add_i32 s4, s43, s21
	v_lshl_add_u64 v[136:137], v[2:3], 0, s[0:1]
	s_mov_b32 m0, s4
	s_nop 0
	global_load_lds_dwordx4 v[136:137], off
	v_lshl_add_u64 v[136:137], v[2:3], 0, s[52:53]
	s_add_i32 m0, s4, 0x2000
	s_nop 0
	global_load_lds_dwordx4 v[136:137], off
	s_waitcnt vmcnt(6)
	s_barrier
	v_mfma_f32_16x16x32_bf16 v[36:39], v[212:215], v[158:161], v[36:39]
	v_mfma_f32_16x16x32_bf16 v[32:35], v[220:223], v[158:161], v[32:35]
	v_mfma_f32_16x16x32_bf16 v[28:31], v[212:215], v[178:181], v[28:31]
	v_mfma_f32_16x16x32_bf16 v[24:27], v[220:223], v[178:181], v[24:27]
	v_mfma_f32_16x16x32_bf16 v[20:23], v[212:215], v[196:199], v[20:23]
	v_mfma_f32_16x16x32_bf16 v[16:19], v[220:223], v[196:199], v[16:19]
	v_mfma_f32_16x16x32_bf16 v[12:15], v[212:215], v[204:207], v[12:15]
	v_mfma_f32_16x16x32_bf16 v[8:11], v[220:223], v[204:207], v[8:11]
	v_mfma_f32_16x16x32_bf16 v[36:39], v[216:219], v[162:165], v[36:39]
	v_mfma_f32_16x16x32_bf16 v[32:35], v[224:227], v[162:165], v[32:35]
	v_mfma_f32_16x16x32_bf16 v[28:31], v[216:219], v[182:185], v[28:31]
	v_mfma_f32_16x16x32_bf16 v[24:27], v[224:227], v[182:185], v[24:27]
	v_mfma_f32_16x16x32_bf16 v[20:23], v[216:219], v[200:203], v[20:23]
	v_mfma_f32_16x16x32_bf16 v[16:19], v[224:227], v[200:203], v[16:19]
	v_mfma_f32_16x16x32_bf16 v[12:15], v[216:219], v[208:211], v[12:15]
	v_mfma_f32_16x16x32_bf16 v[8:11], v[224:227], v[208:211], v[8:11]
	s_barrier
; #define G_STAGE(bufoff, gbase, o0, h64) do { \
;         __builtin_amdgcn_global_load_lds((const unsigned*)((const char*)(gbase) + (o0)), (LAS unsigned*)(lds + (bufoff) + ldsw), 16, 0, 0); \
;         __builtin_amdgcn_global_load_lds((const unsigned*)((const char*)(gbase) + (h64) + (o0)), (LAS unsigned*)(lds + (bufoff) + ldsw + 8192), 16, 0, 0); } while (0)
; #define G_LDA(dst, b, h) do { _Pragma("unroll") for (int m = 0; m < 4; ++m) _Pragma("unroll") for (int k = 0; k < 2; ++k) dst[m][k] = *(const LAS bf16x8*)(lds + G_SA(b, h) + aoff + m * 2048 + k * 1024); } while (0)
; #define G_LDB(dst, b, h) do { _Pragma("unroll") for (int n = 0; n < 2; ++n) _Pragma("unroll") for (int k = 0; k < 2; ++k) dst[n][k] = *(const LAS bf16x8*)(lds + G_SB(b, h) + boff + n * 2048 + k * 1024); } while (0)
; #define G_WAIT_V(n) asm volatile("s_waitcnt vmcnt(" #n ")" ::: "memory")
; #define G_WAIT_L(n) asm volatile("s_waitcnt lgkmcnt(" #n ")" ::: "memory")
; #define G_BAR __builtin_amdgcn_s_barrier()
; #define G_SCHED __builtin_amdgcn_sched_barrier(0)
;     ...
;             G_LDB(B0, 1, 0); G_SCHED; G_LDA(At, 1, 0); G_STAGE(G_SA(0, 1), a2 + chA, cA0, qA);
;             G_WAIT_L(8); G_BAR; G_WAIT_L(0); G_MMA(0, 0, At, B0); G_BAR; G_SCHED;
;             G_LDB(B1, 1, 1); G_STAGE(G_SB(1, 0), b3, cB0, qB);
;             G_BAR; G_WAIT_L(0); G_MMA(0, 1, At, B1); G_BAR;
;             G_LDA(At, 1, 1); G_STAGE(G_SA(1, 0), a3, cA0, qA);
;             G_BAR; G_WAIT_L(0); G_MMA(1, 0, At, B0); G_BAR; G_SCHED;
;             G_STAGE(G_SB(1, 1), b3 + chB, cB0, qB);
;             G_WAIT_V(6); G_BAR; G_MMA(1, 1, At, B1); G_BAR;
;         }
	s_add_i32 s4, 0, 0x18000
	ds_read_b128 v[136:139], v239 offset:32768
	ds_read_b128 v[140:143], v239 offset:33792
	ds_read_b128 v[144:147], v239 offset:34816
	ds_read_b128 v[148:151], v239 offset:35840
	s_mov_b32 m0, s24
	v_lshl_add_u64 v[172:173], v[166:167], 0, s[88:89]
	ds_read_b128 v[158:161], v176 offset:32768
	ds_read_b128 v[162:165], v176 offset:33792
	ds_read_b128 v[178:181], v176 offset:34816
	ds_read_b128 v[182:185], v176 offset:35840
	ds_read_b128 v[196:199], v176 offset:36864
	ds_read_b128 v[200:203], v176 offset:37888
	ds_read_b128 v[204:207], v176 offset:38912
	ds_read_b128 v[208:211], v176 offset:39936
	global_load_lds_dwordx4 v[172:173], off
	v_lshl_add_u64 v[172:173], v[166:167], 0, s[64:65]
	s_mov_b32 m0, s25
	s_nop 0
	global_load_lds_dwordx4 v[172:173], off
	s_waitcnt lgkmcnt(8)
	s_barrier
	s_waitcnt lgkmcnt(0)
	v_mfma_f32_16x16x32_bf16 v[104:107], v[136:139], v[158:161], v[104:107]
	v_mfma_f32_16x16x32_bf16 v[108:111], v[144:147], v[158:161], v[108:111]
	v_mfma_f32_16x16x32_bf16 v[132:135], v[136:139], v[178:181], v[132:135]
	v_mfma_f32_16x16x32_bf16 v[128:131], v[144:147], v[178:181], v[128:131]
	v_mfma_f32_16x16x32_bf16 v[124:127], v[136:139], v[196:199], v[124:127]
	v_mfma_f32_16x16x32_bf16 v[120:123], v[144:147], v[196:199], v[120:123]
	v_mfma_f32_16x16x32_bf16 v[116:119], v[136:139], v[204:207], v[116:119]
	v_mfma_f32_16x16x32_bf16 v[112:115], v[144:147], v[204:207], v[112:115]
	v_mfma_f32_16x16x32_bf16 v[104:107], v[140:143], v[162:165], v[104:107]
	v_mfma_f32_16x16x32_bf16 v[108:111], v[148:151], v[162:165], v[108:111]
	v_mfma_f32_16x16x32_bf16 v[132:135], v[140:143], v[182:185], v[132:135]
	v_mfma_f32_16x16x32_bf16 v[128:131], v[148:151], v[182:185], v[128:131]
	v_mfma_f32_16x16x32_bf16 v[124:127], v[140:143], v[200:203], v[124:127]
	v_mfma_f32_16x16x32_bf16 v[120:123], v[148:151], v[200:203], v[120:123]
	v_mfma_f32_16x16x32_bf16 v[116:119], v[140:143], v[208:211], v[116:119]
	v_mfma_f32_16x16x32_bf16 v[112:115], v[148:151], v[208:211], v[112:115]
	s_barrier
	s_add_i32 s5, 0, 0x1c000
	s_add_i32 s4, s4, s21
	v_lshl_add_u64 v[172:173], v[2:3], 0, s[46:47]
	s_mov_b32 m0, s4
	ds_read_b128 v[212:215], v239 offset:49152
	ds_read_b128 v[216:219], v239 offset:50176
	ds_read_b128 v[220:223], v239 offset:51200
	ds_read_b128 v[224:227], v239 offset:52224
	global_load_lds_dwordx4 v[172:173], off
	v_lshl_add_u64 v[172:173], v[2:3], 0, s[54:55]
	s_add_i32 m0, s4, 0x2000
	s_nop 0
	global_load_lds_dwordx4 v[172:173], off
	s_barrier
	s_waitcnt lgkmcnt(0)
	v_mfma_f32_16x16x32_bf16 v[100:103], v[212:215], v[158:161], v[100:103]
	v_mfma_f32_16x16x32_bf16 v[96:99], v[220:223], v[158:161], v[96:99]
	v_mfma_f32_16x16x32_bf16 v[92:95], v[212:215], v[178:181], v[92:95]
	v_mfma_f32_16x16x32_bf16 v[88:91], v[220:223], v[178:181], v[88:91]
	v_mfma_f32_16x16x32_bf16 v[84:87], v[212:215], v[196:199], v[84:87]
	v_mfma_f32_16x16x32_bf16 v[80:83], v[220:223], v[196:199], v[80:83]
	v_mfma_f32_16x16x32_bf16 v[76:79], v[212:215], v[204:207], v[76:79]
	v_mfma_f32_16x16x32_bf16 v[72:75], v[220:223], v[204:207], v[72:75]
	v_mfma_f32_16x16x32_bf16 v[100:103], v[216:219], v[162:165], v[100:103]
	v_mfma_f32_16x16x32_bf16 v[96:99], v[224:227], v[162:165], v[96:99]
	v_mfma_f32_16x16x32_bf16 v[92:95], v[216:219], v[182:185], v[92:95]
	v_mfma_f32_16x16x32_bf16 v[88:91], v[224:227], v[182:185], v[88:91]
	v_mfma_f32_16x16x32_bf16 v[84:87], v[216:219], v[200:203], v[84:87]
	v_mfma_f32_16x16x32_bf16 v[80:83], v[224:227], v[200:203], v[80:83]
	v_mfma_f32_16x16x32_bf16 v[76:79], v[216:219], v[208:211], v[76:79]
	v_mfma_f32_16x16x32_bf16 v[72:75], v[224:227], v[208:211], v[72:75]
	s_barrier
	s_mov_b32 m0, s26
	v_lshl_add_u64 v[172:173], v[166:167], 0, s[46:47]
	ds_read_b128 v[158:161], v176 offset:49152
	ds_read_b128 v[162:165], v176 offset:50176
	ds_read_b128 v[178:181], v176 offset:51200
	ds_read_b128 v[182:185], v176 offset:52224
	ds_read_b128 v[196:199], v176 offset:53248
	ds_read_b128 v[200:203], v176 offset:54272
	ds_read_b128 v[204:207], v176 offset:55296
	ds_read_b128 v[208:211], v176 offset:56320
	global_load_lds_dwordx4 v[172:173], off
	v_lshl_add_u64 v[166:167], v[166:167], 0, s[66:67]
	s_mov_b32 m0, s27
	s_nop 0
	global_load_lds_dwordx4 v[166:167], off
	s_barrier
	s_waitcnt lgkmcnt(0)
	v_mfma_f32_16x16x32_bf16 v[68:71], v[136:139], v[158:161], v[68:71]
	v_mfma_f32_16x16x32_bf16 v[64:67], v[144:147], v[158:161], v[64:67]
	v_mfma_f32_16x16x32_bf16 v[60:63], v[136:139], v[178:181], v[60:63]
	v_mfma_f32_16x16x32_bf16 v[56:59], v[144:147], v[178:181], v[56:59]
	v_mfma_f32_16x16x32_bf16 v[52:55], v[136:139], v[196:199], v[52:55]
	v_mfma_f32_16x16x32_bf16 v[48:51], v[144:147], v[196:199], v[48:51]
	v_mfma_f32_16x16x32_bf16 v[44:47], v[136:139], v[204:207], v[44:47]
	v_mfma_f32_16x16x32_bf16 v[40:43], v[144:147], v[204:207], v[40:43]
	v_mfma_f32_16x16x32_bf16 v[68:71], v[140:143], v[162:165], v[68:71]
	v_mfma_f32_16x16x32_bf16 v[64:67], v[148:151], v[162:165], v[64:67]
	v_mfma_f32_16x16x32_bf16 v[60:63], v[140:143], v[182:185], v[60:63]
	v_mfma_f32_16x16x32_bf16 v[56:59], v[148:151], v[182:185], v[56:59]
	v_mfma_f32_16x16x32_bf16 v[52:55], v[140:143], v[200:203], v[52:55]
	v_mfma_f32_16x16x32_bf16 v[48:51], v[148:151], v[200:203], v[48:51]
	v_mfma_f32_16x16x32_bf16 v[44:47], v[140:143], v[208:211], v[44:47]
	v_mfma_f32_16x16x32_bf16 v[40:43], v[148:151], v[208:211], v[40:43]
	s_barrier
	s_add_i32 s4, s5, s21
	v_lshl_add_u64 v[136:137], v[2:3], 0, s[50:51]
	s_mov_b32 m0, s4
	v_lshl_add_u64 v[2:3], v[2:3], 0, s[58:59]
	global_load_lds_dwordx4 v[136:137], off
	s_add_i32 m0, s4, 0x2000
	s_nop 0
	global_load_lds_dwordx4 v[2:3], off
	s_add_i32 s18, s18, 2
	s_add_u32 s6, s6, 0x100
	s_addc_u32 s7, s7, 0
	s_add_u32 s8, s8, 0x100
	s_addc_u32 s9, s9, 0
	s_cmp_gt_u32 s18, 5
	s_waitcnt vmcnt(6)
	s_barrier
	v_mfma_f32_16x16x32_bf16 v[36:39], v[212:215], v[158:161], v[36:39]
	v_mfma_f32_16x16x32_bf16 v[32:35], v[220:223], v[158:161], v[32:35]
	v_mfma_f32_16x16x32_bf16 v[28:31], v[212:215], v[178:181], v[28:31]
	v_mfma_f32_16x16x32_bf16 v[24:27], v[220:223], v[178:181], v[24:27]
	v_mfma_f32_16x16x32_bf16 v[20:23], v[212:215], v[196:199], v[20:23]
	v_mfma_f32_16x16x32_bf16 v[16:19], v[220:223], v[196:199], v[16:19]
	v_mfma_f32_16x16x32_bf16 v[12:15], v[212:215], v[204:207], v[12:15]
	v_mfma_f32_16x16x32_bf16 v[8:11], v[220:223], v[204:207], v[8:11]
	v_mfma_f32_16x16x32_bf16 v[36:39], v[216:219], v[162:165], v[36:39]
	v_mfma_f32_16x16x32_bf16 v[32:35], v[224:227], v[162:165], v[32:35]
	v_mfma_f32_16x16x32_bf16 v[28:31], v[216:219], v[182:185], v[28:31]
	v_mfma_f32_16x16x32_bf16 v[24:27], v[224:227], v[182:185], v[24:27]
	v_mfma_f32_16x16x32_bf16 v[20:23], v[216:219], v[200:203], v[20:23]
	v_mfma_f32_16x16x32_bf16 v[16:19], v[224:227], v[200:203], v[16:19]
	v_mfma_f32_16x16x32_bf16 v[12:15], v[216:219], v[208:211], v[12:15]
	v_mfma_f32_16x16x32_bf16 v[8:11], v[224:227], v[208:211], v[8:11]
	s_cbranch_scc1 .Ldb_MG1_xl

;     template <int KIND> __device__ __forceinline__ void run(f32x4 (&acc)[2][2][4][2], const Unit& u, int tid_in) const {
;     ...
;         if constexpr (KIND == K_MG_B) { const int r = u.aux;
;             const u32x4* gst = (const u32x4*)((unsigned char*)x + 32 * MiB) + ((size_t)(blockIdx.x * 2 + (u.ord & 1)) * 3) * 4096;
; #pragma unroll
;             for (int ai = 0; ai < 2; ++ai)
; #pragma unroll
;                 for (int mh = 0; mh < 2; ++mh) { u32x4 qa[2], qb[2];
; #pragma unroll
;                     for (int ml = 0; ml < 2; ++ml) { const int m = mh * 2 + ml; qa[ml] = gst[(size_t)r * 4096 + (ai * 4 + m) * 512 + tid]; qb[ml] = (r < 2) ? gst[(size_t)(r + 1) * 4096 + (ai * 4 + m) * 512 + tid] : qa[ml]; }
; #pragma unroll
;                     for (int ml = 0; ml < 2; ++ml) { const int m = mh * 2 + ml; int row = rbase + ai * 128 + m * 16; asm volatile("" : "+v"(row));
; #pragma unroll
;                         for (int bj = 0; bj < 2; ++bj) {
;                             const f32x4 n0 = unpack4_raw(bj == 0 ? qa[ml].x : qa[ml].z), n1 = unpack4_raw(bj == 0 ? qa[ml].y : qa[ml].w);
;                             if (r < 2) { const f32x4 d0 = unpack4_raw(bj == 0 ? qb[ml].x : qb[ml].z), d1 = unpack4_raw(bj == 0 ? qb[ml].y : qb[ml].w);
; #pragma unroll
;                                 for (int j = 0; j < 4; ++j) { acc[ai][bj][m][0][j] *= n0[j] * __builtin_amdgcn_rcpf(d0[j]); acc[ai][bj][m][1][j] *= n1[j] * __builtin_amdgcn_rcpf(d1[j]); } }
.Ldb_MG1_young:
	s_setprio 3
	s_mov_b32 s101, 2
	s_branch .Ldb_MG1_exit
.Ldb_MG1_exit:
	s_and_b32 s3, s3, 1
	s_or_b32 s3, s3, s60
	s_mul_hi_u32 s4, s3, 0x30000
	s_mul_i32 s3, s3, 0x30000
	s_add_u32 s6, s35, s3
	s_addc_u32 s7, s36, s4
	s_ashr_i32 s3, s2, 31
	s_lshl_b64 s[4:5], s[2:3], 16
	s_add_u32 s4, s6, s4
	s_addc_u32 s5, s7, s5
	v_lshlrev_b32_e32 v166, 4, v174
	s_cmp_gt_i32 s2, 1
	s_cbranch_scc1 .Lmg1_r2
	s_add_u32 s8, s4, 0x10000
	s_addc_u32 s9, s5, 0
	global_load_dwordx4 v[136:139], v166, s[4:5]
	global_load_dwordx4 v[212:215], v166, s[8:9]
	s_add_u32 s4, s4, 0x2000
	s_addc_u32 s5, s5, 0
	s_add_u32 s8, s8, 0x2000
	s_addc_u32 s9, s9, 0
	global_load_dwordx4 v[140:143], v166, s[4:5]
	global_load_dwordx4 v[216:219], v166, s[8:9]
	s_add_u32 s4, s4, 0x2000
	s_addc_u32 s5, s5, 0
	s_add_u32 s8, s8, 0x2000
	s_addc_u32 s9, s9, 0
	global_load_dwordx4 v[144:147], v166, s[4:5]
	global_load_dwordx4 v[220:223], v166, s[8:9]
	s_add_u32 s4, s4, 0x2000
	s_addc_u32 s5, s5, 0
	s_add_u32 s8, s8, 0x2000
	s_addc_u32 s9, s9, 0
	global_load_dwordx4 v[148:151], v166, s[4:5]
	global_load_dwordx4 v[224:227], v166, s[8:9]
	s_add_u32 s4, s4, 0x2000
	s_addc_u32 s5, s5, 0
	s_add_u32 s8, s8, 0x2000
	s_addc_u32 s9, s9, 0
	global_load_dwordx4 v[196:199], v166, s[4:5]
	global_load_dwordx4 v[178:181], v166, s[8:9]
	s_add_u32 s4, s4, 0x2000
	s_addc_u32 s5, s5, 0
	s_add_u32 s8, s8, 0x2000
	s_addc_u32 s9, s9, 0
	global_load_dwordx4 v[200:203], v166, s[4:5]
	global_load_dwordx4 v[182:185], v166, s[8:9]
	s_add_u32 s4, s4, 0x2000
	s_addc_u32 s5, s5, 0
	s_add_u32 s8, s8, 0x2000
	s_addc_u32 s9, s9, 0
	global_load_dwordx4 v[204:207], v166, s[4:5]
	global_load_dwordx4 v[158:161], v166, s[8:9]
	s_add_u32 s4, s4, 0x2000
	s_addc_u32 s5, s5, 0
	s_add_u32 s8, s8, 0x2000
	s_addc_u32 s9, s9, 0
	global_load_dwordx4 v[208:211], v166, s[4:5]
	global_load_dwordx4 v[162:165], v166, s[8:9]
	s_waitcnt vmcnt(14)
	v_cvt_f32_ubyte0_e32 v240, v136
	v_cvt_f32_ubyte1_e32 v241, v136
	v_cvt_f32_ubyte2_e32 v242, v136
	v_cvt_f32_ubyte3_e32 v243, v136
	v_cvt_f32_ubyte0_e32 v244, v137
	v_cvt_f32_ubyte1_e32 v245, v137
	v_cvt_f32_ubyte2_e32 v246, v137
	v_cvt_f32_ubyte3_e32 v247, v137
	v_cvt_f32_ubyte0_e32 v248, v212
	v_cvt_f32_ubyte1_e32 v249, v212
	v_cvt_f32_ubyte2_e32 v250, v212
	v_cvt_f32_ubyte3_e32 v251, v212
	v_cvt_f32_ubyte0_e32 v252, v213
	v_cvt_f32_ubyte1_e32 v253, v213
	v_cvt_f32_ubyte2_e32 v254, v213
	v_cvt_f32_ubyte3_e32 v255, v213
	v_rcp_iflag_f32_e32 v248, v248
	v_rcp_iflag_f32_e32 v249, v249
	v_rcp_iflag_f32_e32 v250, v250
	v_rcp_iflag_f32_e32 v251, v251
	v_rcp_iflag_f32_e32 v252, v252
	v_rcp_iflag_f32_e32 v253, v253
	v_rcp_iflag_f32_e32 v254, v254
	v_rcp_iflag_f32_e32 v255, v255
	v_pk_mul_f32 v[240:241], v[248:249], v[240:241]
	v_pk_mul_f32 v[242:243], v[250:251], v[242:243]
	v_pk_mul_f32 v[244:245], v[252:253], v[244:245]
	v_pk_mul_f32 v[246:247], v[254:255], v[246:247]
	v_pk_mul_f32 v[104:105], v[104:105], v[240:241]
	v_pk_mul_f32 v[106:107], v[106:107], v[242:243]
	v_pk_mul_f32 v[108:109], v[108:109], v[244:245]
	v_pk_mul_f32 v[110:111], v[110:111], v[246:247]
	v_cvt_f32_ubyte0_e32 v240, v138
	v_cvt_f32_ubyte1_e32 v241, v138
	v_cvt_f32_ubyte2_e32 v242, v138
	v_cvt_f32_ubyte3_e32 v243, v138
	v_cvt_f32_ubyte0_e32 v244, v139
	v_cvt_f32_ubyte1_e32 v245, v139
	v_cvt_f32_ubyte2_e32 v246, v139
	v_cvt_f32_ubyte3_e32 v247, v139
	v_cvt_f32_ubyte0_e32 v248, v214
	v_cvt_f32_ubyte1_e32 v249, v214
	v_cvt_f32_ubyte2_e32 v250, v214
	v_cvt_f32_ubyte3_e32 v251, v214
	v_cvt_f32_ubyte0_e32 v252, v215
	v_cvt_f32_ubyte1_e32 v253, v215
	v_cvt_f32_ubyte2_e32 v254, v215
	v_cvt_f32_ubyte3_e32 v255, v215
	v_rcp_iflag_f32_e32 v248, v248
	v_rcp_iflag_f32_e32 v249, v249
	v_rcp_iflag_f32_e32 v250, v250
	v_rcp_iflag_f32_e32 v251, v251
	v_rcp_iflag_f32_e32 v252, v252
	v_rcp_iflag_f32_e32 v253, v253
	v_rcp_iflag_f32_e32 v254, v254
	v_rcp_iflag_f32_e32 v255, v255
	v_pk_mul_f32 v[240:241], v[248:249], v[240:241]
	v_pk_mul_f32 v[242:243], v[250:251], v[242:243]
	v_pk_mul_f32 v[244:245], v[252:253], v[244:245]
	v_pk_mul_f32 v[246:247], v[254:255], v[246:247]
	v_pk_mul_f32 v[100:101], v[100:101], v[240:241]
	v_pk_mul_f32 v[102:103], v[102:103], v[242:243]
	v_pk_mul_f32 v[96:97], v[96:97], v[244:245]
	v_pk_mul_f32 v[98:99], v[98:99], v[246:247]
	s_waitcnt vmcnt(12)
	v_cvt_f32_ubyte0_e32 v240, v140
	v_cvt_f32_ubyte1_e32 v241, v140
	v_cvt_f32_ubyte2_e32 v242, v140
	v_cvt_f32_ubyte3_e32 v243, v140
	v_cvt_f32_ubyte0_e32 v244, v141
	v_cvt_f32_ubyte1_e32 v245, v141
	v_cvt_f32_ubyte2_e32 v246, v141
	v_cvt_f32_ubyte3_e32 v247, v141
	v_cvt_f32_ubyte0_e32 v248, v216
	v_cvt_f32_ubyte1_e32 v249, v216
	v_cvt_f32_ubyte2_e32 v250, v216
	v_cvt_f32_ubyte3_e32 v251, v216
	v_cvt_f32_ubyte0_e32 v252, v217
	v_cvt_f32_ubyte1_e32 v253, v217
	v_cvt_f32_ubyte2_e32 v254, v217
	v_cvt_f32_ubyte3_e32 v255, v217
	v_rcp_iflag_f32_e32 v248, v248
	v_rcp_iflag_f32_e32 v249, v249
	v_rcp_iflag_f32_e32 v250, v250
	v_rcp_iflag_f32_e32 v251, v251
	v_rcp_iflag_f32_e32 v252, v252
	v_rcp_iflag_f32_e32 v253, v253
	v_rcp_iflag_f32_e32 v254, v254
	v_rcp_iflag_f32_e32 v255, v255
	v_pk_mul_f32 v[240:241], v[248:249], v[240:241]
	v_pk_mul_f32 v[242:243], v[250:251], v[242:243]
	v_pk_mul_f32 v[244:245], v[252:253], v[244:245]
	v_pk_mul_f32 v[246:247], v[254:255], v[246:247]
	v_pk_mul_f32 v[132:133], v[132:133], v[240:241]
	v_pk_mul_f32 v[134:135], v[134:135], v[242:243]
	v_pk_mul_f32 v[128:129], v[128:129], v[244:245]
	v_pk_mul_f32 v[130:131], v[130:131], v[246:247]
	v_cvt_f32_ubyte0_e32 v240, v142
	v_cvt_f32_ubyte1_e32 v241, v142
	v_cvt_f32_ubyte2_e32 v242, v142
	v_cvt_f32_ubyte3_e32 v243, v142
	v_cvt_f32_ubyte0_e32 v244, v143
	v_cvt_f32_ubyte1_e32 v245, v143
	v_cvt_f32_ubyte2_e32 v246, v143
	v_cvt_f32_ubyte3_e32 v247, v143
	v_cvt_f32_ubyte0_e32 v248, v218
	v_cvt_f32_ubyte1_e32 v249, v218
	v_cvt_f32_ubyte2_e32 v250, v218
	v_cvt_f32_ubyte3_e32 v251, v218
	v_cvt_f32_ubyte0_e32 v252, v219
	v_cvt_f32_ubyte1_e32 v253, v219
	v_cvt_f32_ubyte2_e32 v254, v219
	v_cvt_f32_ubyte3_e32 v255, v219
	v_rcp_iflag_f32_e32 v248, v248
	v_rcp_iflag_f32_e32 v249, v249
	v_rcp_iflag_f32_e32 v250, v250
	v_rcp_iflag_f32_e32 v251, v251
	v_rcp_iflag_f32_e32 v252, v252
	v_rcp_iflag_f32_e32 v253, v253
	v_rcp_iflag_f32_e32 v254, v254
	v_rcp_iflag_f32_e32 v255, v255
	v_pk_mul_f32 v[240:241], v[248:249], v[240:241]
	v_pk_mul_f32 v[242:243], v[250:251], v[242:243]
	v_pk_mul_f32 v[244:245], v[252:253], v[244:245]
	v_pk_mul_f32 v[246:247], v[254:255], v[246:247]
	v_pk_mul_f32 v[92:93], v[92:93], v[240:241]
	v_pk_mul_f32 v[94:95], v[94:95], v[242:243]
	v_pk_mul_f32 v[88:89], v[88:89], v[244:245]
	v_pk_mul_f32 v[90:91], v[90:91], v[246:247]
	s_waitcnt vmcnt(10)
;     template <int KIND> __device__ __forceinline__ void run(f32x4 (&acc)[2][2][4][2], const Unit& u, int tid_in) const {
;     ...
;                     for (int ml = 0; ml < 2; ++ml) { const int m = mh * 2 + ml; qa[ml] = gst[(size_t)r * 4096 + (ai * 4 + m) * 512 + tid]; qb[ml] = (r < 2) ? gst[(size_t)(r + 1) * 4096 + (ai * 4 + m) * 512 + tid] : qa[ml]; }
; #pragma unroll
;                     for (int ml = 0; ml < 2; ++ml) { const int m = mh * 2 + ml; int row = rbase + ai * 128 + m * 16; asm volatile("" : "+v"(row));
; #pragma unroll
;                         for (int bj = 0; bj < 2; ++bj) {
;                             const f32x4 n0 = unpack4_raw(bj == 0 ? qa[ml].x : qa[ml].z), n1 = unpack4_raw(bj == 0 ? qa[ml].y : qa[ml].w);
;                             if (r < 2) { const f32x4 d0 = unpack4_raw(bj == 0 ? qb[ml].x : qb[ml].z), d1 = unpack4_raw(bj == 0 ? qb[ml].y : qb[ml].w);
; #pragma unroll
;                                 for (int j = 0; j < 4; ++j) { acc[ai][bj][m][0][j] *= n0[j] * __builtin_amdgcn_rcpf(d0[j]); acc[ai][bj][m][1][j] *= n1[j] * __builtin_amdgcn_rcpf(d1[j]); } }
	v_cvt_f32_ubyte0_e32 v240, v144
	v_cvt_f32_ubyte1_e32 v241, v144
	v_cvt_f32_ubyte2_e32 v242, v144
	v_cvt_f32_ubyte3_e32 v243, v144
	v_cvt_f32_ubyte0_e32 v244, v145
	v_cvt_f32_ubyte1_e32 v245, v145
	v_cvt_f32_ubyte2_e32 v246, v145
	v_cvt_f32_ubyte3_e32 v247, v145
	v_cvt_f32_ubyte0_e32 v248, v220
	v_cvt_f32_ubyte1_e32 v249, v220
	v_cvt_f32_ubyte2_e32 v250, v220
	v_cvt_f32_ubyte3_e32 v251, v220
	v_cvt_f32_ubyte0_e32 v252, v221
	v_cvt_f32_ubyte1_e32 v253, v221
	v_cvt_f32_ubyte2_e32 v254, v221
	v_cvt_f32_ubyte3_e32 v255, v221
	v_rcp_iflag_f32_e32 v248, v248
	v_rcp_iflag_f32_e32 v249, v249
	v_rcp_iflag_f32_e32 v250, v250
	v_rcp_iflag_f32_e32 v251, v251
	v_rcp_iflag_f32_e32 v252, v252
	v_rcp_iflag_f32_e32 v253, v253
	v_rcp_iflag_f32_e32 v254, v254
	v_rcp_iflag_f32_e32 v255, v255
	v_pk_mul_f32 v[240:241], v[248:249], v[240:241]
	v_pk_mul_f32 v[242:243], v[250:251], v[242:243]
	v_pk_mul_f32 v[244:245], v[252:253], v[244:245]
	v_pk_mul_f32 v[246:247], v[254:255], v[246:247]
	v_pk_mul_f32 v[124:125], v[124:125], v[240:241]
	v_pk_mul_f32 v[126:127], v[126:127], v[242:243]
	v_pk_mul_f32 v[120:121], v[120:121], v[244:245]
	v_pk_mul_f32 v[122:123], v[122:123], v[246:247]
	v_cvt_f32_ubyte0_e32 v240, v146
	v_cvt_f32_ubyte1_e32 v241, v146
	v_cvt_f32_ubyte2_e32 v242, v146
	v_cvt_f32_ubyte3_e32 v243, v146
	v_cvt_f32_ubyte0_e32 v244, v147
	v_cvt_f32_ubyte1_e32 v245, v147
	v_cvt_f32_ubyte2_e32 v246, v147
	v_cvt_f32_ubyte3_e32 v247, v147
	v_cvt_f32_ubyte0_e32 v248, v222
	v_cvt_f32_ubyte1_e32 v249, v222
	v_cvt_f32_ubyte2_e32 v250, v222
	v_cvt_f32_ubyte3_e32 v251, v222
	v_cvt_f32_ubyte0_e32 v252, v223
	v_cvt_f32_ubyte1_e32 v253, v223
	v_cvt_f32_ubyte2_e32 v254, v223
	v_cvt_f32_ubyte3_e32 v255, v223
	v_rcp_iflag_f32_e32 v248, v248
	v_rcp_iflag_f32_e32 v249, v249
	v_rcp_iflag_f32_e32 v250, v250
	v_rcp_iflag_f32_e32 v251, v251
	v_rcp_iflag_f32_e32 v252, v252
	v_rcp_iflag_f32_e32 v253, v253
	v_rcp_iflag_f32_e32 v254, v254
	v_rcp_iflag_f32_e32 v255, v255
	v_pk_mul_f32 v[240:241], v[248:249], v[240:241]
	v_pk_mul_f32 v[242:243], v[250:251], v[242:243]
	v_pk_mul_f32 v[244:245], v[252:253], v[244:245]
	v_pk_mul_f32 v[246:247], v[254:255], v[246:247]
	v_pk_mul_f32 v[84:85], v[84:85], v[240:241]
	v_pk_mul_f32 v[86:87], v[86:87], v[242:243]
	v_pk_mul_f32 v[80:81], v[80:81], v[244:245]
	v_pk_mul_f32 v[82:83], v[82:83], v[246:247]
	s_waitcnt vmcnt(8)
	v_cvt_f32_ubyte0_e32 v240, v148
	v_cvt_f32_ubyte1_e32 v241, v148
	v_cvt_f32_ubyte2_e32 v242, v148
	v_cvt_f32_ubyte3_e32 v243, v148
	v_cvt_f32_ubyte0_e32 v244, v149
	v_cvt_f32_ubyte1_e32 v245, v149
	v_cvt_f32_ubyte2_e32 v246, v149
	v_cvt_f32_ubyte3_e32 v247, v149
	v_cvt_f32_ubyte0_e32 v248, v224
	v_cvt_f32_ubyte1_e32 v249, v224
	v_cvt_f32_ubyte2_e32 v250, v224
	v_cvt_f32_ubyte3_e32 v251, v224
	v_cvt_f32_ubyte0_e32 v252, v225
	v_cvt_f32_ubyte1_e32 v253, v225
	v_cvt_f32_ubyte2_e32 v254, v225
	v_cvt_f32_ubyte3_e32 v255, v225
	v_rcp_iflag_f32_e32 v248, v248
	v_rcp_iflag_f32_e32 v249, v249
	v_rcp_iflag_f32_e32 v250, v250
	v_rcp_iflag_f32_e32 v251, v251
	v_rcp_iflag_f32_e32 v252, v252
	v_rcp_iflag_f32_e32 v253, v253
	v_rcp_iflag_f32_e32 v254, v254
	v_rcp_iflag_f32_e32 v255, v255
	v_pk_mul_f32 v[240:241], v[248:249], v[240:241]
	v_pk_mul_f32 v[242:243], v[250:251], v[242:243]
	v_pk_mul_f32 v[244:245], v[252:253], v[244:245]
	v_pk_mul_f32 v[246:247], v[254:255], v[246:247]
	v_pk_mul_f32 v[116:117], v[116:117], v[240:241]
	v_pk_mul_f32 v[118:119], v[118:119], v[242:243]
	v_pk_mul_f32 v[112:113], v[112:113], v[244:245]
	v_pk_mul_f32 v[114:115], v[114:115], v[246:247]
	v_cvt_f32_ubyte0_e32 v240, v150
	v_cvt_f32_ubyte1_e32 v241, v150
	v_cvt_f32_ubyte2_e32 v242, v150
	v_cvt_f32_ubyte3_e32 v243, v150
	v_cvt_f32_ubyte0_e32 v244, v151
	v_cvt_f32_ubyte1_e32 v245, v151
	v_cvt_f32_ubyte2_e32 v246, v151
	v_cvt_f32_ubyte3_e32 v247, v151
	v_cvt_f32_ubyte0_e32 v248, v226
	v_cvt_f32_ubyte1_e32 v249, v226
	v_cvt_f32_ubyte2_e32 v250, v226
	v_cvt_f32_ubyte3_e32 v251, v226
	v_cvt_f32_ubyte0_e32 v252, v227
	v_cvt_f32_ubyte1_e32 v253, v227
	v_cvt_f32_ubyte2_e32 v254, v227
	v_cvt_f32_ubyte3_e32 v255, v227
	v_rcp_iflag_f32_e32 v248, v248
	v_rcp_iflag_f32_e32 v249, v249
	v_rcp_iflag_f32_e32 v250, v250
	v_rcp_iflag_f32_e32 v251, v251
	v_rcp_iflag_f32_e32 v252, v252
	v_rcp_iflag_f32_e32 v253, v253
	v_rcp_iflag_f32_e32 v254, v254
	v_rcp_iflag_f32_e32 v255, v255
	v_pk_mul_f32 v[240:241], v[248:249], v[240:241]
	v_pk_mul_f32 v[242:243], v[250:251], v[242:243]
	v_pk_mul_f32 v[244:245], v[252:253], v[244:245]
	v_pk_mul_f32 v[246:247], v[254:255], v[246:247]
	v_pk_mul_f32 v[76:77], v[76:77], v[240:241]
	v_pk_mul_f32 v[78:79], v[78:79], v[242:243]
	v_pk_mul_f32 v[72:73], v[72:73], v[244:245]
	v_pk_mul_f32 v[74:75], v[74:75], v[246:247]
	s_waitcnt vmcnt(6)
;     template <int KIND> __device__ __forceinline__ void run(f32x4 (&acc)[2][2][4][2], const Unit& u, int tid_in) const {
;     ...
;                     for (int ml = 0; ml < 2; ++ml) { const int m = mh * 2 + ml; qa[ml] = gst[(size_t)r * 4096 + (ai * 4 + m) * 512 + tid]; qb[ml] = (r < 2) ? gst[(size_t)(r + 1) * 4096 + (ai * 4 + m) * 512 + tid] : qa[ml]; }
; #pragma unroll
;                     for (int ml = 0; ml < 2; ++ml) { const int m = mh * 2 + ml; int row = rbase + ai * 128 + m * 16; asm volatile("" : "+v"(row));
; #pragma unroll
;                         for (int bj = 0; bj < 2; ++bj) {
;                             const f32x4 n0 = unpack4_raw(bj == 0 ? qa[ml].x : qa[ml].z), n1 = unpack4_raw(bj == 0 ? qa[ml].y : qa[ml].w);
;                             if (r < 2) { const f32x4 d0 = unpack4_raw(bj == 0 ? qb[ml].x : qb[ml].z), d1 = unpack4_raw(bj == 0 ? qb[ml].y : qb[ml].w);
; #pragma unroll
;                                 for (int j = 0; j < 4; ++j) { acc[ai][bj][m][0][j] *= n0[j] * __builtin_amdgcn_rcpf(d0[j]); acc[ai][bj][m][1][j] *= n1[j] * __builtin_amdgcn_rcpf(d1[j]); } }
	v_cvt_f32_ubyte0_e32 v240, v196
	v_cvt_f32_ubyte1_e32 v241, v196
	v_cvt_f32_ubyte2_e32 v242, v196
	v_cvt_f32_ubyte3_e32 v243, v196
	v_cvt_f32_ubyte0_e32 v244, v197
	v_cvt_f32_ubyte1_e32 v245, v197
	v_cvt_f32_ubyte2_e32 v246, v197
	v_cvt_f32_ubyte3_e32 v247, v197
	v_cvt_f32_ubyte0_e32 v248, v178
	v_cvt_f32_ubyte1_e32 v249, v178
	v_cvt_f32_ubyte2_e32 v250, v178
	v_cvt_f32_ubyte3_e32 v251, v178
	v_cvt_f32_ubyte0_e32 v252, v179
	v_cvt_f32_ubyte1_e32 v253, v179
	v_cvt_f32_ubyte2_e32 v254, v179
	v_cvt_f32_ubyte3_e32 v255, v179
	v_rcp_iflag_f32_e32 v248, v248
	v_rcp_iflag_f32_e32 v249, v249
	v_rcp_iflag_f32_e32 v250, v250
	v_rcp_iflag_f32_e32 v251, v251
	v_rcp_iflag_f32_e32 v252, v252
	v_rcp_iflag_f32_e32 v253, v253
	v_rcp_iflag_f32_e32 v254, v254
	v_rcp_iflag_f32_e32 v255, v255
	v_pk_mul_f32 v[240:241], v[248:249], v[240:241]
	v_pk_mul_f32 v[242:243], v[250:251], v[242:243]
	v_pk_mul_f32 v[244:245], v[252:253], v[244:245]
	v_pk_mul_f32 v[246:247], v[254:255], v[246:247]
	v_pk_mul_f32 v[68:69], v[68:69], v[240:241]
	v_pk_mul_f32 v[70:71], v[70:71], v[242:243]
	v_pk_mul_f32 v[64:65], v[64:65], v[244:245]
	v_pk_mul_f32 v[66:67], v[66:67], v[246:247]
	v_cvt_f32_ubyte0_e32 v240, v198
	v_cvt_f32_ubyte1_e32 v241, v198
	v_cvt_f32_ubyte2_e32 v242, v198
	v_cvt_f32_ubyte3_e32 v243, v198
	v_cvt_f32_ubyte0_e32 v244, v199
	v_cvt_f32_ubyte1_e32 v245, v199
	v_cvt_f32_ubyte2_e32 v246, v199
	v_cvt_f32_ubyte3_e32 v247, v199
	v_cvt_f32_ubyte0_e32 v248, v180
	v_cvt_f32_ubyte1_e32 v249, v180
	v_cvt_f32_ubyte2_e32 v250, v180
	v_cvt_f32_ubyte3_e32 v251, v180
	v_cvt_f32_ubyte0_e32 v252, v181
	v_cvt_f32_ubyte1_e32 v253, v181
	v_cvt_f32_ubyte2_e32 v254, v181
	v_cvt_f32_ubyte3_e32 v255, v181
	v_rcp_iflag_f32_e32 v248, v248
	v_rcp_iflag_f32_e32 v249, v249
	v_rcp_iflag_f32_e32 v250, v250
	v_rcp_iflag_f32_e32 v251, v251
	v_rcp_iflag_f32_e32 v252, v252
	v_rcp_iflag_f32_e32 v253, v253
	v_rcp_iflag_f32_e32 v254, v254
	v_rcp_iflag_f32_e32 v255, v255
	v_pk_mul_f32 v[240:241], v[248:249], v[240:241]
	v_pk_mul_f32 v[242:243], v[250:251], v[242:243]
	v_pk_mul_f32 v[244:245], v[252:253], v[244:245]
	v_pk_mul_f32 v[246:247], v[254:255], v[246:247]
	v_pk_mul_f32 v[36:37], v[36:37], v[240:241]
	v_pk_mul_f32 v[38:39], v[38:39], v[242:243]
	v_pk_mul_f32 v[32:33], v[32:33], v[244:245]
	v_pk_mul_f32 v[34:35], v[34:35], v[246:247]
	s_waitcnt vmcnt(4)
	v_cvt_f32_ubyte0_e32 v240, v200
	v_cvt_f32_ubyte1_e32 v241, v200
	v_cvt_f32_ubyte2_e32 v242, v200
	v_cvt_f32_ubyte3_e32 v243, v200
	v_cvt_f32_ubyte0_e32 v244, v201
	v_cvt_f32_ubyte1_e32 v245, v201
	v_cvt_f32_ubyte2_e32 v246, v201
	v_cvt_f32_ubyte3_e32 v247, v201
	v_cvt_f32_ubyte0_e32 v248, v182
	v_cvt_f32_ubyte1_e32 v249, v182
	v_cvt_f32_ubyte2_e32 v250, v182
	v_cvt_f32_ubyte3_e32 v251, v182
	v_cvt_f32_ubyte0_e32 v252, v183
	v_cvt_f32_ubyte1_e32 v253, v183
	v_cvt_f32_ubyte2_e32 v254, v183
	v_cvt_f32_ubyte3_e32 v255, v183
	v_rcp_iflag_f32_e32 v248, v248
	v_rcp_iflag_f32_e32 v249, v249
	v_rcp_iflag_f32_e32 v250, v250
	v_rcp_iflag_f32_e32 v251, v251
	v_rcp_iflag_f32_e32 v252, v252
	v_rcp_iflag_f32_e32 v253, v253
	v_rcp_iflag_f32_e32 v254, v254
	v_rcp_iflag_f32_e32 v255, v255
	v_pk_mul_f32 v[240:241], v[248:249], v[240:241]
	v_pk_mul_f32 v[242:243], v[250:251], v[242:243]
	v_pk_mul_f32 v[244:245], v[252:253], v[244:245]
	v_pk_mul_f32 v[246:247], v[254:255], v[246:247]
	v_pk_mul_f32 v[60:61], v[60:61], v[240:241]
	v_pk_mul_f32 v[62:63], v[62:63], v[242:243]
	v_pk_mul_f32 v[56:57], v[56:57], v[244:245]
	v_pk_mul_f32 v[58:59], v[58:59], v[246:247]
	v_cvt_f32_ubyte0_e32 v240, v202
	v_cvt_f32_ubyte1_e32 v241, v202
	v_cvt_f32_ubyte2_e32 v242, v202
	v_cvt_f32_ubyte3_e32 v243, v202
	v_cvt_f32_ubyte0_e32 v244, v203
	v_cvt_f32_ubyte1_e32 v245, v203
	v_cvt_f32_ubyte2_e32 v246, v203
	v_cvt_f32_ubyte3_e32 v247, v203
	v_cvt_f32_ubyte0_e32 v248, v184
	v_cvt_f32_ubyte1_e32 v249, v184
	v_cvt_f32_ubyte2_e32 v250, v184
	v_cvt_f32_ubyte3_e32 v251, v184
	v_cvt_f32_ubyte0_e32 v252, v185
	v_cvt_f32_ubyte1_e32 v253, v185
	v_cvt_f32_ubyte2_e32 v254, v185
	v_cvt_f32_ubyte3_e32 v255, v185
	v_rcp_iflag_f32_e32 v248, v248
	v_rcp_iflag_f32_e32 v249, v249
	v_rcp_iflag_f32_e32 v250, v250
	v_rcp_iflag_f32_e32 v251, v251
	v_rcp_iflag_f32_e32 v252, v252
	v_rcp_iflag_f32_e32 v253, v253
	v_rcp_iflag_f32_e32 v254, v254
	v_rcp_iflag_f32_e32 v255, v255
	v_pk_mul_f32 v[240:241], v[248:249], v[240:241]
	v_pk_mul_f32 v[242:243], v[250:251], v[242:243]
	v_pk_mul_f32 v[244:245], v[252:253], v[244:245]
	v_pk_mul_f32 v[246:247], v[254:255], v[246:247]
	v_pk_mul_f32 v[28:29], v[28:29], v[240:241]
	v_pk_mul_f32 v[30:31], v[30:31], v[242:243]
	v_pk_mul_f32 v[24:25], v[24:25], v[244:245]
	v_pk_mul_f32 v[26:27], v[26:27], v[246:247]
	s_waitcnt vmcnt(2)
;     template <int KIND> __device__ __forceinline__ void run(f32x4 (&acc)[2][2][4][2], const Unit& u, int tid_in) const {
;     ...
;                             const f32x4 n0 = unpack4_raw(bj == 0 ? qa[ml].x : qa[ml].z), n1 = unpack4_raw(bj == 0 ? qa[ml].y : qa[ml].w);
;                             if (r < 2) { const f32x4 d0 = unpack4_raw(bj == 0 ? qb[ml].x : qb[ml].z), d1 = unpack4_raw(bj == 0 ? qb[ml].y : qb[ml].w);
; #pragma unroll
;                                 for (int j = 0; j < 4; ++j) { acc[ai][bj][m][0][j] *= n0[j] * __builtin_amdgcn_rcpf(d0[j]); acc[ai][bj][m][1][j] *= n1[j] * __builtin_amdgcn_rcpf(d1[j]); } }
	v_cvt_f32_ubyte0_e32 v240, v204
	v_cvt_f32_ubyte1_e32 v241, v204
	v_cvt_f32_ubyte2_e32 v242, v204
	v_cvt_f32_ubyte3_e32 v243, v204
	v_cvt_f32_ubyte0_e32 v244, v205
	v_cvt_f32_ubyte1_e32 v245, v205
	v_cvt_f32_ubyte2_e32 v246, v205
	v_cvt_f32_ubyte3_e32 v247, v205
	v_cvt_f32_ubyte0_e32 v248, v158
	v_cvt_f32_ubyte1_e32 v249, v158
	v_cvt_f32_ubyte2_e32 v250, v158
	v_cvt_f32_ubyte3_e32 v251, v158
	v_cvt_f32_ubyte0_e32 v252, v159
	v_cvt_f32_ubyte1_e32 v253, v159
	v_cvt_f32_ubyte2_e32 v254, v159
	v_cvt_f32_ubyte3_e32 v255, v159
	v_rcp_iflag_f32_e32 v248, v248
	v_rcp_iflag_f32_e32 v249, v249
	v_rcp_iflag_f32_e32 v250, v250
	v_rcp_iflag_f32_e32 v251, v251
	v_rcp_iflag_f32_e32 v252, v252
	v_rcp_iflag_f32_e32 v253, v253
	v_rcp_iflag_f32_e32 v254, v254
	v_rcp_iflag_f32_e32 v255, v255
	v_pk_mul_f32 v[240:241], v[248:249], v[240:241]
	v_pk_mul_f32 v[242:243], v[250:251], v[242:243]
	v_pk_mul_f32 v[244:245], v[252:253], v[244:245]
	v_pk_mul_f32 v[246:247], v[254:255], v[246:247]
	v_pk_mul_f32 v[52:53], v[52:53], v[240:241]
	v_pk_mul_f32 v[54:55], v[54:55], v[242:243]
	v_pk_mul_f32 v[48:49], v[48:49], v[244:245]
	v_pk_mul_f32 v[50:51], v[50:51], v[246:247]
	v_cvt_f32_ubyte0_e32 v240, v206
	v_cvt_f32_ubyte1_e32 v241, v206
	v_cvt_f32_ubyte2_e32 v242, v206
	v_cvt_f32_ubyte3_e32 v243, v206
	v_cvt_f32_ubyte0_e32 v244, v207
	v_cvt_f32_ubyte1_e32 v245, v207
	v_cvt_f32_ubyte2_e32 v246, v207
	v_cvt_f32_ubyte3_e32 v247, v207
	v_cvt_f32_ubyte0_e32 v248, v160
	v_cvt_f32_ubyte1_e32 v249, v160
	v_cvt_f32_ubyte2_e32 v250, v160
	v_cvt_f32_ubyte3_e32 v251, v160
	v_cvt_f32_ubyte0_e32 v252, v161
	v_cvt_f32_ubyte1_e32 v253, v161
	v_cvt_f32_ubyte2_e32 v254, v161
	v_cvt_f32_ubyte3_e32 v255, v161
	v_rcp_iflag_f32_e32 v248, v248
	v_rcp_iflag_f32_e32 v249, v249
	v_rcp_iflag_f32_e32 v250, v250
	v_rcp_iflag_f32_e32 v251, v251
	v_rcp_iflag_f32_e32 v252, v252
	v_rcp_iflag_f32_e32 v253, v253
	v_rcp_iflag_f32_e32 v254, v254
	v_rcp_iflag_f32_e32 v255, v255
	v_pk_mul_f32 v[240:241], v[248:249], v[240:241]
	v_pk_mul_f32 v[242:243], v[250:251], v[242:243]
	v_pk_mul_f32 v[244:245], v[252:253], v[244:245]
	v_pk_mul_f32 v[246:247], v[254:255], v[246:247]
	v_pk_mul_f32 v[20:21], v[20:21], v[240:241]
	v_pk_mul_f32 v[22:23], v[22:23], v[242:243]
	v_pk_mul_f32 v[16:17], v[16:17], v[244:245]
	v_pk_mul_f32 v[18:19], v[18:19], v[246:247]
	s_waitcnt vmcnt(0)
	v_cvt_f32_ubyte0_e32 v240, v208
	v_cvt_f32_ubyte1_e32 v241, v208
	v_cvt_f32_ubyte2_e32 v242, v208
	v_cvt_f32_ubyte3_e32 v243, v208
	v_cvt_f32_ubyte0_e32 v244, v209
	v_cvt_f32_ubyte1_e32 v245, v209
	v_cvt_f32_ubyte2_e32 v246, v209
	v_cvt_f32_ubyte3_e32 v247, v209
	v_cvt_f32_ubyte0_e32 v248, v162
	v_cvt_f32_ubyte1_e32 v249, v162
	v_cvt_f32_ubyte2_e32 v250, v162
	v_cvt_f32_ubyte3_e32 v251, v162
	v_cvt_f32_ubyte0_e32 v252, v163
	v_cvt_f32_ubyte1_e32 v253, v163
	v_cvt_f32_ubyte2_e32 v254, v163
	v_cvt_f32_ubyte3_e32 v255, v163
	v_rcp_iflag_f32_e32 v248, v248
	v_rcp_iflag_f32_e32 v249, v249
	v_rcp_iflag_f32_e32 v250, v250
	v_rcp_iflag_f32_e32 v251, v251
	v_rcp_iflag_f32_e32 v252, v252
	v_rcp_iflag_f32_e32 v253, v253
	v_rcp_iflag_f32_e32 v254, v254
	v_rcp_iflag_f32_e32 v255, v255
	v_pk_mul_f32 v[240:241], v[248:249], v[240:241]
	v_pk_mul_f32 v[242:243], v[250:251], v[242:243]
	v_pk_mul_f32 v[244:245], v[252:253], v[244:245]
	v_pk_mul_f32 v[246:247], v[254:255], v[246:247]
	v_pk_mul_f32 v[44:45], v[44:45], v[240:241]
	v_pk_mul_f32 v[46:47], v[46:47], v[242:243]
	v_pk_mul_f32 v[40:41], v[40:41], v[244:245]
	v_pk_mul_f32 v[42:43], v[42:43], v[246:247]
	v_cvt_f32_ubyte0_e32 v240, v210
	v_cvt_f32_ubyte1_e32 v241, v210
	v_cvt_f32_ubyte2_e32 v242, v210
	v_cvt_f32_ubyte3_e32 v243, v210
	v_cvt_f32_ubyte0_e32 v244, v211
	v_cvt_f32_ubyte1_e32 v245, v211
	v_cvt_f32_ubyte2_e32 v246, v211
	v_cvt_f32_ubyte3_e32 v247, v211
	v_cvt_f32_ubyte0_e32 v248, v164
	v_cvt_f32_ubyte1_e32 v249, v164
	v_cvt_f32_ubyte2_e32 v250, v164
	v_cvt_f32_ubyte3_e32 v251, v164
	v_cvt_f32_ubyte0_e32 v252, v165
	v_cvt_f32_ubyte1_e32 v253, v165
	v_cvt_f32_ubyte2_e32 v254, v165
	v_cvt_f32_ubyte3_e32 v255, v165
	v_rcp_iflag_f32_e32 v248, v248
	v_rcp_iflag_f32_e32 v249, v249
	v_rcp_iflag_f32_e32 v250, v250
	v_rcp_iflag_f32_e32 v251, v251
	v_rcp_iflag_f32_e32 v252, v252
	v_rcp_iflag_f32_e32 v253, v253
	v_rcp_iflag_f32_e32 v254, v254
	v_rcp_iflag_f32_e32 v255, v255
	v_pk_mul_f32 v[240:241], v[248:249], v[240:241]
	v_pk_mul_f32 v[242:243], v[250:251], v[242:243]
	v_pk_mul_f32 v[244:245], v[252:253], v[244:245]
	v_pk_mul_f32 v[246:247], v[254:255], v[246:247]
	v_pk_mul_f32 v[12:13], v[12:13], v[240:241]
	v_pk_mul_f32 v[14:15], v[14:15], v[242:243]
	v_pk_mul_f32 v[8:9], v[8:9], v[244:245]
	v_pk_mul_f32 v[10:11], v[10:11], v[246:247]
	s_mov_b64 s[6:7], -1
	s_branch .Lmg1_done

; #define G_STAGE(bufoff, gbase, o0, h64) do { \
;         __builtin_amdgcn_global_load_lds((const unsigned*)((const char*)(gbase) + (o0)), (LAS unsigned*)(lds + (bufoff) + ldsw), 16, 0, 0); \
;         __builtin_amdgcn_global_load_lds((const unsigned*)((const char*)(gbase) + (h64) + (o0)), (LAS unsigned*)(lds + (bufoff) + ldsw + 8192), 16, 0, 0); } while (0)
; #define G_LDA(dst, b, h) do { _Pragma("unroll") for (int m = 0; m < 4; ++m) _Pragma("unroll") for (int k = 0; k < 2; ++k) dst[m][k] = *(const LAS bf16x8*)(lds + G_SA(b, h) + aoff + m * 2048 + k * 1024); } while (0)
; #define G_LDB(dst, b, h) do { _Pragma("unroll") for (int n = 0; n < 2; ++n) _Pragma("unroll") for (int k = 0; k < 2; ++k) dst[n][k] = *(const LAS bf16x8*)(lds + G_SB(b, h) + boff + n * 2048 + k * 1024); } while (0)
; #define G_WAIT_V(n) asm volatile("s_waitcnt vmcnt(" #n ")" ::: "memory")
; #define G_WAIT_L(n) asm volatile("s_waitcnt lgkmcnt(" #n ")" ::: "memory")
; #define G_BAR __builtin_amdgcn_s_barrier()
; #define G_SCHED __builtin_amdgcn_sched_barrier(0)
;     ...
;             G_LDB(B0, 0, 0); G_SCHED; G_LDA(At, 0, 0); G_STAGE(G_SA(1, 1), a1 + chA, cA0, qA);
;             G_WAIT_L(8); G_BAR; G_WAIT_L(0); G_MMA(0, 0, At, B0); G_BAR; G_SCHED;
;             G_LDB(B1, 0, 1); G_STAGE(G_SB(0, 0), b2, cB0, qB);
;             G_BAR; G_WAIT_L(0); G_MMA(0, 1, At, B1); G_BAR;
;             G_LDA(At, 0, 1); G_STAGE(G_SA(0, 0), a2, cA0, qA);
;             G_BAR; G_WAIT_L(0); G_MMA(1, 0, At, B0); G_BAR; G_SCHED;
;             G_STAGE(G_SB(0, 1), b2 + chB, cB0, qB);
;             G_WAIT_V(6); G_BAR; G_MMA(1, 1, At, B1); G_BAR;
.LBB0_1037:
	s_add_u32 s4, s2, 0xfffc0080
	s_addc_u32 s5, s3, -1
	s_add_i32 s33, 0, 0x10000
	ds_read_b128 v[136:139], v255 offset:0
	ds_read_b128 v[140:143], v255 offset:1024
	ds_read_b128 v[144:147], v255 offset:2048
	ds_read_b128 v[148:151], v255 offset:3072
	s_cmp_eq_u32 s15, 12
	s_cselect_b32 s5, s17, s5
	s_cselect_b32 s4, s16, s4
	s_cselect_b32 s21, s19, s7
	s_cselect_b32 s20, s18, s6
	s_add_i32 m0, s24, 0xc000
	ds_read_b128 v[152:155], v182
	ds_read_b128 v[156:159], v182 offset:1024
	ds_read_b128 v[160:163], v182 offset:2048
	ds_read_b128 v[172:175], v182 offset:3072
	ds_read_b128 v[176:179], v182 offset:4096
	ds_read_b128 v[196:199], v182 offset:5120
	ds_read_b128 v[200:203], v182 offset:6144
	ds_read_b128 v[204:207], v182 offset:7168
	global_load_lds_dwordx4 v166, s[2:3]
	s_add_i32 m0, s24, 0xe000
	s_nop 0
	s_add_u32 vcc_lo, s2, s0
	s_addc_u32 vcc_hi, s3, s1
	global_load_lds_dwordx4 v166, vcc
	s_waitcnt lgkmcnt(8)
	s_barrier
	s_waitcnt lgkmcnt(0)
	v_mfma_f32_16x16x32_bf16 v[132:135], v[136:139], v[152:155], v[132:135]
	v_mfma_f32_16x16x32_bf16 v[128:131], v[144:147], v[152:155], v[128:131]
	v_mfma_f32_16x16x32_bf16 v[116:119], v[136:139], v[160:163], v[116:119]
	v_mfma_f32_16x16x32_bf16 v[112:115], v[144:147], v[160:163], v[112:115]
	v_mfma_f32_16x16x32_bf16 v[100:103], v[136:139], v[176:179], v[100:103]
	v_mfma_f32_16x16x32_bf16 v[96:99], v[144:147], v[176:179], v[96:99]
	v_mfma_f32_16x16x32_bf16 v[84:87], v[136:139], v[200:203], v[84:87]
	v_mfma_f32_16x16x32_bf16 v[80:83], v[144:147], v[200:203], v[80:83]
	v_mfma_f32_16x16x32_bf16 v[132:135], v[140:143], v[156:159], v[132:135]
	v_mfma_f32_16x16x32_bf16 v[128:131], v[148:151], v[156:159], v[128:131]
	v_mfma_f32_16x16x32_bf16 v[116:119], v[140:143], v[172:175], v[116:119]
	v_mfma_f32_16x16x32_bf16 v[112:115], v[148:151], v[172:175], v[112:115]
	v_mfma_f32_16x16x32_bf16 v[100:103], v[140:143], v[196:199], v[100:103]
	v_mfma_f32_16x16x32_bf16 v[96:99], v[148:151], v[196:199], v[96:99]
	v_mfma_f32_16x16x32_bf16 v[84:87], v[140:143], v[204:207], v[84:87]
	v_mfma_f32_16x16x32_bf16 v[80:83], v[148:151], v[204:207], v[80:83]
	s_barrier
	s_add_i32 s41, 0, 0x14000
	s_add_i32 s100, s33, s23
	s_mov_b32 m0, s100
	ds_read_b128 v[208:211], v255 offset:16384
	ds_read_b128 v[212:215], v255 offset:17408
	ds_read_b128 v[216:219], v255 offset:18432
	ds_read_b128 v[220:223], v255 offset:19456
	global_load_lds_dwordx4 v164, s[20:21]
	s_add_i32 m0, s100, 0x2000
	s_nop 0
	s_add_u32 vcc_lo, s20, s0
	s_addc_u32 vcc_hi, s21, s1
	global_load_lds_dwordx4 v164, vcc
	s_barrier
	s_waitcnt lgkmcnt(0)
	v_mfma_f32_16x16x32_bf16 v[124:127], v[208:211], v[152:155], v[124:127]
	v_mfma_f32_16x16x32_bf16 v[120:123], v[216:219], v[152:155], v[120:123]
	v_mfma_f32_16x16x32_bf16 v[108:111], v[208:211], v[160:163], v[108:111]
	v_mfma_f32_16x16x32_bf16 v[104:107], v[216:219], v[160:163], v[104:107]
	v_mfma_f32_16x16x32_bf16 v[92:95], v[208:211], v[176:179], v[92:95]
	v_mfma_f32_16x16x32_bf16 v[88:91], v[216:219], v[176:179], v[88:91]
	v_mfma_f32_16x16x32_bf16 v[76:79], v[208:211], v[200:203], v[76:79]
	v_mfma_f32_16x16x32_bf16 v[72:75], v[216:219], v[200:203], v[72:75]
	v_mfma_f32_16x16x32_bf16 v[124:127], v[212:215], v[156:159], v[124:127]
	v_mfma_f32_16x16x32_bf16 v[120:123], v[220:223], v[156:159], v[120:123]
	v_mfma_f32_16x16x32_bf16 v[108:111], v[212:215], v[172:175], v[108:111]
	v_mfma_f32_16x16x32_bf16 v[104:107], v[220:223], v[172:175], v[104:107]
	v_mfma_f32_16x16x32_bf16 v[92:95], v[212:215], v[196:199], v[92:95]
	v_mfma_f32_16x16x32_bf16 v[88:91], v[220:223], v[196:199], v[88:91]
	v_mfma_f32_16x16x32_bf16 v[76:79], v[212:215], v[204:207], v[76:79]
	v_mfma_f32_16x16x32_bf16 v[72:75], v[220:223], v[204:207], v[72:75]
	s_barrier
	s_mov_b32 m0, s24
	v_lshl_add_u64 v[224:225], s[4:5], 0, v[2:3]
	ds_read_b128 v[152:155], v182 offset:16384
	ds_read_b128 v[156:159], v182 offset:17408
	ds_read_b128 v[160:163], v182 offset:18432
	ds_read_b128 v[172:175], v182 offset:19456
	ds_read_b128 v[176:179], v182 offset:20480
	ds_read_b128 v[196:199], v182 offset:21504
	ds_read_b128 v[200:203], v182 offset:22528
	ds_read_b128 v[204:207], v182 offset:23552
	global_load_lds_dwordx4 v2, s[4:5]
	s_mov_b32 m0, s25
	s_nop 0
	s_add_u32 vcc_lo, s4, s0
	s_addc_u32 vcc_hi, s5, s1
	global_load_lds_dwordx4 v2, vcc
	s_barrier
	s_waitcnt lgkmcnt(0)
	v_mfma_f32_16x16x32_bf16 v[68:71], v[136:139], v[152:155], v[68:71]
	v_mfma_f32_16x16x32_bf16 v[64:67], v[144:147], v[152:155], v[64:67]
	v_mfma_f32_16x16x32_bf16 v[52:55], v[136:139], v[160:163], v[52:55]
	v_mfma_f32_16x16x32_bf16 v[48:51], v[144:147], v[160:163], v[48:51]
	v_mfma_f32_16x16x32_bf16 v[36:39], v[136:139], v[176:179], v[36:39]
	v_mfma_f32_16x16x32_bf16 v[32:35], v[144:147], v[176:179], v[32:35]
	v_mfma_f32_16x16x32_bf16 v[20:23], v[136:139], v[200:203], v[20:23]
	v_mfma_f32_16x16x32_bf16 v[16:19], v[144:147], v[200:203], v[16:19]
	v_mfma_f32_16x16x32_bf16 v[68:71], v[140:143], v[156:159], v[68:71]
	v_mfma_f32_16x16x32_bf16 v[64:67], v[148:151], v[156:159], v[64:67]
	v_mfma_f32_16x16x32_bf16 v[52:55], v[140:143], v[172:175], v[52:55]
	v_mfma_f32_16x16x32_bf16 v[48:51], v[148:151], v[172:175], v[48:51]
	v_mfma_f32_16x16x32_bf16 v[36:39], v[140:143], v[196:199], v[36:39]
	v_mfma_f32_16x16x32_bf16 v[32:35], v[148:151], v[196:199], v[32:35]
	v_mfma_f32_16x16x32_bf16 v[20:23], v[140:143], v[204:207], v[20:23]
	v_mfma_f32_16x16x32_bf16 v[16:19], v[148:151], v[204:207], v[16:19]
	s_barrier
	s_add_i32 s100, s41, s23
	s_mov_b32 m0, s100
	s_nop 0
	s_add_u32 vcc_lo, s20, s42
	s_addc_u32 vcc_hi, s21, s43
	global_load_lds_dwordx4 v164, vcc
	s_add_i32 m0, s100, 0x2000
	s_nop 0
	s_add_u32 vcc_lo, s20, s50
	s_addc_u32 vcc_hi, s21, s51
	global_load_lds_dwordx4 v164, vcc
	s_waitcnt vmcnt(6)
	s_barrier
; #define G_STAGE(bufoff, gbase, o0, h64) do { \
;         __builtin_amdgcn_global_load_lds((const unsigned*)((const char*)(gbase) + (o0)), (LAS unsigned*)(lds + (bufoff) + ldsw), 16, 0, 0); \
;         __builtin_amdgcn_global_load_lds((const unsigned*)((const char*)(gbase) + (h64) + (o0)), (LAS unsigned*)(lds + (bufoff) + ldsw + 8192), 16, 0, 0); } while (0)
; #define G_LDA(dst, b, h) do { _Pragma("unroll") for (int m = 0; m < 4; ++m) _Pragma("unroll") for (int k = 0; k < 2; ++k) dst[m][k] = *(const LAS bf16x8*)(lds + G_SA(b, h) + aoff + m * 2048 + k * 1024); } while (0)
; #define G_LDB(dst, b, h) do { _Pragma("unroll") for (int n = 0; n < 2; ++n) _Pragma("unroll") for (int k = 0; k < 2; ++k) dst[n][k] = *(const LAS bf16x8*)(lds + G_SB(b, h) + boff + n * 2048 + k * 1024); } while (0)
; #define G_WAIT_V(n) asm volatile("s_waitcnt vmcnt(" #n ")" ::: "memory")
; #define G_WAIT_L(n) asm volatile("s_waitcnt lgkmcnt(" #n ")" ::: "memory")
; #define G_BAR __builtin_amdgcn_s_barrier()
; #define G_SCHED __builtin_amdgcn_sched_barrier(0)
;     ...
;             G_WAIT_V(6); G_BAR; G_MMA(1, 1, At, B1); G_BAR;
;             G_LDB(B0, 1, 0); G_SCHED; G_LDA(At, 1, 0); G_STAGE(G_SA(0, 1), a2 + chA, cA0, qA);
;             G_WAIT_L(8); G_BAR; G_WAIT_L(0); G_MMA(0, 0, At, B0); G_BAR; G_SCHED;
;             G_LDB(B1, 1, 1); G_STAGE(G_SB(1, 0), b3, cB0, qB);
;             G_BAR; G_WAIT_L(0); G_MMA(0, 1, At, B1); G_BAR;
;             G_LDA(At, 1, 1); G_STAGE(G_SA(1, 0), a3, cA0, qA);
	v_mfma_f32_16x16x32_bf16 v[60:63], v[208:211], v[152:155], v[60:63]
	v_mfma_f32_16x16x32_bf16 v[56:59], v[216:219], v[152:155], v[56:59]
	v_mfma_f32_16x16x32_bf16 v[44:47], v[208:211], v[160:163], v[44:47]
	v_mfma_f32_16x16x32_bf16 v[40:43], v[216:219], v[160:163], v[40:43]
	v_mfma_f32_16x16x32_bf16 v[28:31], v[208:211], v[176:179], v[28:31]
	v_mfma_f32_16x16x32_bf16 v[24:27], v[216:219], v[176:179], v[24:27]
	v_mfma_f32_16x16x32_bf16 v[12:15], v[208:211], v[200:203], v[12:15]
	v_mfma_f32_16x16x32_bf16 v[8:11], v[216:219], v[200:203], v[8:11]
	v_mfma_f32_16x16x32_bf16 v[60:63], v[212:215], v[156:159], v[60:63]
	v_mfma_f32_16x16x32_bf16 v[56:59], v[220:223], v[156:159], v[56:59]
	v_mfma_f32_16x16x32_bf16 v[44:47], v[212:215], v[172:175], v[44:47]
	v_mfma_f32_16x16x32_bf16 v[40:43], v[220:223], v[172:175], v[40:43]
	v_mfma_f32_16x16x32_bf16 v[28:31], v[212:215], v[196:199], v[28:31]
	v_mfma_f32_16x16x32_bf16 v[24:27], v[220:223], v[196:199], v[24:27]
	v_mfma_f32_16x16x32_bf16 v[12:15], v[212:215], v[204:207], v[12:15]
	v_mfma_f32_16x16x32_bf16 v[8:11], v[220:223], v[204:207], v[8:11]
	s_barrier
	s_add_i32 s100, 0, 0x18000
	ds_read_b128 v[136:139], v255 offset:32768
	ds_read_b128 v[140:143], v255 offset:33792
	ds_read_b128 v[144:147], v255 offset:34816
	ds_read_b128 v[148:151], v255 offset:35840
	s_mov_b32 m0, s26
	ds_read_b128 v[152:155], v182 offset:32768
	ds_read_b128 v[156:159], v182 offset:33792
	ds_read_b128 v[160:163], v182 offset:34816
	ds_read_b128 v[172:175], v182 offset:35840
	ds_read_b128 v[176:179], v182 offset:36864
	ds_read_b128 v[196:199], v182 offset:37888
	ds_read_b128 v[200:203], v182 offset:38912
	ds_read_b128 v[204:207], v182 offset:39936
	s_add_u32 vcc_lo, s4, s42
	s_addc_u32 vcc_hi, s5, s43
	global_load_lds_dwordx4 v2, vcc
	s_mov_b32 m0, s27
	s_nop 0
	s_add_u32 vcc_lo, s4, s50
	s_addc_u32 vcc_hi, s5, s51
	global_load_lds_dwordx4 v2, vcc
	s_waitcnt lgkmcnt(8)
	s_barrier
	s_waitcnt lgkmcnt(0)
	v_mfma_f32_16x16x32_bf16 v[132:135], v[136:139], v[152:155], v[132:135]
	v_mfma_f32_16x16x32_bf16 v[128:131], v[144:147], v[152:155], v[128:131]
	v_mfma_f32_16x16x32_bf16 v[116:119], v[136:139], v[160:163], v[116:119]
	v_mfma_f32_16x16x32_bf16 v[112:115], v[144:147], v[160:163], v[112:115]
	v_mfma_f32_16x16x32_bf16 v[100:103], v[136:139], v[176:179], v[100:103]
	v_mfma_f32_16x16x32_bf16 v[96:99], v[144:147], v[176:179], v[96:99]
	v_mfma_f32_16x16x32_bf16 v[84:87], v[136:139], v[200:203], v[84:87]
	v_mfma_f32_16x16x32_bf16 v[80:83], v[144:147], v[200:203], v[80:83]
	v_mfma_f32_16x16x32_bf16 v[132:135], v[140:143], v[156:159], v[132:135]
	v_mfma_f32_16x16x32_bf16 v[128:131], v[148:151], v[156:159], v[128:131]
	v_mfma_f32_16x16x32_bf16 v[116:119], v[140:143], v[172:175], v[116:119]
	v_mfma_f32_16x16x32_bf16 v[112:115], v[148:151], v[172:175], v[112:115]
	v_mfma_f32_16x16x32_bf16 v[100:103], v[140:143], v[196:199], v[100:103]
	v_mfma_f32_16x16x32_bf16 v[96:99], v[148:151], v[196:199], v[96:99]
	v_mfma_f32_16x16x32_bf16 v[84:87], v[140:143], v[204:207], v[84:87]
	v_mfma_f32_16x16x32_bf16 v[80:83], v[148:151], v[204:207], v[80:83]
	s_barrier
	s_add_i32 s5, 0, 0x1c000
	s_add_i32 s4, s100, s23
	s_mov_b32 m0, s4
	ds_read_b128 v[208:211], v255 offset:49152
	ds_read_b128 v[212:215], v255 offset:50176
	ds_read_b128 v[216:219], v255 offset:51200
	ds_read_b128 v[220:223], v255 offset:52224
	s_add_u32 vcc_lo, s20, s46
	s_addc_u32 vcc_hi, s21, s47
	global_load_lds_dwordx4 v164, vcc
	s_add_i32 m0, s4, 0x2000
	s_nop 0
	s_add_u32 vcc_lo, s20, s52
	s_addc_u32 vcc_hi, s21, s53
	global_load_lds_dwordx4 v164, vcc
	s_barrier
; #define G_STAGE(bufoff, gbase, o0, h64) do { \
;         __builtin_amdgcn_global_load_lds((const unsigned*)((const char*)(gbase) + (o0)), (LAS unsigned*)(lds + (bufoff) + ldsw), 16, 0, 0); \
;         __builtin_amdgcn_global_load_lds((const unsigned*)((const char*)(gbase) + (h64) + (o0)), (LAS unsigned*)(lds + (bufoff) + ldsw + 8192), 16, 0, 0); } while (0)
; #define G_WAIT_V(n) asm volatile("s_waitcnt vmcnt(" #n ")" ::: "memory")
; #define G_WAIT_L(n) asm volatile("s_waitcnt lgkmcnt(" #n ")" ::: "memory")
; #define G_BAR __builtin_amdgcn_s_barrier()
; #define G_SCHED __builtin_amdgcn_sched_barrier(0)
;     ...
;             G_BAR; G_WAIT_L(0); G_MMA(1, 0, At, B0); G_BAR; G_SCHED;
;             G_STAGE(G_SB(1, 1), b3 + chB, cB0, qB);
;             G_WAIT_V(6); G_BAR; G_MMA(1, 1, At, B1); G_BAR;
	s_waitcnt lgkmcnt(0)
	v_mfma_f32_16x16x32_bf16 v[124:127], v[208:211], v[152:155], v[124:127]
	v_mfma_f32_16x16x32_bf16 v[120:123], v[216:219], v[152:155], v[120:123]
	v_mfma_f32_16x16x32_bf16 v[108:111], v[208:211], v[160:163], v[108:111]
	v_mfma_f32_16x16x32_bf16 v[104:107], v[216:219], v[160:163], v[104:107]
	v_mfma_f32_16x16x32_bf16 v[92:95], v[208:211], v[176:179], v[92:95]
	v_mfma_f32_16x16x32_bf16 v[88:91], v[216:219], v[176:179], v[88:91]
	v_mfma_f32_16x16x32_bf16 v[76:79], v[208:211], v[200:203], v[76:79]
	v_mfma_f32_16x16x32_bf16 v[72:75], v[216:219], v[200:203], v[72:75]
	v_mfma_f32_16x16x32_bf16 v[124:127], v[212:215], v[156:159], v[124:127]
	v_mfma_f32_16x16x32_bf16 v[120:123], v[220:223], v[156:159], v[120:123]
	v_mfma_f32_16x16x32_bf16 v[108:111], v[212:215], v[172:175], v[108:111]
	v_mfma_f32_16x16x32_bf16 v[104:107], v[220:223], v[172:175], v[104:107]
	v_mfma_f32_16x16x32_bf16 v[92:95], v[212:215], v[196:199], v[92:95]
	v_mfma_f32_16x16x32_bf16 v[88:91], v[220:223], v[196:199], v[88:91]
	v_mfma_f32_16x16x32_bf16 v[76:79], v[212:215], v[204:207], v[76:79]
	v_mfma_f32_16x16x32_bf16 v[72:75], v[220:223], v[204:207], v[72:75]
	s_barrier
	s_mov_b32 m0, s29
	v_lshl_add_u64 v[226:227], v[224:225], 0, s[46:47]
	ds_read_b128 v[152:155], v182 offset:49152
	ds_read_b128 v[156:159], v182 offset:50176
	ds_read_b128 v[160:163], v182 offset:51200
	ds_read_b128 v[172:175], v182 offset:52224
	ds_read_b128 v[176:179], v182 offset:53248
	ds_read_b128 v[196:199], v182 offset:54272
	ds_read_b128 v[200:203], v182 offset:55296
	ds_read_b128 v[204:207], v182 offset:56320
	global_load_lds_dwordx4 v[226:227], off
	v_lshl_add_u64 v[224:225], v[224:225], 0, s[52:53]
	s_mov_b32 m0, s30
	s_nop 0
	global_load_lds_dwordx4 v[224:225], off
	s_barrier
	s_waitcnt lgkmcnt(0)
	v_mfma_f32_16x16x32_bf16 v[68:71], v[136:139], v[152:155], v[68:71]
	v_mfma_f32_16x16x32_bf16 v[64:67], v[144:147], v[152:155], v[64:67]
	v_mfma_f32_16x16x32_bf16 v[52:55], v[136:139], v[160:163], v[52:55]
	v_mfma_f32_16x16x32_bf16 v[48:51], v[144:147], v[160:163], v[48:51]
	v_mfma_f32_16x16x32_bf16 v[36:39], v[136:139], v[176:179], v[36:39]
	v_mfma_f32_16x16x32_bf16 v[32:35], v[144:147], v[176:179], v[32:35]
	v_mfma_f32_16x16x32_bf16 v[20:23], v[136:139], v[200:203], v[20:23]
	v_mfma_f32_16x16x32_bf16 v[16:19], v[144:147], v[200:203], v[16:19]
	v_mfma_f32_16x16x32_bf16 v[68:71], v[140:143], v[156:159], v[68:71]
	v_mfma_f32_16x16x32_bf16 v[64:67], v[148:151], v[156:159], v[64:67]
	v_mfma_f32_16x16x32_bf16 v[52:55], v[140:143], v[172:175], v[52:55]
	v_mfma_f32_16x16x32_bf16 v[48:51], v[148:151], v[172:175], v[48:51]
	v_mfma_f32_16x16x32_bf16 v[36:39], v[140:143], v[196:199], v[36:39]
	v_mfma_f32_16x16x32_bf16 v[32:35], v[148:151], v[196:199], v[32:35]
	v_mfma_f32_16x16x32_bf16 v[20:23], v[140:143], v[204:207], v[20:23]
	v_mfma_f32_16x16x32_bf16 v[16:19], v[148:151], v[204:207], v[16:19]
	s_barrier
	s_add_i32 s4, s5, s23
	s_mov_b32 m0, s4
	s_nop 0
	s_add_u32 vcc_lo, s20, s54
	s_addc_u32 vcc_hi, s21, s55
	global_load_lds_dwordx4 v164, vcc
	s_add_i32 m0, s4, 0x2000
	s_nop 0
	s_add_u32 vcc_lo, s20, s58
	s_addc_u32 vcc_hi, s21, s59
	global_load_lds_dwordx4 v164, vcc
	s_add_i32 s15, s15, 2
	s_add_u32 s2, s2, 0x100
	s_addc_u32 s3, s3, 0
	s_add_u32 s6, s6, 0x100
	s_addc_u32 s7, s7, 0
	s_cmp_gt_u32 s15, 13
	s_waitcnt vmcnt(6)
	s_barrier
	v_mfma_f32_16x16x32_bf16 v[60:63], v[208:211], v[152:155], v[60:63]
	v_mfma_f32_16x16x32_bf16 v[56:59], v[216:219], v[152:155], v[56:59]
	v_mfma_f32_16x16x32_bf16 v[44:47], v[208:211], v[160:163], v[44:47]
	v_mfma_f32_16x16x32_bf16 v[40:43], v[216:219], v[160:163], v[40:43]
	v_mfma_f32_16x16x32_bf16 v[28:31], v[208:211], v[176:179], v[28:31]
	v_mfma_f32_16x16x32_bf16 v[24:27], v[216:219], v[176:179], v[24:27]
	v_mfma_f32_16x16x32_bf16 v[12:15], v[208:211], v[200:203], v[12:15]
	v_mfma_f32_16x16x32_bf16 v[8:11], v[216:219], v[200:203], v[8:11]
	v_mfma_f32_16x16x32_bf16 v[60:63], v[212:215], v[156:159], v[60:63]
	v_mfma_f32_16x16x32_bf16 v[56:59], v[220:223], v[156:159], v[56:59]
	v_mfma_f32_16x16x32_bf16 v[44:47], v[212:215], v[172:175], v[44:47]
	v_mfma_f32_16x16x32_bf16 v[40:43], v[220:223], v[172:175], v[40:43]
	v_mfma_f32_16x16x32_bf16 v[28:31], v[212:215], v[196:199], v[28:31]
	v_mfma_f32_16x16x32_bf16 v[24:27], v[220:223], v[196:199], v[24:27]
	v_mfma_f32_16x16x32_bf16 v[12:15], v[212:215], v[204:207], v[12:15]
	v_mfma_f32_16x16x32_bf16 v[8:11], v[220:223], v[204:207], v[8:11]
	s_cbranch_scc1 .Ldb_WOUT_xl

; __device__ __forceinline__ u32x4 pack8(const f32x4 a, const f32x4 b) { u32x4 w; w.x = cvt_pk_bf16(a[0], a[1]); w.y = cvt_pk_bf16(a[2], a[3]); w.z = cvt_pk_bf16(b[0], b[1]); w.w = cvt_pk_bf16(b[2], b[3]); return w; }
; __device__ __forceinline__ void unpack8(const u32x4 w, f32x4& a, f32x4& b) { a[0] = bf_lo(w.x); a[1] = bf_hi(w.x); a[2] = bf_lo(w.y); a[3] = bf_hi(w.y); b[0] = bf_lo(w.z); b[1] = bf_hi(w.z); b[2] = bf_lo(w.w); b[3] = bf_hi(w.w); }
; #define MEMFENCE asm volatile("" ::: "memory")
; #define XLOAD(gi, bufi) do { _Pragma("unroll") for (int ml = 0; ml < 2; ++ml) { const int m_ = ((gi) & 1) * 2 + ml; int row_ = rbase + ((gi) >> 1) * 128 + m_ * 16; asm volatile("" : "+v"(row_)); \
;                 _Pragma("unroll") for (int bj = 0; bj < 2; ++bj) xv[bufi][ml][bj] = *(const u32x4*)(xsrc + (size_t)row_ * 1024 + u.pn * 256 + bj * 128 + cl); } } while (0)
;     template <int KIND> __device__ __forceinline__ void run(f32x4 (&acc)[2][2][4][2], const Unit& u, int tid_in) const {
;     ...
;             const bf16_t* xsrc = xb0; bf16_t* xbo = (u.aux ? mg : xb0); float* sso = (u.aux ? ssq2 : ssq1);
;             u32x4 xv[2][2][2];
;     ...
;             XLOAD(0, 0);
; #pragma unroll
;             for (int gi = 0; gi < 4; ++gi) { const int ai = gi >> 1, mh = gi & 1, bufi = gi & 1;
;                 if (gi < 3) XLOAD(gi + 1, (gi + 1) & 1);
; #pragma unroll
;                 for (int ml = 0; ml < 2; ++ml) { const int m = mh * 2 + ml; int row = rbase + ai * 128 + m * 16; asm volatile("" : "+v"(row)); float ss = 0.f;
; #pragma unroll
;                     for (int bj = 0; bj < 2; ++bj) { const size_t off = (size_t)row * 1024 + u.pn * 256 + bj * 128 + cl; f32x4 x0, x1; unpack8(xv[bufi][ml][bj], x0, x1);
;                         const f32x4 o0 = x0 + acc[ai][bj][m][0], o1 = x1 + acc[ai][bj][m][1];
;                         *(u32x4*)(xbo + off) = pack8(o0, o1);
;                         ss += (o0[0] * o0[0] + o0[1] * o0[1]) + (o0[2] * o0[2] + o0[3] * o0[3]) + (o1[0] * o1[0] + o1[1] * o1[1]) + (o1[2] * o1[2] + o1[3] * o1[3]); }
;                     ss += __shfl_xor(ss, 16); ss += __shfl_xor(ss, 32);
;                     if (fq == 0) sso[((size_t)u.pn * T_TOK + row) * 4 + wc] = ss; }
;                 MEMFENCE; }
.Ldb_WOUT_young:
	s_setprio 3
	s_mov_b32 s101, 2
	s_branch .Ldb_WOUT_exit
.Ldb_WOUT_exit:
	v_mov_b32_e32 v0, v180
	s_lshl_b32 s3, s9, 8
	v_readfirstlane_b32 s2, v0
	s_bfe_u32 s15, s2, 0x20006
	s_ashr_i32 s2, s2, 2
	s_andn2_b32 s2, s2, 63
	s_add_i32 s2, s2, s3
	v_and_or_b32 v183, v0, 15, s2
	v_mov_b32_e32 v136, v183
	v_bfe_u32 v138, v0, 4, 2
	s_lshl_b32 s2, s8, 8
	v_ashrrev_i32_e32 v137, 31, v136
	v_lshlrev_b32_e32 v0, 3, v138
	v_lshlrev_b64 v[136:137], 11, v[136:137]
	s_ashr_i32 s3, s2, 31
	v_lshl_or_b32 v0, s15, 5, v0
	v_lshl_add_u64 v[136:137], s[10:11], 0, v[136:137]
	s_lshl_b64 s[20:21], s[2:3], 1
	v_lshl_add_u64 v[136:137], v[136:137], 0, s[20:21]
	v_lshlrev_b32_e32 v0, 1, v0
	v_lshl_add_u64 v[136:137], v[136:137], 0, v[0:1]
	global_load_dwordx4 v[196:199], v[136:137], off
	global_load_dwordx4 v[160:163], v[136:137], off offset:256
	v_or_b32_e32 v176, 16, v183
	v_mov_b32_e32 v136, v176
	v_or_b32_e32 v174, 32, v183
	v_ashrrev_i32_e32 v137, 31, v136
	v_lshlrev_b64 v[136:137], 11, v[136:137]
	v_lshl_add_u64 v[136:137], s[10:11], 0, v[136:137]
	v_lshl_add_u64 v[136:137], v[136:137], 0, s[20:21]
	v_lshl_add_u64 v[136:137], v[136:137], 0, v[0:1]
	global_load_dwordx4 v[156:159], v[136:137], off
	global_load_dwordx4 v[152:155], v[136:137], off offset:256
	v_mov_b32_e32 v136, v174
	v_or_b32_e32 v172, 48, v183
	v_ashrrev_i32_e32 v137, 31, v136
	v_lshlrev_b64 v[136:137], 11, v[136:137]
	v_lshl_add_u64 v[136:137], s[10:11], 0, v[136:137]
	v_lshl_add_u64 v[136:137], v[136:137], 0, s[20:21]
	v_lshl_add_u64 v[136:137], v[136:137], 0, v[0:1]
	global_load_dwordx4 v[148:151], v[136:137], off
	global_load_dwordx4 v[140:143], v[136:137], off offset:256
	v_mov_b32_e32 v136, v172
	v_cmp_eq_u32_e32 vcc, 0, v138
	v_ashrrev_i32_e32 v137, 31, v136
	v_lshlrev_b64 v[136:137], 11, v[136:137]
	v_lshl_add_u64 v[136:137], s[10:11], 0, v[136:137]
	v_lshl_add_u64 v[136:137], v[136:137], 0, s[20:21]
	v_lshl_add_u64 v[136:137], v[136:137], 0, v[0:1]
	global_load_dwordx4 v[144:147], v[136:137], off
	s_nop 0
	global_load_dwordx4 v[136:139], v[136:137], off offset:256
	v_mov_b32_e32 v178, v183
	s_waitcnt vmcnt(0)
	v_lshlrev_b32_e32 v200, 16, v196
	v_ashrrev_i32_e32 v179, 31, v178
	v_lshlrev_b64 v[184:185], 11, v[178:179]
	v_lshl_add_u64 v[184:185], s[10:11], 0, v[184:185]
	v_and_b32_e32 v201, 0xffff0000, v196
	v_lshlrev_b32_e32 v196, 16, v197
	v_and_b32_e32 v197, 0xffff0000, v197
	v_lshlrev_b32_e32 v202, 16, v198
	v_and_b32_e32 v203, 0xffff0000, v198
	v_lshlrev_b32_e32 v198, 16, v199
	v_and_b32_e32 v199, 0xffff0000, v199
	v_lshl_add_u64 v[184:185], v[184:185], 0, s[20:21]
	v_pk_add_f32 v[134:135], v[134:135], v[196:197]
	v_pk_add_f32 v[132:133], v[132:133], v[200:201]
	v_pk_add_f32 v[196:197], v[130:131], v[198:199]
	v_pk_add_f32 v[198:199], v[128:129], v[202:203]
	v_cvt_pk_bf16_f32 v128, v132, v133
	v_cvt_pk_bf16_f32 v129, v134, v135
	v_lshl_add_u64 v[184:185], v[184:185], 0, v[0:1]
	v_cvt_pk_bf16_f32 v130, v198, v199
	v_cvt_pk_bf16_f32 v131, v196, v197
	global_store_dwordx4 v[184:185], v[128:131], off
	s_nop 1
	v_mul_f32_e32 v128, v133, v133
	v_mul_f32_e32 v129, v135, v135
	v_fmac_f32_e32 v128, v132, v132
	v_fmac_f32_e32 v129, v134, v134
	v_add_f32_e32 v128, v128, v129
	v_mul_f32_e32 v129, v199, v199
	v_fmac_f32_e32 v129, v198, v198
	v_add_f32_e32 v128, v129, v128
	v_mul_f32_e32 v129, v197, v197
	v_fmac_f32_e32 v129, v196, v196
	v_add_f32_e32 v173, v129, v128
	v_lshlrev_b32_e32 v128, 16, v160
	v_and_b32_e32 v129, 0xffff0000, v160
	v_lshlrev_b32_e32 v130, 16, v161
	v_and_b32_e32 v131, 0xffff0000, v161
	v_lshlrev_b32_e32 v132, 16, v162
	v_and_b32_e32 v133, 0xffff0000, v162
	v_lshlrev_b32_e32 v134, 16, v163
	v_and_b32_e32 v135, 0xffff0000, v163
	v_pk_add_f32 v[126:127], v[126:127], v[130:131]
	v_pk_add_f32 v[124:125], v[124:125], v[128:129]
	v_pk_add_f32 v[130:131], v[120:121], v[132:133]
	v_cvt_pk_bf16_f32 v120, v124, v125
	v_cvt_pk_bf16_f32 v121, v126, v127
	v_pk_add_f32 v[128:129], v[122:123], v[134:135]
	v_cvt_pk_bf16_f32 v122, v130, v131
	s_nop 0
	v_cvt_pk_bf16_f32 v123, v128, v129
	global_store_dwordx4 v[184:185], v[120:123], off offset:256
	s_nop 1
	v_mul_f32_e32 v120, v125, v125
	v_mul_f32_e32 v121, v127, v127
	v_fmac_f32_e32 v120, v124, v124
	v_fmac_f32_e32 v121, v126, v126
	v_add_f32_e32 v120, v120, v121
	v_mul_f32_e32 v121, v131, v131
	v_fmac_f32_e32 v121, v130, v130
	v_add_f32_e32 v120, v121, v120
	v_mul_f32_e32 v121, v129, v129
	v_fmac_f32_e32 v121, v128, v128
	v_add_f32_e32 v120, v121, v120
	v_xor_b32_e32 v121, 16, v190
	v_cmp_lt_i32_e64 s[6:7], v121, v192
	v_add_f32_e32 v120, v173, v120
	s_nop 0
	v_cndmask_b32_e64 v121, v190, v121, s[6:7]
	v_lshlrev_b32_e32 v124, 2, v121
	ds_bpermute_b32 v121, v124, v120
	s_waitcnt lgkmcnt(0)
	v_add_f32_e32 v120, v120, v121
	v_xor_b32_e32 v121, 32, v190
	v_cmp_lt_i32_e64 s[6:7], v121, v192
	s_nop 1
	v_cndmask_b32_e64 v121, v190, v121, s[6:7]
	v_lshlrev_b32_e32 v125, 2, v121
	ds_bpermute_b32 v121, v125, v120
	s_and_saveexec_b64 s[6:7], vcc
	s_cbranch_execz .LBB0_1040
	s_ashr_i32 s9, s8, 31
	s_lshl_b64 s[4:5], s[8:9], 19
	s_add_u32 s4, s38, s4
	s_addc_u32 s5, s39, s5
	s_waitcnt lgkmcnt(0)
	v_add_f32_e32 v122, v120, v121
	v_lshl_add_u64 v[120:121], v[178:179], 4, s[4:5]
	s_lshl_b32 s74, s15, 2
	v_lshl_add_u64 v[120:121], v[120:121], 0, s[74:75]
	global_store_dword v[120:121], v122, off

; #define G_STAGE(bufoff, gbase, o0, h64) do { \
;         __builtin_amdgcn_global_load_lds((const unsigned*)((const char*)(gbase) + (o0)), (LAS unsigned*)(lds + (bufoff) + ldsw), 16, 0, 0); \
;         __builtin_amdgcn_global_load_lds((const unsigned*)((const char*)(gbase) + (h64) + (o0)), (LAS unsigned*)(lds + (bufoff) + ldsw + 8192), 16, 0, 0); } while (0)
; #define G_LDA(dst, b, h) do { _Pragma("unroll") for (int m = 0; m < 4; ++m) _Pragma("unroll") for (int k = 0; k < 2; ++k) dst[m][k] = *(const LAS bf16x8*)(lds + G_SA(b, h) + aoff + m * 2048 + k * 1024); } while (0)
; #define G_LDB(dst, b, h) do { _Pragma("unroll") for (int n = 0; n < 2; ++n) _Pragma("unroll") for (int k = 0; k < 2; ++k) dst[n][k] = *(const LAS bf16x8*)(lds + G_SB(b, h) + boff + n * 2048 + k * 1024); } while (0)
; #define G_WAIT_V(n) asm volatile("s_waitcnt vmcnt(" #n ")" ::: "memory")
; #define G_WAIT_L(n) asm volatile("s_waitcnt lgkmcnt(" #n ")" ::: "memory")
; #define G_BAR __builtin_amdgcn_s_barrier()
; #define G_SCHED __builtin_amdgcn_sched_barrier(0)
;     ...
;             G_LDB(B0, 0, 0); G_SCHED; G_LDA(At, 0, 0); G_STAGE(G_SA(1, 1), a1 + chA, cA0, qA);
;             G_WAIT_L(8); G_BAR; G_WAIT_L(0); G_MMA(0, 0, At, B0); G_BAR; G_SCHED;
;             G_LDB(B1, 0, 1); G_STAGE(G_SB(0, 0), b2, cB0, qB);
;             G_BAR; G_WAIT_L(0); G_MMA(0, 1, At, B1); G_BAR;
;             G_LDA(At, 0, 1); G_STAGE(G_SA(0, 0), a2, cA0, qA);
;             G_BAR; G_WAIT_L(0); G_MMA(1, 0, At, B0); G_BAR; G_SCHED;
;             G_STAGE(G_SB(0, 1), b2 + chB, cB0, qB);
;             G_WAIT_V(6); G_BAR; G_MMA(1, 1, At, B1); G_BAR;
.LBB0_1120:
	s_add_u32 s4, s2, 0xfffc0080
	s_addc_u32 s5, s3, -1
	s_add_i32 s19, 0, 0x10000
	ds_read_b128 v[140:143], v235 offset:0
	ds_read_b128 v[144:147], v235 offset:1024
	ds_read_b128 v[152:155], v235 offset:2048
	ds_read_b128 v[156:159], v235 offset:3072
	s_cmp_eq_u32 s18, 12
	s_cselect_b32 s5, s13, s5
	s_cselect_b32 s4, s12, s4
	s_cselect_b32 s41, s15, s17
	s_cselect_b32 s40, s14, s16
	s_add_i32 m0, s26, 0xc000
	ds_read_b128 v[160:163], v150
	ds_read_b128 v[164:167], v150 offset:1024
	ds_read_b128 v[172:175], v150 offset:2048
	ds_read_b128 v[176:179], v150 offset:3072
	ds_read_b128 v[180:183], v150 offset:4096
	ds_read_b128 v[196:199], v150 offset:5120
	ds_read_b128 v[200:203], v150 offset:6144
	ds_read_b128 v[204:207], v150 offset:7168
	global_load_lds_dwordx4 v138, s[2:3]
	s_add_i32 m0, s26, 0xe000
	s_nop 0
	s_add_u32 vcc_lo, s2, s0
	s_addc_u32 vcc_hi, s3, s1
	global_load_lds_dwordx4 v138, vcc
	s_waitcnt lgkmcnt(8)
	s_barrier
	s_waitcnt lgkmcnt(0)
	v_mfma_f32_16x16x32_bf16 v[132:135], v[140:143], v[160:163], v[132:135]
	v_mfma_f32_16x16x32_bf16 v[124:127], v[152:155], v[160:163], v[124:127]
	v_mfma_f32_16x16x32_bf16 v[116:119], v[140:143], v[172:175], v[116:119]
	v_mfma_f32_16x16x32_bf16 v[108:111], v[152:155], v[172:175], v[108:111]
	v_mfma_f32_16x16x32_bf16 v[100:103], v[140:143], v[180:183], v[100:103]
	v_mfma_f32_16x16x32_bf16 v[92:95], v[152:155], v[180:183], v[92:95]
	v_mfma_f32_16x16x32_bf16 v[84:87], v[140:143], v[200:203], v[84:87]
	v_mfma_f32_16x16x32_bf16 v[76:79], v[152:155], v[200:203], v[76:79]
	v_mfma_f32_16x16x32_bf16 v[132:135], v[144:147], v[164:167], v[132:135]
	v_mfma_f32_16x16x32_bf16 v[124:127], v[156:159], v[164:167], v[124:127]
	v_mfma_f32_16x16x32_bf16 v[116:119], v[144:147], v[176:179], v[116:119]
	v_mfma_f32_16x16x32_bf16 v[108:111], v[156:159], v[176:179], v[108:111]
	v_mfma_f32_16x16x32_bf16 v[100:103], v[144:147], v[196:199], v[100:103]
	v_mfma_f32_16x16x32_bf16 v[92:95], v[156:159], v[196:199], v[92:95]
	v_mfma_f32_16x16x32_bf16 v[84:87], v[144:147], v[204:207], v[84:87]
	v_mfma_f32_16x16x32_bf16 v[76:79], v[156:159], v[204:207], v[76:79]
	s_barrier
	s_add_i32 s39, 0, 0x14000
	s_add_i32 s19, s19, s21
	s_mov_b32 m0, s19
	ds_read_b128 v[208:211], v235 offset:16384
	ds_read_b128 v[212:215], v235 offset:17408
	ds_read_b128 v[216:219], v235 offset:18432
	ds_read_b128 v[220:223], v235 offset:19456
	global_load_lds_dwordx4 v2, s[40:41]
	s_add_i32 m0, s19, 0x2000
	s_nop 0
	s_add_u32 vcc_lo, s40, s0
	s_addc_u32 vcc_hi, s41, s1
	global_load_lds_dwordx4 v2, vcc
	s_barrier
	s_waitcnt lgkmcnt(0)
	v_mfma_f32_16x16x32_bf16 v[128:131], v[208:211], v[160:163], v[128:131]
	v_mfma_f32_16x16x32_bf16 v[120:123], v[216:219], v[160:163], v[120:123]
	v_mfma_f32_16x16x32_bf16 v[112:115], v[208:211], v[172:175], v[112:115]
	v_mfma_f32_16x16x32_bf16 v[104:107], v[216:219], v[172:175], v[104:107]
	v_mfma_f32_16x16x32_bf16 v[96:99], v[208:211], v[180:183], v[96:99]
	v_mfma_f32_16x16x32_bf16 v[88:91], v[216:219], v[180:183], v[88:91]
	v_mfma_f32_16x16x32_bf16 v[80:83], v[208:211], v[200:203], v[80:83]
	v_mfma_f32_16x16x32_bf16 v[72:75], v[216:219], v[200:203], v[72:75]
	v_mfma_f32_16x16x32_bf16 v[128:131], v[212:215], v[164:167], v[128:131]
	v_mfma_f32_16x16x32_bf16 v[120:123], v[220:223], v[164:167], v[120:123]
	v_mfma_f32_16x16x32_bf16 v[112:115], v[212:215], v[176:179], v[112:115]
	v_mfma_f32_16x16x32_bf16 v[104:107], v[220:223], v[176:179], v[104:107]
	v_mfma_f32_16x16x32_bf16 v[96:99], v[212:215], v[196:199], v[96:99]
	v_mfma_f32_16x16x32_bf16 v[88:91], v[220:223], v[196:199], v[88:91]
	v_mfma_f32_16x16x32_bf16 v[80:83], v[212:215], v[204:207], v[80:83]
	v_mfma_f32_16x16x32_bf16 v[72:75], v[220:223], v[204:207], v[72:75]
	s_barrier
	s_mov_b32 m0, s26
	v_lshl_add_u64 v[224:225], s[4:5], 0, v[136:137]
	ds_read_b128 v[160:163], v150 offset:16384
	ds_read_b128 v[164:167], v150 offset:17408
	ds_read_b128 v[172:175], v150 offset:18432
	ds_read_b128 v[176:179], v150 offset:19456
	ds_read_b128 v[180:183], v150 offset:20480
	ds_read_b128 v[196:199], v150 offset:21504
	ds_read_b128 v[200:203], v150 offset:22528
	ds_read_b128 v[204:207], v150 offset:23552
	global_load_lds_dwordx4 v136, s[4:5]
	s_mov_b32 m0, s27
	s_nop 0
	s_add_u32 vcc_lo, s4, s0
	s_addc_u32 vcc_hi, s5, s1
	global_load_lds_dwordx4 v136, vcc
	s_barrier
	s_waitcnt lgkmcnt(0)
	v_mfma_f32_16x16x32_bf16 v[68:71], v[140:143], v[160:163], v[68:71]
	v_mfma_f32_16x16x32_bf16 v[60:63], v[152:155], v[160:163], v[60:63]
	v_mfma_f32_16x16x32_bf16 v[52:55], v[140:143], v[172:175], v[52:55]
	v_mfma_f32_16x16x32_bf16 v[44:47], v[152:155], v[172:175], v[44:47]
	v_mfma_f32_16x16x32_bf16 v[36:39], v[140:143], v[180:183], v[36:39]
	v_mfma_f32_16x16x32_bf16 v[28:31], v[152:155], v[180:183], v[28:31]
	v_mfma_f32_16x16x32_bf16 v[20:23], v[140:143], v[200:203], v[20:23]
	v_mfma_f32_16x16x32_bf16 v[12:15], v[152:155], v[200:203], v[12:15]
	v_mfma_f32_16x16x32_bf16 v[68:71], v[144:147], v[164:167], v[68:71]
	v_mfma_f32_16x16x32_bf16 v[60:63], v[156:159], v[164:167], v[60:63]
	v_mfma_f32_16x16x32_bf16 v[52:55], v[144:147], v[176:179], v[52:55]
	v_mfma_f32_16x16x32_bf16 v[44:47], v[156:159], v[176:179], v[44:47]
	v_mfma_f32_16x16x32_bf16 v[36:39], v[144:147], v[196:199], v[36:39]
	v_mfma_f32_16x16x32_bf16 v[28:31], v[156:159], v[196:199], v[28:31]
	v_mfma_f32_16x16x32_bf16 v[20:23], v[144:147], v[204:207], v[20:23]
	v_mfma_f32_16x16x32_bf16 v[12:15], v[156:159], v[204:207], v[12:15]
	s_barrier
	s_add_i32 s100, s39, s21
	s_mov_b32 m0, s100
	s_nop 0
	s_add_u32 vcc_lo, s40, s42
	s_addc_u32 vcc_hi, s41, s43
	global_load_lds_dwordx4 v2, vcc
	s_add_i32 m0, s100, 0x2000
	s_nop 0
	s_add_u32 vcc_lo, s40, s50
	s_addc_u32 vcc_hi, s41, s51
	global_load_lds_dwordx4 v2, vcc
	s_waitcnt vmcnt(6)
	s_barrier
; #define G_STAGE(bufoff, gbase, o0, h64) do { \
;         __builtin_amdgcn_global_load_lds((const unsigned*)((const char*)(gbase) + (o0)), (LAS unsigned*)(lds + (bufoff) + ldsw), 16, 0, 0); \
;         __builtin_amdgcn_global_load_lds((const unsigned*)((const char*)(gbase) + (h64) + (o0)), (LAS unsigned*)(lds + (bufoff) + ldsw + 8192), 16, 0, 0); } while (0)
; #define G_LDA(dst, b, h) do { _Pragma("unroll") for (int m = 0; m < 4; ++m) _Pragma("unroll") for (int k = 0; k < 2; ++k) dst[m][k] = *(const LAS bf16x8*)(lds + G_SA(b, h) + aoff + m * 2048 + k * 1024); } while (0)
; #define G_LDB(dst, b, h) do { _Pragma("unroll") for (int n = 0; n < 2; ++n) _Pragma("unroll") for (int k = 0; k < 2; ++k) dst[n][k] = *(const LAS bf16x8*)(lds + G_SB(b, h) + boff + n * 2048 + k * 1024); } while (0)
; #define G_WAIT_V(n) asm volatile("s_waitcnt vmcnt(" #n ")" ::: "memory")
; #define G_WAIT_L(n) asm volatile("s_waitcnt lgkmcnt(" #n ")" ::: "memory")
; #define G_BAR __builtin_amdgcn_s_barrier()
; #define G_SCHED __builtin_amdgcn_sched_barrier(0)
;     ...
;             G_WAIT_V(6); G_BAR; G_MMA(1, 1, At, B1); G_BAR;
;             G_LDB(B0, 1, 0); G_SCHED; G_LDA(At, 1, 0); G_STAGE(G_SA(0, 1), a2 + chA, cA0, qA);
;             G_WAIT_L(8); G_BAR; G_WAIT_L(0); G_MMA(0, 0, At, B0); G_BAR; G_SCHED;
;             G_LDB(B1, 1, 1); G_STAGE(G_SB(1, 0), b3, cB0, qB);
;             G_BAR; G_WAIT_L(0); G_MMA(0, 1, At, B1); G_BAR;
;             G_LDA(At, 1, 1); G_STAGE(G_SA(1, 0), a3, cA0, qA);
	v_mfma_f32_16x16x32_bf16 v[64:67], v[208:211], v[160:163], v[64:67]
	v_mfma_f32_16x16x32_bf16 v[56:59], v[216:219], v[160:163], v[56:59]
	v_mfma_f32_16x16x32_bf16 v[48:51], v[208:211], v[172:175], v[48:51]
	v_mfma_f32_16x16x32_bf16 v[40:43], v[216:219], v[172:175], v[40:43]
	v_mfma_f32_16x16x32_bf16 v[32:35], v[208:211], v[180:183], v[32:35]
	v_mfma_f32_16x16x32_bf16 v[24:27], v[216:219], v[180:183], v[24:27]
	v_mfma_f32_16x16x32_bf16 v[16:19], v[208:211], v[200:203], v[16:19]
	v_mfma_f32_16x16x32_bf16 v[8:11], v[216:219], v[200:203], v[8:11]
	v_mfma_f32_16x16x32_bf16 v[64:67], v[212:215], v[164:167], v[64:67]
	v_mfma_f32_16x16x32_bf16 v[56:59], v[220:223], v[164:167], v[56:59]
	v_mfma_f32_16x16x32_bf16 v[48:51], v[212:215], v[176:179], v[48:51]
	v_mfma_f32_16x16x32_bf16 v[40:43], v[220:223], v[176:179], v[40:43]
	v_mfma_f32_16x16x32_bf16 v[32:35], v[212:215], v[196:199], v[32:35]
	v_mfma_f32_16x16x32_bf16 v[24:27], v[220:223], v[196:199], v[24:27]
	v_mfma_f32_16x16x32_bf16 v[16:19], v[212:215], v[204:207], v[16:19]
	v_mfma_f32_16x16x32_bf16 v[8:11], v[220:223], v[204:207], v[8:11]
	s_barrier
	s_add_i32 s100, 0, 0x18000
	ds_read_b128 v[140:143], v235 offset:32768
	ds_read_b128 v[144:147], v235 offset:33792
	ds_read_b128 v[152:155], v235 offset:34816
	ds_read_b128 v[156:159], v235 offset:35840
	s_mov_b32 m0, s29
	ds_read_b128 v[160:163], v150 offset:32768
	ds_read_b128 v[164:167], v150 offset:33792
	ds_read_b128 v[172:175], v150 offset:34816
	ds_read_b128 v[176:179], v150 offset:35840
	ds_read_b128 v[180:183], v150 offset:36864
	ds_read_b128 v[196:199], v150 offset:37888
	ds_read_b128 v[200:203], v150 offset:38912
	ds_read_b128 v[204:207], v150 offset:39936
	s_add_u32 vcc_lo, s4, s42
	s_addc_u32 vcc_hi, s5, s43
	global_load_lds_dwordx4 v136, vcc
	s_mov_b32 m0, s30
	s_nop 0
	s_add_u32 vcc_lo, s4, s50
	s_addc_u32 vcc_hi, s5, s51
	global_load_lds_dwordx4 v136, vcc
	s_waitcnt lgkmcnt(8)
	s_barrier
	s_waitcnt lgkmcnt(0)
	v_mfma_f32_16x16x32_bf16 v[132:135], v[140:143], v[160:163], v[132:135]
	v_mfma_f32_16x16x32_bf16 v[124:127], v[152:155], v[160:163], v[124:127]
	v_mfma_f32_16x16x32_bf16 v[116:119], v[140:143], v[172:175], v[116:119]
	v_mfma_f32_16x16x32_bf16 v[108:111], v[152:155], v[172:175], v[108:111]
	v_mfma_f32_16x16x32_bf16 v[100:103], v[140:143], v[180:183], v[100:103]
	v_mfma_f32_16x16x32_bf16 v[92:95], v[152:155], v[180:183], v[92:95]
	v_mfma_f32_16x16x32_bf16 v[84:87], v[140:143], v[200:203], v[84:87]
	v_mfma_f32_16x16x32_bf16 v[76:79], v[152:155], v[200:203], v[76:79]
	v_mfma_f32_16x16x32_bf16 v[132:135], v[144:147], v[164:167], v[132:135]
	v_mfma_f32_16x16x32_bf16 v[124:127], v[156:159], v[164:167], v[124:127]
	v_mfma_f32_16x16x32_bf16 v[116:119], v[144:147], v[176:179], v[116:119]
	v_mfma_f32_16x16x32_bf16 v[108:111], v[156:159], v[176:179], v[108:111]
	v_mfma_f32_16x16x32_bf16 v[100:103], v[144:147], v[196:199], v[100:103]
	v_mfma_f32_16x16x32_bf16 v[92:95], v[156:159], v[196:199], v[92:95]
	v_mfma_f32_16x16x32_bf16 v[84:87], v[144:147], v[204:207], v[84:87]
	v_mfma_f32_16x16x32_bf16 v[76:79], v[156:159], v[204:207], v[76:79]
	s_barrier
	s_add_i32 s5, 0, 0x1c000
	s_add_i32 s4, s100, s21
	s_mov_b32 m0, s4
	ds_read_b128 v[208:211], v235 offset:49152
	ds_read_b128 v[212:215], v235 offset:50176
	ds_read_b128 v[216:219], v235 offset:51200
	ds_read_b128 v[220:223], v235 offset:52224
	s_add_u32 vcc_lo, s40, s46
	s_addc_u32 vcc_hi, s41, s47
	global_load_lds_dwordx4 v2, vcc
	s_add_i32 m0, s4, 0x2000
	s_nop 0
	s_add_u32 vcc_lo, s40, s52
	s_addc_u32 vcc_hi, s41, s53
	global_load_lds_dwordx4 v2, vcc
	s_barrier
; #define G_STAGE(bufoff, gbase, o0, h64) do { \
;         __builtin_amdgcn_global_load_lds((const unsigned*)((const char*)(gbase) + (o0)), (LAS unsigned*)(lds + (bufoff) + ldsw), 16, 0, 0); \
;         __builtin_amdgcn_global_load_lds((const unsigned*)((const char*)(gbase) + (h64) + (o0)), (LAS unsigned*)(lds + (bufoff) + ldsw + 8192), 16, 0, 0); } while (0)
; #define G_WAIT_V(n) asm volatile("s_waitcnt vmcnt(" #n ")" ::: "memory")
; #define G_WAIT_L(n) asm volatile("s_waitcnt lgkmcnt(" #n ")" ::: "memory")
; #define G_BAR __builtin_amdgcn_s_barrier()
; #define G_SCHED __builtin_amdgcn_sched_barrier(0)
;     ...
;             G_BAR; G_WAIT_L(0); G_MMA(1, 0, At, B0); G_BAR; G_SCHED;
;             G_STAGE(G_SB(1, 1), b3 + chB, cB0, qB);
;             G_WAIT_V(6); G_BAR; G_MMA(1, 1, At, B1); G_BAR;
	s_waitcnt lgkmcnt(0)
	v_mfma_f32_16x16x32_bf16 v[128:131], v[208:211], v[160:163], v[128:131]
	v_mfma_f32_16x16x32_bf16 v[120:123], v[216:219], v[160:163], v[120:123]
	v_mfma_f32_16x16x32_bf16 v[112:115], v[208:211], v[172:175], v[112:115]
	v_mfma_f32_16x16x32_bf16 v[104:107], v[216:219], v[172:175], v[104:107]
	v_mfma_f32_16x16x32_bf16 v[96:99], v[208:211], v[180:183], v[96:99]
	v_mfma_f32_16x16x32_bf16 v[88:91], v[216:219], v[180:183], v[88:91]
	v_mfma_f32_16x16x32_bf16 v[80:83], v[208:211], v[200:203], v[80:83]
	v_mfma_f32_16x16x32_bf16 v[72:75], v[216:219], v[200:203], v[72:75]
	v_mfma_f32_16x16x32_bf16 v[128:131], v[212:215], v[164:167], v[128:131]
	v_mfma_f32_16x16x32_bf16 v[120:123], v[220:223], v[164:167], v[120:123]
	v_mfma_f32_16x16x32_bf16 v[112:115], v[212:215], v[176:179], v[112:115]
	v_mfma_f32_16x16x32_bf16 v[104:107], v[220:223], v[176:179], v[104:107]
	v_mfma_f32_16x16x32_bf16 v[96:99], v[212:215], v[196:199], v[96:99]
	v_mfma_f32_16x16x32_bf16 v[88:91], v[220:223], v[196:199], v[88:91]
	v_mfma_f32_16x16x32_bf16 v[80:83], v[212:215], v[204:207], v[80:83]
	v_mfma_f32_16x16x32_bf16 v[72:75], v[220:223], v[204:207], v[72:75]
	s_barrier
	s_mov_b32 m0, s31
	v_lshl_add_u64 v[226:227], v[224:225], 0, s[46:47]
	ds_read_b128 v[160:163], v150 offset:49152
	ds_read_b128 v[164:167], v150 offset:50176
	ds_read_b128 v[172:175], v150 offset:51200
	ds_read_b128 v[176:179], v150 offset:52224
	ds_read_b128 v[180:183], v150 offset:53248
	ds_read_b128 v[196:199], v150 offset:54272
	ds_read_b128 v[200:203], v150 offset:55296
	ds_read_b128 v[204:207], v150 offset:56320
	global_load_lds_dwordx4 v[226:227], off
	v_lshl_add_u64 v[224:225], v[224:225], 0, s[52:53]
	s_mov_b32 m0, s34
	s_nop 0
	global_load_lds_dwordx4 v[224:225], off
	s_barrier
	s_waitcnt lgkmcnt(0)
	v_mfma_f32_16x16x32_bf16 v[68:71], v[140:143], v[160:163], v[68:71]
	v_mfma_f32_16x16x32_bf16 v[60:63], v[152:155], v[160:163], v[60:63]
	v_mfma_f32_16x16x32_bf16 v[52:55], v[140:143], v[172:175], v[52:55]
	v_mfma_f32_16x16x32_bf16 v[44:47], v[152:155], v[172:175], v[44:47]
	v_mfma_f32_16x16x32_bf16 v[36:39], v[140:143], v[180:183], v[36:39]
	v_mfma_f32_16x16x32_bf16 v[28:31], v[152:155], v[180:183], v[28:31]
	v_mfma_f32_16x16x32_bf16 v[20:23], v[140:143], v[200:203], v[20:23]
	v_mfma_f32_16x16x32_bf16 v[12:15], v[152:155], v[200:203], v[12:15]
	v_mfma_f32_16x16x32_bf16 v[68:71], v[144:147], v[164:167], v[68:71]
	v_mfma_f32_16x16x32_bf16 v[60:63], v[156:159], v[164:167], v[60:63]
	v_mfma_f32_16x16x32_bf16 v[52:55], v[144:147], v[176:179], v[52:55]
	v_mfma_f32_16x16x32_bf16 v[44:47], v[156:159], v[176:179], v[44:47]
	v_mfma_f32_16x16x32_bf16 v[36:39], v[144:147], v[196:199], v[36:39]
	v_mfma_f32_16x16x32_bf16 v[28:31], v[156:159], v[196:199], v[28:31]
	v_mfma_f32_16x16x32_bf16 v[20:23], v[144:147], v[204:207], v[20:23]
	v_mfma_f32_16x16x32_bf16 v[12:15], v[156:159], v[204:207], v[12:15]
	s_barrier
	s_add_i32 s4, s5, s21
	s_mov_b32 m0, s4
	s_nop 0
	s_add_u32 vcc_lo, s40, s54
	s_addc_u32 vcc_hi, s41, s55
	global_load_lds_dwordx4 v2, vcc
	s_add_i32 m0, s4, 0x2000
	s_nop 0
	s_add_u32 vcc_lo, s40, s58
	s_addc_u32 vcc_hi, s41, s59
	global_load_lds_dwordx4 v2, vcc
	s_add_i32 s18, s18, 2
	s_add_u32 s2, s2, 0x100
	s_addc_u32 s3, s3, 0
	s_add_u32 s16, s16, 0x100
	s_addc_u32 s17, s17, 0
	s_cmp_gt_u32 s18, 13
	s_waitcnt vmcnt(6)
	s_barrier
	v_mfma_f32_16x16x32_bf16 v[64:67], v[208:211], v[160:163], v[64:67]
	v_mfma_f32_16x16x32_bf16 v[56:59], v[216:219], v[160:163], v[56:59]
	v_mfma_f32_16x16x32_bf16 v[48:51], v[208:211], v[172:175], v[48:51]
	v_mfma_f32_16x16x32_bf16 v[40:43], v[216:219], v[172:175], v[40:43]
	v_mfma_f32_16x16x32_bf16 v[32:35], v[208:211], v[180:183], v[32:35]
	v_mfma_f32_16x16x32_bf16 v[24:27], v[216:219], v[180:183], v[24:27]
	v_mfma_f32_16x16x32_bf16 v[16:19], v[208:211], v[200:203], v[16:19]
	v_mfma_f32_16x16x32_bf16 v[8:11], v[216:219], v[200:203], v[8:11]
	v_mfma_f32_16x16x32_bf16 v[64:67], v[212:215], v[164:167], v[64:67]
	v_mfma_f32_16x16x32_bf16 v[56:59], v[220:223], v[164:167], v[56:59]
	v_mfma_f32_16x16x32_bf16 v[48:51], v[212:215], v[176:179], v[48:51]
	v_mfma_f32_16x16x32_bf16 v[40:43], v[220:223], v[176:179], v[40:43]
	v_mfma_f32_16x16x32_bf16 v[32:35], v[212:215], v[196:199], v[32:35]
	v_mfma_f32_16x16x32_bf16 v[24:27], v[220:223], v[196:199], v[24:27]
	v_mfma_f32_16x16x32_bf16 v[16:19], v[212:215], v[204:207], v[16:19]
	v_mfma_f32_16x16x32_bf16 v[8:11], v[220:223], v[204:207], v[8:11]
	s_cbranch_scc1 .Ldb_FFI_xl

; __device__ __forceinline__ float sigmoidf_(float v) { return __builtin_amdgcn_rcpf(1.0f + __expf(-v)); }
; __device__ __forceinline__ u32x4 pack8(const f32x4 a, const f32x4 b) { u32x4 w; w.x = cvt_pk_bf16(a[0], a[1]); w.y = cvt_pk_bf16(a[2], a[3]); w.z = cvt_pk_bf16(b[0], b[1]); w.w = cvt_pk_bf16(b[2], b[3]); return w; }
; #define MEMFENCE asm volatile("" ::: "memory")
;     template <int KIND> __device__ __forceinline__ void run(f32x4 (&acc)[2][2][4][2], const Unit& u, int tid_in) const {
;     ...
;         if constexpr (KIND == K_FFI) { bf16_t* act = zb; float rs[8]; get_rs(u, wr, fr, rs);
; #pragma unroll
;             for (int ai = 0; ai < 2; ++ai)
; #pragma unroll
;                 for (int m = 0; m < 4; ++m) { int row = rbase + ai * 128 + m * 16; asm volatile("" : "+v"(row)); const float r = rs[ai * 4 + m]; f32x4 o[2];
; #pragma unroll
;                     for (int n = 0; n < 2; ++n) { const f32x4 g = acc[ai][0][m][n] * r, v = acc[ai][1][m][n] * r;
; #pragma unroll
;                         for (int j = 0; j < 4; ++j) o[n][j] = g[j] * sigmoidf_(g[j]) * v[j]; }
;                     *(u32x4*)(act + (size_t)row * ZW + u.pn * 128 + cl) = pack8(o[0], o[1]); MEMFENCE; }
.Ldb_FFI_young:
	s_setprio 3
	s_mov_b32 s101, 2
	s_branch .Ldb_FFI_exit
.Ldb_FFI_exit:
	v_readfirstlane_b32 s2, v148
	s_lshr_b32 s4, s2, 1
	s_and_b32 s4, s4, 0x60
	v_lshrrev_b32_e32 v0, 1, v148
	v_and_or_b32 v0, v0, 24, s4
	v_and_b32_e32 v140, 15, v148
	s_lshl_b32 s4, s38, 10
	s_and_b32 s3, s2, 0xffffff00
	s_add_i32 s4, s4, s3
	v_lshl_add_u32 v141, v140, 2, s4
	v_add_u32_e32 v141, 0x20010, v141
	ds_read_b32 v240, v141
	ds_read_b32 v242, v141 offset:64
	ds_read_b32 v244, v141 offset:128
	ds_read_b32 v246, v141 offset:192
	ds_read_b32 v248, v141 offset:512
	ds_read_b32 v250, v141 offset:576
	ds_read_b32 v252, v141 offset:640
	ds_read_b32 v254, v141 offset:704
	s_ashr_i32 s3, s2, 2
	s_andn2_b32 s3, s3, 63
	v_or_b32_e32 v140, s3, v140
	v_lshl_add_u32 v140, s37, 8, v140
	v_mul_lo_u32 v140, v140, s76
	s_lshl_b32 s3, s33, 8
	v_lshlrev_b32_e32 v0, 1, v0
	v_add3_u32 v140, v140, v0, s3
	s_mov_b64 s[4:5], s[6:7]
	s_mov_b32 s2, 0xbfb8aa3b
	s_mov_b32 s100, 1.0
	s_waitcnt lgkmcnt(0)
	v_pk_mul_f32 v[132:133], v[132:133], v[240:241] op_sel_hi:[1,0]
	v_pk_mul_f32 v[128:129], v[128:129], v[240:241] op_sel_hi:[1,0]
	v_pk_mul_f32 v[216:217], v[132:133], s[2:3] op_sel_hi:[1,0]
	v_pk_mul_f32 v[134:135], v[134:135], v[240:241] op_sel_hi:[1,0]
	v_pk_mul_f32 v[130:131], v[130:131], v[240:241] op_sel_hi:[1,0]
	v_pk_mul_f32 v[218:219], v[134:135], s[2:3] op_sel_hi:[1,0]
	v_pk_mul_f32 v[124:125], v[124:125], v[240:241] op_sel_hi:[1,0]
	v_pk_mul_f32 v[120:121], v[120:121], v[240:241] op_sel_hi:[1,0]
	v_pk_mul_f32 v[220:221], v[124:125], s[2:3] op_sel_hi:[1,0]
	v_pk_mul_f32 v[126:127], v[126:127], v[240:241] op_sel_hi:[1,0]
	v_pk_mul_f32 v[122:123], v[122:123], v[240:241] op_sel_hi:[1,0]
	v_pk_mul_f32 v[222:223], v[126:127], s[2:3] op_sel_hi:[1,0]
	v_exp_f32_e32 v216, v216
	v_exp_f32_e32 v217, v217
	v_exp_f32_e32 v218, v218
	v_exp_f32_e32 v219, v219
	v_exp_f32_e32 v220, v220
	v_exp_f32_e32 v221, v221
	v_exp_f32_e32 v222, v222
	v_exp_f32_e32 v223, v223
	v_pk_add_f32 v[216:217], v[216:217], s[100:101] op_sel_hi:[1,0]
	v_pk_add_f32 v[218:219], v[218:219], s[100:101] op_sel_hi:[1,0]
	v_pk_add_f32 v[220:221], v[220:221], s[100:101] op_sel_hi:[1,0]
	v_pk_add_f32 v[222:223], v[222:223], s[100:101] op_sel_hi:[1,0]
	v_rcp_f32_e32 v216, v216
	v_rcp_f32_e32 v217, v217
	v_rcp_f32_e32 v218, v218
	v_rcp_f32_e32 v219, v219
	v_rcp_f32_e32 v220, v220
	v_rcp_f32_e32 v221, v221
	v_rcp_f32_e32 v222, v222
	v_rcp_f32_e32 v223, v223
	v_pk_mul_f32 v[132:133], v[132:133], v[216:217]
	v_pk_mul_f32 v[134:135], v[134:135], v[218:219]
	v_pk_mul_f32 v[124:125], v[124:125], v[220:221]
	v_pk_mul_f32 v[126:127], v[126:127], v[222:223]
	v_pk_mul_f32 v[132:133], v[132:133], v[128:129]
	v_pk_mul_f32 v[134:135], v[134:135], v[130:131]
	v_pk_mul_f32 v[124:125], v[124:125], v[120:121]
	v_pk_mul_f32 v[126:127], v[126:127], v[122:123]
	v_cvt_pk_bf16_f32 v236, v132, v133
	v_cvt_pk_bf16_f32 v237, v134, v135
	v_cvt_pk_bf16_f32 v238, v124, v125
	v_cvt_pk_bf16_f32 v239, v126, v127
	global_store_dwordx4 v140, v[236:239], s[4:5]
	s_add_u32 s4, s4, 0x16000
	s_addc_u32 s5, s5, 0
	v_pk_mul_f32 v[116:117], v[116:117], v[242:243] op_sel_hi:[1,0]
	v_pk_mul_f32 v[112:113], v[112:113], v[242:243] op_sel_hi:[1,0]
	v_pk_mul_f32 v[216:217], v[116:117], s[2:3] op_sel_hi:[1,0]
	v_pk_mul_f32 v[118:119], v[118:119], v[242:243] op_sel_hi:[1,0]
	v_pk_mul_f32 v[114:115], v[114:115], v[242:243] op_sel_hi:[1,0]
	v_pk_mul_f32 v[218:219], v[118:119], s[2:3] op_sel_hi:[1,0]
	v_pk_mul_f32 v[108:109], v[108:109], v[242:243] op_sel_hi:[1,0]
	v_pk_mul_f32 v[104:105], v[104:105], v[242:243] op_sel_hi:[1,0]
	v_pk_mul_f32 v[220:221], v[108:109], s[2:3] op_sel_hi:[1,0]
	v_pk_mul_f32 v[110:111], v[110:111], v[242:243] op_sel_hi:[1,0]
	v_pk_mul_f32 v[106:107], v[106:107], v[242:243] op_sel_hi:[1,0]
	v_pk_mul_f32 v[222:223], v[110:111], s[2:3] op_sel_hi:[1,0]
	v_exp_f32_e32 v216, v216
	v_exp_f32_e32 v217, v217
	v_exp_f32_e32 v218, v218
	v_exp_f32_e32 v219, v219
	v_exp_f32_e32 v220, v220
	v_exp_f32_e32 v221, v221
	v_exp_f32_e32 v222, v222
	v_exp_f32_e32 v223, v223
	v_pk_add_f32 v[216:217], v[216:217], s[100:101] op_sel_hi:[1,0]
	v_pk_add_f32 v[218:219], v[218:219], s[100:101] op_sel_hi:[1,0]
	v_pk_add_f32 v[220:221], v[220:221], s[100:101] op_sel_hi:[1,0]
	v_pk_add_f32 v[222:223], v[222:223], s[100:101] op_sel_hi:[1,0]
	v_rcp_f32_e32 v216, v216
	v_rcp_f32_e32 v217, v217
	v_rcp_f32_e32 v218, v218
	v_rcp_f32_e32 v219, v219
	v_rcp_f32_e32 v220, v220
	v_rcp_f32_e32 v221, v221
	v_rcp_f32_e32 v222, v222
	v_rcp_f32_e32 v223, v223
	v_pk_mul_f32 v[116:117], v[116:117], v[216:217]
	v_pk_mul_f32 v[118:119], v[118:119], v[218:219]
	v_pk_mul_f32 v[108:109], v[108:109], v[220:221]
	v_pk_mul_f32 v[110:111], v[110:111], v[222:223]
	v_pk_mul_f32 v[116:117], v[116:117], v[112:113]
	v_pk_mul_f32 v[118:119], v[118:119], v[114:115]
	v_pk_mul_f32 v[108:109], v[108:109], v[104:105]
	v_pk_mul_f32 v[110:111], v[110:111], v[106:107]
	v_cvt_pk_bf16_f32 v236, v116, v117
	v_cvt_pk_bf16_f32 v237, v118, v119
	v_cvt_pk_bf16_f32 v238, v108, v109
	v_cvt_pk_bf16_f32 v239, v110, v111
	global_store_dwordx4 v140, v[236:239], s[4:5]
	s_add_u32 s4, s4, 0x16000
	s_addc_u32 s5, s5, 0
	v_pk_mul_f32 v[100:101], v[100:101], v[244:245] op_sel_hi:[1,0]
	v_pk_mul_f32 v[96:97], v[96:97], v[244:245] op_sel_hi:[1,0]
	v_pk_mul_f32 v[216:217], v[100:101], s[2:3] op_sel_hi:[1,0]
	v_pk_mul_f32 v[102:103], v[102:103], v[244:245] op_sel_hi:[1,0]
	v_pk_mul_f32 v[98:99], v[98:99], v[244:245] op_sel_hi:[1,0]
	v_pk_mul_f32 v[218:219], v[102:103], s[2:3] op_sel_hi:[1,0]
	v_pk_mul_f32 v[92:93], v[92:93], v[244:245] op_sel_hi:[1,0]
	v_pk_mul_f32 v[88:89], v[88:89], v[244:245] op_sel_hi:[1,0]
; __device__ __forceinline__ float sigmoidf_(float v) { return __builtin_amdgcn_rcpf(1.0f + __expf(-v)); }
; __device__ __forceinline__ u32x4 pack8(const f32x4 a, const f32x4 b) { u32x4 w; w.x = cvt_pk_bf16(a[0], a[1]); w.y = cvt_pk_bf16(a[2], a[3]); w.z = cvt_pk_bf16(b[0], b[1]); w.w = cvt_pk_bf16(b[2], b[3]); return w; }
; #define MEMFENCE asm volatile("" ::: "memory")
;     template <int KIND> __device__ __forceinline__ void run(f32x4 (&acc)[2][2][4][2], const Unit& u, int tid_in) const {
;     ...
;                 for (int m = 0; m < 4; ++m) { int row = rbase + ai * 128 + m * 16; asm volatile("" : "+v"(row)); const float r = rs[ai * 4 + m]; f32x4 o[2];
; #pragma unroll
;                     for (int n = 0; n < 2; ++n) { const f32x4 g = acc[ai][0][m][n] * r, v = acc[ai][1][m][n] * r;
; #pragma unroll
;                         for (int j = 0; j < 4; ++j) o[n][j] = g[j] * sigmoidf_(g[j]) * v[j]; }
;                     *(u32x4*)(act + (size_t)row * ZW + u.pn * 128 + cl) = pack8(o[0], o[1]); MEMFENCE; }
	v_pk_mul_f32 v[220:221], v[92:93], s[2:3] op_sel_hi:[1,0]
	v_pk_mul_f32 v[94:95], v[94:95], v[244:245] op_sel_hi:[1,0]
	v_pk_mul_f32 v[90:91], v[90:91], v[244:245] op_sel_hi:[1,0]
	v_pk_mul_f32 v[222:223], v[94:95], s[2:3] op_sel_hi:[1,0]
	v_exp_f32_e32 v216, v216
	v_exp_f32_e32 v217, v217
	v_exp_f32_e32 v218, v218
	v_exp_f32_e32 v219, v219
	v_exp_f32_e32 v220, v220
	v_exp_f32_e32 v221, v221
	v_exp_f32_e32 v222, v222
	v_exp_f32_e32 v223, v223
	v_pk_add_f32 v[216:217], v[216:217], s[100:101] op_sel_hi:[1,0]
	v_pk_add_f32 v[218:219], v[218:219], s[100:101] op_sel_hi:[1,0]
	v_pk_add_f32 v[220:221], v[220:221], s[100:101] op_sel_hi:[1,0]
	v_pk_add_f32 v[222:223], v[222:223], s[100:101] op_sel_hi:[1,0]
	v_rcp_f32_e32 v216, v216
	v_rcp_f32_e32 v217, v217
	v_rcp_f32_e32 v218, v218
	v_rcp_f32_e32 v219, v219
	v_rcp_f32_e32 v220, v220
	v_rcp_f32_e32 v221, v221
	v_rcp_f32_e32 v222, v222
	v_rcp_f32_e32 v223, v223
	v_pk_mul_f32 v[100:101], v[100:101], v[216:217]
	v_pk_mul_f32 v[102:103], v[102:103], v[218:219]
	v_pk_mul_f32 v[92:93], v[92:93], v[220:221]
	v_pk_mul_f32 v[94:95], v[94:95], v[222:223]
	v_pk_mul_f32 v[100:101], v[100:101], v[96:97]
	v_pk_mul_f32 v[102:103], v[102:103], v[98:99]
	v_pk_mul_f32 v[92:93], v[92:93], v[88:89]
	v_pk_mul_f32 v[94:95], v[94:95], v[90:91]
	v_cvt_pk_bf16_f32 v236, v100, v101
	v_cvt_pk_bf16_f32 v237, v102, v103
	v_cvt_pk_bf16_f32 v238, v92, v93
	v_cvt_pk_bf16_f32 v239, v94, v95
	global_store_dwordx4 v140, v[236:239], s[4:5]
	s_add_u32 s4, s4, 0x16000
	s_addc_u32 s5, s5, 0
	v_pk_mul_f32 v[84:85], v[84:85], v[246:247] op_sel_hi:[1,0]
	v_pk_mul_f32 v[80:81], v[80:81], v[246:247] op_sel_hi:[1,0]
	v_pk_mul_f32 v[216:217], v[84:85], s[2:3] op_sel_hi:[1,0]
	v_pk_mul_f32 v[86:87], v[86:87], v[246:247] op_sel_hi:[1,0]
	v_pk_mul_f32 v[82:83], v[82:83], v[246:247] op_sel_hi:[1,0]
	v_pk_mul_f32 v[218:219], v[86:87], s[2:3] op_sel_hi:[1,0]
	v_pk_mul_f32 v[76:77], v[76:77], v[246:247] op_sel_hi:[1,0]
	v_pk_mul_f32 v[72:73], v[72:73], v[246:247] op_sel_hi:[1,0]
	v_pk_mul_f32 v[220:221], v[76:77], s[2:3] op_sel_hi:[1,0]
	v_pk_mul_f32 v[78:79], v[78:79], v[246:247] op_sel_hi:[1,0]
	v_pk_mul_f32 v[74:75], v[74:75], v[246:247] op_sel_hi:[1,0]
	v_pk_mul_f32 v[222:223], v[78:79], s[2:3] op_sel_hi:[1,0]
	v_exp_f32_e32 v216, v216
	v_exp_f32_e32 v217, v217
	v_exp_f32_e32 v218, v218
	v_exp_f32_e32 v219, v219
	v_exp_f32_e32 v220, v220
	v_exp_f32_e32 v221, v221
	v_exp_f32_e32 v222, v222
	v_exp_f32_e32 v223, v223
	v_pk_add_f32 v[216:217], v[216:217], s[100:101] op_sel_hi:[1,0]
	v_pk_add_f32 v[218:219], v[218:219], s[100:101] op_sel_hi:[1,0]
	v_pk_add_f32 v[220:221], v[220:221], s[100:101] op_sel_hi:[1,0]
	v_pk_add_f32 v[222:223], v[222:223], s[100:101] op_sel_hi:[1,0]
	v_rcp_f32_e32 v216, v216
	v_rcp_f32_e32 v217, v217
	v_rcp_f32_e32 v218, v218
	v_rcp_f32_e32 v219, v219
	v_rcp_f32_e32 v220, v220
	v_rcp_f32_e32 v221, v221
	v_rcp_f32_e32 v222, v222
	v_rcp_f32_e32 v223, v223
	v_pk_mul_f32 v[84:85], v[84:85], v[216:217]
	v_pk_mul_f32 v[86:87], v[86:87], v[218:219]
	v_pk_mul_f32 v[76:77], v[76:77], v[220:221]
	v_pk_mul_f32 v[78:79], v[78:79], v[222:223]
	v_pk_mul_f32 v[84:85], v[84:85], v[80:81]
	v_pk_mul_f32 v[86:87], v[86:87], v[82:83]
	v_pk_mul_f32 v[76:77], v[76:77], v[72:73]
	v_pk_mul_f32 v[78:79], v[78:79], v[74:75]
	v_cvt_pk_bf16_f32 v236, v84, v85
	v_cvt_pk_bf16_f32 v237, v86, v87
	v_cvt_pk_bf16_f32 v238, v76, v77
	v_cvt_pk_bf16_f32 v239, v78, v79
	global_store_dwordx4 v140, v[236:239], s[4:5]
	s_add_u32 s4, s4, 0x6e000
	s_addc_u32 s5, s5, 0
	v_pk_mul_f32 v[68:69], v[68:69], v[248:249] op_sel_hi:[1,0]
	v_pk_mul_f32 v[64:65], v[64:65], v[248:249] op_sel_hi:[1,0]
	v_pk_mul_f32 v[216:217], v[68:69], s[2:3] op_sel_hi:[1,0]
	v_pk_mul_f32 v[70:71], v[70:71], v[248:249] op_sel_hi:[1,0]
	v_pk_mul_f32 v[66:67], v[66:67], v[248:249] op_sel_hi:[1,0]
	v_pk_mul_f32 v[218:219], v[70:71], s[2:3] op_sel_hi:[1,0]
	v_pk_mul_f32 v[60:61], v[60:61], v[248:249] op_sel_hi:[1,0]
	v_pk_mul_f32 v[56:57], v[56:57], v[248:249] op_sel_hi:[1,0]
	v_pk_mul_f32 v[220:221], v[60:61], s[2:3] op_sel_hi:[1,0]
	v_pk_mul_f32 v[62:63], v[62:63], v[248:249] op_sel_hi:[1,0]
	v_pk_mul_f32 v[58:59], v[58:59], v[248:249] op_sel_hi:[1,0]
	v_pk_mul_f32 v[222:223], v[62:63], s[2:3] op_sel_hi:[1,0]
	v_exp_f32_e32 v216, v216
	v_exp_f32_e32 v217, v217
	v_exp_f32_e32 v218, v218
	v_exp_f32_e32 v219, v219
	v_exp_f32_e32 v220, v220
	v_exp_f32_e32 v221, v221
	v_exp_f32_e32 v222, v222
	v_exp_f32_e32 v223, v223
	v_pk_add_f32 v[216:217], v[216:217], s[100:101] op_sel_hi:[1,0]
	v_pk_add_f32 v[218:219], v[218:219], s[100:101] op_sel_hi:[1,0]
	v_pk_add_f32 v[220:221], v[220:221], s[100:101] op_sel_hi:[1,0]
	v_pk_add_f32 v[222:223], v[222:223], s[100:101] op_sel_hi:[1,0]
	v_rcp_f32_e32 v216, v216
	v_rcp_f32_e32 v217, v217
	v_rcp_f32_e32 v218, v218
	v_rcp_f32_e32 v219, v219
	v_rcp_f32_e32 v220, v220
	v_rcp_f32_e32 v221, v221
	v_rcp_f32_e32 v222, v222
	v_rcp_f32_e32 v223, v223
	v_pk_mul_f32 v[68:69], v[68:69], v[216:217]
	v_pk_mul_f32 v[70:71], v[70:71], v[218:219]
	v_pk_mul_f32 v[60:61], v[60:61], v[220:221]
	v_pk_mul_f32 v[62:63], v[62:63], v[222:223]
	v_pk_mul_f32 v[68:69], v[68:69], v[64:65]
	v_pk_mul_f32 v[70:71], v[70:71], v[66:67]
	v_pk_mul_f32 v[60:61], v[60:61], v[56:57]
	v_pk_mul_f32 v[62:63], v[62:63], v[58:59]
	v_cvt_pk_bf16_f32 v236, v68, v69
	v_cvt_pk_bf16_f32 v237, v70, v71
	v_cvt_pk_bf16_f32 v238, v60, v61
	v_cvt_pk_bf16_f32 v239, v62, v63
	global_store_dwordx4 v140, v[236:239], s[4:5]
	s_add_u32 s4, s4, 0x16000
	s_addc_u32 s5, s5, 0
	v_pk_mul_f32 v[52:53], v[52:53], v[250:251] op_sel_hi:[1,0]
	v_pk_mul_f32 v[48:49], v[48:49], v[250:251] op_sel_hi:[1,0]
	v_pk_mul_f32 v[216:217], v[52:53], s[2:3] op_sel_hi:[1,0]
; __device__ __forceinline__ float sigmoidf_(float v) { return __builtin_amdgcn_rcpf(1.0f + __expf(-v)); }
; __device__ __forceinline__ u32x4 pack8(const f32x4 a, const f32x4 b) { u32x4 w; w.x = cvt_pk_bf16(a[0], a[1]); w.y = cvt_pk_bf16(a[2], a[3]); w.z = cvt_pk_bf16(b[0], b[1]); w.w = cvt_pk_bf16(b[2], b[3]); return w; }
; #define MEMFENCE asm volatile("" ::: "memory")
;     template <int KIND> __device__ __forceinline__ void run(f32x4 (&acc)[2][2][4][2], const Unit& u, int tid_in) const {
;     ...
;                 for (int m = 0; m < 4; ++m) { int row = rbase + ai * 128 + m * 16; asm volatile("" : "+v"(row)); const float r = rs[ai * 4 + m]; f32x4 o[2];
; #pragma unroll
;                     for (int n = 0; n < 2; ++n) { const f32x4 g = acc[ai][0][m][n] * r, v = acc[ai][1][m][n] * r;
; #pragma unroll
;                         for (int j = 0; j < 4; ++j) o[n][j] = g[j] * sigmoidf_(g[j]) * v[j]; }
;                     *(u32x4*)(act + (size_t)row * ZW + u.pn * 128 + cl) = pack8(o[0], o[1]); MEMFENCE; }
;     ...
;         E.template run<cs.kind>(acc, cur, tid);
;         if (!has_next) break;
;         if (!(cs.kind == K_MG_B && cur.aux < 2))
; #pragma unroll
;         for (int a = 0; a < 2; ++a)
; #pragma unroll
;             for (int b = 0; b < 2; ++b)
; #pragma unroll
;                 for (int m = 0; m < 4; ++m)
; #pragma unroll
;                     for (int n = 0; n < 2; ++n) acc[a][b][m][n] = (f32x4){0.f, 0.f, 0.f, 0.f};
;         cur = nxt; cA = nA; cB = nB; ++ui;
	v_pk_mul_f32 v[54:55], v[54:55], v[250:251] op_sel_hi:[1,0]
	v_pk_mul_f32 v[50:51], v[50:51], v[250:251] op_sel_hi:[1,0]
	v_pk_mul_f32 v[218:219], v[54:55], s[2:3] op_sel_hi:[1,0]
	v_pk_mul_f32 v[44:45], v[44:45], v[250:251] op_sel_hi:[1,0]
	v_pk_mul_f32 v[40:41], v[40:41], v[250:251] op_sel_hi:[1,0]
	v_pk_mul_f32 v[220:221], v[44:45], s[2:3] op_sel_hi:[1,0]
	v_pk_mul_f32 v[46:47], v[46:47], v[250:251] op_sel_hi:[1,0]
	v_pk_mul_f32 v[42:43], v[42:43], v[250:251] op_sel_hi:[1,0]
	v_pk_mul_f32 v[222:223], v[46:47], s[2:3] op_sel_hi:[1,0]
	v_exp_f32_e32 v216, v216
	v_exp_f32_e32 v217, v217
	v_exp_f32_e32 v218, v218
	v_exp_f32_e32 v219, v219
	v_exp_f32_e32 v220, v220
	v_exp_f32_e32 v221, v221
	v_exp_f32_e32 v222, v222
	v_exp_f32_e32 v223, v223
	v_pk_add_f32 v[216:217], v[216:217], s[100:101] op_sel_hi:[1,0]
	v_pk_add_f32 v[218:219], v[218:219], s[100:101] op_sel_hi:[1,0]
	v_pk_add_f32 v[220:221], v[220:221], s[100:101] op_sel_hi:[1,0]
	v_pk_add_f32 v[222:223], v[222:223], s[100:101] op_sel_hi:[1,0]
	v_rcp_f32_e32 v216, v216
	v_rcp_f32_e32 v217, v217
	v_rcp_f32_e32 v218, v218
	v_rcp_f32_e32 v219, v219
	v_rcp_f32_e32 v220, v220
	v_rcp_f32_e32 v221, v221
	v_rcp_f32_e32 v222, v222
	v_rcp_f32_e32 v223, v223
	v_pk_mul_f32 v[52:53], v[52:53], v[216:217]
	v_pk_mul_f32 v[54:55], v[54:55], v[218:219]
	v_pk_mul_f32 v[44:45], v[44:45], v[220:221]
	v_pk_mul_f32 v[46:47], v[46:47], v[222:223]
	v_pk_mul_f32 v[52:53], v[52:53], v[48:49]
	v_pk_mul_f32 v[54:55], v[54:55], v[50:51]
	v_pk_mul_f32 v[44:45], v[44:45], v[40:41]
	v_pk_mul_f32 v[46:47], v[46:47], v[42:43]
	v_cvt_pk_bf16_f32 v236, v52, v53
	v_cvt_pk_bf16_f32 v237, v54, v55
	v_cvt_pk_bf16_f32 v238, v44, v45
	v_cvt_pk_bf16_f32 v239, v46, v47
	global_store_dwordx4 v140, v[236:239], s[4:5]
	s_add_u32 s4, s4, 0x16000
	s_addc_u32 s5, s5, 0
	v_pk_mul_f32 v[36:37], v[36:37], v[252:253] op_sel_hi:[1,0]
	v_pk_mul_f32 v[32:33], v[32:33], v[252:253] op_sel_hi:[1,0]
	v_pk_mul_f32 v[216:217], v[36:37], s[2:3] op_sel_hi:[1,0]
	v_pk_mul_f32 v[38:39], v[38:39], v[252:253] op_sel_hi:[1,0]
	v_pk_mul_f32 v[34:35], v[34:35], v[252:253] op_sel_hi:[1,0]
	v_pk_mul_f32 v[218:219], v[38:39], s[2:3] op_sel_hi:[1,0]
	v_pk_mul_f32 v[28:29], v[28:29], v[252:253] op_sel_hi:[1,0]
	v_pk_mul_f32 v[24:25], v[24:25], v[252:253] op_sel_hi:[1,0]
	v_pk_mul_f32 v[220:221], v[28:29], s[2:3] op_sel_hi:[1,0]
	v_pk_mul_f32 v[30:31], v[30:31], v[252:253] op_sel_hi:[1,0]
	v_pk_mul_f32 v[26:27], v[26:27], v[252:253] op_sel_hi:[1,0]
	v_pk_mul_f32 v[222:223], v[30:31], s[2:3] op_sel_hi:[1,0]
	v_exp_f32_e32 v216, v216
	v_exp_f32_e32 v217, v217
	v_exp_f32_e32 v218, v218
	v_exp_f32_e32 v219, v219
	v_exp_f32_e32 v220, v220
	v_exp_f32_e32 v221, v221
	v_exp_f32_e32 v222, v222
	v_exp_f32_e32 v223, v223
	v_pk_add_f32 v[216:217], v[216:217], s[100:101] op_sel_hi:[1,0]
	v_pk_add_f32 v[218:219], v[218:219], s[100:101] op_sel_hi:[1,0]
	v_pk_add_f32 v[220:221], v[220:221], s[100:101] op_sel_hi:[1,0]
	v_pk_add_f32 v[222:223], v[222:223], s[100:101] op_sel_hi:[1,0]
	v_rcp_f32_e32 v216, v216
	v_rcp_f32_e32 v217, v217
	v_rcp_f32_e32 v218, v218
	v_rcp_f32_e32 v219, v219
	v_rcp_f32_e32 v220, v220
	v_rcp_f32_e32 v221, v221
	v_rcp_f32_e32 v222, v222
	v_rcp_f32_e32 v223, v223
	v_pk_mul_f32 v[36:37], v[36:37], v[216:217]
	v_pk_mul_f32 v[38:39], v[38:39], v[218:219]
	v_pk_mul_f32 v[28:29], v[28:29], v[220:221]
	v_pk_mul_f32 v[30:31], v[30:31], v[222:223]
	v_pk_mul_f32 v[36:37], v[36:37], v[32:33]
	v_pk_mul_f32 v[38:39], v[38:39], v[34:35]
	v_pk_mul_f32 v[28:29], v[28:29], v[24:25]
	v_pk_mul_f32 v[30:31], v[30:31], v[26:27]
	v_cvt_pk_bf16_f32 v236, v36, v37
	v_cvt_pk_bf16_f32 v237, v38, v39
	v_cvt_pk_bf16_f32 v238, v28, v29
	v_cvt_pk_bf16_f32 v239, v30, v31
	global_store_dwordx4 v140, v[236:239], s[4:5]
	s_add_u32 s4, s4, 0x16000
	s_addc_u32 s5, s5, 0
	v_pk_mul_f32 v[20:21], v[20:21], v[254:255] op_sel_hi:[1,0]
	v_pk_mul_f32 v[16:17], v[16:17], v[254:255] op_sel_hi:[1,0]
	v_pk_mul_f32 v[216:217], v[20:21], s[2:3] op_sel_hi:[1,0]
	v_pk_mul_f32 v[22:23], v[22:23], v[254:255] op_sel_hi:[1,0]
	v_pk_mul_f32 v[18:19], v[18:19], v[254:255] op_sel_hi:[1,0]
	v_pk_mul_f32 v[218:219], v[22:23], s[2:3] op_sel_hi:[1,0]
	v_pk_mul_f32 v[12:13], v[12:13], v[254:255] op_sel_hi:[1,0]
	v_pk_mul_f32 v[8:9], v[8:9], v[254:255] op_sel_hi:[1,0]
	v_pk_mul_f32 v[220:221], v[12:13], s[2:3] op_sel_hi:[1,0]
	v_pk_mul_f32 v[14:15], v[14:15], v[254:255] op_sel_hi:[1,0]
	v_pk_mul_f32 v[10:11], v[10:11], v[254:255] op_sel_hi:[1,0]
	v_pk_mul_f32 v[222:223], v[14:15], s[2:3] op_sel_hi:[1,0]
	v_exp_f32_e32 v216, v216
	v_exp_f32_e32 v217, v217
	v_exp_f32_e32 v218, v218
	v_exp_f32_e32 v219, v219
	v_exp_f32_e32 v220, v220
	v_exp_f32_e32 v221, v221
	v_exp_f32_e32 v222, v222
	v_exp_f32_e32 v223, v223
	v_pk_add_f32 v[216:217], v[216:217], s[100:101] op_sel_hi:[1,0]
	v_pk_add_f32 v[218:219], v[218:219], s[100:101] op_sel_hi:[1,0]
	v_pk_add_f32 v[220:221], v[220:221], s[100:101] op_sel_hi:[1,0]
	v_pk_add_f32 v[222:223], v[222:223], s[100:101] op_sel_hi:[1,0]
	v_rcp_f32_e32 v216, v216
	v_rcp_f32_e32 v217, v217
	v_rcp_f32_e32 v218, v218
	v_rcp_f32_e32 v219, v219
	v_rcp_f32_e32 v220, v220
	v_rcp_f32_e32 v221, v221
	v_rcp_f32_e32 v222, v222
	v_rcp_f32_e32 v223, v223
	v_pk_mul_f32 v[20:21], v[20:21], v[216:217]
	v_pk_mul_f32 v[22:23], v[22:23], v[218:219]
	v_pk_mul_f32 v[12:13], v[12:13], v[220:221]
	v_pk_mul_f32 v[14:15], v[14:15], v[222:223]
	v_pk_mul_f32 v[20:21], v[20:21], v[16:17]
	v_pk_mul_f32 v[22:23], v[22:23], v[18:19]
	v_pk_mul_f32 v[12:13], v[12:13], v[8:9]
	v_pk_mul_f32 v[14:15], v[14:15], v[10:11]
	v_cvt_pk_bf16_f32 v236, v20, v21
	v_cvt_pk_bf16_f32 v237, v22, v23
	v_cvt_pk_bf16_f32 v238, v12, v13
	v_cvt_pk_bf16_f32 v239, v14, v15
	global_store_dwordx4 v140, v[236:239], s[4:5]
	s_mov_b32 s38, s11
	s_mov_b32 s37, s10
	s_mov_b64 s[18:19], s[14:15]
	s_mov_b64 s[16:17], s[12:13]
	s_mov_b32 s33, s36
	s_and_b64 vcc, exec, s[8:9]
	s_cbranch_vccz .LBB0_1115
	s_cmp_eq_u32 s101, 2
	s_cbranch_scc0 .Ldbj_FFI_pe
	s_barrier

; #define G_STAGE(bufoff, gbase, o0, h64) do { \
;         __builtin_amdgcn_global_load_lds((const unsigned*)((const char*)(gbase) + (o0)), (LAS unsigned*)(lds + (bufoff) + ldsw), 16, 0, 0); \
;         __builtin_amdgcn_global_load_lds((const unsigned*)((const char*)(gbase) + (h64) + (o0)), (LAS unsigned*)(lds + (bufoff) + ldsw + 8192), 16, 0, 0); } while (0)
; #define G_LDA(dst, b, h) do { _Pragma("unroll") for (int m = 0; m < 4; ++m) _Pragma("unroll") for (int k = 0; k < 2; ++k) dst[m][k] = *(const LAS bf16x8*)(lds + G_SA(b, h) + aoff + m * 2048 + k * 1024); } while (0)
; #define G_LDB(dst, b, h) do { _Pragma("unroll") for (int n = 0; n < 2; ++n) _Pragma("unroll") for (int k = 0; k < 2; ++k) dst[n][k] = *(const LAS bf16x8*)(lds + G_SB(b, h) + boff + n * 2048 + k * 1024); } while (0)
; #define G_WAIT_V(n) asm volatile("s_waitcnt vmcnt(" #n ")" ::: "memory")
; #define G_WAIT_L(n) asm volatile("s_waitcnt lgkmcnt(" #n ")" ::: "memory")
; #define G_BAR __builtin_amdgcn_s_barrier()
; #define G_SCHED __builtin_amdgcn_sched_barrier(0)
;     ...
;             G_LDB(B0, 0, 0); G_SCHED; G_LDA(At, 0, 0); G_STAGE(G_SA(1, 1), a1 + chA, cA0, qA);
;             G_WAIT_L(8); G_BAR; G_WAIT_L(0); G_MMA(0, 0, At, B0); G_BAR; G_SCHED;
;             G_LDB(B1, 0, 1); G_STAGE(G_SB(0, 0), b2, cB0, qB);
;             G_BAR; G_WAIT_L(0); G_MMA(0, 1, At, B1); G_BAR;
;             G_LDA(At, 0, 1); G_STAGE(G_SA(0, 0), a2, cA0, qA);
;             G_BAR; G_WAIT_L(0); G_MMA(1, 0, At, B0); G_BAR; G_SCHED;
;             G_STAGE(G_SB(0, 1), b2 + chB, cB0, qB);
;             G_WAIT_V(6); G_BAR; G_MMA(1, 1, At, B1); G_BAR;
.LBB0_1185:
	s_add_u32 s4, s2, 0xfff50080
	s_addc_u32 s5, s3, -1
	s_add_i32 s33, 0, 0x10000
	ds_read_b128 v[136:139], v255 offset:0
	ds_read_b128 v[140:143], v255 offset:1024
	ds_read_b128 v[144:147], v255 offset:2048
	ds_read_b128 v[148:151], v255 offset:3072
	s_cmp_eq_u32 s21, 40
	s_cselect_b32 s5, s17, s5
	s_cselect_b32 s4, s16, s4
	s_cselect_b32 s23, s19, s7
	s_cselect_b32 s22, s18, s6
	s_add_i32 m0, s26, 0xc000
	ds_read_b128 v[152:155], v195
	ds_read_b128 v[156:159], v195 offset:1024
	ds_read_b128 v[160:163], v195 offset:2048
	ds_read_b128 v[164:167], v195 offset:3072
	ds_read_b128 v[176:179], v195 offset:4096
	ds_read_b128 v[180:183], v195 offset:5120
	ds_read_b128 v[196:199], v195 offset:6144
	ds_read_b128 v[200:203], v195 offset:7168
	global_load_lds_dwordx4 v174, s[2:3]
	s_add_i32 m0, s26, 0xe000
	s_nop 0
	s_add_u32 vcc_lo, s2, s86
	s_addc_u32 vcc_hi, s3, s87
	global_load_lds_dwordx4 v174, vcc
	s_waitcnt lgkmcnt(8)
	s_barrier
	s_waitcnt lgkmcnt(0)
	v_mfma_f32_16x16x32_bf16 v[132:135], v[136:139], v[152:155], v[132:135]
	v_mfma_f32_16x16x32_bf16 v[128:131], v[144:147], v[152:155], v[128:131]
	v_mfma_f32_16x16x32_bf16 v[116:119], v[136:139], v[160:163], v[116:119]
	v_mfma_f32_16x16x32_bf16 v[112:115], v[144:147], v[160:163], v[112:115]
	v_mfma_f32_16x16x32_bf16 v[100:103], v[136:139], v[176:179], v[100:103]
	v_mfma_f32_16x16x32_bf16 v[96:99], v[144:147], v[176:179], v[96:99]
	v_mfma_f32_16x16x32_bf16 v[84:87], v[136:139], v[196:199], v[84:87]
	v_mfma_f32_16x16x32_bf16 v[80:83], v[144:147], v[196:199], v[80:83]
	v_mfma_f32_16x16x32_bf16 v[132:135], v[140:143], v[156:159], v[132:135]
	v_mfma_f32_16x16x32_bf16 v[128:131], v[148:151], v[156:159], v[128:131]
	v_mfma_f32_16x16x32_bf16 v[116:119], v[140:143], v[164:167], v[116:119]
	v_mfma_f32_16x16x32_bf16 v[112:115], v[148:151], v[164:167], v[112:115]
	v_mfma_f32_16x16x32_bf16 v[100:103], v[140:143], v[180:183], v[100:103]
	v_mfma_f32_16x16x32_bf16 v[96:99], v[148:151], v[180:183], v[96:99]
	v_mfma_f32_16x16x32_bf16 v[84:87], v[140:143], v[200:203], v[84:87]
	v_mfma_f32_16x16x32_bf16 v[80:83], v[148:151], v[200:203], v[80:83]
	s_barrier
	s_add_i32 s44, 0, 0x14000
	s_add_i32 s100, s33, s25
	s_mov_b32 m0, s100
	ds_read_b128 v[204:207], v255 offset:16384
	ds_read_b128 v[208:211], v255 offset:17408
	ds_read_b128 v[212:215], v255 offset:18432
	ds_read_b128 v[216:219], v255 offset:19456
	global_load_lds_dwordx4 v172, s[22:23]
	s_add_i32 m0, s100, 0x2000
	s_nop 0
	s_add_u32 vcc_lo, s22, s86
	s_addc_u32 vcc_hi, s23, s87
	global_load_lds_dwordx4 v172, vcc
	s_barrier
	s_waitcnt lgkmcnt(0)
	v_mfma_f32_16x16x32_bf16 v[124:127], v[204:207], v[152:155], v[124:127]
	v_mfma_f32_16x16x32_bf16 v[120:123], v[212:215], v[152:155], v[120:123]
	v_mfma_f32_16x16x32_bf16 v[108:111], v[204:207], v[160:163], v[108:111]
	v_mfma_f32_16x16x32_bf16 v[104:107], v[212:215], v[160:163], v[104:107]
	v_mfma_f32_16x16x32_bf16 v[92:95], v[204:207], v[176:179], v[92:95]
	v_mfma_f32_16x16x32_bf16 v[88:91], v[212:215], v[176:179], v[88:91]
	v_mfma_f32_16x16x32_bf16 v[76:79], v[204:207], v[196:199], v[76:79]
	v_mfma_f32_16x16x32_bf16 v[72:75], v[212:215], v[196:199], v[72:75]
	v_mfma_f32_16x16x32_bf16 v[124:127], v[208:211], v[156:159], v[124:127]
	v_mfma_f32_16x16x32_bf16 v[120:123], v[216:219], v[156:159], v[120:123]
	v_mfma_f32_16x16x32_bf16 v[108:111], v[208:211], v[164:167], v[108:111]
	v_mfma_f32_16x16x32_bf16 v[104:107], v[216:219], v[164:167], v[104:107]
	v_mfma_f32_16x16x32_bf16 v[92:95], v[208:211], v[180:183], v[92:95]
	v_mfma_f32_16x16x32_bf16 v[88:91], v[216:219], v[180:183], v[88:91]
	v_mfma_f32_16x16x32_bf16 v[76:79], v[208:211], v[200:203], v[76:79]
	v_mfma_f32_16x16x32_bf16 v[72:75], v[216:219], v[200:203], v[72:75]
	s_barrier
	s_mov_b32 m0, s26
	v_lshl_add_u64 v[222:223], s[4:5], 0, v[2:3]
	ds_read_b128 v[152:155], v195 offset:16384
	ds_read_b128 v[156:159], v195 offset:17408
	ds_read_b128 v[160:163], v195 offset:18432
	ds_read_b128 v[164:167], v195 offset:19456
	ds_read_b128 v[176:179], v195 offset:20480
	ds_read_b128 v[180:183], v195 offset:21504
	ds_read_b128 v[196:199], v195 offset:22528
	ds_read_b128 v[200:203], v195 offset:23552
	global_load_lds_dwordx4 v2, s[4:5]
	s_mov_b32 m0, s27
	s_nop 0
	s_add_u32 vcc_lo, s4, s86
	s_addc_u32 vcc_hi, s5, s87
	global_load_lds_dwordx4 v2, vcc
	s_barrier
	s_waitcnt lgkmcnt(0)
	v_mfma_f32_16x16x32_bf16 v[68:71], v[136:139], v[152:155], v[68:71]
	v_mfma_f32_16x16x32_bf16 v[64:67], v[144:147], v[152:155], v[64:67]
	v_mfma_f32_16x16x32_bf16 v[52:55], v[136:139], v[160:163], v[52:55]
	v_mfma_f32_16x16x32_bf16 v[48:51], v[144:147], v[160:163], v[48:51]
	v_mfma_f32_16x16x32_bf16 v[36:39], v[136:139], v[176:179], v[36:39]
	v_mfma_f32_16x16x32_bf16 v[32:35], v[144:147], v[176:179], v[32:35]
	v_mfma_f32_16x16x32_bf16 v[20:23], v[136:139], v[196:199], v[20:23]
	v_mfma_f32_16x16x32_bf16 v[16:19], v[144:147], v[196:199], v[16:19]
	v_mfma_f32_16x16x32_bf16 v[68:71], v[140:143], v[156:159], v[68:71]
	v_mfma_f32_16x16x32_bf16 v[64:67], v[148:151], v[156:159], v[64:67]
	v_mfma_f32_16x16x32_bf16 v[52:55], v[140:143], v[164:167], v[52:55]
	v_mfma_f32_16x16x32_bf16 v[48:51], v[148:151], v[164:167], v[48:51]
	v_mfma_f32_16x16x32_bf16 v[36:39], v[140:143], v[180:183], v[36:39]
	v_mfma_f32_16x16x32_bf16 v[32:35], v[148:151], v[180:183], v[32:35]
	v_mfma_f32_16x16x32_bf16 v[20:23], v[140:143], v[200:203], v[20:23]
	v_mfma_f32_16x16x32_bf16 v[16:19], v[148:151], v[200:203], v[16:19]
	s_barrier
	s_add_i32 s100, s44, s25
	s_mov_b32 m0, s100
	s_nop 0
	s_add_u32 vcc_lo, s22, s88
	s_addc_u32 vcc_hi, s23, s89
	global_load_lds_dwordx4 v172, vcc
	s_add_i32 m0, s100, 0x2000
	s_nop 0
	s_add_u32 vcc_lo, s22, s64
	s_addc_u32 vcc_hi, s23, s65
	global_load_lds_dwordx4 v172, vcc
	s_waitcnt vmcnt(6)
	s_barrier
; #define G_STAGE(bufoff, gbase, o0, h64) do { \
;         __builtin_amdgcn_global_load_lds((const unsigned*)((const char*)(gbase) + (o0)), (LAS unsigned*)(lds + (bufoff) + ldsw), 16, 0, 0); \
;         __builtin_amdgcn_global_load_lds((const unsigned*)((const char*)(gbase) + (h64) + (o0)), (LAS unsigned*)(lds + (bufoff) + ldsw + 8192), 16, 0, 0); } while (0)
; #define G_LDA(dst, b, h) do { _Pragma("unroll") for (int m = 0; m < 4; ++m) _Pragma("unroll") for (int k = 0; k < 2; ++k) dst[m][k] = *(const LAS bf16x8*)(lds + G_SA(b, h) + aoff + m * 2048 + k * 1024); } while (0)
; #define G_LDB(dst, b, h) do { _Pragma("unroll") for (int n = 0; n < 2; ++n) _Pragma("unroll") for (int k = 0; k < 2; ++k) dst[n][k] = *(const LAS bf16x8*)(lds + G_SB(b, h) + boff + n * 2048 + k * 1024); } while (0)
; #define G_WAIT_V(n) asm volatile("s_waitcnt vmcnt(" #n ")" ::: "memory")
; #define G_WAIT_L(n) asm volatile("s_waitcnt lgkmcnt(" #n ")" ::: "memory")
; #define G_BAR __builtin_amdgcn_s_barrier()
; #define G_SCHED __builtin_amdgcn_sched_barrier(0)
;     ...
;             G_WAIT_V(6); G_BAR; G_MMA(1, 1, At, B1); G_BAR;
;             G_LDB(B0, 1, 0); G_SCHED; G_LDA(At, 1, 0); G_STAGE(G_SA(0, 1), a2 + chA, cA0, qA);
;             G_WAIT_L(8); G_BAR; G_WAIT_L(0); G_MMA(0, 0, At, B0); G_BAR; G_SCHED;
;             G_LDB(B1, 1, 1); G_STAGE(G_SB(1, 0), b3, cB0, qB);
;             G_BAR; G_WAIT_L(0); G_MMA(0, 1, At, B1); G_BAR;
;             G_LDA(At, 1, 1); G_STAGE(G_SA(1, 0), a3, cA0, qA);
	v_mfma_f32_16x16x32_bf16 v[60:63], v[204:207], v[152:155], v[60:63]
	v_mfma_f32_16x16x32_bf16 v[56:59], v[212:215], v[152:155], v[56:59]
	v_mfma_f32_16x16x32_bf16 v[44:47], v[204:207], v[160:163], v[44:47]
	v_mfma_f32_16x16x32_bf16 v[40:43], v[212:215], v[160:163], v[40:43]
	v_mfma_f32_16x16x32_bf16 v[28:31], v[204:207], v[176:179], v[28:31]
	v_mfma_f32_16x16x32_bf16 v[24:27], v[212:215], v[176:179], v[24:27]
	v_mfma_f32_16x16x32_bf16 v[12:15], v[204:207], v[196:199], v[12:15]
	v_mfma_f32_16x16x32_bf16 v[8:11], v[212:215], v[196:199], v[8:11]
	v_mfma_f32_16x16x32_bf16 v[60:63], v[208:211], v[156:159], v[60:63]
	v_mfma_f32_16x16x32_bf16 v[56:59], v[216:219], v[156:159], v[56:59]
	v_mfma_f32_16x16x32_bf16 v[44:47], v[208:211], v[164:167], v[44:47]
	v_mfma_f32_16x16x32_bf16 v[40:43], v[216:219], v[164:167], v[40:43]
	v_mfma_f32_16x16x32_bf16 v[28:31], v[208:211], v[180:183], v[28:31]
	v_mfma_f32_16x16x32_bf16 v[24:27], v[216:219], v[180:183], v[24:27]
	v_mfma_f32_16x16x32_bf16 v[12:15], v[208:211], v[200:203], v[12:15]
	v_mfma_f32_16x16x32_bf16 v[8:11], v[216:219], v[200:203], v[8:11]
	s_barrier
	s_add_i32 s100, 0, 0x18000
	ds_read_b128 v[136:139], v255 offset:32768
	ds_read_b128 v[140:143], v255 offset:33792
	ds_read_b128 v[144:147], v255 offset:34816
	ds_read_b128 v[148:151], v255 offset:35840
	s_mov_b32 m0, s29
	ds_read_b128 v[152:155], v195 offset:32768
	ds_read_b128 v[156:159], v195 offset:33792
	ds_read_b128 v[160:163], v195 offset:34816
	ds_read_b128 v[164:167], v195 offset:35840
	ds_read_b128 v[176:179], v195 offset:36864
	ds_read_b128 v[180:183], v195 offset:37888
	ds_read_b128 v[196:199], v195 offset:38912
	ds_read_b128 v[200:203], v195 offset:39936
	s_add_u32 vcc_lo, s4, s88
	s_addc_u32 vcc_hi, s5, s89
	global_load_lds_dwordx4 v2, vcc
	s_mov_b32 m0, s30
	s_nop 0
	s_add_u32 vcc_lo, s4, s64
	s_addc_u32 vcc_hi, s5, s65
	global_load_lds_dwordx4 v2, vcc
	s_waitcnt lgkmcnt(8)
	s_barrier
	s_waitcnt lgkmcnt(0)
	v_mfma_f32_16x16x32_bf16 v[132:135], v[136:139], v[152:155], v[132:135]
	v_mfma_f32_16x16x32_bf16 v[128:131], v[144:147], v[152:155], v[128:131]
	v_mfma_f32_16x16x32_bf16 v[116:119], v[136:139], v[160:163], v[116:119]
	v_mfma_f32_16x16x32_bf16 v[112:115], v[144:147], v[160:163], v[112:115]
	v_mfma_f32_16x16x32_bf16 v[100:103], v[136:139], v[176:179], v[100:103]
	v_mfma_f32_16x16x32_bf16 v[96:99], v[144:147], v[176:179], v[96:99]
	v_mfma_f32_16x16x32_bf16 v[84:87], v[136:139], v[196:199], v[84:87]
	v_mfma_f32_16x16x32_bf16 v[80:83], v[144:147], v[196:199], v[80:83]
	v_mfma_f32_16x16x32_bf16 v[132:135], v[140:143], v[156:159], v[132:135]
	v_mfma_f32_16x16x32_bf16 v[128:131], v[148:151], v[156:159], v[128:131]
	v_mfma_f32_16x16x32_bf16 v[116:119], v[140:143], v[164:167], v[116:119]
	v_mfma_f32_16x16x32_bf16 v[112:115], v[148:151], v[164:167], v[112:115]
	v_mfma_f32_16x16x32_bf16 v[100:103], v[140:143], v[180:183], v[100:103]
	v_mfma_f32_16x16x32_bf16 v[96:99], v[148:151], v[180:183], v[96:99]
	v_mfma_f32_16x16x32_bf16 v[84:87], v[140:143], v[200:203], v[84:87]
	v_mfma_f32_16x16x32_bf16 v[80:83], v[148:151], v[200:203], v[80:83]
	s_barrier
	s_add_i32 s5, 0, 0x1c000
	s_add_i32 s4, s100, s25
	s_mov_b32 m0, s4
	ds_read_b128 v[204:207], v255 offset:49152
	ds_read_b128 v[208:211], v255 offset:50176
	ds_read_b128 v[212:215], v255 offset:51200
	ds_read_b128 v[216:219], v255 offset:52224
	s_add_u32 vcc_lo, s22, s46
	s_addc_u32 vcc_hi, s23, s47
	global_load_lds_dwordx4 v172, vcc
	s_add_i32 m0, s4, 0x2000
	s_nop 0
	s_add_u32 vcc_lo, s22, s66
	s_addc_u32 vcc_hi, s23, s67
	global_load_lds_dwordx4 v172, vcc
	s_barrier
; #define G_STAGE(bufoff, gbase, o0, h64) do { \
;         __builtin_amdgcn_global_load_lds((const unsigned*)((const char*)(gbase) + (o0)), (LAS unsigned*)(lds + (bufoff) + ldsw), 16, 0, 0); \
;         __builtin_amdgcn_global_load_lds((const unsigned*)((const char*)(gbase) + (h64) + (o0)), (LAS unsigned*)(lds + (bufoff) + ldsw + 8192), 16, 0, 0); } while (0)
; #define G_WAIT_V(n) asm volatile("s_waitcnt vmcnt(" #n ")" ::: "memory")
; #define G_WAIT_L(n) asm volatile("s_waitcnt lgkmcnt(" #n ")" ::: "memory")
; #define G_BAR __builtin_amdgcn_s_barrier()
; #define G_SCHED __builtin_amdgcn_sched_barrier(0)
;     ...
;             G_BAR; G_WAIT_L(0); G_MMA(1, 0, At, B0); G_BAR; G_SCHED;
;             G_STAGE(G_SB(1, 1), b3 + chB, cB0, qB);
;             G_WAIT_V(6); G_BAR; G_MMA(1, 1, At, B1); G_BAR;
	s_waitcnt lgkmcnt(0)
	v_mfma_f32_16x16x32_bf16 v[124:127], v[204:207], v[152:155], v[124:127]
	v_mfma_f32_16x16x32_bf16 v[120:123], v[212:215], v[152:155], v[120:123]
	v_mfma_f32_16x16x32_bf16 v[108:111], v[204:207], v[160:163], v[108:111]
	v_mfma_f32_16x16x32_bf16 v[104:107], v[212:215], v[160:163], v[104:107]
	v_mfma_f32_16x16x32_bf16 v[92:95], v[204:207], v[176:179], v[92:95]
	v_mfma_f32_16x16x32_bf16 v[88:91], v[212:215], v[176:179], v[88:91]
	v_mfma_f32_16x16x32_bf16 v[76:79], v[204:207], v[196:199], v[76:79]
	v_mfma_f32_16x16x32_bf16 v[72:75], v[212:215], v[196:199], v[72:75]
	v_mfma_f32_16x16x32_bf16 v[124:127], v[208:211], v[156:159], v[124:127]
	v_mfma_f32_16x16x32_bf16 v[120:123], v[216:219], v[156:159], v[120:123]
	v_mfma_f32_16x16x32_bf16 v[108:111], v[208:211], v[164:167], v[108:111]
	v_mfma_f32_16x16x32_bf16 v[104:107], v[216:219], v[164:167], v[104:107]
	v_mfma_f32_16x16x32_bf16 v[92:95], v[208:211], v[180:183], v[92:95]
	v_mfma_f32_16x16x32_bf16 v[88:91], v[216:219], v[180:183], v[88:91]
	v_mfma_f32_16x16x32_bf16 v[76:79], v[208:211], v[200:203], v[76:79]
	v_mfma_f32_16x16x32_bf16 v[72:75], v[216:219], v[200:203], v[72:75]
	s_barrier
	s_mov_b32 m0, s31
	v_lshl_add_u64 v[224:225], v[222:223], 0, s[46:47]
	ds_read_b128 v[152:155], v195 offset:49152
	ds_read_b128 v[156:159], v195 offset:50176
	ds_read_b128 v[160:163], v195 offset:51200
	ds_read_b128 v[164:167], v195 offset:52224
	ds_read_b128 v[176:179], v195 offset:53248
	ds_read_b128 v[180:183], v195 offset:54272
	ds_read_b128 v[196:199], v195 offset:55296
	ds_read_b128 v[200:203], v195 offset:56320
	global_load_lds_dwordx4 v[224:225], off
	v_lshl_add_u64 v[222:223], v[222:223], 0, s[66:67]
	s_mov_b32 m0, s34
	s_nop 0
	global_load_lds_dwordx4 v[222:223], off
	s_barrier
	s_waitcnt lgkmcnt(0)
	v_mfma_f32_16x16x32_bf16 v[68:71], v[136:139], v[152:155], v[68:71]
	v_mfma_f32_16x16x32_bf16 v[64:67], v[144:147], v[152:155], v[64:67]
	v_mfma_f32_16x16x32_bf16 v[52:55], v[136:139], v[160:163], v[52:55]
	v_mfma_f32_16x16x32_bf16 v[48:51], v[144:147], v[160:163], v[48:51]
	v_mfma_f32_16x16x32_bf16 v[36:39], v[136:139], v[176:179], v[36:39]
	v_mfma_f32_16x16x32_bf16 v[32:35], v[144:147], v[176:179], v[32:35]
	v_mfma_f32_16x16x32_bf16 v[20:23], v[136:139], v[196:199], v[20:23]
	v_mfma_f32_16x16x32_bf16 v[16:19], v[144:147], v[196:199], v[16:19]
	v_mfma_f32_16x16x32_bf16 v[68:71], v[140:143], v[156:159], v[68:71]
	v_mfma_f32_16x16x32_bf16 v[64:67], v[148:151], v[156:159], v[64:67]
	v_mfma_f32_16x16x32_bf16 v[52:55], v[140:143], v[164:167], v[52:55]
	v_mfma_f32_16x16x32_bf16 v[48:51], v[148:151], v[164:167], v[48:51]
	v_mfma_f32_16x16x32_bf16 v[36:39], v[140:143], v[180:183], v[36:39]
	v_mfma_f32_16x16x32_bf16 v[32:35], v[148:151], v[180:183], v[32:35]
	v_mfma_f32_16x16x32_bf16 v[20:23], v[140:143], v[200:203], v[20:23]
	v_mfma_f32_16x16x32_bf16 v[16:19], v[148:151], v[200:203], v[16:19]
	s_barrier
	s_add_i32 s4, s5, s25
	s_mov_b32 m0, s4
	s_nop 0
	s_add_u32 vcc_lo, s22, s52
	s_addc_u32 vcc_hi, s23, s53
	global_load_lds_dwordx4 v172, vcc
	s_add_i32 m0, s4, 0x2000
	s_nop 0
	s_add_u32 vcc_lo, s22, s54
	s_addc_u32 vcc_hi, s23, s55
	global_load_lds_dwordx4 v172, vcc
	s_add_i32 s21, s21, 2
	s_add_u32 s2, s2, 0x100
	s_addc_u32 s3, s3, 0
	s_add_u32 s6, s6, 0x100
	s_addc_u32 s7, s7, 0
	s_cmp_gt_u32 s21, 41
	s_waitcnt vmcnt(6)
	s_barrier
	v_mfma_f32_16x16x32_bf16 v[60:63], v[204:207], v[152:155], v[60:63]
	v_mfma_f32_16x16x32_bf16 v[56:59], v[212:215], v[152:155], v[56:59]
	v_mfma_f32_16x16x32_bf16 v[44:47], v[204:207], v[160:163], v[44:47]
	v_mfma_f32_16x16x32_bf16 v[40:43], v[212:215], v[160:163], v[40:43]
	v_mfma_f32_16x16x32_bf16 v[28:31], v[204:207], v[176:179], v[28:31]
	v_mfma_f32_16x16x32_bf16 v[24:27], v[212:215], v[176:179], v[24:27]
	v_mfma_f32_16x16x32_bf16 v[12:15], v[204:207], v[196:199], v[12:15]
	v_mfma_f32_16x16x32_bf16 v[8:11], v[212:215], v[196:199], v[8:11]
	v_mfma_f32_16x16x32_bf16 v[60:63], v[208:211], v[156:159], v[60:63]
	v_mfma_f32_16x16x32_bf16 v[56:59], v[216:219], v[156:159], v[56:59]
	v_mfma_f32_16x16x32_bf16 v[44:47], v[208:211], v[164:167], v[44:47]
	v_mfma_f32_16x16x32_bf16 v[40:43], v[216:219], v[164:167], v[40:43]
	v_mfma_f32_16x16x32_bf16 v[28:31], v[208:211], v[180:183], v[28:31]
	v_mfma_f32_16x16x32_bf16 v[24:27], v[216:219], v[180:183], v[24:27]
	v_mfma_f32_16x16x32_bf16 v[12:15], v[208:211], v[200:203], v[12:15]
	v_mfma_f32_16x16x32_bf16 v[8:11], v[216:219], v[200:203], v[8:11]
	s_cbranch_scc1 .Ldb_FFO_xl

; __device__ __forceinline__ u32x4 pack8(const f32x4 a, const f32x4 b) { u32x4 w; w.x = cvt_pk_bf16(a[0], a[1]); w.y = cvt_pk_bf16(a[2], a[3]); w.z = cvt_pk_bf16(b[0], b[1]); w.w = cvt_pk_bf16(b[2], b[3]); return w; }
; __device__ __forceinline__ void unpack8(const u32x4 w, f32x4& a, f32x4& b) { a[0] = bf_lo(w.x); a[1] = bf_hi(w.x); a[2] = bf_lo(w.y); a[3] = bf_hi(w.y); b[0] = bf_lo(w.z); b[1] = bf_hi(w.z); b[2] = bf_lo(w.w); b[3] = bf_hi(w.w); }
; #define MEMFENCE asm volatile("" ::: "memory")
; #define XLOAD(gi, bufi) do { _Pragma("unroll") for (int ml = 0; ml < 2; ++ml) { const int m_ = ((gi) & 1) * 2 + ml; int row_ = rbase + ((gi) >> 1) * 128 + m_ * 16; asm volatile("" : "+v"(row_)); \
;                 _Pragma("unroll") for (int bj = 0; bj < 2; ++bj) xv[bufi][ml][bj] = *(const u32x4*)(xsrc + (size_t)row_ * 1024 + u.pn * 256 + bj * 128 + cl); } } while (0)
;     template <int KIND> __device__ __forceinline__ void run(f32x4 (&acc)[2][2][4][2], const Unit& u, int tid_in) const {
;     ...
;             const bf16_t* xsrc = xb0; bf16_t* xbo = (u.aux ? mg : xb0); float* sso = (u.aux ? ssq2 : ssq1);
;             u32x4 xv[2][2][2];
;     ...
;             XLOAD(0, 0);
; #pragma unroll
;             for (int gi = 0; gi < 4; ++gi) { const int ai = gi >> 1, mh = gi & 1, bufi = gi & 1;
;                 if (gi < 3) XLOAD(gi + 1, (gi + 1) & 1);
; #pragma unroll
;                 for (int ml = 0; ml < 2; ++ml) { const int m = mh * 2 + ml; int row = rbase + ai * 128 + m * 16; asm volatile("" : "+v"(row)); float ss = 0.f;
; #pragma unroll
;                     for (int bj = 0; bj < 2; ++bj) { const size_t off = (size_t)row * 1024 + u.pn * 256 + bj * 128 + cl; f32x4 x0, x1; unpack8(xv[bufi][ml][bj], x0, x1);
;                         const f32x4 o0 = x0 + acc[ai][bj][m][0], o1 = x1 + acc[ai][bj][m][1];
;                         *(u32x4*)(xbo + off) = pack8(o0, o1);
;                         ss += (o0[0] * o0[0] + o0[1] * o0[1]) + (o0[2] * o0[2] + o0[3] * o0[3]) + (o1[0] * o1[0] + o1[1] * o1[1]) + (o1[2] * o1[2] + o1[3] * o1[3]); }
;                     ss += __shfl_xor(ss, 16); ss += __shfl_xor(ss, 32);
;                     if (fq == 0) sso[((size_t)u.pn * T_TOK + row) * 4 + wc] = ss; }
;                 MEMFENCE; }
.Ldb_FFO_young:
	s_setprio 3
	s_mov_b32 s101, 2
	s_branch .Ldb_FFO_exit
.Ldb_FFO_exit:
	v_mov_b32_e32 v0, v184
	s_lshl_b32 s3, s20, 8
	v_readfirstlane_b32 s2, v0
	s_bfe_u32 s33, s2, 0x20006
	s_ashr_i32 s2, s2, 2
	s_andn2_b32 s2, s2, 63
	s_add_i32 s2, s2, s3
	v_and_or_b32 v196, v0, 15, s2
	v_mov_b32_e32 v136, v196
	v_bfe_u32 v138, v0, 4, 2
	s_lshl_b32 s2, s10, 8
	v_lshlrev_b32_e32 v0, 3, v138
	v_ashrrev_i32_e32 v137, 31, v136
	s_ashr_i32 s3, s2, 31
	v_lshlrev_b64 v[136:137], 11, v[136:137]
	v_lshl_or_b32 v0, s33, 5, v0
	s_lshl_b64 s[22:23], s[2:3], 1
	v_lshl_add_u64 v[136:137], s[12:13], 0, v[136:137]
	v_lshl_add_u64 v[136:137], v[136:137], 0, s[22:23]
	v_lshlrev_b32_e32 v0, 1, v0
	v_lshl_add_u64 v[136:137], v[136:137], 0, v[0:1]
	global_load_dwordx4 v[164:167], v[136:137], off
	global_load_dwordx4 v[160:163], v[136:137], off offset:256
	v_or_b32_e32 v180, 16, v196
	v_mov_b32_e32 v136, v180
	v_or_b32_e32 v178, 32, v196
	v_ashrrev_i32_e32 v137, 31, v136
	v_lshlrev_b64 v[136:137], 11, v[136:137]
	v_lshl_add_u64 v[136:137], s[12:13], 0, v[136:137]
	v_lshl_add_u64 v[136:137], v[136:137], 0, s[22:23]
	v_lshl_add_u64 v[136:137], v[136:137], 0, v[0:1]
	global_load_dwordx4 v[156:159], v[136:137], off
	global_load_dwordx4 v[152:155], v[136:137], off offset:256
	v_mov_b32_e32 v136, v178
	v_or_b32_e32 v176, 48, v196
	v_ashrrev_i32_e32 v137, 31, v136
	v_lshlrev_b64 v[136:137], 11, v[136:137]
	v_lshl_add_u64 v[136:137], s[12:13], 0, v[136:137]
	v_lshl_add_u64 v[136:137], v[136:137], 0, s[22:23]
	v_lshl_add_u64 v[136:137], v[136:137], 0, v[0:1]
	global_load_dwordx4 v[148:151], v[136:137], off
	global_load_dwordx4 v[140:143], v[136:137], off offset:256
	v_mov_b32_e32 v136, v176
	v_cmp_eq_u32_e32 vcc, 0, v138
	v_ashrrev_i32_e32 v137, 31, v136
	v_lshlrev_b64 v[136:137], 11, v[136:137]
	v_lshl_add_u64 v[136:137], s[12:13], 0, v[136:137]
	v_lshl_add_u64 v[136:137], v[136:137], 0, s[22:23]
	v_lshl_add_u64 v[136:137], v[136:137], 0, v[0:1]
	global_load_dwordx4 v[144:147], v[136:137], off
	s_nop 0
	global_load_dwordx4 v[136:139], v[136:137], off offset:256
	v_mov_b32_e32 v182, v196
	s_cmp_eq_u32 s11, 0
	s_cselect_b32 s21, s13, s41
	v_ashrrev_i32_e32 v183, 31, v182
	s_cselect_b32 s20, s12, s40
	v_lshlrev_b64 v[198:199], 11, v[182:183]
	v_lshl_add_u64 v[198:199], s[20:21], 0, v[198:199]
	v_lshl_add_u64 v[198:199], v[198:199], 0, s[22:23]
	v_lshl_add_u64 v[198:199], v[198:199], 0, v[0:1]
	s_mov_b32 s4, 0xaa00000
	s_cselect_b32 s4, s4, 0xac00000
	s_add_u32 s51, s8, s4
	s_addc_u32 s52, s9, 0
	s_waitcnt vmcnt(0)
	v_lshlrev_b32_e32 v200, 16, v164
	v_and_b32_e32 v201, 0xffff0000, v164
	v_lshlrev_b32_e32 v164, 16, v165
	v_and_b32_e32 v165, 0xffff0000, v165
	v_lshlrev_b32_e32 v202, 16, v166
	v_and_b32_e32 v203, 0xffff0000, v166
	v_lshlrev_b32_e32 v166, 16, v167
	v_and_b32_e32 v167, 0xffff0000, v167
	v_pk_add_f32 v[134:135], v[134:135], v[164:165]
	v_pk_add_f32 v[132:133], v[132:133], v[200:201]
	v_pk_add_f32 v[164:165], v[130:131], v[166:167]
	v_pk_add_f32 v[166:167], v[128:129], v[202:203]
	v_cvt_pk_bf16_f32 v128, v132, v133
	v_cvt_pk_bf16_f32 v129, v134, v135
	s_nop 0
	v_cvt_pk_bf16_f32 v130, v166, v167
	v_cvt_pk_bf16_f32 v131, v164, v165
	global_store_dwordx4 v[198:199], v[128:131], off
	s_nop 1
	v_mul_f32_e32 v128, v133, v133
	v_mul_f32_e32 v129, v135, v135
	v_fmac_f32_e32 v128, v132, v132
	v_fmac_f32_e32 v129, v134, v134
	v_add_f32_e32 v128, v128, v129
	v_mul_f32_e32 v129, v167, v167
	v_fmac_f32_e32 v129, v166, v166
	v_add_f32_e32 v128, v129, v128
	v_mul_f32_e32 v129, v165, v165
	v_fmac_f32_e32 v129, v164, v164
	v_add_f32_e32 v164, v129, v128
	v_lshlrev_b32_e32 v128, 16, v160
	v_and_b32_e32 v129, 0xffff0000, v160
	v_lshlrev_b32_e32 v130, 16, v161
	v_and_b32_e32 v131, 0xffff0000, v161
	v_lshlrev_b32_e32 v132, 16, v162
	v_and_b32_e32 v133, 0xffff0000, v162
	v_lshlrev_b32_e32 v134, 16, v163
	v_and_b32_e32 v135, 0xffff0000, v163
	v_pk_add_f32 v[126:127], v[126:127], v[130:131]
	v_pk_add_f32 v[124:125], v[124:125], v[128:129]
	v_pk_add_f32 v[130:131], v[120:121], v[132:133]
	v_cvt_pk_bf16_f32 v120, v124, v125
	v_cvt_pk_bf16_f32 v121, v126, v127
	v_pk_add_f32 v[128:129], v[122:123], v[134:135]
	v_cvt_pk_bf16_f32 v122, v130, v131
	s_nop 0
	v_cvt_pk_bf16_f32 v123, v128, v129
	global_store_dwordx4 v[198:199], v[120:123], off offset:256
	s_nop 1
	v_mul_f32_e32 v120, v125, v125
	v_mul_f32_e32 v121, v127, v127
	v_fmac_f32_e32 v120, v124, v124
	v_fmac_f32_e32 v121, v126, v126
	v_add_f32_e32 v120, v120, v121
	v_mul_f32_e32 v121, v131, v131
	v_fmac_f32_e32 v121, v130, v130
	v_add_f32_e32 v120, v121, v120
	v_mul_f32_e32 v121, v129, v129
	v_fmac_f32_e32 v121, v128, v128
	v_add_f32_e32 v120, v121, v120
	v_xor_b32_e32 v121, 16, v190
	v_cmp_lt_i32_e64 s[6:7], v121, v192
	v_add_f32_e32 v120, v164, v120
	s_nop 0
	v_cndmask_b32_e64 v121, v190, v121, s[6:7]
	v_lshlrev_b32_e32 v124, 2, v121
	ds_bpermute_b32 v121, v124, v120
	s_waitcnt lgkmcnt(0)
	v_add_f32_e32 v120, v120, v121
	v_xor_b32_e32 v121, 32, v190
	v_cmp_lt_i32_e64 s[6:7], v121, v192
	s_nop 1
	v_cndmask_b32_e64 v121, v190, v121, s[6:7]
	v_lshlrev_b32_e32 v125, 2, v121
	ds_bpermute_b32 v121, v125, v120
	s_and_saveexec_b64 s[6:7], vcc
	s_cbranch_execz .LBB0_1188
	s_ashr_i32 s11, s10, 31
	s_lshl_b64 s[4:5], s[10:11], 19
	s_add_u32 s4, s51, s4
	s_addc_u32 s5, s52, s5
	s_waitcnt lgkmcnt(0)
	v_add_f32_e32 v122, v120, v121
	v_lshl_add_u64 v[120:121], v[182:183], 4, s[4:5]
	s_lshl_b32 s74, s33, 2
	v_lshl_add_u64 v[120:121], v[120:121], 0, s[74:75]
	global_store_dword v[120:121], v122, off

; #define G_STAGE(bufoff, gbase, o0, h64) do { \
;         __builtin_amdgcn_global_load_lds((const unsigned*)((const char*)(gbase) + (o0)), (LAS unsigned*)(lds + (bufoff) + ldsw), 16, 0, 0); \
;         __builtin_amdgcn_global_load_lds((const unsigned*)((const char*)(gbase) + (h64) + (o0)), (LAS unsigned*)(lds + (bufoff) + ldsw + 8192), 16, 0, 0); } while (0)
; #define G_LDA(dst, b, h) do { _Pragma("unroll") for (int m = 0; m < 4; ++m) _Pragma("unroll") for (int k = 0; k < 2; ++k) dst[m][k] = *(const LAS bf16x8*)(lds + G_SA(b, h) + aoff + m * 2048 + k * 1024); } while (0)
; #define G_LDB(dst, b, h) do { _Pragma("unroll") for (int n = 0; n < 2; ++n) _Pragma("unroll") for (int k = 0; k < 2; ++k) dst[n][k] = *(const LAS bf16x8*)(lds + G_SB(b, h) + boff + n * 2048 + k * 1024); } while (0)
; #define G_WAIT_L(n) asm volatile("s_waitcnt lgkmcnt(" #n ")" ::: "memory")
; #define G_BAR __builtin_amdgcn_s_barrier()
; #define G_SCHED __builtin_amdgcn_sched_barrier(0)
;     ...
;         for (int t = 0; t < nt; t += 2) {
;             const bool last = (t == nt - 2);
;             const char* a1 = cA + (size_t)(t + 1) * ckA;
;             const char* a2 = last ? nA : cA + (size_t)(t + 2) * ckA; const char* b2 = last ? nB : cB + (size_t)(t + 2) * kB;
;             const char* a3 = a2 + ckA; const char* b3 = b2 + kB;
;             G_LDB(B0, 0, 0); G_SCHED; G_LDA(At, 0, 0); G_STAGE(G_SA(1, 1), a1 + chA, cA0, qA);
;             G_WAIT_L(8); G_BAR; G_WAIT_L(0); G_MMA(0, 0, At, B0); G_BAR; G_SCHED;
;             G_LDB(B1, 0, 1); G_STAGE(G_SB(0, 0), b2, cB0, qB);
;             G_BAR; G_WAIT_L(0); G_MMA(0, 1, At, B1); G_BAR;
;             G_LDA(At, 0, 1); G_STAGE(G_SA(0, 0), a2, cA0, qA);
;             G_BAR; G_WAIT_L(0); G_MMA(1, 0, At, B0); G_BAR; G_SCHED;
.LBB0_1260:
	s_add_u32 s22, s10, s18
	s_addc_u32 s23, s11, s19
	s_add_u32 s20, s22, 0x100
	s_addc_u32 s21, s23, 0
	s_and_b64 s[4:5], s[16:17], exec
	s_cselect_b32 s20, s6, s20
	s_cselect_b32 s21, s7, s21
	s_add_u32 s4, s12, s18
	s_addc_u32 s5, s13, s19
	s_add_u32 s18, s4, 0x100
	s_addc_u32 s19, s5, 0
	s_add_i32 s44, 0, 0x10000
	ds_read_b128 v[140:143], v255 offset:0
	ds_read_b128 v[144:147], v255 offset:1024
	ds_read_b128 v[148:151], v255 offset:2048
	ds_read_b128 v[152:155], v255 offset:3072
	s_and_b64 s[4:5], s[16:17], exec
	s_cselect_b32 s16, s8, s18
	s_cselect_b32 s17, s9, s19
	s_add_i32 s5, 0, 0x14000
	s_add_i32 s43, 0, 0x18000
	s_add_i32 s18, 0, 0x1c000
	s_add_i32 s45, s44, s25
	s_add_i32 s51, s5, s25
	s_add_i32 s19, s43, s25
	s_add_i32 s53, s18, s25
	s_mov_b64 s[64:65], 0x8000
	s_mov_b64 s[62:63], 0x10080
	s_add_i32 m0, s31, 0xc000
	s_add_i32 s4, s31, 0xe000
	s_add_i32 s54, s45, 0x2000
	s_add_i32 s50, s51, 0x2000
	s_add_i32 s44, s19, 0x2000
	s_add_i32 s52, s53, 0x2000
	ds_read_b128 v[156:159], v138
	ds_read_b128 v[160:163], v138 offset:1024
	ds_read_b128 v[164:167], v138 offset:2048
	ds_read_b128 v[172:175], v138 offset:3072
	ds_read_b128 v[176:179], v138 offset:4096
	ds_read_b128 v[180:183], v138 offset:5120
	ds_read_b128 v[196:199], v138 offset:6144
	ds_read_b128 v[200:203], v138 offset:7168
	s_add_u32 vcc_lo, s22, s62
	s_addc_u32 vcc_hi, s23, s63
	global_load_lds_dwordx4 v2, vcc
	s_mov_b32 m0, s4
	s_nop 0
	s_add_u32 vcc_lo, s22, s68
	s_addc_u32 vcc_hi, s23, s69
	global_load_lds_dwordx4 v2, vcc
	s_waitcnt lgkmcnt(8)
	s_barrier
	s_waitcnt lgkmcnt(0)
	v_mfma_f32_16x16x32_bf16 v[132:135], v[140:143], v[156:159], v[132:135]
	v_mfma_f32_16x16x32_bf16 v[128:131], v[148:151], v[156:159], v[128:131]
	v_mfma_f32_16x16x32_bf16 v[124:127], v[140:143], v[164:167], v[124:127]
	v_mfma_f32_16x16x32_bf16 v[116:119], v[148:151], v[164:167], v[116:119]
	v_mfma_f32_16x16x32_bf16 v[108:111], v[140:143], v[176:179], v[108:111]
	v_mfma_f32_16x16x32_bf16 v[100:103], v[148:151], v[176:179], v[100:103]
	v_mfma_f32_16x16x32_bf16 v[92:95], v[140:143], v[196:199], v[92:95]
	v_mfma_f32_16x16x32_bf16 v[84:87], v[148:151], v[196:199], v[84:87]
	v_mfma_f32_16x16x32_bf16 v[132:135], v[144:147], v[160:163], v[132:135]
	v_mfma_f32_16x16x32_bf16 v[128:131], v[152:155], v[160:163], v[128:131]
	v_mfma_f32_16x16x32_bf16 v[124:127], v[144:147], v[172:175], v[124:127]
	v_mfma_f32_16x16x32_bf16 v[116:119], v[152:155], v[172:175], v[116:119]
	v_mfma_f32_16x16x32_bf16 v[108:111], v[144:147], v[180:183], v[108:111]
	v_mfma_f32_16x16x32_bf16 v[100:103], v[152:155], v[180:183], v[100:103]
	v_mfma_f32_16x16x32_bf16 v[92:95], v[144:147], v[200:203], v[92:95]
	v_mfma_f32_16x16x32_bf16 v[84:87], v[152:155], v[200:203], v[84:87]
	s_barrier
	s_mov_b32 m0, s45
	v_lshl_add_u64 v[184:185], s[16:17], 0, v[0:1]
	ds_read_b128 v[204:207], v255 offset:16384
	ds_read_b128 v[208:211], v255 offset:17408
	ds_read_b128 v[212:215], v255 offset:18432
	ds_read_b128 v[216:219], v255 offset:19456
	global_load_lds_dwordx4 v0, s[16:17]
	s_mov_b32 m0, s54
	s_nop 0
	s_add_u32 vcc_lo, s16, s64
	s_addc_u32 vcc_hi, s17, s65
	global_load_lds_dwordx4 v0, vcc
	s_barrier
	s_waitcnt lgkmcnt(0)
	v_mfma_f32_16x16x32_bf16 v[120:123], v[204:207], v[156:159], v[120:123]
	v_mfma_f32_16x16x32_bf16 v[112:115], v[212:215], v[156:159], v[112:115]
	v_mfma_f32_16x16x32_bf16 v[104:107], v[204:207], v[164:167], v[104:107]
	v_mfma_f32_16x16x32_bf16 v[96:99], v[212:215], v[164:167], v[96:99]
	v_mfma_f32_16x16x32_bf16 v[88:91], v[204:207], v[176:179], v[88:91]
	v_mfma_f32_16x16x32_bf16 v[80:83], v[212:215], v[176:179], v[80:83]
	v_mfma_f32_16x16x32_bf16 v[76:79], v[204:207], v[196:199], v[76:79]
	v_mfma_f32_16x16x32_bf16 v[72:75], v[212:215], v[196:199], v[72:75]
	v_mfma_f32_16x16x32_bf16 v[120:123], v[208:211], v[160:163], v[120:123]
	v_mfma_f32_16x16x32_bf16 v[112:115], v[216:219], v[160:163], v[112:115]
	v_mfma_f32_16x16x32_bf16 v[104:107], v[208:211], v[172:175], v[104:107]
	v_mfma_f32_16x16x32_bf16 v[96:99], v[216:219], v[172:175], v[96:99]
	v_mfma_f32_16x16x32_bf16 v[88:91], v[208:211], v[180:183], v[88:91]
	v_mfma_f32_16x16x32_bf16 v[80:83], v[216:219], v[180:183], v[80:83]
	v_mfma_f32_16x16x32_bf16 v[76:79], v[208:211], v[200:203], v[76:79]
	v_mfma_f32_16x16x32_bf16 v[72:75], v[216:219], v[200:203], v[72:75]
	s_barrier
	s_mov_b32 m0, s31
	v_lshl_add_u64 v[220:221], s[20:21], 0, v[2:3]
	s_mov_b64 s[4:5], 0x8000
	ds_read_b128 v[156:159], v138 offset:16384
	ds_read_b128 v[160:163], v138 offset:17408
	ds_read_b128 v[164:167], v138 offset:18432
	ds_read_b128 v[172:175], v138 offset:19456
	ds_read_b128 v[176:179], v138 offset:20480
	ds_read_b128 v[180:183], v138 offset:21504
	ds_read_b128 v[196:199], v138 offset:22528
	ds_read_b128 v[200:203], v138 offset:23552
	global_load_lds_dwordx4 v2, s[20:21]
	s_mov_b32 m0, s33
	s_mov_b64 s[16:17], 0x18000
	s_add_u32 vcc_lo, s20, s4
	s_addc_u32 vcc_hi, s21, s5
	global_load_lds_dwordx4 v2, vcc
	s_barrier
	s_waitcnt lgkmcnt(0)
	s_mov_b64 s[20:21], 0x8080
	s_waitcnt lgkmcnt(0)
	v_mfma_f32_16x16x32_bf16 v[68:71], v[140:143], v[156:159], v[68:71]
	v_mfma_f32_16x16x32_bf16 v[64:67], v[148:151], v[156:159], v[64:67]
	v_mfma_f32_16x16x32_bf16 v[60:63], v[140:143], v[164:167], v[60:63]
	v_mfma_f32_16x16x32_bf16 v[52:55], v[148:151], v[164:167], v[52:55]
	v_mfma_f32_16x16x32_bf16 v[44:47], v[140:143], v[176:179], v[44:47]
	v_mfma_f32_16x16x32_bf16 v[36:39], v[148:151], v[176:179], v[36:39]
	v_mfma_f32_16x16x32_bf16 v[28:31], v[140:143], v[196:199], v[28:31]
	v_mfma_f32_16x16x32_bf16 v[20:23], v[148:151], v[196:199], v[20:23]
	v_mfma_f32_16x16x32_bf16 v[68:71], v[144:147], v[160:163], v[68:71]
	v_mfma_f32_16x16x32_bf16 v[64:67], v[152:155], v[160:163], v[64:67]
	v_mfma_f32_16x16x32_bf16 v[60:63], v[144:147], v[172:175], v[60:63]
	v_mfma_f32_16x16x32_bf16 v[52:55], v[152:155], v[172:175], v[52:55]
	v_mfma_f32_16x16x32_bf16 v[44:47], v[144:147], v[180:183], v[44:47]
	v_mfma_f32_16x16x32_bf16 v[36:39], v[152:155], v[180:183], v[36:39]
	v_mfma_f32_16x16x32_bf16 v[28:31], v[144:147], v[200:203], v[28:31]
	v_mfma_f32_16x16x32_bf16 v[20:23], v[152:155], v[200:203], v[20:23]
	s_barrier
; #define G_STAGE(bufoff, gbase, o0, h64) do { \
;         __builtin_amdgcn_global_load_lds((const unsigned*)((const char*)(gbase) + (o0)), (LAS unsigned*)(lds + (bufoff) + ldsw), 16, 0, 0); \
;         __builtin_amdgcn_global_load_lds((const unsigned*)((const char*)(gbase) + (h64) + (o0)), (LAS unsigned*)(lds + (bufoff) + ldsw + 8192), 16, 0, 0); } while (0)
; #define G_LDA(dst, b, h) do { _Pragma("unroll") for (int m = 0; m < 4; ++m) _Pragma("unroll") for (int k = 0; k < 2; ++k) dst[m][k] = *(const LAS bf16x8*)(lds + G_SA(b, h) + aoff + m * 2048 + k * 1024); } while (0)
; #define G_LDB(dst, b, h) do { _Pragma("unroll") for (int n = 0; n < 2; ++n) _Pragma("unroll") for (int k = 0; k < 2; ++k) dst[n][k] = *(const LAS bf16x8*)(lds + G_SB(b, h) + boff + n * 2048 + k * 1024); } while (0)
; #define G_WAIT_V(n) asm volatile("s_waitcnt vmcnt(" #n ")" ::: "memory")
; #define G_WAIT_L(n) asm volatile("s_waitcnt lgkmcnt(" #n ")" ::: "memory")
; #define G_BAR __builtin_amdgcn_s_barrier()
; #define G_SCHED __builtin_amdgcn_sched_barrier(0)
;     ...
;             G_BAR; G_WAIT_L(0); G_MMA(1, 0, At, B0); G_BAR; G_SCHED;
;             G_STAGE(G_SB(0, 1), b2 + chB, cB0, qB);
;             G_WAIT_V(6); G_BAR; G_MMA(1, 1, At, B1); G_BAR;
;             G_LDB(B0, 1, 0); G_SCHED; G_LDA(At, 1, 0); G_STAGE(G_SA(0, 1), a2 + chA, cA0, qA);
;             G_WAIT_L(8); G_BAR; G_WAIT_L(0); G_MMA(0, 0, At, B0); G_BAR; G_SCHED;
;             G_LDB(B1, 1, 1); G_STAGE(G_SB(1, 0), b3, cB0, qB);
	s_mov_b32 m0, s51
	v_lshl_add_u64 v[140:141], v[184:185], 0, s[58:59]
	global_load_lds_dwordx4 v[140:141], off
	v_lshl_add_u64 v[140:141], v[184:185], 0, s[16:17]
	s_mov_b32 m0, s50
	s_nop 0
	global_load_lds_dwordx4 v[140:141], off
	s_waitcnt vmcnt(6)
	s_barrier
	v_mfma_f32_16x16x32_bf16 v[56:59], v[204:207], v[156:159], v[56:59]
	v_mfma_f32_16x16x32_bf16 v[48:51], v[212:215], v[156:159], v[48:51]
	v_mfma_f32_16x16x32_bf16 v[40:43], v[204:207], v[164:167], v[40:43]
	v_mfma_f32_16x16x32_bf16 v[32:35], v[212:215], v[164:167], v[32:35]
	v_mfma_f32_16x16x32_bf16 v[24:27], v[204:207], v[176:179], v[24:27]
	v_mfma_f32_16x16x32_bf16 v[16:19], v[212:215], v[176:179], v[16:19]
	v_mfma_f32_16x16x32_bf16 v[12:15], v[204:207], v[196:199], v[12:15]
	v_mfma_f32_16x16x32_bf16 v[8:11], v[212:215], v[196:199], v[8:11]
	v_mfma_f32_16x16x32_bf16 v[56:59], v[208:211], v[160:163], v[56:59]
	v_mfma_f32_16x16x32_bf16 v[48:51], v[216:219], v[160:163], v[48:51]
	v_mfma_f32_16x16x32_bf16 v[40:43], v[208:211], v[172:175], v[40:43]
	v_mfma_f32_16x16x32_bf16 v[32:35], v[216:219], v[172:175], v[32:35]
	v_mfma_f32_16x16x32_bf16 v[24:27], v[208:211], v[180:183], v[24:27]
	v_mfma_f32_16x16x32_bf16 v[16:19], v[216:219], v[180:183], v[16:19]
	v_mfma_f32_16x16x32_bf16 v[12:15], v[208:211], v[200:203], v[12:15]
	v_mfma_f32_16x16x32_bf16 v[8:11], v[216:219], v[200:203], v[8:11]
	s_barrier
	ds_read_b128 v[140:143], v255 offset:32768
	ds_read_b128 v[144:147], v255 offset:33792
	ds_read_b128 v[148:151], v255 offset:34816
	ds_read_b128 v[152:155], v255 offset:35840
	s_mov_b32 m0, s34
	v_lshl_add_u64 v[204:205], v[220:221], 0, s[58:59]
	ds_read_b128 v[156:159], v138 offset:32768
	ds_read_b128 v[160:163], v138 offset:33792
	ds_read_b128 v[164:167], v138 offset:34816
	ds_read_b128 v[172:175], v138 offset:35840
	ds_read_b128 v[176:179], v138 offset:36864
	ds_read_b128 v[180:183], v138 offset:37888
	ds_read_b128 v[196:199], v138 offset:38912
	ds_read_b128 v[200:203], v138 offset:39936
	global_load_lds_dwordx4 v[204:205], off
	v_lshl_add_u64 v[204:205], v[220:221], 0, s[16:17]
	s_mov_b32 m0, s35
	s_nop 0
	global_load_lds_dwordx4 v[204:205], off
	s_waitcnt lgkmcnt(8)
	s_barrier
	s_waitcnt lgkmcnt(0)
	v_mfma_f32_16x16x32_bf16 v[132:135], v[140:143], v[156:159], v[132:135]
	v_mfma_f32_16x16x32_bf16 v[128:131], v[148:151], v[156:159], v[128:131]
	v_mfma_f32_16x16x32_bf16 v[124:127], v[140:143], v[164:167], v[124:127]
	v_mfma_f32_16x16x32_bf16 v[116:119], v[148:151], v[164:167], v[116:119]
	v_mfma_f32_16x16x32_bf16 v[108:111], v[140:143], v[176:179], v[108:111]
	v_mfma_f32_16x16x32_bf16 v[100:103], v[148:151], v[176:179], v[100:103]
	v_mfma_f32_16x16x32_bf16 v[92:95], v[140:143], v[196:199], v[92:95]
	v_mfma_f32_16x16x32_bf16 v[84:87], v[148:151], v[196:199], v[84:87]
	v_mfma_f32_16x16x32_bf16 v[132:135], v[144:147], v[160:163], v[132:135]
	v_mfma_f32_16x16x32_bf16 v[128:131], v[152:155], v[160:163], v[128:131]
	v_mfma_f32_16x16x32_bf16 v[124:127], v[144:147], v[172:175], v[124:127]
	v_mfma_f32_16x16x32_bf16 v[116:119], v[152:155], v[172:175], v[116:119]
	v_mfma_f32_16x16x32_bf16 v[108:111], v[144:147], v[180:183], v[108:111]
	v_mfma_f32_16x16x32_bf16 v[100:103], v[152:155], v[180:183], v[100:103]
	v_mfma_f32_16x16x32_bf16 v[92:95], v[144:147], v[200:203], v[92:95]
	v_mfma_f32_16x16x32_bf16 v[84:87], v[152:155], v[200:203], v[84:87]
	s_barrier
	s_mov_b32 m0, s19
	v_lshl_add_u64 v[222:223], v[184:185], 0, s[46:47]
	ds_read_b128 v[204:207], v255 offset:49152
	ds_read_b128 v[208:211], v255 offset:50176
	ds_read_b128 v[212:215], v255 offset:51200
	ds_read_b128 v[216:219], v255 offset:52224
	global_load_lds_dwordx4 v[222:223], off
	v_lshl_add_u64 v[222:223], v[184:185], 0, s[20:21]
	s_mov_b32 m0, s44
	s_mov_b64 s[4:5], 0x10080
	global_load_lds_dwordx4 v[222:223], off
	s_barrier
; #define G_STAGE(bufoff, gbase, o0, h64) do { \
;         __builtin_amdgcn_global_load_lds((const unsigned*)((const char*)(gbase) + (o0)), (LAS unsigned*)(lds + (bufoff) + ldsw), 16, 0, 0); \
;         __builtin_amdgcn_global_load_lds((const unsigned*)((const char*)(gbase) + (h64) + (o0)), (LAS unsigned*)(lds + (bufoff) + ldsw + 8192), 16, 0, 0); } while (0)
; #define G_LDA(dst, b, h) do { _Pragma("unroll") for (int m = 0; m < 4; ++m) _Pragma("unroll") for (int k = 0; k < 2; ++k) dst[m][k] = *(const LAS bf16x8*)(lds + G_SA(b, h) + aoff + m * 2048 + k * 1024); } while (0)
; #define G_WAIT_V(n) asm volatile("s_waitcnt vmcnt(" #n ")" ::: "memory")
; #define G_WAIT_L(n) asm volatile("s_waitcnt lgkmcnt(" #n ")" ::: "memory")
; #define G_BAR __builtin_amdgcn_s_barrier()
; #define G_SCHED __builtin_amdgcn_sched_barrier(0)
;     ...
;             G_BAR; G_WAIT_L(0); G_MMA(0, 1, At, B1); G_BAR;
;             G_LDA(At, 1, 1); G_STAGE(G_SA(1, 0), a3, cA0, qA);
;             G_BAR; G_WAIT_L(0); G_MMA(1, 0, At, B0); G_BAR; G_SCHED;
;             G_STAGE(G_SB(1, 1), b3 + chB, cB0, qB);
;             G_WAIT_V(6); G_BAR; G_MMA(1, 1, At, B1); G_BAR;
	s_waitcnt lgkmcnt(0)
	v_mfma_f32_16x16x32_bf16 v[120:123], v[204:207], v[156:159], v[120:123]
	v_mfma_f32_16x16x32_bf16 v[112:115], v[212:215], v[156:159], v[112:115]
	v_mfma_f32_16x16x32_bf16 v[104:107], v[204:207], v[164:167], v[104:107]
	v_mfma_f32_16x16x32_bf16 v[96:99], v[212:215], v[164:167], v[96:99]
	v_mfma_f32_16x16x32_bf16 v[88:91], v[204:207], v[176:179], v[88:91]
	v_mfma_f32_16x16x32_bf16 v[80:83], v[212:215], v[176:179], v[80:83]
	v_mfma_f32_16x16x32_bf16 v[76:79], v[204:207], v[196:199], v[76:79]
	v_mfma_f32_16x16x32_bf16 v[72:75], v[212:215], v[196:199], v[72:75]
	v_mfma_f32_16x16x32_bf16 v[120:123], v[208:211], v[160:163], v[120:123]
	v_mfma_f32_16x16x32_bf16 v[112:115], v[216:219], v[160:163], v[112:115]
	v_mfma_f32_16x16x32_bf16 v[104:107], v[208:211], v[172:175], v[104:107]
	v_mfma_f32_16x16x32_bf16 v[96:99], v[216:219], v[172:175], v[96:99]
	v_mfma_f32_16x16x32_bf16 v[88:91], v[208:211], v[180:183], v[88:91]
	v_mfma_f32_16x16x32_bf16 v[80:83], v[216:219], v[180:183], v[80:83]
	v_mfma_f32_16x16x32_bf16 v[76:79], v[208:211], v[200:203], v[76:79]
	v_mfma_f32_16x16x32_bf16 v[72:75], v[216:219], v[200:203], v[72:75]
	s_barrier
	s_mov_b32 m0, s36
	v_lshl_add_u64 v[222:223], v[220:221], 0, s[46:47]
	ds_read_b128 v[156:159], v138 offset:49152
	ds_read_b128 v[160:163], v138 offset:50176
	ds_read_b128 v[164:167], v138 offset:51200
	ds_read_b128 v[172:175], v138 offset:52224
	ds_read_b128 v[176:179], v138 offset:53248
	ds_read_b128 v[180:183], v138 offset:54272
	ds_read_b128 v[196:199], v138 offset:55296
	ds_read_b128 v[200:203], v138 offset:56320
	global_load_lds_dwordx4 v[222:223], off
	v_lshl_add_u64 v[220:221], v[220:221], 0, s[20:21]
	s_mov_b32 m0, s37
	s_nop 0
	global_load_lds_dwordx4 v[220:221], off
	s_barrier
	s_waitcnt lgkmcnt(0)
	v_mfma_f32_16x16x32_bf16 v[68:71], v[140:143], v[156:159], v[68:71]
	v_mfma_f32_16x16x32_bf16 v[64:67], v[148:151], v[156:159], v[64:67]
	v_mfma_f32_16x16x32_bf16 v[60:63], v[140:143], v[164:167], v[60:63]
	v_mfma_f32_16x16x32_bf16 v[52:55], v[148:151], v[164:167], v[52:55]
	v_mfma_f32_16x16x32_bf16 v[44:47], v[140:143], v[176:179], v[44:47]
	v_mfma_f32_16x16x32_bf16 v[36:39], v[148:151], v[176:179], v[36:39]
	v_mfma_f32_16x16x32_bf16 v[28:31], v[140:143], v[196:199], v[28:31]
	v_mfma_f32_16x16x32_bf16 v[20:23], v[148:151], v[196:199], v[20:23]
	v_mfma_f32_16x16x32_bf16 v[68:71], v[144:147], v[160:163], v[68:71]
	v_mfma_f32_16x16x32_bf16 v[64:67], v[152:155], v[160:163], v[64:67]
	v_mfma_f32_16x16x32_bf16 v[60:63], v[144:147], v[172:175], v[60:63]
	v_mfma_f32_16x16x32_bf16 v[52:55], v[152:155], v[172:175], v[52:55]
	v_mfma_f32_16x16x32_bf16 v[44:47], v[144:147], v[180:183], v[44:47]
	v_mfma_f32_16x16x32_bf16 v[36:39], v[152:155], v[180:183], v[36:39]
	v_mfma_f32_16x16x32_bf16 v[28:31], v[144:147], v[200:203], v[28:31]
	v_mfma_f32_16x16x32_bf16 v[20:23], v[152:155], v[200:203], v[20:23]
	s_barrier
	s_mov_b32 m0, s53
	v_lshl_add_u64 v[140:141], v[184:185], 0, s[4:5]
	global_load_lds_dwordx4 v[140:141], off
	v_lshl_add_u64 v[140:141], v[184:185], 0, s[68:69]
	s_mov_b32 m0, s52
	s_nop 0
	global_load_lds_dwordx4 v[140:141], off
	s_waitcnt vmcnt(6)
	s_barrier
	v_mfma_f32_16x16x32_bf16 v[56:59], v[204:207], v[156:159], v[56:59]
	v_mfma_f32_16x16x32_bf16 v[48:51], v[212:215], v[156:159], v[48:51]
	v_mfma_f32_16x16x32_bf16 v[40:43], v[204:207], v[164:167], v[40:43]
	v_mfma_f32_16x16x32_bf16 v[32:35], v[212:215], v[164:167], v[32:35]
	v_mfma_f32_16x16x32_bf16 v[24:27], v[204:207], v[176:179], v[24:27]
	v_mfma_f32_16x16x32_bf16 v[16:19], v[212:215], v[176:179], v[16:19]
	v_mfma_f32_16x16x32_bf16 v[12:15], v[204:207], v[196:199], v[12:15]
	v_mfma_f32_16x16x32_bf16 v[8:11], v[212:215], v[196:199], v[8:11]
	v_mfma_f32_16x16x32_bf16 v[56:59], v[208:211], v[160:163], v[56:59]
	v_mfma_f32_16x16x32_bf16 v[48:51], v[216:219], v[160:163], v[48:51]
	v_mfma_f32_16x16x32_bf16 v[40:43], v[208:211], v[172:175], v[40:43]
	v_mfma_f32_16x16x32_bf16 v[32:35], v[216:219], v[172:175], v[32:35]
	v_mfma_f32_16x16x32_bf16 v[24:27], v[208:211], v[180:183], v[24:27]
	v_mfma_f32_16x16x32_bf16 v[16:19], v[216:219], v[180:183], v[16:19]
	v_mfma_f32_16x16x32_bf16 v[12:15], v[208:211], v[200:203], v[12:15]
	v_mfma_f32_16x16x32_bf16 v[8:11], v[216:219], v[200:203], v[8:11]
	s_andn2_b64 vcc, exec, s[14:15]
	s_mov_b64 s[16:17], -1
	s_mov_b64 s[14:15], 0
	s_mov_b64 s[18:19], 0x100
	s_cbranch_vccnz .Ldb_PLE0_xl

; __device__ __forceinline__ u32x4 pack8(const f32x4 a, const f32x4 b) { u32x4 w; w.x = cvt_pk_bf16(a[0], a[1]); w.y = cvt_pk_bf16(a[2], a[3]); w.z = cvt_pk_bf16(b[0], b[1]); w.w = cvt_pk_bf16(b[2], b[3]); return w; }
; #define MEMFENCE asm volatile("" ::: "memory")
;     template <int KIND> __device__ __forceinline__ void run(f32x4 (&acc)[2][2][4][2], const Unit& u, int tid_in) const {
;     ...
;         if constexpr (KIND == K_PP) {
; #pragma unroll
;             for (int ai = 0; ai < 2; ++ai)
; #pragma unroll
;                 for (int m = 0; m < 4; ++m)
; #pragma unroll
;                     for (int bj = 0; bj < 2; ++bj) { scr[((ai * 4 + m) * 2 + bj) * 512 + tid] = pack8(acc[ai][bj][m][0], acc[ai][bj][m][1]); if (bj == 1) MEMFENCE; }
;         }
.Ldb_PLE0_young:
	s_setprio 3
	s_mov_b32 s101, 2
	s_branch .Ldb_PLE0_exit
.Ldb_PLE0_exit:
	s_lshl_b32 s4, s42, 17
	s_and_b32 s4, s4, 0x20000
	v_mov_b32_e32 v140, v136
	s_add_u32 s4, s38, s4
	s_addc_u32 s5, s39, 0
	v_ashrrev_i32_e32 v141, 31, v140
	v_cvt_pk_bf16_f32 v132, v132, v133
	v_cvt_pk_bf16_f32 v133, v134, v135
	v_cvt_pk_bf16_f32 v134, v128, v129
	v_lshl_add_u64 v[128:129], v[140:141], 4, s[4:5]
	s_movk_i32 s4, 0x2000
	v_cvt_pk_bf16_f32 v135, v130, v131
	global_store_dwordx4 v[128:129], v[132:135], off
	v_cvt_pk_bf16_f32 v120, v120, v121
	v_cvt_pk_bf16_f32 v121, v122, v123
	v_cvt_pk_bf16_f32 v122, v112, v113
	v_add_co_u32_e32 v112, vcc, s4, v128
	v_cvt_pk_bf16_f32 v123, v114, v115
	s_movk_i32 s4, 0x6000
	s_nop 0
	v_addc_co_u32_e32 v113, vcc, 0, v129, vcc
	global_store_dwordx4 v[112:113], v[120:123], off
	v_cvt_pk_bf16_f32 v112, v124, v125
	v_cvt_pk_bf16_f32 v113, v126, v127
	v_cvt_pk_bf16_f32 v114, v116, v117
	v_add_co_u32_e32 v116, vcc, s49, v128
	v_cvt_pk_bf16_f32 v115, v118, v119
	s_mov_b32 s42, s41
	s_nop 0
	v_addc_co_u32_e32 v117, vcc, 0, v129, vcc
	global_store_dwordx4 v[116:117], v[112:115], off
	v_cvt_pk_bf16_f32 v104, v104, v105
	v_cvt_pk_bf16_f32 v105, v106, v107
	v_cvt_pk_bf16_f32 v106, v96, v97
	v_add_co_u32_e32 v96, vcc, s4, v128
	v_cvt_pk_bf16_f32 v107, v98, v99
	s_mov_b32 s4, 0xa000
	s_nop 0
	v_addc_co_u32_e32 v97, vcc, 0, v129, vcc
	global_store_dwordx4 v[96:97], v[104:107], off
	v_cvt_pk_bf16_f32 v96, v108, v109
	v_cvt_pk_bf16_f32 v97, v110, v111
	v_cvt_pk_bf16_f32 v98, v100, v101
	v_add_co_u32_e32 v100, vcc, s77, v128
	v_cvt_pk_bf16_f32 v99, v102, v103
	s_mov_b64 s[12:13], s[8:9]
	s_nop 0
	v_addc_co_u32_e32 v101, vcc, 0, v129, vcc
	global_store_dwordx4 v[100:101], v[96:99], off
	v_cvt_pk_bf16_f32 v88, v88, v89
	v_cvt_pk_bf16_f32 v89, v90, v91
	v_cvt_pk_bf16_f32 v90, v80, v81
	v_add_co_u32_e32 v80, vcc, s4, v128
	v_cvt_pk_bf16_f32 v91, v82, v83
	s_mov_b32 s4, 0xc000
	s_nop 0
	v_addc_co_u32_e32 v81, vcc, 0, v129, vcc
	global_store_dwordx4 v[80:81], v[88:91], off
	v_cvt_pk_bf16_f32 v80, v92, v93
	v_cvt_pk_bf16_f32 v81, v94, v95
	v_cvt_pk_bf16_f32 v82, v84, v85
	v_add_co_u32_e32 v84, vcc, s4, v128
	s_mov_b32 s4, 0xe000
	s_nop 0
	v_addc_co_u32_e32 v85, vcc, 0, v129, vcc
	v_cvt_pk_bf16_f32 v83, v86, v87
	global_store_dwordx4 v[84:85], v[80:83], off
	v_cvt_pk_bf16_f32 v76, v76, v77
	v_cvt_pk_bf16_f32 v77, v78, v79
	v_cvt_pk_bf16_f32 v78, v72, v73
	v_add_co_u32_e32 v72, vcc, s4, v128
	v_cvt_pk_bf16_f32 v79, v74, v75
	s_mov_b32 s4, 0x12000
	s_nop 0
	v_addc_co_u32_e32 v73, vcc, 0, v129, vcc
	global_store_dwordx4 v[72:73], v[76:79], off
	v_cvt_pk_bf16_f32 v68, v68, v69
	v_cvt_pk_bf16_f32 v69, v70, v71
	v_cvt_pk_bf16_f32 v70, v64, v65
	v_add_co_u32_e32 v64, vcc, s91, v128
	v_cvt_pk_bf16_f32 v71, v66, v67
	s_mov_b64 s[10:11], s[6:7]
	s_nop 0
	v_addc_co_u32_e32 v65, vcc, 0, v129, vcc
	global_store_dwordx4 v[64:65], v[68:71], off
	v_cvt_pk_bf16_f32 v56, v56, v57
	v_cvt_pk_bf16_f32 v57, v58, v59
	v_cvt_pk_bf16_f32 v58, v48, v49
	v_add_co_u32_e32 v48, vcc, s4, v128
	v_cvt_pk_bf16_f32 v59, v50, v51
	s_mov_b32 s4, 0x14000
	s_nop 0
	v_addc_co_u32_e32 v49, vcc, 0, v129, vcc
	global_store_dwordx4 v[48:49], v[56:59], off
	v_cvt_pk_bf16_f32 v48, v60, v61
	v_cvt_pk_bf16_f32 v49, v62, v63
	v_cvt_pk_bf16_f32 v50, v52, v53
	v_add_co_u32_e32 v52, vcc, s4, v128
	s_mov_b32 s4, 0x16000
	s_nop 0
	v_addc_co_u32_e32 v53, vcc, 0, v129, vcc
	v_cvt_pk_bf16_f32 v51, v54, v55
	global_store_dwordx4 v[52:53], v[48:51], off
	v_cvt_pk_bf16_f32 v40, v40, v41
	v_cvt_pk_bf16_f32 v41, v42, v43
	v_cvt_pk_bf16_f32 v42, v32, v33
	v_add_co_u32_e32 v32, vcc, s4, v128
	v_cvt_pk_bf16_f32 v43, v34, v35
	s_mov_b32 s4, 0x18000
	s_nop 0
	v_addc_co_u32_e32 v33, vcc, 0, v129, vcc
	global_store_dwordx4 v[32:33], v[40:43], off
	v_cvt_pk_bf16_f32 v32, v44, v45
	v_cvt_pk_bf16_f32 v33, v46, v47
	v_cvt_pk_bf16_f32 v34, v36, v37
	v_add_co_u32_e32 v36, vcc, s4, v128
	s_mov_b32 s4, 0x1a000
	s_nop 0
	v_addc_co_u32_e32 v37, vcc, 0, v129, vcc
	v_cvt_pk_bf16_f32 v35, v38, v39
	global_store_dwordx4 v[36:37], v[32:35], off
	v_cvt_pk_bf16_f32 v24, v24, v25
	v_cvt_pk_bf16_f32 v25, v26, v27
	v_cvt_pk_bf16_f32 v26, v16, v17
	v_add_co_u32_e32 v16, vcc, s4, v128
	v_cvt_pk_bf16_f32 v27, v18, v19
	s_mov_b32 s4, 0x1c000
	s_nop 0
	v_addc_co_u32_e32 v17, vcc, 0, v129, vcc
	global_store_dwordx4 v[16:17], v[24:27], off
	v_cvt_pk_bf16_f32 v16, v28, v29
	v_cvt_pk_bf16_f32 v17, v30, v31
	v_cvt_pk_bf16_f32 v18, v20, v21
	v_add_co_u32_e32 v20, vcc, s4, v128
	v_cvt_pk_bf16_f32 v19, v22, v23
	s_nop 1
	v_addc_co_u32_e32 v21, vcc, 0, v129, vcc
	global_store_dwordx4 v[20:21], v[16:19], off
	v_cvt_pk_bf16_f32 v12, v12, v13
	v_cvt_pk_bf16_f32 v13, v14, v15
	v_cvt_pk_bf16_f32 v14, v8, v9
	v_add_co_u32_e32 v8, vcc, 0x1e000, v128
	v_cvt_pk_bf16_f32 v15, v10, v11
	s_nop 1
	v_addc_co_u32_e32 v9, vcc, 0, v129, vcc
	global_store_dwordx4 v[8:9], v[12:15], off
	s_and_b64 vcc, exec, s[2:3]
	s_cbranch_vccz .LBB0_1257
	s_cmp_eq_u32 s101, 2
	s_cbranch_scc0 .Ldbj_PLE0_pe
	s_barrier

; #define G_STAGE(bufoff, gbase, o0, h64) do { \
;         __builtin_amdgcn_global_load_lds((const unsigned*)((const char*)(gbase) + (o0)), (LAS unsigned*)(lds + (bufoff) + ldsw), 16, 0, 0); \
;         __builtin_amdgcn_global_load_lds((const unsigned*)((const char*)(gbase) + (h64) + (o0)), (LAS unsigned*)(lds + (bufoff) + ldsw + 8192), 16, 0, 0); } while (0)
; #define G_LDA(dst, b, h) do { _Pragma("unroll") for (int m = 0; m < 4; ++m) _Pragma("unroll") for (int k = 0; k < 2; ++k) dst[m][k] = *(const LAS bf16x8*)(lds + G_SA(b, h) + aoff + m * 2048 + k * 1024); } while (0)
; #define G_LDB(dst, b, h) do { _Pragma("unroll") for (int n = 0; n < 2; ++n) _Pragma("unroll") for (int k = 0; k < 2; ++k) dst[n][k] = *(const LAS bf16x8*)(lds + G_SB(b, h) + boff + n * 2048 + k * 1024); } while (0)
; #define G_WAIT_V(n) asm volatile("s_waitcnt vmcnt(" #n ")" ::: "memory")
; #define G_WAIT_L(n) asm volatile("s_waitcnt lgkmcnt(" #n ")" ::: "memory")
; #define G_BAR __builtin_amdgcn_s_barrier()
; #define G_SCHED __builtin_amdgcn_sched_barrier(0)
;     ...
;             G_LDB(B0, 0, 0); G_SCHED; G_LDA(At, 0, 0); G_STAGE(G_SA(1, 1), a1 + chA, cA0, qA);
;             G_WAIT_L(8); G_BAR; G_WAIT_L(0); G_MMA(0, 0, At, B0); G_BAR; G_SCHED;
;             G_LDB(B1, 0, 1); G_STAGE(G_SB(0, 0), b2, cB0, qB);
;             G_BAR; G_WAIT_L(0); G_MMA(0, 1, At, B1); G_BAR;
;             G_LDA(At, 0, 1); G_STAGE(G_SA(0, 0), a2, cA0, qA);
;             G_BAR; G_WAIT_L(0); G_MMA(1, 0, At, B0); G_BAR; G_SCHED;
;             G_STAGE(G_SB(0, 1), b2 + chB, cB0, qB);
;             G_WAIT_V(6); G_BAR; G_MMA(1, 1, At, B1); G_BAR;
.LBB0_1283:
	s_add_u32 s4, s2, 0xfffc0080
	s_addc_u32 s5, s3, -1
	s_add_i32 s25, 0, 0x10000
	ds_read_b128 v[136:139], v255 offset:0
	ds_read_b128 v[140:143], v255 offset:1024
	ds_read_b128 v[144:147], v255 offset:2048
	ds_read_b128 v[148:151], v255 offset:3072
	s_cmp_eq_u32 s24, 12
	s_cselect_b32 s5, s19, s5
	s_cselect_b32 s4, s18, s4
	s_cselect_b32 s41, s21, s23
	s_cselect_b32 s40, s20, s22
	s_add_i32 m0, s29, 0xc000
	ds_read_b128 v[152:155], v182
	ds_read_b128 v[160:163], v182 offset:1024
	ds_read_b128 v[164:167], v182 offset:2048
	ds_read_b128 v[172:175], v182 offset:3072
	ds_read_b128 v[176:179], v182 offset:4096
	ds_read_b128 v[196:199], v182 offset:5120
	ds_read_b128 v[200:203], v182 offset:6144
	ds_read_b128 v[204:207], v182 offset:7168
	global_load_lds_dwordx4 v158, s[2:3]
	s_add_i32 m0, s29, 0xe000
	s_nop 0
	s_add_u32 vcc_lo, s2, s0
	s_addc_u32 vcc_hi, s3, s1
	global_load_lds_dwordx4 v158, vcc
	s_waitcnt lgkmcnt(8)
	s_barrier
	s_waitcnt lgkmcnt(0)
	v_mfma_f32_16x16x32_bf16 v[132:135], v[136:139], v[152:155], v[132:135]
	v_mfma_f32_16x16x32_bf16 v[128:131], v[144:147], v[152:155], v[128:131]
	v_mfma_f32_16x16x32_bf16 v[116:119], v[136:139], v[164:167], v[116:119]
	v_mfma_f32_16x16x32_bf16 v[112:115], v[144:147], v[164:167], v[112:115]
	v_mfma_f32_16x16x32_bf16 v[100:103], v[136:139], v[176:179], v[100:103]
	v_mfma_f32_16x16x32_bf16 v[96:99], v[144:147], v[176:179], v[96:99]
	v_mfma_f32_16x16x32_bf16 v[84:87], v[136:139], v[200:203], v[84:87]
	v_mfma_f32_16x16x32_bf16 v[80:83], v[144:147], v[200:203], v[80:83]
	v_mfma_f32_16x16x32_bf16 v[132:135], v[140:143], v[160:163], v[132:135]
	v_mfma_f32_16x16x32_bf16 v[128:131], v[148:151], v[160:163], v[128:131]
	v_mfma_f32_16x16x32_bf16 v[116:119], v[140:143], v[172:175], v[116:119]
	v_mfma_f32_16x16x32_bf16 v[112:115], v[148:151], v[172:175], v[112:115]
	v_mfma_f32_16x16x32_bf16 v[100:103], v[140:143], v[196:199], v[100:103]
	v_mfma_f32_16x16x32_bf16 v[96:99], v[148:151], v[196:199], v[96:99]
	v_mfma_f32_16x16x32_bf16 v[84:87], v[140:143], v[204:207], v[84:87]
	v_mfma_f32_16x16x32_bf16 v[80:83], v[148:151], v[204:207], v[80:83]
	s_barrier
	s_add_i32 s44, 0, 0x14000
	s_add_i32 s25, s25, s27
	s_mov_b32 m0, s25
	ds_read_b128 v[208:211], v255 offset:16384
	ds_read_b128 v[212:215], v255 offset:17408
	ds_read_b128 v[216:219], v255 offset:18432
	ds_read_b128 v[220:223], v255 offset:19456
	global_load_lds_dwordx4 v156, s[40:41]
	s_add_i32 m0, s25, 0x2000
	s_nop 0
	s_add_u32 vcc_lo, s40, s0
	s_addc_u32 vcc_hi, s41, s1
	global_load_lds_dwordx4 v156, vcc
	s_barrier
	s_waitcnt lgkmcnt(0)
	v_mfma_f32_16x16x32_bf16 v[124:127], v[208:211], v[152:155], v[124:127]
	v_mfma_f32_16x16x32_bf16 v[120:123], v[216:219], v[152:155], v[120:123]
	v_mfma_f32_16x16x32_bf16 v[108:111], v[208:211], v[164:167], v[108:111]
	v_mfma_f32_16x16x32_bf16 v[104:107], v[216:219], v[164:167], v[104:107]
	v_mfma_f32_16x16x32_bf16 v[92:95], v[208:211], v[176:179], v[92:95]
	v_mfma_f32_16x16x32_bf16 v[88:91], v[216:219], v[176:179], v[88:91]
	v_mfma_f32_16x16x32_bf16 v[76:79], v[208:211], v[200:203], v[76:79]
	v_mfma_f32_16x16x32_bf16 v[72:75], v[216:219], v[200:203], v[72:75]
	v_mfma_f32_16x16x32_bf16 v[124:127], v[212:215], v[160:163], v[124:127]
	v_mfma_f32_16x16x32_bf16 v[120:123], v[220:223], v[160:163], v[120:123]
	v_mfma_f32_16x16x32_bf16 v[108:111], v[212:215], v[172:175], v[108:111]
	v_mfma_f32_16x16x32_bf16 v[104:107], v[220:223], v[172:175], v[104:107]
	v_mfma_f32_16x16x32_bf16 v[92:95], v[212:215], v[196:199], v[92:95]
	v_mfma_f32_16x16x32_bf16 v[88:91], v[220:223], v[196:199], v[88:91]
	v_mfma_f32_16x16x32_bf16 v[76:79], v[212:215], v[204:207], v[76:79]
	v_mfma_f32_16x16x32_bf16 v[72:75], v[220:223], v[204:207], v[72:75]
	s_barrier
	s_mov_b32 m0, s29
	v_lshl_add_u64 v[224:225], s[4:5], 0, v[2:3]
	ds_read_b128 v[152:155], v182 offset:16384
	ds_read_b128 v[160:163], v182 offset:17408
	ds_read_b128 v[164:167], v182 offset:18432
	ds_read_b128 v[172:175], v182 offset:19456
	ds_read_b128 v[176:179], v182 offset:20480
	ds_read_b128 v[196:199], v182 offset:21504
	ds_read_b128 v[200:203], v182 offset:22528
	ds_read_b128 v[204:207], v182 offset:23552
	global_load_lds_dwordx4 v2, s[4:5]
	s_mov_b32 m0, s30
	s_nop 0
	s_add_u32 vcc_lo, s4, s0
	s_addc_u32 vcc_hi, s5, s1
	global_load_lds_dwordx4 v2, vcc
	s_barrier
	s_waitcnt lgkmcnt(0)
	v_mfma_f32_16x16x32_bf16 v[68:71], v[136:139], v[152:155], v[68:71]
	v_mfma_f32_16x16x32_bf16 v[64:67], v[144:147], v[152:155], v[64:67]
	v_mfma_f32_16x16x32_bf16 v[52:55], v[136:139], v[164:167], v[52:55]
	v_mfma_f32_16x16x32_bf16 v[48:51], v[144:147], v[164:167], v[48:51]
	v_mfma_f32_16x16x32_bf16 v[36:39], v[136:139], v[176:179], v[36:39]
	v_mfma_f32_16x16x32_bf16 v[32:35], v[144:147], v[176:179], v[32:35]
	v_mfma_f32_16x16x32_bf16 v[20:23], v[136:139], v[200:203], v[20:23]
	v_mfma_f32_16x16x32_bf16 v[16:19], v[144:147], v[200:203], v[16:19]
	v_mfma_f32_16x16x32_bf16 v[68:71], v[140:143], v[160:163], v[68:71]
	v_mfma_f32_16x16x32_bf16 v[64:67], v[148:151], v[160:163], v[64:67]
	v_mfma_f32_16x16x32_bf16 v[52:55], v[140:143], v[172:175], v[52:55]
	v_mfma_f32_16x16x32_bf16 v[48:51], v[148:151], v[172:175], v[48:51]
	v_mfma_f32_16x16x32_bf16 v[36:39], v[140:143], v[196:199], v[36:39]
	v_mfma_f32_16x16x32_bf16 v[32:35], v[148:151], v[196:199], v[32:35]
	v_mfma_f32_16x16x32_bf16 v[20:23], v[140:143], v[204:207], v[20:23]
	v_mfma_f32_16x16x32_bf16 v[16:19], v[148:151], v[204:207], v[16:19]
	s_barrier
	s_add_i32 s100, s44, s27
	s_mov_b32 m0, s100
	s_nop 0
	s_add_u32 vcc_lo, s40, s54
	s_addc_u32 vcc_hi, s41, s55
	global_load_lds_dwordx4 v156, vcc
	s_add_i32 m0, s100, 0x2000
	s_nop 0
	s_add_u32 vcc_lo, s40, s58
	s_addc_u32 vcc_hi, s41, s59
	global_load_lds_dwordx4 v156, vcc
	s_waitcnt vmcnt(6)
	s_barrier
; #define G_STAGE(bufoff, gbase, o0, h64) do { \
;         __builtin_amdgcn_global_load_lds((const unsigned*)((const char*)(gbase) + (o0)), (LAS unsigned*)(lds + (bufoff) + ldsw), 16, 0, 0); \
;         __builtin_amdgcn_global_load_lds((const unsigned*)((const char*)(gbase) + (h64) + (o0)), (LAS unsigned*)(lds + (bufoff) + ldsw + 8192), 16, 0, 0); } while (0)
; #define G_LDA(dst, b, h) do { _Pragma("unroll") for (int m = 0; m < 4; ++m) _Pragma("unroll") for (int k = 0; k < 2; ++k) dst[m][k] = *(const LAS bf16x8*)(lds + G_SA(b, h) + aoff + m * 2048 + k * 1024); } while (0)
; #define G_LDB(dst, b, h) do { _Pragma("unroll") for (int n = 0; n < 2; ++n) _Pragma("unroll") for (int k = 0; k < 2; ++k) dst[n][k] = *(const LAS bf16x8*)(lds + G_SB(b, h) + boff + n * 2048 + k * 1024); } while (0)
; #define G_WAIT_V(n) asm volatile("s_waitcnt vmcnt(" #n ")" ::: "memory")
; #define G_WAIT_L(n) asm volatile("s_waitcnt lgkmcnt(" #n ")" ::: "memory")
; #define G_BAR __builtin_amdgcn_s_barrier()
; #define G_SCHED __builtin_amdgcn_sched_barrier(0)
;     ...
;             G_WAIT_V(6); G_BAR; G_MMA(1, 1, At, B1); G_BAR;
;             G_LDB(B0, 1, 0); G_SCHED; G_LDA(At, 1, 0); G_STAGE(G_SA(0, 1), a2 + chA, cA0, qA);
;             G_WAIT_L(8); G_BAR; G_WAIT_L(0); G_MMA(0, 0, At, B0); G_BAR; G_SCHED;
;             G_LDB(B1, 1, 1); G_STAGE(G_SB(1, 0), b3, cB0, qB);
;             G_BAR; G_WAIT_L(0); G_MMA(0, 1, At, B1); G_BAR;
;             G_LDA(At, 1, 1); G_STAGE(G_SA(1, 0), a3, cA0, qA);
	v_mfma_f32_16x16x32_bf16 v[60:63], v[208:211], v[152:155], v[60:63]
	v_mfma_f32_16x16x32_bf16 v[56:59], v[216:219], v[152:155], v[56:59]
	v_mfma_f32_16x16x32_bf16 v[44:47], v[208:211], v[164:167], v[44:47]
	v_mfma_f32_16x16x32_bf16 v[40:43], v[216:219], v[164:167], v[40:43]
	v_mfma_f32_16x16x32_bf16 v[28:31], v[208:211], v[176:179], v[28:31]
	v_mfma_f32_16x16x32_bf16 v[24:27], v[216:219], v[176:179], v[24:27]
	v_mfma_f32_16x16x32_bf16 v[12:15], v[208:211], v[200:203], v[12:15]
	v_mfma_f32_16x16x32_bf16 v[8:11], v[216:219], v[200:203], v[8:11]
	v_mfma_f32_16x16x32_bf16 v[60:63], v[212:215], v[160:163], v[60:63]
	v_mfma_f32_16x16x32_bf16 v[56:59], v[220:223], v[160:163], v[56:59]
	v_mfma_f32_16x16x32_bf16 v[44:47], v[212:215], v[172:175], v[44:47]
	v_mfma_f32_16x16x32_bf16 v[40:43], v[220:223], v[172:175], v[40:43]
	v_mfma_f32_16x16x32_bf16 v[28:31], v[212:215], v[196:199], v[28:31]
	v_mfma_f32_16x16x32_bf16 v[24:27], v[220:223], v[196:199], v[24:27]
	v_mfma_f32_16x16x32_bf16 v[12:15], v[212:215], v[204:207], v[12:15]
	v_mfma_f32_16x16x32_bf16 v[8:11], v[220:223], v[204:207], v[8:11]
	s_barrier
	s_add_i32 s100, 0, 0x18000
	ds_read_b128 v[136:139], v255 offset:32768
	ds_read_b128 v[140:143], v255 offset:33792
	ds_read_b128 v[144:147], v255 offset:34816
	ds_read_b128 v[148:151], v255 offset:35840
	s_mov_b32 m0, s31
	ds_read_b128 v[152:155], v182 offset:32768
	ds_read_b128 v[160:163], v182 offset:33792
	ds_read_b128 v[164:167], v182 offset:34816
	ds_read_b128 v[172:175], v182 offset:35840
	ds_read_b128 v[176:179], v182 offset:36864
	ds_read_b128 v[196:199], v182 offset:37888
	ds_read_b128 v[200:203], v182 offset:38912
	ds_read_b128 v[204:207], v182 offset:39936
	s_add_u32 vcc_lo, s4, s54
	s_addc_u32 vcc_hi, s5, s55
	global_load_lds_dwordx4 v2, vcc
	s_mov_b32 m0, s34
	s_nop 0
	s_add_u32 vcc_lo, s4, s58
	s_addc_u32 vcc_hi, s5, s59
	global_load_lds_dwordx4 v2, vcc
	s_waitcnt lgkmcnt(8)
	s_barrier
	s_waitcnt lgkmcnt(0)
	v_mfma_f32_16x16x32_bf16 v[132:135], v[136:139], v[152:155], v[132:135]
	v_mfma_f32_16x16x32_bf16 v[128:131], v[144:147], v[152:155], v[128:131]
	v_mfma_f32_16x16x32_bf16 v[116:119], v[136:139], v[164:167], v[116:119]
	v_mfma_f32_16x16x32_bf16 v[112:115], v[144:147], v[164:167], v[112:115]
	v_mfma_f32_16x16x32_bf16 v[100:103], v[136:139], v[176:179], v[100:103]
	v_mfma_f32_16x16x32_bf16 v[96:99], v[144:147], v[176:179], v[96:99]
	v_mfma_f32_16x16x32_bf16 v[84:87], v[136:139], v[200:203], v[84:87]
	v_mfma_f32_16x16x32_bf16 v[80:83], v[144:147], v[200:203], v[80:83]
	v_mfma_f32_16x16x32_bf16 v[132:135], v[140:143], v[160:163], v[132:135]
	v_mfma_f32_16x16x32_bf16 v[128:131], v[148:151], v[160:163], v[128:131]
	v_mfma_f32_16x16x32_bf16 v[116:119], v[140:143], v[172:175], v[116:119]
	v_mfma_f32_16x16x32_bf16 v[112:115], v[148:151], v[172:175], v[112:115]
	v_mfma_f32_16x16x32_bf16 v[100:103], v[140:143], v[196:199], v[100:103]
	v_mfma_f32_16x16x32_bf16 v[96:99], v[148:151], v[196:199], v[96:99]
	v_mfma_f32_16x16x32_bf16 v[84:87], v[140:143], v[204:207], v[84:87]
	v_mfma_f32_16x16x32_bf16 v[80:83], v[148:151], v[204:207], v[80:83]
	s_barrier
	s_add_i32 s5, 0, 0x1c000
	s_add_i32 s4, s100, s27
	s_mov_b32 m0, s4
	ds_read_b128 v[208:211], v255 offset:49152
	ds_read_b128 v[212:215], v255 offset:50176
	ds_read_b128 v[216:219], v255 offset:51200
	ds_read_b128 v[220:223], v255 offset:52224
	s_add_u32 vcc_lo, s40, s46
	s_addc_u32 vcc_hi, s41, s47
	global_load_lds_dwordx4 v156, vcc
	s_add_i32 m0, s4, 0x2000
	s_nop 0
	s_add_u32 vcc_lo, s40, s62
	s_addc_u32 vcc_hi, s41, s63
	global_load_lds_dwordx4 v156, vcc
	s_barrier
; #define G_STAGE(bufoff, gbase, o0, h64) do { \
;         __builtin_amdgcn_global_load_lds((const unsigned*)((const char*)(gbase) + (o0)), (LAS unsigned*)(lds + (bufoff) + ldsw), 16, 0, 0); \
;         __builtin_amdgcn_global_load_lds((const unsigned*)((const char*)(gbase) + (h64) + (o0)), (LAS unsigned*)(lds + (bufoff) + ldsw + 8192), 16, 0, 0); } while (0)
; #define G_WAIT_V(n) asm volatile("s_waitcnt vmcnt(" #n ")" ::: "memory")
; #define G_WAIT_L(n) asm volatile("s_waitcnt lgkmcnt(" #n ")" ::: "memory")
; #define G_BAR __builtin_amdgcn_s_barrier()
; #define G_SCHED __builtin_amdgcn_sched_barrier(0)
;     ...
;             G_BAR; G_WAIT_L(0); G_MMA(1, 0, At, B0); G_BAR; G_SCHED;
;             G_STAGE(G_SB(1, 1), b3 + chB, cB0, qB);
;             G_WAIT_V(6); G_BAR; G_MMA(1, 1, At, B1); G_BAR;
	s_waitcnt lgkmcnt(0)
	v_mfma_f32_16x16x32_bf16 v[124:127], v[208:211], v[152:155], v[124:127]
	v_mfma_f32_16x16x32_bf16 v[120:123], v[216:219], v[152:155], v[120:123]
	v_mfma_f32_16x16x32_bf16 v[108:111], v[208:211], v[164:167], v[108:111]
	v_mfma_f32_16x16x32_bf16 v[104:107], v[216:219], v[164:167], v[104:107]
	v_mfma_f32_16x16x32_bf16 v[92:95], v[208:211], v[176:179], v[92:95]
	v_mfma_f32_16x16x32_bf16 v[88:91], v[216:219], v[176:179], v[88:91]
	v_mfma_f32_16x16x32_bf16 v[76:79], v[208:211], v[200:203], v[76:79]
	v_mfma_f32_16x16x32_bf16 v[72:75], v[216:219], v[200:203], v[72:75]
	v_mfma_f32_16x16x32_bf16 v[124:127], v[212:215], v[160:163], v[124:127]
	v_mfma_f32_16x16x32_bf16 v[120:123], v[220:223], v[160:163], v[120:123]
	v_mfma_f32_16x16x32_bf16 v[108:111], v[212:215], v[172:175], v[108:111]
	v_mfma_f32_16x16x32_bf16 v[104:107], v[220:223], v[172:175], v[104:107]
	v_mfma_f32_16x16x32_bf16 v[92:95], v[212:215], v[196:199], v[92:95]
	v_mfma_f32_16x16x32_bf16 v[88:91], v[220:223], v[196:199], v[88:91]
	v_mfma_f32_16x16x32_bf16 v[76:79], v[212:215], v[204:207], v[76:79]
	v_mfma_f32_16x16x32_bf16 v[72:75], v[220:223], v[204:207], v[72:75]
	s_barrier
	s_mov_b32 m0, s35
	v_lshl_add_u64 v[226:227], v[224:225], 0, s[46:47]
	ds_read_b128 v[152:155], v182 offset:49152
	ds_read_b128 v[160:163], v182 offset:50176
	ds_read_b128 v[164:167], v182 offset:51200
	ds_read_b128 v[172:175], v182 offset:52224
	ds_read_b128 v[176:179], v182 offset:53248
	ds_read_b128 v[196:199], v182 offset:54272
	ds_read_b128 v[200:203], v182 offset:55296
	ds_read_b128 v[204:207], v182 offset:56320
	global_load_lds_dwordx4 v[226:227], off
	v_lshl_add_u64 v[224:225], v[224:225], 0, s[62:63]
	s_mov_b32 m0, s36
	s_nop 0
	global_load_lds_dwordx4 v[224:225], off
	s_barrier
	s_waitcnt lgkmcnt(0)
	v_mfma_f32_16x16x32_bf16 v[68:71], v[136:139], v[152:155], v[68:71]
	v_mfma_f32_16x16x32_bf16 v[64:67], v[144:147], v[152:155], v[64:67]
	v_mfma_f32_16x16x32_bf16 v[52:55], v[136:139], v[164:167], v[52:55]
	v_mfma_f32_16x16x32_bf16 v[48:51], v[144:147], v[164:167], v[48:51]
	v_mfma_f32_16x16x32_bf16 v[36:39], v[136:139], v[176:179], v[36:39]
	v_mfma_f32_16x16x32_bf16 v[32:35], v[144:147], v[176:179], v[32:35]
	v_mfma_f32_16x16x32_bf16 v[20:23], v[136:139], v[200:203], v[20:23]
	v_mfma_f32_16x16x32_bf16 v[16:19], v[144:147], v[200:203], v[16:19]
	v_mfma_f32_16x16x32_bf16 v[68:71], v[140:143], v[160:163], v[68:71]
	v_mfma_f32_16x16x32_bf16 v[64:67], v[148:151], v[160:163], v[64:67]
	v_mfma_f32_16x16x32_bf16 v[52:55], v[140:143], v[172:175], v[52:55]
	v_mfma_f32_16x16x32_bf16 v[48:51], v[148:151], v[172:175], v[48:51]
	v_mfma_f32_16x16x32_bf16 v[36:39], v[140:143], v[196:199], v[36:39]
	v_mfma_f32_16x16x32_bf16 v[32:35], v[148:151], v[196:199], v[32:35]
	v_mfma_f32_16x16x32_bf16 v[20:23], v[140:143], v[204:207], v[20:23]
	v_mfma_f32_16x16x32_bf16 v[16:19], v[148:151], v[204:207], v[16:19]
	s_barrier
	s_add_i32 s4, s5, s27
	s_mov_b32 m0, s4
	s_nop 0
	s_add_u32 vcc_lo, s40, s64
	s_addc_u32 vcc_hi, s41, s65
	global_load_lds_dwordx4 v156, vcc
	s_add_i32 m0, s4, 0x2000
	s_nop 0
	s_add_u32 vcc_lo, s40, s66
	s_addc_u32 vcc_hi, s41, s67
	global_load_lds_dwordx4 v156, vcc
	s_add_i32 s24, s24, 2
	s_add_u32 s2, s2, 0x100
	s_addc_u32 s3, s3, 0
	s_add_u32 s22, s22, 0x100
	s_addc_u32 s23, s23, 0
	s_cmp_gt_u32 s24, 13
	s_waitcnt vmcnt(6)
	s_barrier
	v_mfma_f32_16x16x32_bf16 v[60:63], v[208:211], v[152:155], v[60:63]
	v_mfma_f32_16x16x32_bf16 v[56:59], v[216:219], v[152:155], v[56:59]
	v_mfma_f32_16x16x32_bf16 v[44:47], v[208:211], v[164:167], v[44:47]
	v_mfma_f32_16x16x32_bf16 v[40:43], v[216:219], v[164:167], v[40:43]
	v_mfma_f32_16x16x32_bf16 v[28:31], v[208:211], v[176:179], v[28:31]
	v_mfma_f32_16x16x32_bf16 v[24:27], v[216:219], v[176:179], v[24:27]
	v_mfma_f32_16x16x32_bf16 v[12:15], v[208:211], v[200:203], v[12:15]
	v_mfma_f32_16x16x32_bf16 v[8:11], v[216:219], v[200:203], v[8:11]
	v_mfma_f32_16x16x32_bf16 v[60:63], v[212:215], v[160:163], v[60:63]
	v_mfma_f32_16x16x32_bf16 v[56:59], v[220:223], v[160:163], v[56:59]
	v_mfma_f32_16x16x32_bf16 v[44:47], v[212:215], v[172:175], v[44:47]
	v_mfma_f32_16x16x32_bf16 v[40:43], v[220:223], v[172:175], v[40:43]
	v_mfma_f32_16x16x32_bf16 v[28:31], v[212:215], v[196:199], v[28:31]
	v_mfma_f32_16x16x32_bf16 v[24:27], v[220:223], v[196:199], v[24:27]
	v_mfma_f32_16x16x32_bf16 v[12:15], v[212:215], v[204:207], v[12:15]
	v_mfma_f32_16x16x32_bf16 v[8:11], v[220:223], v[204:207], v[8:11]
	s_cbranch_scc1 .Ldb_PLE1_xl

; __device__ __forceinline__ float sigmoidf_(float v) { return __builtin_amdgcn_rcpf(1.0f + __expf(-v)); }
; __device__ __forceinline__ void unpack8(const u32x4 w, f32x4& a, f32x4& b) { a[0] = bf_lo(w.x); a[1] = bf_hi(w.x); a[2] = bf_lo(w.y); a[3] = bf_hi(w.y); b[0] = bf_lo(w.z); b[1] = bf_hi(w.z); b[2] = bf_lo(w.w); b[3] = bf_hi(w.w); }
;     template <int KIND> __device__ __forceinline__ void run(f32x4 (&acc)[2][2][4][2], const Unit& u, int tid_in) const {
;     ...
;         if constexpr (KIND == K_PLE) {
;             const bf16_t* xsrc = mg; float rs[8]; get_rs(u, wr, fr, rs);
; #pragma unroll
;             for (int ai = 0; ai < 2; ++ai)
; #pragma unroll
;                 for (int mh = 0; mh < 2; ++mh) { u32x4 xv[2][2], pv[2][2];
; #pragma unroll
;                     for (int ml = 0; ml < 2; ++ml) { const int m = mh * 2 + ml; int row = rbase + ai * 128 + m * 16; asm volatile("" : "+v"(row));
; #pragma unroll
;                         for (int bj = 0; bj < 2; ++bj) { xv[ml][bj] = *(const u32x4*)(xsrc + (size_t)row * 1024 + u.pn * 256 + bj * 128 + cl); pv[ml][bj] = scr[((ai * 4 + m) * 2 + bj) * 512 + tid]; } }
; #pragma unroll
;                     for (int ml = 0; ml < 2; ++ml) { const int m = mh * 2 + ml; int row = rbase + ai * 128 + m * 16; asm volatile("" : "+v"(row)); float ss = 0.f; const float r = rs[ai * 4 + m];
; #pragma unroll
;                         for (int bj = 0; bj < 2; ++bj) { const size_t off = (size_t)row * 1024 + u.pn * 256 + bj * 128 + cl; f32x4 a = acc[ai][bj][m][0], b = acc[ai][bj][m][1], p0, p1, x0, x1;
;                             unpack8(pv[ml][bj], p0, p1); unpack8(xv[ml][bj], x0, x1);
; #pragma unroll
;                             for (int j = 0; j < 4; ++j) { a[j] = sigmoidf_(a[j] * r) * p0[j]; b[j] = sigmoidf_(b[j] * r) * p1[j]; }
.Ldb_PLE1_young:
	s_setprio 3
	s_mov_b32 s101, 2
	s_branch .Ldb_PLE1_exit
.Ldb_PLE1_exit:
	v_mov_b32_e32 v136, v180
	s_lshl_b32 s2, s33, 17
	v_readfirstlane_b32 s4, v136
	s_bfe_u32 s53, s4, 0x20006
	s_and_b32 s2, s2, 0x20000
	s_add_u32 s2, s43, s2
	s_addc_u32 s3, s50, 0
	s_lshl_b32 s5, s7, 8
	s_ashr_i32 s7, s4, 2
	s_andn2_b32 s7, s7, 63
	s_add_i32 s7, s7, s5
	s_lshl_b32 s5, s33, 10
	s_add_i32 s5, s5, 0
	s_and_b32 s4, s4, 0xffffff00
	v_and_b32_e32 v0, 15, v136
	s_add_i32 s5, s5, s4
	v_or_b32_e32 v183, s7, v0
	v_lshl_add_u32 v0, v0, 2, s5
	v_add_u32_e32 v0, 0x20010, v0
	v_mov_b32_e32 v138, v183
	v_bfe_u32 v140, v136, 4, 2
	ds_read2_b32 v[176:177], v0 offset1:16
	ds_read2_b32 v[172:173], v0 offset0:32 offset1:48
	ds_read2_b32 v[166:167], v0 offset0:128 offset1:144
	ds_read2_b32 v[160:161], v0 offset0:160 offset1:176
	s_lshl_b32 s22, s6, 8
	v_ashrrev_i32_e32 v139, 31, v138
	v_lshlrev_b32_e32 v137, 3, v140
	v_lshlrev_b64 v[138:139], 11, v[138:139]
	s_ashr_i32 s23, s22, 31
	v_lshl_or_b32 v162, s53, 5, v137
	v_lshl_add_u64 v[138:139], s[8:9], 0, v[138:139]
	s_lshl_b64 s[24:25], s[22:23], 1
	v_lshl_add_u64 v[138:139], v[138:139], 0, s[24:25]
	v_lshlrev_b32_e32 v0, 1, v162
	v_ashrrev_i32_e32 v137, 31, v136
	v_lshl_add_u64 v[138:139], v[138:139], 0, v[0:1]
	v_lshl_add_u64 v[164:165], v[136:137], 4, s[2:3]
	global_load_dwordx4 v[196:199], v[138:139], off
	global_load_dwordx4 v[200:203], v[164:165], off
	s_movk_i32 s2, 0x2000
	v_add_co_u32_e32 v136, vcc, s2, v164
	v_cmp_eq_u32_e64 s[40:41], 0, v140
	s_nop 0
	v_addc_co_u32_e32 v137, vcc, 0, v165, vcc
	global_load_dwordx4 v[204:207], v[138:139], off offset:256
	global_load_dwordx4 v[152:155], v[136:137], off
	v_add_co_u32_e32 v140, vcc, s49, v164
	v_or_b32_e32 v174, 16, v183
	s_nop 0
	v_addc_co_u32_e32 v141, vcc, 0, v165, vcc
	s_movk_i32 s2, 0x6000
	v_mov_b32_e32 v148, v174
	s_waitcnt lgkmcnt(0)
	v_mul_f32_e32 v132, v132, v176
	v_mul_f32_e32 v133, v133, v176
	v_add_co_u32_e32 v142, vcc, s2, v164
	v_mul_f32_e32 v132, 0xbfb8aa3b, v132
	v_mul_f32_e32 v133, 0xbfb8aa3b, v133
	v_ashrrev_i32_e32 v149, 31, v148
	v_addc_co_u32_e32 v143, vcc, 0, v165, vcc
	global_load_dwordx4 v[144:147], v[140:141], off
	global_load_dwordx4 v[136:139], v[142:143], off
	v_exp_f32_e32 v140, v132
	v_exp_f32_e32 v195, v133
	v_lshlrev_b64 v[132:133], 11, v[148:149]
	v_lshl_add_u64 v[132:133], s[8:9], 0, v[132:133]
	v_mul_f32_e32 v128, v128, v176
	v_lshl_add_u64 v[132:133], v[132:133], 0, s[24:25]
	v_mul_f32_e32 v128, 0xbfb8aa3b, v128
	v_lshl_add_u64 v[132:133], v[132:133], 0, v[0:1]
	v_exp_f32_e32 v175, v128
	v_add_f32_e32 v128, 1.0, v140
	global_load_dwordx4 v[148:151], v[132:133], off
	global_load_dwordx4 v[140:143], v[132:133], off offset:256
	v_mul_f32_e32 v129, v129, v176
	v_add_f32_e32 v175, 1.0, v175
	v_mul_f32_e32 v129, 0xbfb8aa3b, v129
	v_rcp_f32_e32 v212, v175
	v_add_f32_e32 v175, 1.0, v195
	v_exp_f32_e32 v195, v129
	v_mul_f32_e32 v134, v134, v176
	v_mul_f32_e32 v134, 0xbfb8aa3b, v134
	v_mul_f32_e32 v130, v130, v176
	v_rcp_f32_e32 v129, v175
	v_add_f32_e32 v175, 1.0, v195
	v_exp_f32_e32 v134, v134
	v_mul_f32_e32 v130, 0xbfb8aa3b, v130
	v_rcp_f32_e32 v213, v175
	v_exp_f32_e32 v175, v130
	v_mul_f32_e32 v130, v135, v176
	v_mul_f32_e32 v130, 0xbfb8aa3b, v130
	v_mul_f32_e32 v131, v131, v176
	v_add_f32_e32 v134, 1.0, v134
	v_exp_f32_e32 v135, v130
	v_mul_f32_e32 v131, 0xbfb8aa3b, v131
	v_rcp_f32_e32 v130, v134
	v_add_f32_e32 v134, 1.0, v175
	v_exp_f32_e32 v175, v131
	v_mov_b32_e32 v178, v183
	v_add_f32_e32 v135, 1.0, v135
	v_mov_b64_e32 v[184:185], s[10:11]
	v_rcp_f32_e32 v128, v128
	v_ashrrev_i32_e32 v179, 31, v178
	v_rcp_f32_e32 v131, v135
	v_add_f32_e32 v135, 1.0, v175
	v_mad_i64_i32 v[132:133], s[2:3], v178, s76, v[184:185]
	v_lshlrev_b64 v[184:185], 11, v[178:179]
	v_rcp_f32_e32 v134, v134
	v_rcp_f32_e32 v135, v135
	v_lshl_add_u64 v[184:185], s[12:13], 0, v[184:185]
	v_lshl_add_u64 v[184:185], v[184:185], 0, s[24:25]
	v_lshl_add_u64 v[184:185], v[184:185], 0, v[0:1]
	v_mov_b32_e32 v163, v1
	v_mul_f32_e32 v124, v124, v176
	s_waitcnt vmcnt(0)
; __device__ __forceinline__ float sigmoidf_(float v) { return __builtin_amdgcn_rcpf(1.0f + __expf(-v)); }
; __device__ __forceinline__ u32x4 pack8(const f32x4 a, const f32x4 b) { u32x4 w; w.x = cvt_pk_bf16(a[0], a[1]); w.y = cvt_pk_bf16(a[2], a[3]); w.z = cvt_pk_bf16(b[0], b[1]); w.w = cvt_pk_bf16(b[2], b[3]); return w; }
; __device__ __forceinline__ void unpack8(const u32x4 w, f32x4& a, f32x4& b) { a[0] = bf_lo(w.x); a[1] = bf_hi(w.x); a[2] = bf_lo(w.y); a[3] = bf_hi(w.y); b[0] = bf_lo(w.z); b[1] = bf_hi(w.z); b[2] = bf_lo(w.w); b[3] = bf_hi(w.w); }
; __device__ __forceinline__ unsigned pack4_fp8(float a, float b, float c, float d) { unsigned w = 0u; w = __builtin_amdgcn_cvt_pk_fp8_f32(a, b, w, false); w = __builtin_amdgcn_cvt_pk_fp8_f32(c, d, w, true); return w; }
;     template <int KIND> __device__ __forceinline__ void run(f32x4 (&acc)[2][2][4][2], const Unit& u, int tid_in) const {
;     ...
;                     for (int ml = 0; ml < 2; ++ml) { const int m = mh * 2 + ml; int row = rbase + ai * 128 + m * 16; asm volatile("" : "+v"(row)); float ss = 0.f; const float r = rs[ai * 4 + m];
; #pragma unroll
;                         for (int bj = 0; bj < 2; ++bj) { const size_t off = (size_t)row * 1024 + u.pn * 256 + bj * 128 + cl; f32x4 a = acc[ai][bj][m][0], b = acc[ai][bj][m][1], p0, p1, x0, x1;
;                             unpack8(pv[ml][bj], p0, p1); unpack8(xv[ml][bj], x0, x1);
; #pragma unroll
;                             for (int j = 0; j < 4; ++j) { a[j] = sigmoidf_(a[j] * r) * p0[j]; b[j] = sigmoidf_(b[j] * r) * p1[j]; }
;                             const f32x4 o0 = x0 + a, o1 = x1 + b;
;                             *(u32x4*)(xb0 + off) = pack8(o0, o1);
;                             { u32x2 w8; w8.x = pack4_fp8(o0[0], o0[1], o0[2], o0[3]); w8.y = pack4_fp8(o1[0], o1[1], o1[2], o1[3]); *(u32x2*)((unsigned char*)zb + (size_t)row * (ZW * 2) + u.pn * 256 + bj * 128 + cl) = w8; }
;                             ss += (o0[0] * o0[0] + o0[1] * o0[1]) + (o0[2] * o0[2] + o0[3] * o0[3]) + (o1[0] * o1[0] + o1[1] * o1[1]) + (o1[2] * o1[2] + o1[3] * o1[3]); }
;                         ss += __shfl_xor(ss, 16); ss += __shfl_xor(ss, 32);
;                         if (fq == 0) ssq0[((size_t)u.pn * T_TOK + row) * 4 + wc] = ss; }
	v_lshlrev_b32_e32 v208, 16, v196
	v_and_b32_e32 v209, 0xffff0000, v196
	v_lshlrev_b32_e32 v196, 16, v197
	v_and_b32_e32 v197, 0xffff0000, v197
	v_lshlrev_b32_e32 v214, 16, v200
	v_and_b32_e32 v215, 0xffff0000, v200
	v_lshlrev_b32_e32 v200, 16, v201
	v_and_b32_e32 v201, 0xffff0000, v201
	v_lshlrev_b32_e32 v210, 16, v198
	v_and_b32_e32 v211, 0xffff0000, v198
	v_lshlrev_b32_e32 v198, 16, v199
	v_and_b32_e32 v199, 0xffff0000, v199
	v_lshlrev_b32_e32 v216, 16, v202
	v_and_b32_e32 v217, 0xffff0000, v202
	v_lshlrev_b32_e32 v202, 16, v203
	v_and_b32_e32 v203, 0xffff0000, v203
	v_pk_fma_f32 v[196:197], v[130:131], v[200:201], v[196:197]
	v_pk_fma_f32 v[200:201], v[128:129], v[214:215], v[208:209]
	v_pk_fma_f32 v[134:135], v[134:135], v[202:203], v[198:199]
	v_cvt_pk_bf16_f32 v128, v200, v201
	v_cvt_pk_bf16_f32 v129, v196, v197
	v_pk_fma_f32 v[198:199], v[212:213], v[216:217], v[210:211]
	v_mul_f32_e32 v0, v201, v201
	v_cvt_pk_bf16_f32 v130, v198, v199
	v_cvt_pk_bf16_f32 v131, v134, v135
	global_store_dwordx4 v[184:185], v[128:131], off
	v_mul_f32_e32 v124, 0xbfb8aa3b, v124
	v_mul_f32_e32 v120, v120, v176
	v_lshl_add_u64 v[128:129], v[132:133], 0, s[22:23]
	v_lshl_add_u64 v[130:131], v[128:129], 0, v[162:163]
	v_mul_f32_e32 v128, v197, v197
	v_fmac_f32_e32 v0, v200, v200
	v_fmac_f32_e32 v128, v196, v196
	v_exp_f32_e32 v124, v124
	v_mul_f32_e32 v120, 0xbfb8aa3b, v120
	v_mul_f32_e32 v122, v122, v176
	v_mov_b32_e32 v203, v1
	v_add_f32_e32 v0, v0, v128
	v_mul_f32_e32 v128, v199, v199
	v_exp_f32_e32 v175, v120
	v_mul_f32_e32 v122, 0xbfb8aa3b, v122
	v_cvt_pk_fp8_f32 v203, v198, v199
	v_fmac_f32_e32 v128, v198, v198
	v_mul_f32_e32 v120, v125, v176
	v_lshlrev_b32_e32 v198, 16, v152
	v_and_b32_e32 v199, 0xffff0000, v152
	v_mul_f32_e32 v126, v126, v176
	v_exp_f32_e32 v152, v122
	v_mul_f32_e32 v122, v127, v176
	v_mul_f32_e32 v120, 0xbfb8aa3b, v120
	v_mul_f32_e32 v121, v121, v176
	v_mul_f32_e32 v126, 0xbfb8aa3b, v126
	v_mul_f32_e32 v122, 0xbfb8aa3b, v122
	v_add_f32_e32 v124, 1.0, v124
	v_exp_f32_e32 v125, v120
	v_mul_f32_e32 v121, 0xbfb8aa3b, v121
	v_exp_f32_e32 v126, v126
	v_exp_f32_e32 v127, v122
	v_rcp_f32_e32 v120, v124
	v_add_f32_e32 v124, 1.0, v175
	v_exp_f32_e32 v175, v121
	v_mul_f32_e32 v123, v123, v176
	v_mov_b32_e32 v202, v1
	v_mul_f32_e32 v123, 0xbfb8aa3b, v123
	v_cvt_pk_fp8_f32 v202, v200, v201
	v_add_f32_e32 v125, 1.0, v125
	v_lshlrev_b32_e32 v200, 16, v154
	v_and_b32_e32 v201, 0xffff0000, v154
	v_add_f32_e32 v126, 1.0, v126
	v_add_f32_e32 v127, 1.0, v127
	v_exp_f32_e32 v154, v123
	v_rcp_f32_e32 v121, v125
	v_add_f32_e32 v125, 1.0, v175
	v_rcp_f32_e32 v122, v126
	v_rcp_f32_e32 v123, v127
	v_add_f32_e32 v0, v128, v0
	v_mul_f32_e32 v128, v135, v135
	v_rcp_f32_e32 v124, v124
	v_rcp_f32_e32 v125, v125
	v_fmac_f32_e32 v128, v134, v134
	v_add_f32_e32 v0, v128, v0
	v_lshlrev_b32_e32 v128, 16, v204
	v_and_b32_e32 v129, 0xffff0000, v204
	v_lshlrev_b32_e32 v132, 16, v205
	v_and_b32_e32 v133, 0xffff0000, v205
	v_add_f32_e32 v126, 1.0, v152
	v_lshlrev_b32_e32 v152, 16, v153
	v_and_b32_e32 v153, 0xffff0000, v153
	v_add_f32_e32 v127, 1.0, v154
	v_cvt_pk_fp8_f32 v203, v134, v135 op_sel:[0,0,1]
	v_lshlrev_b32_e32 v134, 16, v206
	v_and_b32_e32 v135, 0xffff0000, v206
	v_rcp_f32_e32 v126, v126
	v_rcp_f32_e32 v127, v127
	v_pk_fma_f32 v[122:123], v[122:123], v[152:153], v[132:133]
	v_pk_fma_f32 v[120:121], v[120:121], v[198:199], v[128:129]
	v_pk_fma_f32 v[128:129], v[124:125], v[200:201], v[134:135]
	v_mul_f32_e32 v124, v121, v121
	v_mul_f32_e32 v125, v123, v123
	v_fmac_f32_e32 v124, v120, v120
	v_fmac_f32_e32 v125, v122, v122
	v_cvt_pk_fp8_f32 v202, v196, v197 op_sel:[0,0,1]
	v_lshlrev_b32_e32 v196, 16, v207
	v_and_b32_e32 v197, 0xffff0000, v207
	v_lshlrev_b32_e32 v154, 16, v155
	v_and_b32_e32 v155, 0xffff0000, v155
	v_add_f32_e32 v124, v124, v125
	v_mul_f32_e32 v125, v129, v129
	v_pk_fma_f32 v[132:133], v[126:127], v[154:155], v[196:197]
	v_fmac_f32_e32 v125, v128, v128
	v_add_f32_e32 v124, v125, v124
	v_mul_f32_e32 v125, v133, v133
	v_fmac_f32_e32 v125, v132, v132
	v_add_f32_e32 v124, v125, v124
	v_add_f32_e32 v0, v0, v124
	v_xor_b32_e32 v124, 16, v190
	v_cmp_lt_i32_e32 vcc, v124, v192
	v_mov_b32_e32 v134, v1
	global_store_dwordx2 v[130:131], v[202:203], off
	v_cndmask_b32_e32 v124, v190, v124, vcc
	v_lshlrev_b32_e32 v124, 2, v124
	ds_bpermute_b32 v125, v124, v0
	v_cvt_pk_fp8_f32 v134, v120, v121
	v_cvt_pk_bf16_f32 v126, v120, v121
	v_xor_b32_e32 v120, 32, v190
	v_mov_b32_e32 v135, v1
	v_cmp_lt_i32_e32 vcc, v120, v192
	v_cvt_pk_fp8_f32 v135, v128, v129
	s_waitcnt lgkmcnt(0)
	v_add_f32_e32 v0, v0, v125
	v_cndmask_b32_e32 v120, v190, v120, vcc
	v_lshlrev_b32_e32 v125, 2, v120
	ds_bpermute_b32 v120, v125, v0
	v_cvt_pk_fp8_f32 v134, v122, v123 op_sel:[0,0,1]
	v_cvt_pk_fp8_f32 v135, v132, v133 op_sel:[0,0,1]
	v_cvt_pk_bf16_f32 v127, v122, v123
	v_cvt_pk_bf16_f32 v128, v128, v129
	v_cvt_pk_bf16_f32 v129, v132, v133
	global_store_dwordx4 v[184:185], v[126:129], off offset:256
	global_store_dwordx2 v[130:131], v[134:135], off offset:128
	s_and_saveexec_b64 s[2:3], s[40:41]
	s_cbranch_execz .LBB0_1286
	s_ashr_i32 s7, s6, 31
	s_lshl_b64 s[4:5], s[6:7], 19
	s_add_u32 s4, s39, s4
	s_addc_u32 s5, s42, s5
	s_waitcnt lgkmcnt(0)
	v_add_f32_e32 v0, v0, v120
	v_lshl_add_u64 v[120:121], v[178:179], 4, s[4:5]
	s_lshl_b32 s74, s53, 2
	v_lshl_add_u64 v[120:121], v[120:121], 0, s[74:75]
	global_store_dword v[120:121], v0, off
